# GEMM priority flips inverted: load segments at prio 2, MFMA clusters at prio 0
# speedup vs baseline: 1.0091x; 1.0024x over previous
; #define PG8_STAGE(bufoff, gbase, voff) do { _Pragma("unroll") for (int _i = 0; _i < 2; ++_i) \
;         __builtin_amdgcn_global_load_lds((const unsigned*)((const char*)(gbase) + (voff)[_i]), (LAS unsigned*)(lds + (bufoff) + ldsw + _i * 8192), 16, 0, 0); } while (0)
; #define PG8_LDA(dst, b, h) do { _Pragma("unroll") for (int m = 0; m < 4; ++m) _Pragma("unroll") for (int k = 0; k < 2; ++k) dst[m][k] = *(const LAS bf16x8*)(lds + PG8_SA(b, h) + aoff + m * 2048 + k * 1024); } while (0)
; #define PG8_LDB(dst, b, h) do { _Pragma("unroll") for (int n = 0; n < 2; ++n) _Pragma("unroll") for (int k = 0; k < 2; ++k) dst[n][k] = *(const LAS bf16x8*)(lds + PG8_SB(b, h) + boff + n * 2048 + k * 1024); } while (0)
; #define PG8_MMA(ai, bj, At, Bt) do { __builtin_amdgcn_s_setprio(1); _Pragma("unroll") for (int m = 0; m < 4; ++m) _Pragma("unroll") for (int n = 0; n < 2; ++n) _Pragma("unroll") for (int k = 0; k < 2; ++k) \
;         acc[ai][bj][m][n] = __builtin_amdgcn_mfma_f32_16x16x32_bf16(Bt[n][k], At[m][k], acc[ai][bj][m][n], 0, 0, 0); __builtin_amdgcn_s_setprio(0); } while (0)
; #define PG8_WAIT_V(n) asm volatile("s_waitcnt vmcnt(" #n ")" ::: "memory")
; #define PG8_WAIT_L(n) asm volatile("s_waitcnt lgkmcnt(" #n ")" ::: "memory")
; #define PG8_BAR __builtin_amdgcn_s_barrier()
; #define PG8_SCHED __builtin_amdgcn_sched_barrier(0)
; template <class Epi>
; __device__ __forceinline__ void gemm_phase(LAS unsigned char* lds, const Gemm g, int G, int c, const Epi& E) {
;     ...
;             const bool last = (t == nt - 2);
;             const char* a1 = cA + (size_t)(t + 1) * kstep;
;             const char* a2 = last ? nA : cA + (size_t)(t + 2) * kstep; const char* b2 = last ? nB : cB + (size_t)(t + 2) * kstep;
;             const char* a3 = a2 + kstep; const char* b3 = b2 + kstep;
;             PG8_LDB(B0, 0, 0); PG8_LDB(B1, 0, 1); PG8_SCHED; PG8_LDA(At, 0, 0); PG8_STAGE(PG8_SA(1, 1), a1 + hstepA, voffA);
;             PG8_WAIT_V(8); PG8_WAIT_L(0); PG8_BAR; PG8_MMA(0, 0, At, B0); PG8_MMA(0, 1, At, B1); PG8_BAR; PG8_SCHED;
;             PG8_LDA(At, 0, 1); PG8_STAGE(PG8_SB(0, 0), b2, voffB); PG8_STAGE(PG8_SB(0, 1), b2 + hstepB, voffB); PG8_STAGE(PG8_SA(0, 0), a2, voffA);
.LBB0_236:
	ds_read_b128 v[146:149], v152
	ds_read_b128 v[158:161], v152 offset:1024
	ds_read_b128 v[162:165], v152 offset:2048
	ds_read_b128 v[166:169], v152 offset:3072
	ds_read_b128 v[170:173], v153
	ds_read_b128 v[174:177], v153 offset:1024
	ds_read_b128 v[178:181], v153 offset:2048
	ds_read_b128 v[182:185], v153 offset:3072
	s_add_u32 s33, s4, 0xfffc0080
	s_addc_u32 s54, s5, -1
	s_cmp_eq_u32 s85, 12
	s_cselect_b32 s57, s47, s54
	s_cselect_b32 s56, s46, s33
	s_cselect_b32 s55, s7, s84
	s_cselect_b32 s54, s43, s45
	v_lshl_add_u64 v[218:219], s[4:5], 0, v[138:139]
	s_add_i32 m0, s11, 0xc000
	ds_read_b128 v[186:189], v154
	ds_read_b128 v[190:193], v154 offset:1024
	ds_read_b128 v[194:197], v154 offset:2048
	ds_read_b128 v[198:201], v154 offset:3072
	ds_read_b128 v[202:205], v154 offset:4096
	ds_read_b128 v[206:209], v154 offset:5120
	ds_read_b128 v[210:213], v154 offset:6144
	ds_read_b128 v[214:217], v154 offset:7168
	global_load_lds_dwordx4 v[218:219], off
	v_lshl_add_u64 v[218:219], s[4:5], 0, v[140:141]
	s_add_i32 m0, s11, 0xe000
	s_nop 0
	global_load_lds_dwordx4 v[218:219], off
	s_waitcnt vmcnt(8)
	s_waitcnt lgkmcnt(0)
	s_barrier
	s_setprio 0
	s_waitcnt lgkmcnt(0)
	v_mfma_f32_16x16x32_bf16 v[126:129], v[146:149], v[186:189], v[126:129]
	v_mfma_f32_16x16x32_bf16 v[122:125], v[162:165], v[186:189], v[122:125]
	v_mfma_f32_16x16x32_bf16 v[110:113], v[146:149], v[194:197], v[110:113]
	v_mfma_f32_16x16x32_bf16 v[106:109], v[162:165], v[194:197], v[106:109]
	v_mfma_f32_16x16x32_bf16 v[94:97], v[146:149], v[202:205], v[94:97]
	v_mfma_f32_16x16x32_bf16 v[90:93], v[162:165], v[202:205], v[90:93]
	v_mfma_f32_16x16x32_bf16 v[78:81], v[146:149], v[210:213], v[78:81]
	v_mfma_f32_16x16x32_bf16 v[74:77], v[162:165], v[210:213], v[74:77]
	v_mfma_f32_16x16x32_bf16 v[126:129], v[158:161], v[190:193], v[126:129]
	v_mfma_f32_16x16x32_bf16 v[122:125], v[166:169], v[190:193], v[122:125]
	v_mfma_f32_16x16x32_bf16 v[110:113], v[158:161], v[198:201], v[110:113]
	v_mfma_f32_16x16x32_bf16 v[106:109], v[166:169], v[198:201], v[106:109]
	v_mfma_f32_16x16x32_bf16 v[94:97], v[158:161], v[206:209], v[94:97]
	v_mfma_f32_16x16x32_bf16 v[90:93], v[166:169], v[206:209], v[90:93]
	v_mfma_f32_16x16x32_bf16 v[78:81], v[158:161], v[214:217], v[78:81]
	v_mfma_f32_16x16x32_bf16 v[74:77], v[166:169], v[214:217], v[74:77]
	s_setprio 2
	s_setprio 0
	v_mfma_f32_16x16x32_bf16 v[118:121], v[170:173], v[186:189], v[118:121]
	v_mfma_f32_16x16x32_bf16 v[114:117], v[178:181], v[186:189], v[114:117]
	v_mfma_f32_16x16x32_bf16 v[102:105], v[170:173], v[194:197], v[102:105]
	v_mfma_f32_16x16x32_bf16 v[98:101], v[178:181], v[194:197], v[98:101]
	v_mfma_f32_16x16x32_bf16 v[86:89], v[170:173], v[202:205], v[86:89]
	v_mfma_f32_16x16x32_bf16 v[82:85], v[178:181], v[202:205], v[82:85]
	v_mfma_f32_16x16x32_bf16 v[70:73], v[170:173], v[210:213], v[70:73]
	v_mfma_f32_16x16x32_bf16 v[66:69], v[178:181], v[210:213], v[66:69]
	v_mfma_f32_16x16x32_bf16 v[118:121], v[174:177], v[190:193], v[118:121]
	v_mfma_f32_16x16x32_bf16 v[114:117], v[182:185], v[190:193], v[114:117]
	v_mfma_f32_16x16x32_bf16 v[102:105], v[174:177], v[198:201], v[102:105]
	v_mfma_f32_16x16x32_bf16 v[98:101], v[182:185], v[198:201], v[98:101]
	v_mfma_f32_16x16x32_bf16 v[86:89], v[174:177], v[206:209], v[86:89]
	v_mfma_f32_16x16x32_bf16 v[82:85], v[182:185], v[206:209], v[82:85]
	v_mfma_f32_16x16x32_bf16 v[70:73], v[174:177], v[214:217], v[70:73]
	v_mfma_f32_16x16x32_bf16 v[66:69], v[182:185], v[214:217], v[66:69]
	s_setprio 2
	s_barrier
	s_add_i32 s33, s79, s60
	v_lshl_add_u64 v[218:219], s[54:55], 0, v[132:133]
	s_mov_b32 m0, s33
	ds_read_b128 v[186:189], v154 offset:16384
	ds_read_b128 v[190:193], v154 offset:17408
	ds_read_b128 v[194:197], v154 offset:18432
	ds_read_b128 v[198:201], v154 offset:19456
	ds_read_b128 v[202:205], v154 offset:20480
	ds_read_b128 v[206:209], v154 offset:21504
	ds_read_b128 v[210:213], v154 offset:22528
	ds_read_b128 v[214:217], v154 offset:23552
	global_load_lds_dwordx4 v[218:219], off
	s_add_i32 m0, s33, 0x2000
	s_add_u32 s62, s54, 0x40000
	v_lshl_add_u64 v[220:221], s[54:55], 0, v[136:137]
	s_addc_u32 s63, s55, 0
	s_add_i32 s33, s80, s60
	global_load_lds_dwordx4 v[220:221], off
	v_lshl_add_u64 v[222:223], s[62:63], 0, v[132:133]
	s_mov_b32 m0, s33
	v_lshl_add_u64 v[224:225], s[56:57], 0, v[134:135]
	global_load_lds_dwordx4 v[222:223], off
	v_lshl_add_u64 v[222:223], s[62:63], 0, v[136:137]
	s_add_i32 m0, s33, 0x2000
	s_nop 0
	global_load_lds_dwordx4 v[222:223], off
	v_lshl_add_u64 v[222:223], s[56:57], 0, v[130:131]
	s_mov_b32 m0, s11
	s_nop 0
	global_load_lds_dwordx4 v[222:223], off
	s_mov_b32 m0, s61
	s_nop 0
	global_load_lds_dwordx4 v[224:225], off
	s_waitcnt vmcnt(8)
	s_waitcnt lgkmcnt(0)
	s_barrier
; #define PG8_STAGE(bufoff, gbase, voff) do { _Pragma("unroll") for (int _i = 0; _i < 2; ++_i) \
;         __builtin_amdgcn_global_load_lds((const unsigned*)((const char*)(gbase) + (voff)[_i]), (LAS unsigned*)(lds + (bufoff) + ldsw + _i * 8192), 16, 0, 0); } while (0)
; #define PG8_LDA(dst, b, h) do { _Pragma("unroll") for (int m = 0; m < 4; ++m) _Pragma("unroll") for (int k = 0; k < 2; ++k) dst[m][k] = *(const LAS bf16x8*)(lds + PG8_SA(b, h) + aoff + m * 2048 + k * 1024); } while (0)
; #define PG8_LDB(dst, b, h) do { _Pragma("unroll") for (int n = 0; n < 2; ++n) _Pragma("unroll") for (int k = 0; k < 2; ++k) dst[n][k] = *(const LAS bf16x8*)(lds + PG8_SB(b, h) + boff + n * 2048 + k * 1024); } while (0)
; #define PG8_MMA(ai, bj, At, Bt) do { __builtin_amdgcn_s_setprio(1); _Pragma("unroll") for (int m = 0; m < 4; ++m) _Pragma("unroll") for (int n = 0; n < 2; ++n) _Pragma("unroll") for (int k = 0; k < 2; ++k) \
;         acc[ai][bj][m][n] = __builtin_amdgcn_mfma_f32_16x16x32_bf16(Bt[n][k], At[m][k], acc[ai][bj][m][n], 0, 0, 0); __builtin_amdgcn_s_setprio(0); } while (0)
; #define PG8_WAIT_V(n) asm volatile("s_waitcnt vmcnt(" #n ")" ::: "memory")
; #define PG8_WAIT_L(n) asm volatile("s_waitcnt lgkmcnt(" #n ")" ::: "memory")
; #define PG8_BAR __builtin_amdgcn_s_barrier()
; #define PG8_SCHED __builtin_amdgcn_sched_barrier(0)
; template <class Epi>
; __device__ __forceinline__ void gemm_phase(LAS unsigned char* lds, const Gemm g, int G, int c, const Epi& E) {
;     ...
;             PG8_WAIT_V(8); PG8_WAIT_L(0); PG8_BAR; PG8_MMA(1, 0, At, B0); PG8_MMA(1, 1, At, B1); PG8_BAR; PG8_SCHED;
;             PG8_LDB(B0, 1, 0); PG8_LDB(B1, 1, 1); PG8_SCHED; PG8_LDA(At, 1, 0); PG8_STAGE(PG8_SA(0, 1), a2 + hstepA, voffA);
;             PG8_WAIT_V(8); PG8_WAIT_L(0); PG8_BAR; PG8_MMA(0, 0, At, B0); PG8_MMA(0, 1, At, B1); PG8_BAR; PG8_SCHED;
	s_setprio 0
	s_waitcnt lgkmcnt(0)
	v_mfma_f32_16x16x32_bf16 v[62:65], v[146:149], v[186:189], v[62:65]
	v_mfma_f32_16x16x32_bf16 v[58:61], v[162:165], v[186:189], v[58:61]
	v_mfma_f32_16x16x32_bf16 v[46:49], v[146:149], v[194:197], v[46:49]
	v_mfma_f32_16x16x32_bf16 v[42:45], v[162:165], v[194:197], v[42:45]
	v_mfma_f32_16x16x32_bf16 v[30:33], v[146:149], v[202:205], v[30:33]
	v_mfma_f32_16x16x32_bf16 v[26:29], v[162:165], v[202:205], v[26:29]
	v_mfma_f32_16x16x32_bf16 v[14:17], v[146:149], v[210:213], v[14:17]
	v_mfma_f32_16x16x32_bf16 v[10:13], v[162:165], v[210:213], v[10:13]
	v_mfma_f32_16x16x32_bf16 v[62:65], v[158:161], v[190:193], v[62:65]
	v_mfma_f32_16x16x32_bf16 v[58:61], v[166:169], v[190:193], v[58:61]
	v_mfma_f32_16x16x32_bf16 v[46:49], v[158:161], v[198:201], v[46:49]
	v_mfma_f32_16x16x32_bf16 v[42:45], v[166:169], v[198:201], v[42:45]
	v_mfma_f32_16x16x32_bf16 v[30:33], v[158:161], v[206:209], v[30:33]
	v_mfma_f32_16x16x32_bf16 v[26:29], v[166:169], v[206:209], v[26:29]
	v_mfma_f32_16x16x32_bf16 v[14:17], v[158:161], v[214:217], v[14:17]
	v_mfma_f32_16x16x32_bf16 v[10:13], v[166:169], v[214:217], v[10:13]
	s_setprio 2
	s_setprio 0
	v_mfma_f32_16x16x32_bf16 v[54:57], v[170:173], v[186:189], v[54:57]
	v_mfma_f32_16x16x32_bf16 v[50:53], v[178:181], v[186:189], v[50:53]
	v_mfma_f32_16x16x32_bf16 v[38:41], v[170:173], v[194:197], v[38:41]
	v_mfma_f32_16x16x32_bf16 v[34:37], v[178:181], v[194:197], v[34:37]
	v_mfma_f32_16x16x32_bf16 v[22:25], v[170:173], v[202:205], v[22:25]
	v_mfma_f32_16x16x32_bf16 v[18:21], v[178:181], v[202:205], v[18:21]
	v_mfma_f32_16x16x32_bf16 v[6:9], v[170:173], v[210:213], v[6:9]
	v_mfma_f32_16x16x32_bf16 v[2:5], v[178:181], v[210:213], v[2:5]
	v_mfma_f32_16x16x32_bf16 v[54:57], v[174:177], v[190:193], v[54:57]
	v_mfma_f32_16x16x32_bf16 v[50:53], v[182:185], v[190:193], v[50:53]
	v_mfma_f32_16x16x32_bf16 v[38:41], v[174:177], v[198:201], v[38:41]
	v_mfma_f32_16x16x32_bf16 v[34:37], v[182:185], v[198:201], v[34:37]
	v_mfma_f32_16x16x32_bf16 v[22:25], v[174:177], v[206:209], v[22:25]
	v_mfma_f32_16x16x32_bf16 v[18:21], v[182:185], v[206:209], v[18:21]
	v_mfma_f32_16x16x32_bf16 v[6:9], v[174:177], v[214:217], v[6:9]
	v_mfma_f32_16x16x32_bf16 v[2:5], v[182:185], v[214:217], v[2:5]
	s_setprio 2
	s_barrier
	s_add_i32 s33, 0, 0x18000
	v_add_u32_e32 v157, s33, v151
	s_add_i32 s62, 0, 0x1c000
	ds_read_b128 v[146:149], v157
	ds_read_b128 v[158:161], v157 offset:1024
	ds_read_b128 v[162:165], v157 offset:2048
	ds_read_b128 v[166:169], v157 offset:3072
	v_add_u32_e32 v157, s62, v151
	ds_read_b128 v[170:173], v157
	ds_read_b128 v[174:177], v157 offset:1024
	ds_read_b128 v[178:181], v157 offset:2048
	ds_read_b128 v[182:185], v157 offset:3072
	s_add_u32 s56, s56, 0x40000
	s_addc_u32 s57, s57, 0
	s_mov_b32 m0, s66
	v_lshl_add_u64 v[226:227], s[56:57], 0, v[130:131]
	ds_read_b128 v[186:189], v154 offset:32768
	ds_read_b128 v[190:193], v154 offset:33792
	ds_read_b128 v[194:197], v154 offset:34816
	ds_read_b128 v[198:201], v154 offset:35840
	ds_read_b128 v[202:205], v154 offset:36864
	ds_read_b128 v[206:209], v154 offset:37888
	ds_read_b128 v[210:213], v154 offset:38912
	ds_read_b128 v[214:217], v154 offset:39936
	global_load_lds_dwordx4 v[226:227], off
	v_lshl_add_u64 v[226:227], s[56:57], 0, v[134:135]
	s_mov_b32 m0, s67
	s_nop 0
	global_load_lds_dwordx4 v[226:227], off
	s_waitcnt vmcnt(8)
	s_waitcnt lgkmcnt(0)
	s_barrier
	s_setprio 0
	s_waitcnt lgkmcnt(0)
	v_mfma_f32_16x16x32_bf16 v[126:129], v[146:149], v[186:189], v[126:129]
	v_mfma_f32_16x16x32_bf16 v[122:125], v[162:165], v[186:189], v[122:125]
	v_mfma_f32_16x16x32_bf16 v[110:113], v[146:149], v[194:197], v[110:113]
	v_mfma_f32_16x16x32_bf16 v[106:109], v[162:165], v[194:197], v[106:109]
	v_mfma_f32_16x16x32_bf16 v[94:97], v[146:149], v[202:205], v[94:97]
	v_mfma_f32_16x16x32_bf16 v[90:93], v[162:165], v[202:205], v[90:93]
	v_mfma_f32_16x16x32_bf16 v[78:81], v[146:149], v[210:213], v[78:81]
	v_mfma_f32_16x16x32_bf16 v[74:77], v[162:165], v[210:213], v[74:77]
	v_mfma_f32_16x16x32_bf16 v[126:129], v[158:161], v[190:193], v[126:129]
	v_mfma_f32_16x16x32_bf16 v[122:125], v[166:169], v[190:193], v[122:125]
	v_mfma_f32_16x16x32_bf16 v[110:113], v[158:161], v[198:201], v[110:113]
	v_mfma_f32_16x16x32_bf16 v[106:109], v[166:169], v[198:201], v[106:109]
	v_mfma_f32_16x16x32_bf16 v[94:97], v[158:161], v[206:209], v[94:97]
	v_mfma_f32_16x16x32_bf16 v[90:93], v[166:169], v[206:209], v[90:93]
	v_mfma_f32_16x16x32_bf16 v[78:81], v[158:161], v[214:217], v[78:81]
	v_mfma_f32_16x16x32_bf16 v[74:77], v[166:169], v[214:217], v[74:77]
	s_setprio 2
	s_setprio 0
	v_mfma_f32_16x16x32_bf16 v[118:121], v[170:173], v[186:189], v[118:121]
	v_mfma_f32_16x16x32_bf16 v[114:117], v[178:181], v[186:189], v[114:117]
	v_mfma_f32_16x16x32_bf16 v[102:105], v[170:173], v[194:197], v[102:105]
	v_mfma_f32_16x16x32_bf16 v[98:101], v[178:181], v[194:197], v[98:101]
	v_mfma_f32_16x16x32_bf16 v[86:89], v[170:173], v[202:205], v[86:89]
	v_mfma_f32_16x16x32_bf16 v[82:85], v[178:181], v[202:205], v[82:85]
	v_mfma_f32_16x16x32_bf16 v[70:73], v[170:173], v[210:213], v[70:73]
	v_mfma_f32_16x16x32_bf16 v[66:69], v[178:181], v[210:213], v[66:69]
	v_mfma_f32_16x16x32_bf16 v[118:121], v[174:177], v[190:193], v[118:121]
	v_mfma_f32_16x16x32_bf16 v[114:117], v[182:185], v[190:193], v[114:117]
	v_mfma_f32_16x16x32_bf16 v[102:105], v[174:177], v[198:201], v[102:105]
	v_mfma_f32_16x16x32_bf16 v[98:101], v[182:185], v[198:201], v[98:101]
	v_mfma_f32_16x16x32_bf16 v[86:89], v[174:177], v[206:209], v[86:89]
	v_mfma_f32_16x16x32_bf16 v[82:85], v[182:185], v[206:209], v[82:85]
	v_mfma_f32_16x16x32_bf16 v[70:73], v[174:177], v[214:217], v[70:73]
	v_mfma_f32_16x16x32_bf16 v[66:69], v[182:185], v[214:217], v[66:69]
	s_setprio 2
	s_barrier
; #define PG8_STAGE(bufoff, gbase, voff) do { _Pragma("unroll") for (int _i = 0; _i < 2; ++_i) \
;         __builtin_amdgcn_global_load_lds((const unsigned*)((const char*)(gbase) + (voff)[_i]), (LAS unsigned*)(lds + (bufoff) + ldsw + _i * 8192), 16, 0, 0); } while (0)
; #define PG8_LDA(dst, b, h) do { _Pragma("unroll") for (int m = 0; m < 4; ++m) _Pragma("unroll") for (int k = 0; k < 2; ++k) dst[m][k] = *(const LAS bf16x8*)(lds + PG8_SA(b, h) + aoff + m * 2048 + k * 1024); } while (0)
; #define PG8_MMA(ai, bj, At, Bt) do { __builtin_amdgcn_s_setprio(1); _Pragma("unroll") for (int m = 0; m < 4; ++m) _Pragma("unroll") for (int n = 0; n < 2; ++n) _Pragma("unroll") for (int k = 0; k < 2; ++k) \
;         acc[ai][bj][m][n] = __builtin_amdgcn_mfma_f32_16x16x32_bf16(Bt[n][k], At[m][k], acc[ai][bj][m][n], 0, 0, 0); __builtin_amdgcn_s_setprio(0); } while (0)
; #define PG8_WAIT_V(n) asm volatile("s_waitcnt vmcnt(" #n ")" ::: "memory")
; #define PG8_WAIT_L(n) asm volatile("s_waitcnt lgkmcnt(" #n ")" ::: "memory")
; #define PG8_BAR __builtin_amdgcn_s_barrier()
; #define PG8_SCHED __builtin_amdgcn_sched_barrier(0)
; template <class Epi>
; __device__ __forceinline__ void gemm_phase(LAS unsigned char* lds, const Gemm g, int G, int c, const Epi& E) {
;     ...
;             PG8_LDA(At, 1, 1); PG8_STAGE(PG8_SB(1, 0), b3, voffB); PG8_STAGE(PG8_SB(1, 1), b3 + hstepB, voffB); PG8_STAGE(PG8_SA(1, 0), a3, voffA);
;             PG8_WAIT_V(8); PG8_WAIT_L(0); PG8_BAR; PG8_MMA(1, 0, At, B0); PG8_MMA(1, 1, At, B1); PG8_BAR; PG8_SCHED;
;         }
;         if (wr == 0) PG8_BAR;
	s_add_i32 s33, s33, s60
	v_lshl_add_u64 v[218:219], v[218:219], 0, s[20:21]
	s_mov_b32 m0, s33
	ds_read_b128 v[186:189], v154 offset:49152
	ds_read_b128 v[190:193], v154 offset:50176
	ds_read_b128 v[194:197], v154 offset:51200
	ds_read_b128 v[198:201], v154 offset:52224
	ds_read_b128 v[202:205], v154 offset:53248
	ds_read_b128 v[206:209], v154 offset:54272
	ds_read_b128 v[210:213], v154 offset:55296
	ds_read_b128 v[214:217], v154 offset:56320
	global_load_lds_dwordx4 v[218:219], off
	s_add_i32 m0, s33, 0x2000
	s_add_u32 s54, s54, 0x40080
	v_lshl_add_u64 v[218:219], v[220:221], 0, s[20:21]
	s_addc_u32 s55, s55, 0
	s_add_i32 s33, s62, s60
	global_load_lds_dwordx4 v[218:219], off
	v_lshl_add_u64 v[218:219], s[54:55], 0, v[132:133]
	s_mov_b32 m0, s33
	s_nop 0
	global_load_lds_dwordx4 v[218:219], off
	v_lshl_add_u64 v[218:219], s[54:55], 0, v[136:137]
	s_add_i32 m0, s33, 0x2000
	s_nop 0
	global_load_lds_dwordx4 v[218:219], off
	v_lshl_add_u64 v[218:219], v[222:223], 0, s[20:21]
	s_mov_b32 m0, s71
	s_nop 0
	global_load_lds_dwordx4 v[218:219], off
	v_lshl_add_u64 v[218:219], v[224:225], 0, s[20:21]
	s_mov_b32 m0, s72
	s_nop 0
	global_load_lds_dwordx4 v[218:219], off
	s_waitcnt vmcnt(8)
	s_waitcnt lgkmcnt(0)
	s_barrier
	s_setprio 0
	s_waitcnt lgkmcnt(0)
	v_mfma_f32_16x16x32_bf16 v[62:65], v[146:149], v[186:189], v[62:65]
	v_mfma_f32_16x16x32_bf16 v[58:61], v[162:165], v[186:189], v[58:61]
	v_mfma_f32_16x16x32_bf16 v[46:49], v[146:149], v[194:197], v[46:49]
	v_mfma_f32_16x16x32_bf16 v[42:45], v[162:165], v[194:197], v[42:45]
	v_mfma_f32_16x16x32_bf16 v[30:33], v[146:149], v[202:205], v[30:33]
	v_mfma_f32_16x16x32_bf16 v[26:29], v[162:165], v[202:205], v[26:29]
	v_mfma_f32_16x16x32_bf16 v[14:17], v[146:149], v[210:213], v[14:17]
	v_mfma_f32_16x16x32_bf16 v[10:13], v[162:165], v[210:213], v[10:13]
	v_mfma_f32_16x16x32_bf16 v[62:65], v[158:161], v[190:193], v[62:65]
	v_mfma_f32_16x16x32_bf16 v[58:61], v[166:169], v[190:193], v[58:61]
	v_mfma_f32_16x16x32_bf16 v[46:49], v[158:161], v[198:201], v[46:49]
	v_mfma_f32_16x16x32_bf16 v[42:45], v[166:169], v[198:201], v[42:45]
	v_mfma_f32_16x16x32_bf16 v[30:33], v[158:161], v[206:209], v[30:33]
	v_mfma_f32_16x16x32_bf16 v[26:29], v[166:169], v[206:209], v[26:29]
	v_mfma_f32_16x16x32_bf16 v[14:17], v[158:161], v[214:217], v[14:17]
	v_mfma_f32_16x16x32_bf16 v[10:13], v[166:169], v[214:217], v[10:13]
	s_setprio 2
	s_setprio 0
	v_mfma_f32_16x16x32_bf16 v[54:57], v[170:173], v[186:189], v[54:57]
	v_mfma_f32_16x16x32_bf16 v[50:53], v[178:181], v[186:189], v[50:53]
	v_mfma_f32_16x16x32_bf16 v[38:41], v[170:173], v[194:197], v[38:41]
	v_mfma_f32_16x16x32_bf16 v[34:37], v[178:181], v[194:197], v[34:37]
	v_mfma_f32_16x16x32_bf16 v[22:25], v[170:173], v[202:205], v[22:25]
	v_mfma_f32_16x16x32_bf16 v[18:21], v[178:181], v[202:205], v[18:21]
	v_mfma_f32_16x16x32_bf16 v[6:9], v[170:173], v[210:213], v[6:9]
	v_mfma_f32_16x16x32_bf16 v[2:5], v[178:181], v[210:213], v[2:5]
	v_mfma_f32_16x16x32_bf16 v[54:57], v[174:177], v[190:193], v[54:57]
	v_mfma_f32_16x16x32_bf16 v[50:53], v[182:185], v[190:193], v[50:53]
	v_mfma_f32_16x16x32_bf16 v[38:41], v[174:177], v[198:201], v[38:41]
	v_mfma_f32_16x16x32_bf16 v[34:37], v[182:185], v[198:201], v[34:37]
	v_mfma_f32_16x16x32_bf16 v[22:25], v[174:177], v[206:209], v[22:25]
	v_mfma_f32_16x16x32_bf16 v[18:21], v[182:185], v[206:209], v[18:21]
	v_mfma_f32_16x16x32_bf16 v[6:9], v[174:177], v[214:217], v[6:9]
	v_mfma_f32_16x16x32_bf16 v[2:5], v[182:185], v[214:217], v[2:5]
	s_setprio 2
	s_barrier
	s_add_i32 s85, s85, 2
	s_add_u32 s4, s4, 0x100
	s_addc_u32 s5, s5, 0
	s_add_u32 s45, s45, 0x100
	s_addc_u32 s84, s84, 0
	s_cmp_gt_u32 s85, 13
	s_cbranch_scc0 .LBB0_236
	s_and_b64 vcc, exec, s[22:23]
	s_cbranch_vccz .LBB0_239
	s_barrier

; #define PG8_STAGE(bufoff, gbase, voff) do { _Pragma("unroll") for (int _i = 0; _i < 2; ++_i) \
;         __builtin_amdgcn_global_load_lds((const unsigned*)((const char*)(gbase) + (voff)[_i]), (LAS unsigned*)(lds + (bufoff) + ldsw + _i * 8192), 16, 0, 0); } while (0)
; #define PG8_LDA(dst, b, h) do { _Pragma("unroll") for (int m = 0; m < 4; ++m) _Pragma("unroll") for (int k = 0; k < 2; ++k) dst[m][k] = *(const LAS bf16x8*)(lds + PG8_SA(b, h) + aoff + m * 2048 + k * 1024); } while (0)
; #define PG8_LDB(dst, b, h) do { _Pragma("unroll") for (int n = 0; n < 2; ++n) _Pragma("unroll") for (int k = 0; k < 2; ++k) dst[n][k] = *(const LAS bf16x8*)(lds + PG8_SB(b, h) + boff + n * 2048 + k * 1024); } while (0)
; #define PG8_MMA(ai, bj, At, Bt) do { __builtin_amdgcn_s_setprio(1); _Pragma("unroll") for (int m = 0; m < 4; ++m) _Pragma("unroll") for (int n = 0; n < 2; ++n) _Pragma("unroll") for (int k = 0; k < 2; ++k) \
;         acc[ai][bj][m][n] = __builtin_amdgcn_mfma_f32_16x16x32_bf16(Bt[n][k], At[m][k], acc[ai][bj][m][n], 0, 0, 0); __builtin_amdgcn_s_setprio(0); } while (0)
; #define PG8_WAIT_V(n) asm volatile("s_waitcnt vmcnt(" #n ")" ::: "memory")
; #define PG8_WAIT_L(n) asm volatile("s_waitcnt lgkmcnt(" #n ")" ::: "memory")
; #define PG8_BAR __builtin_amdgcn_s_barrier()
; #define PG8_SCHED __builtin_amdgcn_sched_barrier(0)
; template <class Epi>
; __device__ __forceinline__ void gemm_phase(LAS unsigned char* lds, const Gemm g, int G, int c, const Epi& E) {
;     ...
;             const bool last = (t == nt - 2);
;             const char* a1 = cA + (size_t)(t + 1) * kstep;
;             const char* a2 = last ? nA : cA + (size_t)(t + 2) * kstep; const char* b2 = last ? nB : cB + (size_t)(t + 2) * kstep;
;             const char* a3 = a2 + kstep; const char* b3 = b2 + kstep;
;             PG8_LDB(B0, 0, 0); PG8_LDB(B1, 0, 1); PG8_SCHED; PG8_LDA(At, 0, 0); PG8_STAGE(PG8_SA(1, 1), a1 + hstepA, voffA);
;             PG8_WAIT_V(8); PG8_WAIT_L(0); PG8_BAR; PG8_MMA(0, 0, At, B0); PG8_MMA(0, 1, At, B1); PG8_BAR; PG8_SCHED;
;             PG8_LDA(At, 0, 1); PG8_STAGE(PG8_SB(0, 0), b2, voffB); PG8_STAGE(PG8_SB(0, 1), b2 + hstepB, voffB); PG8_STAGE(PG8_SA(0, 0), a2, voffA);
.LBB0_368:
	s_add_u32 s33, s20, s13
	s_addc_u32 s42, s21, 0
	s_add_u32 s43, s33, 0x100
	s_addc_u32 s44, s42, 0
	s_and_b64 s[38:39], s[24:25], exec
	s_cselect_b32 s45, s5, s44
	s_cselect_b32 s44, s4, s43
	s_add_u32 s13, s18, s13
	s_addc_u32 s38, s19, 0
	s_add_u32 s13, s13, 0x100
	s_addc_u32 s38, s38, 0
	s_and_b64 s[24:25], s[24:25], exec
	s_cselect_b32 s47, s17, s38
	s_cselect_b32 s46, s16, s13
	s_add_u32 s54, s33, 0xb0080
	s_addc_u32 s55, s42, 0
	s_add_i32 s65, s81, s56
	ds_read_b128 v[142:145], v148
	ds_read_b128 v[152:155], v148 offset:1024
	ds_read_b128 v[156:159], v148 offset:2048
	ds_read_b128 v[160:163], v148 offset:3072
	ds_read_b128 v[164:167], v149
	ds_read_b128 v[168:171], v149 offset:1024
	ds_read_b128 v[172:175], v149 offset:2048
	ds_read_b128 v[176:179], v149 offset:3072
	s_add_i32 m0, s57, 0xc000
	s_add_i32 s74, s57, 0xe000
	s_add_i32 s62, s65, 0x2000
	s_add_u32 s52, s46, 0xb0000
	s_addc_u32 s53, s47, 0
	s_add_i32 s64, s82, s56
	s_add_i32 s63, s64, 0x2000
	s_add_i32 s73, 0, 0x18000
	s_add_i32 s33, 0, 0x1c000
	s_add_u32 s42, s44, 0xb0000
	s_addc_u32 s43, s45, 0
	s_add_i32 s88, s73, s56
	s_add_i32 s38, s88, 0x2000
	s_add_u32 s24, s46, 0xb0080
	s_addc_u32 s25, s47, 0
	s_add_i32 s39, s33, s56
	s_add_i32 s13, s39, 0x2000
	v_lshl_add_u64 v[212:213], s[54:55], 0, v[136:137]
	ds_read_b128 v[180:183], v150
	ds_read_b128 v[184:187], v150 offset:1024
	ds_read_b128 v[188:191], v150 offset:2048
	ds_read_b128 v[192:195], v150 offset:3072
	ds_read_b128 v[196:199], v150 offset:4096
	ds_read_b128 v[200:203], v150 offset:5120
	ds_read_b128 v[204:207], v150 offset:6144
	ds_read_b128 v[208:211], v150 offset:7168
	global_load_lds_dwordx4 v[212:213], off
	v_lshl_add_u64 v[212:213], s[54:55], 0, v[132:133]
	s_mov_b32 m0, s74
	s_nop 0
	global_load_lds_dwordx4 v[212:213], off
	s_waitcnt vmcnt(8)
	s_waitcnt lgkmcnt(0)
	s_barrier
	s_setprio 0
	s_waitcnt lgkmcnt(0)
	v_mfma_f32_16x16x32_bf16 v[126:129], v[142:145], v[180:183], v[126:129]
	v_mfma_f32_16x16x32_bf16 v[122:125], v[156:159], v[180:183], v[122:125]
	v_mfma_f32_16x16x32_bf16 v[118:121], v[142:145], v[188:191], v[118:121]
	v_mfma_f32_16x16x32_bf16 v[110:113], v[156:159], v[188:191], v[110:113]
	v_mfma_f32_16x16x32_bf16 v[102:105], v[142:145], v[196:199], v[102:105]
	v_mfma_f32_16x16x32_bf16 v[94:97], v[156:159], v[196:199], v[94:97]
	v_mfma_f32_16x16x32_bf16 v[86:89], v[142:145], v[204:207], v[86:89]
	v_mfma_f32_16x16x32_bf16 v[78:81], v[156:159], v[204:207], v[78:81]
	v_mfma_f32_16x16x32_bf16 v[126:129], v[152:155], v[184:187], v[126:129]
	v_mfma_f32_16x16x32_bf16 v[122:125], v[160:163], v[184:187], v[122:125]
	v_mfma_f32_16x16x32_bf16 v[118:121], v[152:155], v[192:195], v[118:121]
	v_mfma_f32_16x16x32_bf16 v[110:113], v[160:163], v[192:195], v[110:113]
	v_mfma_f32_16x16x32_bf16 v[102:105], v[152:155], v[200:203], v[102:105]
	v_mfma_f32_16x16x32_bf16 v[94:97], v[160:163], v[200:203], v[94:97]
	v_mfma_f32_16x16x32_bf16 v[86:89], v[152:155], v[208:211], v[86:89]
	v_mfma_f32_16x16x32_bf16 v[78:81], v[160:163], v[208:211], v[78:81]
	s_setprio 2
	s_setprio 0
	v_mfma_f32_16x16x32_bf16 v[114:117], v[164:167], v[180:183], v[114:117]
	v_mfma_f32_16x16x32_bf16 v[106:109], v[172:175], v[180:183], v[106:109]
	v_mfma_f32_16x16x32_bf16 v[98:101], v[164:167], v[188:191], v[98:101]
	v_mfma_f32_16x16x32_bf16 v[90:93], v[172:175], v[188:191], v[90:93]
	v_mfma_f32_16x16x32_bf16 v[82:85], v[164:167], v[196:199], v[82:85]
	v_mfma_f32_16x16x32_bf16 v[74:77], v[172:175], v[196:199], v[74:77]
	v_mfma_f32_16x16x32_bf16 v[70:73], v[164:167], v[204:207], v[70:73]
	v_mfma_f32_16x16x32_bf16 v[66:69], v[172:175], v[204:207], v[66:69]
	v_mfma_f32_16x16x32_bf16 v[114:117], v[168:171], v[184:187], v[114:117]
	v_mfma_f32_16x16x32_bf16 v[106:109], v[176:179], v[184:187], v[106:109]
	v_mfma_f32_16x16x32_bf16 v[98:101], v[168:171], v[192:195], v[98:101]
	v_mfma_f32_16x16x32_bf16 v[90:93], v[176:179], v[192:195], v[90:93]
	v_mfma_f32_16x16x32_bf16 v[82:85], v[168:171], v[200:203], v[82:85]
	v_mfma_f32_16x16x32_bf16 v[74:77], v[176:179], v[200:203], v[74:77]
	v_mfma_f32_16x16x32_bf16 v[70:73], v[168:171], v[208:211], v[70:73]
	v_mfma_f32_16x16x32_bf16 v[66:69], v[176:179], v[208:211], v[66:69]
	s_setprio 2
	s_barrier
	s_mov_b32 m0, s65
	v_lshl_add_u64 v[212:213], s[46:47], 0, v[134:135]
	ds_read_b128 v[180:183], v150 offset:16384
	ds_read_b128 v[184:187], v150 offset:17408
	ds_read_b128 v[188:191], v150 offset:18432
	ds_read_b128 v[192:195], v150 offset:19456
	ds_read_b128 v[196:199], v150 offset:20480
	ds_read_b128 v[200:203], v150 offset:21504
	ds_read_b128 v[204:207], v150 offset:22528
	ds_read_b128 v[208:211], v150 offset:23552
	global_load_lds_dwordx4 v[212:213], off
	v_lshl_add_u64 v[214:215], s[46:47], 0, v[130:131]
	s_mov_b32 m0, s62
	v_lshl_add_u64 v[216:217], s[52:53], 0, v[134:135]
	global_load_lds_dwordx4 v[214:215], off
	s_mov_b32 m0, s64
	v_lshl_add_u64 v[218:219], s[44:45], 0, v[132:133]
	global_load_lds_dwordx4 v[216:217], off
	v_lshl_add_u64 v[216:217], s[52:53], 0, v[130:131]
	s_mov_b32 m0, s63
	s_nop 0
	global_load_lds_dwordx4 v[216:217], off
	v_lshl_add_u64 v[216:217], s[44:45], 0, v[136:137]
	s_mov_b32 m0, s57
	s_nop 0
	global_load_lds_dwordx4 v[216:217], off
	s_mov_b32 m0, s58
	s_nop 0
	global_load_lds_dwordx4 v[218:219], off
	s_waitcnt vmcnt(8)
	s_waitcnt lgkmcnt(0)
	s_barrier
; #define PG8_STAGE(bufoff, gbase, voff) do { _Pragma("unroll") for (int _i = 0; _i < 2; ++_i) \
;         __builtin_amdgcn_global_load_lds((const unsigned*)((const char*)(gbase) + (voff)[_i]), (LAS unsigned*)(lds + (bufoff) + ldsw + _i * 8192), 16, 0, 0); } while (0)
; #define PG8_LDA(dst, b, h) do { _Pragma("unroll") for (int m = 0; m < 4; ++m) _Pragma("unroll") for (int k = 0; k < 2; ++k) dst[m][k] = *(const LAS bf16x8*)(lds + PG8_SA(b, h) + aoff + m * 2048 + k * 1024); } while (0)
; #define PG8_LDB(dst, b, h) do { _Pragma("unroll") for (int n = 0; n < 2; ++n) _Pragma("unroll") for (int k = 0; k < 2; ++k) dst[n][k] = *(const LAS bf16x8*)(lds + PG8_SB(b, h) + boff + n * 2048 + k * 1024); } while (0)
; #define PG8_MMA(ai, bj, At, Bt) do { __builtin_amdgcn_s_setprio(1); _Pragma("unroll") for (int m = 0; m < 4; ++m) _Pragma("unroll") for (int n = 0; n < 2; ++n) _Pragma("unroll") for (int k = 0; k < 2; ++k) \
;         acc[ai][bj][m][n] = __builtin_amdgcn_mfma_f32_16x16x32_bf16(Bt[n][k], At[m][k], acc[ai][bj][m][n], 0, 0, 0); __builtin_amdgcn_s_setprio(0); } while (0)
; #define PG8_WAIT_V(n) asm volatile("s_waitcnt vmcnt(" #n ")" ::: "memory")
; #define PG8_WAIT_L(n) asm volatile("s_waitcnt lgkmcnt(" #n ")" ::: "memory")
; #define PG8_BAR __builtin_amdgcn_s_barrier()
; #define PG8_SCHED __builtin_amdgcn_sched_barrier(0)
; template <class Epi>
; __device__ __forceinline__ void gemm_phase(LAS unsigned char* lds, const Gemm g, int G, int c, const Epi& E) {
;     ...
;             PG8_WAIT_V(8); PG8_WAIT_L(0); PG8_BAR; PG8_MMA(1, 0, At, B0); PG8_MMA(1, 1, At, B1); PG8_BAR; PG8_SCHED;
;             PG8_LDB(B0, 1, 0); PG8_LDB(B1, 1, 1); PG8_SCHED; PG8_LDA(At, 1, 0); PG8_STAGE(PG8_SA(0, 1), a2 + hstepA, voffA);
;             PG8_WAIT_V(8); PG8_WAIT_L(0); PG8_BAR; PG8_MMA(0, 0, At, B0); PG8_MMA(0, 1, At, B1); PG8_BAR; PG8_SCHED;
	s_setprio 0
	s_waitcnt lgkmcnt(0)
	v_mfma_f32_16x16x32_bf16 v[62:65], v[142:145], v[180:183], v[62:65]
	v_mfma_f32_16x16x32_bf16 v[58:61], v[156:159], v[180:183], v[58:61]
	v_mfma_f32_16x16x32_bf16 v[54:57], v[142:145], v[188:191], v[54:57]
	v_mfma_f32_16x16x32_bf16 v[46:49], v[156:159], v[188:191], v[46:49]
	v_mfma_f32_16x16x32_bf16 v[38:41], v[142:145], v[196:199], v[38:41]
	v_mfma_f32_16x16x32_bf16 v[30:33], v[156:159], v[196:199], v[30:33]
	v_mfma_f32_16x16x32_bf16 v[22:25], v[142:145], v[204:207], v[22:25]
	v_mfma_f32_16x16x32_bf16 v[14:17], v[156:159], v[204:207], v[14:17]
	v_mfma_f32_16x16x32_bf16 v[62:65], v[152:155], v[184:187], v[62:65]
	v_mfma_f32_16x16x32_bf16 v[58:61], v[160:163], v[184:187], v[58:61]
	v_mfma_f32_16x16x32_bf16 v[54:57], v[152:155], v[192:195], v[54:57]
	v_mfma_f32_16x16x32_bf16 v[46:49], v[160:163], v[192:195], v[46:49]
	v_mfma_f32_16x16x32_bf16 v[38:41], v[152:155], v[200:203], v[38:41]
	v_mfma_f32_16x16x32_bf16 v[30:33], v[160:163], v[200:203], v[30:33]
	v_mfma_f32_16x16x32_bf16 v[22:25], v[152:155], v[208:211], v[22:25]
	v_mfma_f32_16x16x32_bf16 v[14:17], v[160:163], v[208:211], v[14:17]
	s_setprio 2
	s_setprio 0
	v_mfma_f32_16x16x32_bf16 v[50:53], v[164:167], v[180:183], v[50:53]
	v_mfma_f32_16x16x32_bf16 v[42:45], v[172:175], v[180:183], v[42:45]
	v_mfma_f32_16x16x32_bf16 v[34:37], v[164:167], v[188:191], v[34:37]
	v_mfma_f32_16x16x32_bf16 v[26:29], v[172:175], v[188:191], v[26:29]
	v_mfma_f32_16x16x32_bf16 v[18:21], v[164:167], v[196:199], v[18:21]
	v_mfma_f32_16x16x32_bf16 v[10:13], v[172:175], v[196:199], v[10:13]
	v_mfma_f32_16x16x32_bf16 v[6:9], v[164:167], v[204:207], v[6:9]
	v_mfma_f32_16x16x32_bf16 v[2:5], v[172:175], v[204:207], v[2:5]
	v_mfma_f32_16x16x32_bf16 v[50:53], v[168:171], v[184:187], v[50:53]
	v_mfma_f32_16x16x32_bf16 v[42:45], v[176:179], v[184:187], v[42:45]
	v_mfma_f32_16x16x32_bf16 v[34:37], v[168:171], v[192:195], v[34:37]
	v_mfma_f32_16x16x32_bf16 v[26:29], v[176:179], v[192:195], v[26:29]
	v_mfma_f32_16x16x32_bf16 v[18:21], v[168:171], v[200:203], v[18:21]
	v_mfma_f32_16x16x32_bf16 v[10:13], v[176:179], v[200:203], v[10:13]
	v_mfma_f32_16x16x32_bf16 v[6:9], v[168:171], v[208:211], v[6:9]
	v_mfma_f32_16x16x32_bf16 v[2:5], v[176:179], v[208:211], v[2:5]
	s_setprio 2
	s_barrier
	v_add_u32_e32 v151, s73, v147
	ds_read_b128 v[142:145], v151
	ds_read_b128 v[152:155], v151 offset:1024
	ds_read_b128 v[156:159], v151 offset:2048
	ds_read_b128 v[160:163], v151 offset:3072
	v_add_u32_e32 v151, s33, v147
	ds_read_b128 v[164:167], v151
	ds_read_b128 v[168:171], v151 offset:1024
	ds_read_b128 v[172:175], v151 offset:2048
	ds_read_b128 v[176:179], v151 offset:3072
	s_mov_b32 m0, s59
	v_lshl_add_u64 v[220:221], s[42:43], 0, v[136:137]
	ds_read_b128 v[180:183], v150 offset:32768
	ds_read_b128 v[184:187], v150 offset:33792
	ds_read_b128 v[188:191], v150 offset:34816
	ds_read_b128 v[192:195], v150 offset:35840
	ds_read_b128 v[196:199], v150 offset:36864
	ds_read_b128 v[200:203], v150 offset:37888
	ds_read_b128 v[204:207], v150 offset:38912
	ds_read_b128 v[208:211], v150 offset:39936
	global_load_lds_dwordx4 v[220:221], off
	v_lshl_add_u64 v[220:221], s[42:43], 0, v[132:133]
	s_mov_b32 m0, s60
	s_nop 0
	global_load_lds_dwordx4 v[220:221], off
	s_waitcnt vmcnt(8)
	s_waitcnt lgkmcnt(0)
	s_barrier
	s_setprio 0
	s_waitcnt lgkmcnt(0)
	v_mfma_f32_16x16x32_bf16 v[126:129], v[142:145], v[180:183], v[126:129]
	v_mfma_f32_16x16x32_bf16 v[122:125], v[156:159], v[180:183], v[122:125]
	v_mfma_f32_16x16x32_bf16 v[118:121], v[142:145], v[188:191], v[118:121]
	v_mfma_f32_16x16x32_bf16 v[110:113], v[156:159], v[188:191], v[110:113]
	v_mfma_f32_16x16x32_bf16 v[102:105], v[142:145], v[196:199], v[102:105]
	v_mfma_f32_16x16x32_bf16 v[94:97], v[156:159], v[196:199], v[94:97]
	v_mfma_f32_16x16x32_bf16 v[86:89], v[142:145], v[204:207], v[86:89]
	v_mfma_f32_16x16x32_bf16 v[78:81], v[156:159], v[204:207], v[78:81]
	v_mfma_f32_16x16x32_bf16 v[126:129], v[152:155], v[184:187], v[126:129]
	v_mfma_f32_16x16x32_bf16 v[122:125], v[160:163], v[184:187], v[122:125]
	v_mfma_f32_16x16x32_bf16 v[118:121], v[152:155], v[192:195], v[118:121]
	v_mfma_f32_16x16x32_bf16 v[110:113], v[160:163], v[192:195], v[110:113]
	v_mfma_f32_16x16x32_bf16 v[102:105], v[152:155], v[200:203], v[102:105]
	v_mfma_f32_16x16x32_bf16 v[94:97], v[160:163], v[200:203], v[94:97]
	v_mfma_f32_16x16x32_bf16 v[86:89], v[152:155], v[208:211], v[86:89]
	v_mfma_f32_16x16x32_bf16 v[78:81], v[160:163], v[208:211], v[78:81]
	s_setprio 2
	s_setprio 0
	v_mfma_f32_16x16x32_bf16 v[114:117], v[164:167], v[180:183], v[114:117]
	v_mfma_f32_16x16x32_bf16 v[106:109], v[172:175], v[180:183], v[106:109]
	v_mfma_f32_16x16x32_bf16 v[98:101], v[164:167], v[188:191], v[98:101]
	v_mfma_f32_16x16x32_bf16 v[90:93], v[172:175], v[188:191], v[90:93]
	v_mfma_f32_16x16x32_bf16 v[82:85], v[164:167], v[196:199], v[82:85]
	v_mfma_f32_16x16x32_bf16 v[74:77], v[172:175], v[196:199], v[74:77]
	v_mfma_f32_16x16x32_bf16 v[70:73], v[164:167], v[204:207], v[70:73]
	v_mfma_f32_16x16x32_bf16 v[66:69], v[172:175], v[204:207], v[66:69]
	v_mfma_f32_16x16x32_bf16 v[114:117], v[168:171], v[184:187], v[114:117]
	v_mfma_f32_16x16x32_bf16 v[106:109], v[176:179], v[184:187], v[106:109]
	v_mfma_f32_16x16x32_bf16 v[98:101], v[168:171], v[192:195], v[98:101]
	v_mfma_f32_16x16x32_bf16 v[90:93], v[176:179], v[192:195], v[90:93]
	v_mfma_f32_16x16x32_bf16 v[82:85], v[168:171], v[200:203], v[82:85]
	v_mfma_f32_16x16x32_bf16 v[74:77], v[176:179], v[200:203], v[74:77]
	v_mfma_f32_16x16x32_bf16 v[70:73], v[168:171], v[208:211], v[70:73]
	v_mfma_f32_16x16x32_bf16 v[66:69], v[176:179], v[208:211], v[66:69]
	s_setprio 2
	s_barrier
; #define PG8_STAGE(bufoff, gbase, voff) do { _Pragma("unroll") for (int _i = 0; _i < 2; ++_i) \
;         __builtin_amdgcn_global_load_lds((const unsigned*)((const char*)(gbase) + (voff)[_i]), (LAS unsigned*)(lds + (bufoff) + ldsw + _i * 8192), 16, 0, 0); } while (0)
; #define PG8_LDA(dst, b, h) do { _Pragma("unroll") for (int m = 0; m < 4; ++m) _Pragma("unroll") for (int k = 0; k < 2; ++k) dst[m][k] = *(const LAS bf16x8*)(lds + PG8_SA(b, h) + aoff + m * 2048 + k * 1024); } while (0)
; #define PG8_MMA(ai, bj, At, Bt) do { __builtin_amdgcn_s_setprio(1); _Pragma("unroll") for (int m = 0; m < 4; ++m) _Pragma("unroll") for (int n = 0; n < 2; ++n) _Pragma("unroll") for (int k = 0; k < 2; ++k) \
;         acc[ai][bj][m][n] = __builtin_amdgcn_mfma_f32_16x16x32_bf16(Bt[n][k], At[m][k], acc[ai][bj][m][n], 0, 0, 0); __builtin_amdgcn_s_setprio(0); } while (0)
; #define PG8_WAIT_V(n) asm volatile("s_waitcnt vmcnt(" #n ")" ::: "memory")
; #define PG8_WAIT_L(n) asm volatile("s_waitcnt lgkmcnt(" #n ")" ::: "memory")
; #define PG8_BAR __builtin_amdgcn_s_barrier()
; #define PG8_SCHED __builtin_amdgcn_sched_barrier(0)
; template <class Epi>
; __device__ __forceinline__ void gemm_phase(LAS unsigned char* lds, const Gemm g, int G, int c, const Epi& E) {
;     ...
;             PG8_LDA(At, 1, 1); PG8_STAGE(PG8_SB(1, 0), b3, voffB); PG8_STAGE(PG8_SB(1, 1), b3 + hstepB, voffB); PG8_STAGE(PG8_SA(1, 0), a3, voffA);
;             PG8_WAIT_V(8); PG8_WAIT_L(0); PG8_BAR; PG8_MMA(1, 0, At, B0); PG8_MMA(1, 1, At, B1); PG8_BAR; PG8_SCHED;
;         }
;         if (wr == 0) PG8_BAR;
	s_mov_b32 m0, s88
	v_lshl_add_u64 v[212:213], v[212:213], 0, s[8:9]
	ds_read_b128 v[180:183], v150 offset:49152
	ds_read_b128 v[184:187], v150 offset:50176
	ds_read_b128 v[188:191], v150 offset:51200
	ds_read_b128 v[192:195], v150 offset:52224
	ds_read_b128 v[196:199], v150 offset:53248
	ds_read_b128 v[200:203], v150 offset:54272
	ds_read_b128 v[204:207], v150 offset:55296
	ds_read_b128 v[208:211], v150 offset:56320
	global_load_lds_dwordx4 v[212:213], off
	v_lshl_add_u64 v[212:213], v[214:215], 0, s[8:9]
	s_mov_b32 m0, s38
	s_nop 0
	global_load_lds_dwordx4 v[212:213], off
	v_lshl_add_u64 v[212:213], s[24:25], 0, v[134:135]
	s_mov_b32 m0, s39
	s_nop 0
	global_load_lds_dwordx4 v[212:213], off
	v_lshl_add_u64 v[212:213], s[24:25], 0, v[130:131]
	s_mov_b32 m0, s13
	s_nop 0
	global_load_lds_dwordx4 v[212:213], off
	v_lshl_add_u64 v[212:213], v[216:217], 0, s[8:9]
	s_mov_b32 m0, s79
	s_nop 0
	global_load_lds_dwordx4 v[212:213], off
	v_lshl_add_u64 v[212:213], v[218:219], 0, s[8:9]
	s_mov_b32 m0, s80
	s_nop 0
	global_load_lds_dwordx4 v[212:213], off
	s_waitcnt vmcnt(8)
	s_waitcnt lgkmcnt(0)
	s_barrier
	s_setprio 0
	s_waitcnt lgkmcnt(0)
	v_mfma_f32_16x16x32_bf16 v[62:65], v[142:145], v[180:183], v[62:65]
	v_mfma_f32_16x16x32_bf16 v[58:61], v[156:159], v[180:183], v[58:61]
	v_mfma_f32_16x16x32_bf16 v[54:57], v[142:145], v[188:191], v[54:57]
	v_mfma_f32_16x16x32_bf16 v[46:49], v[156:159], v[188:191], v[46:49]
	v_mfma_f32_16x16x32_bf16 v[38:41], v[142:145], v[196:199], v[38:41]
	v_mfma_f32_16x16x32_bf16 v[30:33], v[156:159], v[196:199], v[30:33]
	v_mfma_f32_16x16x32_bf16 v[22:25], v[142:145], v[204:207], v[22:25]
	v_mfma_f32_16x16x32_bf16 v[14:17], v[156:159], v[204:207], v[14:17]
	v_mfma_f32_16x16x32_bf16 v[62:65], v[152:155], v[184:187], v[62:65]
	v_mfma_f32_16x16x32_bf16 v[58:61], v[160:163], v[184:187], v[58:61]
	v_mfma_f32_16x16x32_bf16 v[54:57], v[152:155], v[192:195], v[54:57]
	v_mfma_f32_16x16x32_bf16 v[46:49], v[160:163], v[192:195], v[46:49]
	v_mfma_f32_16x16x32_bf16 v[38:41], v[152:155], v[200:203], v[38:41]
	v_mfma_f32_16x16x32_bf16 v[30:33], v[160:163], v[200:203], v[30:33]
	v_mfma_f32_16x16x32_bf16 v[22:25], v[152:155], v[208:211], v[22:25]
	v_mfma_f32_16x16x32_bf16 v[14:17], v[160:163], v[208:211], v[14:17]
	s_setprio 2
	s_setprio 0
	v_mfma_f32_16x16x32_bf16 v[50:53], v[164:167], v[180:183], v[50:53]
	v_mfma_f32_16x16x32_bf16 v[42:45], v[172:175], v[180:183], v[42:45]
	v_mfma_f32_16x16x32_bf16 v[34:37], v[164:167], v[188:191], v[34:37]
	v_mfma_f32_16x16x32_bf16 v[26:29], v[172:175], v[188:191], v[26:29]
	v_mfma_f32_16x16x32_bf16 v[18:21], v[164:167], v[196:199], v[18:21]
	v_mfma_f32_16x16x32_bf16 v[10:13], v[172:175], v[196:199], v[10:13]
	v_mfma_f32_16x16x32_bf16 v[6:9], v[164:167], v[204:207], v[6:9]
	v_mfma_f32_16x16x32_bf16 v[2:5], v[172:175], v[204:207], v[2:5]
	v_mfma_f32_16x16x32_bf16 v[50:53], v[168:171], v[184:187], v[50:53]
	v_mfma_f32_16x16x32_bf16 v[42:45], v[176:179], v[184:187], v[42:45]
	v_mfma_f32_16x16x32_bf16 v[34:37], v[168:171], v[192:195], v[34:37]
	v_mfma_f32_16x16x32_bf16 v[26:29], v[176:179], v[192:195], v[26:29]
	v_mfma_f32_16x16x32_bf16 v[18:21], v[168:171], v[200:203], v[18:21]
	v_mfma_f32_16x16x32_bf16 v[10:13], v[176:179], v[200:203], v[10:13]
	v_mfma_f32_16x16x32_bf16 v[6:9], v[168:171], v[208:211], v[6:9]
	v_mfma_f32_16x16x32_bf16 v[2:5], v[176:179], v[208:211], v[2:5]
	s_setprio 2
	s_barrier
	s_movk_i32 s13, 0x100
	s_andn2_b64 vcc, exec, s[22:23]
	s_mov_b64 s[24:25], -1
	s_mov_b64 s[22:23], 0
	s_cbranch_vccz .LBB0_368
	s_and_b64 vcc, exec, s[10:11]
	s_cbranch_vccz .LBB0_371
	s_barrier

; #define PG8_STAGE(bufoff, gbase, voff) do { _Pragma("unroll") for (int _i = 0; _i < 2; ++_i) \
;         __builtin_amdgcn_global_load_lds((const unsigned*)((const char*)(gbase) + (voff)[_i]), (LAS unsigned*)(lds + (bufoff) + ldsw + _i * 8192), 16, 0, 0); } while (0)
; #define PG8_LDA(dst, b, h) do { _Pragma("unroll") for (int m = 0; m < 4; ++m) _Pragma("unroll") for (int k = 0; k < 2; ++k) dst[m][k] = *(const LAS bf16x8*)(lds + PG8_SA(b, h) + aoff + m * 2048 + k * 1024); } while (0)
; #define PG8_LDB(dst, b, h) do { _Pragma("unroll") for (int n = 0; n < 2; ++n) _Pragma("unroll") for (int k = 0; k < 2; ++k) dst[n][k] = *(const LAS bf16x8*)(lds + PG8_SB(b, h) + boff + n * 2048 + k * 1024); } while (0)
; #define PG8_MMA(ai, bj, At, Bt) do { __builtin_amdgcn_s_setprio(1); _Pragma("unroll") for (int m = 0; m < 4; ++m) _Pragma("unroll") for (int n = 0; n < 2; ++n) _Pragma("unroll") for (int k = 0; k < 2; ++k) \
;         acc[ai][bj][m][n] = __builtin_amdgcn_mfma_f32_16x16x32_bf16(Bt[n][k], At[m][k], acc[ai][bj][m][n], 0, 0, 0); __builtin_amdgcn_s_setprio(0); } while (0)
; #define PG8_WAIT_V(n) asm volatile("s_waitcnt vmcnt(" #n ")" ::: "memory")
; #define PG8_WAIT_L(n) asm volatile("s_waitcnt lgkmcnt(" #n ")" ::: "memory")
; #define PG8_BAR __builtin_amdgcn_s_barrier()
; #define PG8_SCHED __builtin_amdgcn_sched_barrier(0)
; template <class Epi>
; __device__ __forceinline__ void gemm_phase(LAS unsigned char* lds, const Gemm g, int G, int c, const Epi& E) {
;     ...
;             const bool last = (t == nt - 2);
;             const char* a1 = cA + (size_t)(t + 1) * kstep;
;             const char* a2 = last ? nA : cA + (size_t)(t + 2) * kstep; const char* b2 = last ? nB : cB + (size_t)(t + 2) * kstep;
;             const char* a3 = a2 + kstep; const char* b3 = b2 + kstep;
;             PG8_LDB(B0, 0, 0); PG8_LDB(B1, 0, 1); PG8_SCHED; PG8_LDA(At, 0, 0); PG8_STAGE(PG8_SA(1, 1), a1 + hstepA, voffA);
;             PG8_WAIT_V(8); PG8_WAIT_L(0); PG8_BAR; PG8_MMA(0, 0, At, B0); PG8_MMA(0, 1, At, B1); PG8_BAR; PG8_SCHED;
;             PG8_LDA(At, 0, 1); PG8_STAGE(PG8_SB(0, 0), b2, voffB); PG8_STAGE(PG8_SB(0, 1), b2 + hstepB, voffB); PG8_STAGE(PG8_SA(0, 0), a2, voffA);
;             PG8_WAIT_V(8); PG8_WAIT_L(0); PG8_BAR; PG8_MMA(1, 0, At, B0); PG8_MMA(1, 1, At, B1); PG8_BAR; PG8_SCHED;
.LBB0_390:
	s_add_u32 s33, s8, s38
	s_addc_u32 s39, s9, 0
	s_add_u32 s56, s33, 0x100
	s_addc_u32 s57, s39, 0
	s_and_b64 s[54:55], s[10:11], exec
	s_cselect_b32 s57, s47, s57
	s_cselect_b32 s56, s46, s56
	s_add_u32 s38, s6, s38
	s_addc_u32 s54, s7, 0
	s_add_u32 s38, s38, 0x100
	s_addc_u32 s54, s54, 0
	s_and_b64 s[10:11], s[10:11], exec
	s_cselect_b32 s59, s53, s54
	s_cselect_b32 s58, s52, s38
	s_add_u32 s66, s33, 0xb0080
	s_addc_u32 s67, s39, 0
	s_add_i32 s65, s87, s14
	ds_read_b128 v[142:145], v160
	ds_read_b128 v[146:149], v160 offset:1024
	ds_read_b128 v[150:153], v160 offset:2048
	ds_read_b128 v[154:157], v160 offset:3072
	ds_read_b128 v[166:169], v161
	ds_read_b128 v[170:173], v161 offset:1024
	ds_read_b128 v[174:177], v161 offset:2048
	ds_read_b128 v[178:181], v161 offset:3072
	s_add_i32 m0, s78, 0xc000
	s_add_i32 s74, s78, 0xe000
	s_add_i32 s62, s65, 0x2000
	s_add_u32 s60, s58, 0xb0000
	s_addc_u32 s61, s59, 0
	s_add_i32 s64, s88, s14
	s_add_i32 s63, s64, 0x2000
	s_add_i32 s73, 0, 0x18000
	s_add_i32 s33, 0, 0x1c000
	s_add_u32 s54, s56, 0xb0000
	s_addc_u32 s55, s57, 0
	s_add_i32 vcc_hi, s73, s14
	s_add_i32 s39, vcc_hi, 0x2000
	s_add_u32 s10, s58, 0xb0080
	s_addc_u32 s11, s59, 0
	s_add_i32 vcc_lo, s33, s14
	s_add_i32 s38, vcc_lo, 0x2000
	v_lshl_add_u64 v[214:215], s[66:67], 0, v[130:131]
	ds_read_b128 v[182:185], v162
	ds_read_b128 v[186:189], v162 offset:1024
	ds_read_b128 v[190:193], v162 offset:2048
	ds_read_b128 v[194:197], v162 offset:3072
	ds_read_b128 v[198:201], v162 offset:4096
	ds_read_b128 v[202:205], v162 offset:5120
	ds_read_b128 v[206:209], v162 offset:6144
	ds_read_b128 v[210:213], v162 offset:7168
	global_load_lds_dwordx4 v[214:215], off
	v_lshl_add_u64 v[214:215], s[66:67], 0, v[134:135]
	s_mov_b32 m0, s74
	s_nop 0
	global_load_lds_dwordx4 v[214:215], off
	s_waitcnt vmcnt(8)
	s_waitcnt lgkmcnt(0)
	s_barrier
	s_setprio 0
	s_waitcnt lgkmcnt(0)
	v_mfma_f32_16x16x32_bf16 v[126:129], v[142:145], v[182:185], v[126:129]
	v_mfma_f32_16x16x32_bf16 v[122:125], v[150:153], v[182:185], v[122:125]
	v_mfma_f32_16x16x32_bf16 v[110:113], v[142:145], v[190:193], v[110:113]
	v_mfma_f32_16x16x32_bf16 v[106:109], v[150:153], v[190:193], v[106:109]
	v_mfma_f32_16x16x32_bf16 v[94:97], v[142:145], v[198:201], v[94:97]
	v_mfma_f32_16x16x32_bf16 v[90:93], v[150:153], v[198:201], v[90:93]
	v_mfma_f32_16x16x32_bf16 v[78:81], v[142:145], v[206:209], v[78:81]
	v_mfma_f32_16x16x32_bf16 v[74:77], v[150:153], v[206:209], v[74:77]
	v_mfma_f32_16x16x32_bf16 v[126:129], v[146:149], v[186:189], v[126:129]
	v_mfma_f32_16x16x32_bf16 v[122:125], v[154:157], v[186:189], v[122:125]
	v_mfma_f32_16x16x32_bf16 v[110:113], v[146:149], v[194:197], v[110:113]
	v_mfma_f32_16x16x32_bf16 v[106:109], v[154:157], v[194:197], v[106:109]
	v_mfma_f32_16x16x32_bf16 v[94:97], v[146:149], v[202:205], v[94:97]
	v_mfma_f32_16x16x32_bf16 v[90:93], v[154:157], v[202:205], v[90:93]
	v_mfma_f32_16x16x32_bf16 v[78:81], v[146:149], v[210:213], v[78:81]
	v_mfma_f32_16x16x32_bf16 v[74:77], v[154:157], v[210:213], v[74:77]
	s_setprio 2
	s_setprio 0
	v_mfma_f32_16x16x32_bf16 v[118:121], v[166:169], v[182:185], v[118:121]
	v_mfma_f32_16x16x32_bf16 v[114:117], v[174:177], v[182:185], v[114:117]
	v_mfma_f32_16x16x32_bf16 v[102:105], v[166:169], v[190:193], v[102:105]
	v_mfma_f32_16x16x32_bf16 v[98:101], v[174:177], v[190:193], v[98:101]
	v_mfma_f32_16x16x32_bf16 v[86:89], v[166:169], v[198:201], v[86:89]
	v_mfma_f32_16x16x32_bf16 v[82:85], v[174:177], v[198:201], v[82:85]
	v_mfma_f32_16x16x32_bf16 v[70:73], v[166:169], v[206:209], v[70:73]
	v_mfma_f32_16x16x32_bf16 v[66:69], v[174:177], v[206:209], v[66:69]
	v_mfma_f32_16x16x32_bf16 v[118:121], v[170:173], v[186:189], v[118:121]
	v_mfma_f32_16x16x32_bf16 v[114:117], v[178:181], v[186:189], v[114:117]
	v_mfma_f32_16x16x32_bf16 v[102:105], v[170:173], v[194:197], v[102:105]
	v_mfma_f32_16x16x32_bf16 v[98:101], v[178:181], v[194:197], v[98:101]
	v_mfma_f32_16x16x32_bf16 v[86:89], v[170:173], v[202:205], v[86:89]
	v_mfma_f32_16x16x32_bf16 v[82:85], v[178:181], v[202:205], v[82:85]
	v_mfma_f32_16x16x32_bf16 v[70:73], v[170:173], v[210:213], v[70:73]
	v_mfma_f32_16x16x32_bf16 v[66:69], v[178:181], v[210:213], v[66:69]
	s_setprio 2
	s_barrier
	s_mov_b32 m0, s65
	v_lshl_add_u64 v[214:215], s[58:59], 0, v[132:133]
	ds_read_b128 v[182:185], v162 offset:16384
	ds_read_b128 v[186:189], v162 offset:17408
	ds_read_b128 v[190:193], v162 offset:18432
	ds_read_b128 v[194:197], v162 offset:19456
	ds_read_b128 v[198:201], v162 offset:20480
	ds_read_b128 v[202:205], v162 offset:21504
	ds_read_b128 v[206:209], v162 offset:22528
	ds_read_b128 v[210:213], v162 offset:23552
	global_load_lds_dwordx4 v[214:215], off
	v_lshl_add_u64 v[216:217], s[58:59], 0, v[136:137]
	s_mov_b32 m0, s62
	v_lshl_add_u64 v[218:219], s[60:61], 0, v[132:133]
	global_load_lds_dwordx4 v[216:217], off
	s_mov_b32 m0, s64
	v_lshl_add_u64 v[220:221], s[56:57], 0, v[134:135]
	global_load_lds_dwordx4 v[218:219], off
	v_lshl_add_u64 v[218:219], s[60:61], 0, v[136:137]
	s_mov_b32 m0, s63
	s_nop 0
	global_load_lds_dwordx4 v[218:219], off
	v_lshl_add_u64 v[218:219], s[56:57], 0, v[130:131]
	s_mov_b32 m0, s78
	s_nop 0
	global_load_lds_dwordx4 v[218:219], off
	s_mov_b32 m0, s79
	s_nop 0
	global_load_lds_dwordx4 v[220:221], off
	s_waitcnt vmcnt(8)
	s_waitcnt lgkmcnt(0)
	s_barrier
; #define PG8_STAGE(bufoff, gbase, voff) do { _Pragma("unroll") for (int _i = 0; _i < 2; ++_i) \
;         __builtin_amdgcn_global_load_lds((const unsigned*)((const char*)(gbase) + (voff)[_i]), (LAS unsigned*)(lds + (bufoff) + ldsw + _i * 8192), 16, 0, 0); } while (0)
; #define PG8_LDA(dst, b, h) do { _Pragma("unroll") for (int m = 0; m < 4; ++m) _Pragma("unroll") for (int k = 0; k < 2; ++k) dst[m][k] = *(const LAS bf16x8*)(lds + PG8_SA(b, h) + aoff + m * 2048 + k * 1024); } while (0)
; #define PG8_LDB(dst, b, h) do { _Pragma("unroll") for (int n = 0; n < 2; ++n) _Pragma("unroll") for (int k = 0; k < 2; ++k) dst[n][k] = *(const LAS bf16x8*)(lds + PG8_SB(b, h) + boff + n * 2048 + k * 1024); } while (0)
; #define PG8_MMA(ai, bj, At, Bt) do { __builtin_amdgcn_s_setprio(1); _Pragma("unroll") for (int m = 0; m < 4; ++m) _Pragma("unroll") for (int n = 0; n < 2; ++n) _Pragma("unroll") for (int k = 0; k < 2; ++k) \
;         acc[ai][bj][m][n] = __builtin_amdgcn_mfma_f32_16x16x32_bf16(Bt[n][k], At[m][k], acc[ai][bj][m][n], 0, 0, 0); __builtin_amdgcn_s_setprio(0); } while (0)
; #define PG8_WAIT_V(n) asm volatile("s_waitcnt vmcnt(" #n ")" ::: "memory")
; #define PG8_WAIT_L(n) asm volatile("s_waitcnt lgkmcnt(" #n ")" ::: "memory")
; #define PG8_BAR __builtin_amdgcn_s_barrier()
; #define PG8_SCHED __builtin_amdgcn_sched_barrier(0)
; template <class Epi>
; __device__ __forceinline__ void gemm_phase(LAS unsigned char* lds, const Gemm g, int G, int c, const Epi& E) {
;     ...
;             PG8_WAIT_V(8); PG8_WAIT_L(0); PG8_BAR; PG8_MMA(1, 0, At, B0); PG8_MMA(1, 1, At, B1); PG8_BAR; PG8_SCHED;
;             PG8_LDB(B0, 1, 0); PG8_LDB(B1, 1, 1); PG8_SCHED; PG8_LDA(At, 1, 0); PG8_STAGE(PG8_SA(0, 1), a2 + hstepA, voffA);
;             PG8_WAIT_V(8); PG8_WAIT_L(0); PG8_BAR; PG8_MMA(0, 0, At, B0); PG8_MMA(0, 1, At, B1); PG8_BAR; PG8_SCHED;
	s_setprio 0
	s_waitcnt lgkmcnt(0)
	v_mfma_f32_16x16x32_bf16 v[62:65], v[142:145], v[182:185], v[62:65]
	v_mfma_f32_16x16x32_bf16 v[58:61], v[150:153], v[182:185], v[58:61]
	v_mfma_f32_16x16x32_bf16 v[46:49], v[142:145], v[190:193], v[46:49]
	v_mfma_f32_16x16x32_bf16 v[42:45], v[150:153], v[190:193], v[42:45]
	v_mfma_f32_16x16x32_bf16 v[30:33], v[142:145], v[198:201], v[30:33]
	v_mfma_f32_16x16x32_bf16 v[26:29], v[150:153], v[198:201], v[26:29]
	v_mfma_f32_16x16x32_bf16 v[14:17], v[142:145], v[206:209], v[14:17]
	v_mfma_f32_16x16x32_bf16 v[10:13], v[150:153], v[206:209], v[10:13]
	v_mfma_f32_16x16x32_bf16 v[62:65], v[146:149], v[186:189], v[62:65]
	v_mfma_f32_16x16x32_bf16 v[58:61], v[154:157], v[186:189], v[58:61]
	v_mfma_f32_16x16x32_bf16 v[46:49], v[146:149], v[194:197], v[46:49]
	v_mfma_f32_16x16x32_bf16 v[42:45], v[154:157], v[194:197], v[42:45]
	v_mfma_f32_16x16x32_bf16 v[30:33], v[146:149], v[202:205], v[30:33]
	v_mfma_f32_16x16x32_bf16 v[26:29], v[154:157], v[202:205], v[26:29]
	v_mfma_f32_16x16x32_bf16 v[14:17], v[146:149], v[210:213], v[14:17]
	v_mfma_f32_16x16x32_bf16 v[10:13], v[154:157], v[210:213], v[10:13]
	s_setprio 2
	s_setprio 0
	v_mfma_f32_16x16x32_bf16 v[54:57], v[166:169], v[182:185], v[54:57]
	v_mfma_f32_16x16x32_bf16 v[50:53], v[174:177], v[182:185], v[50:53]
	v_mfma_f32_16x16x32_bf16 v[38:41], v[166:169], v[190:193], v[38:41]
	v_mfma_f32_16x16x32_bf16 v[34:37], v[174:177], v[190:193], v[34:37]
	v_mfma_f32_16x16x32_bf16 v[22:25], v[166:169], v[198:201], v[22:25]
	v_mfma_f32_16x16x32_bf16 v[18:21], v[174:177], v[198:201], v[18:21]
	v_mfma_f32_16x16x32_bf16 v[6:9], v[166:169], v[206:209], v[6:9]
	v_mfma_f32_16x16x32_bf16 v[2:5], v[174:177], v[206:209], v[2:5]
	v_mfma_f32_16x16x32_bf16 v[54:57], v[170:173], v[186:189], v[54:57]
	v_mfma_f32_16x16x32_bf16 v[50:53], v[178:181], v[186:189], v[50:53]
	v_mfma_f32_16x16x32_bf16 v[38:41], v[170:173], v[194:197], v[38:41]
	v_mfma_f32_16x16x32_bf16 v[34:37], v[178:181], v[194:197], v[34:37]
	v_mfma_f32_16x16x32_bf16 v[22:25], v[170:173], v[202:205], v[22:25]
	v_mfma_f32_16x16x32_bf16 v[18:21], v[178:181], v[202:205], v[18:21]
	v_mfma_f32_16x16x32_bf16 v[6:9], v[170:173], v[210:213], v[6:9]
	v_mfma_f32_16x16x32_bf16 v[2:5], v[178:181], v[210:213], v[2:5]
	s_setprio 2
	s_barrier
	v_add_u32_e32 v154, s73, v159
	v_add_u32_e32 v178, s33, v159
	ds_read_b128 v[142:145], v154
	ds_read_b128 v[146:149], v154 offset:1024
	ds_read_b128 v[150:153], v154 offset:2048
	ds_read_b128 v[154:157], v154 offset:3072
	ds_read_b128 v[166:169], v178
	ds_read_b128 v[170:173], v178 offset:1024
	ds_read_b128 v[174:177], v178 offset:2048
	ds_read_b128 v[178:181], v178 offset:3072
	s_mov_b32 m0, s80
	v_lshl_add_u64 v[222:223], s[54:55], 0, v[130:131]
	ds_read_b128 v[182:185], v162 offset:32768
	ds_read_b128 v[186:189], v162 offset:33792
	ds_read_b128 v[190:193], v162 offset:34816
	ds_read_b128 v[194:197], v162 offset:35840
	ds_read_b128 v[198:201], v162 offset:36864
	ds_read_b128 v[202:205], v162 offset:37888
	ds_read_b128 v[206:209], v162 offset:38912
	ds_read_b128 v[210:213], v162 offset:39936
	global_load_lds_dwordx4 v[222:223], off
	v_lshl_add_u64 v[222:223], s[54:55], 0, v[134:135]
	s_mov_b32 m0, s81
	s_nop 0
	global_load_lds_dwordx4 v[222:223], off
	s_waitcnt vmcnt(8)
	s_waitcnt lgkmcnt(0)
	s_barrier
	s_setprio 0
	s_waitcnt lgkmcnt(0)
	v_mfma_f32_16x16x32_bf16 v[126:129], v[142:145], v[182:185], v[126:129]
	v_mfma_f32_16x16x32_bf16 v[122:125], v[150:153], v[182:185], v[122:125]
	v_mfma_f32_16x16x32_bf16 v[110:113], v[142:145], v[190:193], v[110:113]
	v_mfma_f32_16x16x32_bf16 v[106:109], v[150:153], v[190:193], v[106:109]
	v_mfma_f32_16x16x32_bf16 v[94:97], v[142:145], v[198:201], v[94:97]
	v_mfma_f32_16x16x32_bf16 v[90:93], v[150:153], v[198:201], v[90:93]
	v_mfma_f32_16x16x32_bf16 v[78:81], v[142:145], v[206:209], v[78:81]
	v_mfma_f32_16x16x32_bf16 v[74:77], v[150:153], v[206:209], v[74:77]
	v_mfma_f32_16x16x32_bf16 v[126:129], v[146:149], v[186:189], v[126:129]
	v_mfma_f32_16x16x32_bf16 v[122:125], v[154:157], v[186:189], v[122:125]
	v_mfma_f32_16x16x32_bf16 v[110:113], v[146:149], v[194:197], v[110:113]
	v_mfma_f32_16x16x32_bf16 v[106:109], v[154:157], v[194:197], v[106:109]
	v_mfma_f32_16x16x32_bf16 v[94:97], v[146:149], v[202:205], v[94:97]
	v_mfma_f32_16x16x32_bf16 v[90:93], v[154:157], v[202:205], v[90:93]
	v_mfma_f32_16x16x32_bf16 v[78:81], v[146:149], v[210:213], v[78:81]
	v_mfma_f32_16x16x32_bf16 v[74:77], v[154:157], v[210:213], v[74:77]
	s_setprio 2
	s_setprio 0
	v_mfma_f32_16x16x32_bf16 v[118:121], v[166:169], v[182:185], v[118:121]
	v_mfma_f32_16x16x32_bf16 v[114:117], v[174:177], v[182:185], v[114:117]
	v_mfma_f32_16x16x32_bf16 v[102:105], v[166:169], v[190:193], v[102:105]
	v_mfma_f32_16x16x32_bf16 v[98:101], v[174:177], v[190:193], v[98:101]
	v_mfma_f32_16x16x32_bf16 v[86:89], v[166:169], v[198:201], v[86:89]
	v_mfma_f32_16x16x32_bf16 v[82:85], v[174:177], v[198:201], v[82:85]
	v_mfma_f32_16x16x32_bf16 v[70:73], v[166:169], v[206:209], v[70:73]
	v_mfma_f32_16x16x32_bf16 v[66:69], v[174:177], v[206:209], v[66:69]
	v_mfma_f32_16x16x32_bf16 v[118:121], v[170:173], v[186:189], v[118:121]
	v_mfma_f32_16x16x32_bf16 v[114:117], v[178:181], v[186:189], v[114:117]
	v_mfma_f32_16x16x32_bf16 v[102:105], v[170:173], v[194:197], v[102:105]
	v_mfma_f32_16x16x32_bf16 v[98:101], v[178:181], v[194:197], v[98:101]
	v_mfma_f32_16x16x32_bf16 v[86:89], v[170:173], v[202:205], v[86:89]
	v_mfma_f32_16x16x32_bf16 v[82:85], v[178:181], v[202:205], v[82:85]
	v_mfma_f32_16x16x32_bf16 v[70:73], v[170:173], v[210:213], v[70:73]
	v_mfma_f32_16x16x32_bf16 v[66:69], v[178:181], v[210:213], v[66:69]
	s_setprio 2
	s_barrier
; #define PG8_STAGE(bufoff, gbase, voff) do { _Pragma("unroll") for (int _i = 0; _i < 2; ++_i) \
;         __builtin_amdgcn_global_load_lds((const unsigned*)((const char*)(gbase) + (voff)[_i]), (LAS unsigned*)(lds + (bufoff) + ldsw + _i * 8192), 16, 0, 0); } while (0)
; #define PG8_LDA(dst, b, h) do { _Pragma("unroll") for (int m = 0; m < 4; ++m) _Pragma("unroll") for (int k = 0; k < 2; ++k) dst[m][k] = *(const LAS bf16x8*)(lds + PG8_SA(b, h) + aoff + m * 2048 + k * 1024); } while (0)
; #define PG8_MMA(ai, bj, At, Bt) do { __builtin_amdgcn_s_setprio(1); _Pragma("unroll") for (int m = 0; m < 4; ++m) _Pragma("unroll") for (int n = 0; n < 2; ++n) _Pragma("unroll") for (int k = 0; k < 2; ++k) \
;         acc[ai][bj][m][n] = __builtin_amdgcn_mfma_f32_16x16x32_bf16(Bt[n][k], At[m][k], acc[ai][bj][m][n], 0, 0, 0); __builtin_amdgcn_s_setprio(0); } while (0)
; #define PG8_WAIT_V(n) asm volatile("s_waitcnt vmcnt(" #n ")" ::: "memory")
; #define PG8_WAIT_L(n) asm volatile("s_waitcnt lgkmcnt(" #n ")" ::: "memory")
; #define PG8_BAR __builtin_amdgcn_s_barrier()
; #define PG8_SCHED __builtin_amdgcn_sched_barrier(0)
; template <class Epi>
; __device__ __forceinline__ void gemm_phase(LAS unsigned char* lds, const Gemm g, int G, int c, const Epi& E) {
;     ...
;             PG8_LDA(At, 1, 1); PG8_STAGE(PG8_SB(1, 0), b3, voffB); PG8_STAGE(PG8_SB(1, 1), b3 + hstepB, voffB); PG8_STAGE(PG8_SA(1, 0), a3, voffA);
;             PG8_WAIT_V(8); PG8_WAIT_L(0); PG8_BAR; PG8_MMA(1, 0, At, B0); PG8_MMA(1, 1, At, B1); PG8_BAR; PG8_SCHED;
;         }
;         if (wr == 0) PG8_BAR;
	s_mov_b32 m0, vcc_hi
	v_lshl_add_u64 v[214:215], v[214:215], 0, s[24:25]
	ds_read_b128 v[182:185], v162 offset:49152
	ds_read_b128 v[186:189], v162 offset:50176
	ds_read_b128 v[190:193], v162 offset:51200
	ds_read_b128 v[194:197], v162 offset:52224
	ds_read_b128 v[198:201], v162 offset:53248
	ds_read_b128 v[202:205], v162 offset:54272
	ds_read_b128 v[206:209], v162 offset:55296
	ds_read_b128 v[210:213], v162 offset:56320
	global_load_lds_dwordx4 v[214:215], off
	v_lshl_add_u64 v[214:215], v[216:217], 0, s[24:25]
	s_mov_b32 m0, s39
	s_nop 0
	global_load_lds_dwordx4 v[214:215], off
	v_lshl_add_u64 v[214:215], s[10:11], 0, v[132:133]
	s_mov_b32 m0, vcc_lo
	s_nop 0
	global_load_lds_dwordx4 v[214:215], off
	v_lshl_add_u64 v[214:215], s[10:11], 0, v[136:137]
	s_mov_b32 m0, s38
	s_nop 0
	global_load_lds_dwordx4 v[214:215], off
	v_lshl_add_u64 v[214:215], v[218:219], 0, s[24:25]
	s_mov_b32 m0, s85
	s_nop 0
	global_load_lds_dwordx4 v[214:215], off
	v_lshl_add_u64 v[214:215], v[220:221], 0, s[24:25]
	s_mov_b32 m0, s86
	s_nop 0
	global_load_lds_dwordx4 v[214:215], off
	s_waitcnt vmcnt(8)
	s_waitcnt lgkmcnt(0)
	s_barrier
	s_setprio 0
	s_waitcnt lgkmcnt(0)
	v_mfma_f32_16x16x32_bf16 v[62:65], v[142:145], v[182:185], v[62:65]
	v_mfma_f32_16x16x32_bf16 v[58:61], v[150:153], v[182:185], v[58:61]
	v_mfma_f32_16x16x32_bf16 v[46:49], v[142:145], v[190:193], v[46:49]
	v_mfma_f32_16x16x32_bf16 v[42:45], v[150:153], v[190:193], v[42:45]
	v_mfma_f32_16x16x32_bf16 v[30:33], v[142:145], v[198:201], v[30:33]
	v_mfma_f32_16x16x32_bf16 v[26:29], v[150:153], v[198:201], v[26:29]
	v_mfma_f32_16x16x32_bf16 v[14:17], v[142:145], v[206:209], v[14:17]
	v_mfma_f32_16x16x32_bf16 v[10:13], v[150:153], v[206:209], v[10:13]
	v_mfma_f32_16x16x32_bf16 v[62:65], v[146:149], v[186:189], v[62:65]
	v_mfma_f32_16x16x32_bf16 v[58:61], v[154:157], v[186:189], v[58:61]
	v_mfma_f32_16x16x32_bf16 v[46:49], v[146:149], v[194:197], v[46:49]
	v_mfma_f32_16x16x32_bf16 v[42:45], v[154:157], v[194:197], v[42:45]
	v_mfma_f32_16x16x32_bf16 v[30:33], v[146:149], v[202:205], v[30:33]
	v_mfma_f32_16x16x32_bf16 v[26:29], v[154:157], v[202:205], v[26:29]
	v_mfma_f32_16x16x32_bf16 v[14:17], v[146:149], v[210:213], v[14:17]
	v_mfma_f32_16x16x32_bf16 v[10:13], v[154:157], v[210:213], v[10:13]
	s_setprio 2
	s_setprio 0
	v_mfma_f32_16x16x32_bf16 v[54:57], v[166:169], v[182:185], v[54:57]
	v_mfma_f32_16x16x32_bf16 v[50:53], v[174:177], v[182:185], v[50:53]
	v_mfma_f32_16x16x32_bf16 v[38:41], v[166:169], v[190:193], v[38:41]
	v_mfma_f32_16x16x32_bf16 v[34:37], v[174:177], v[190:193], v[34:37]
	v_mfma_f32_16x16x32_bf16 v[22:25], v[166:169], v[198:201], v[22:25]
	v_mfma_f32_16x16x32_bf16 v[18:21], v[174:177], v[198:201], v[18:21]
	v_mfma_f32_16x16x32_bf16 v[6:9], v[166:169], v[206:209], v[6:9]
	v_mfma_f32_16x16x32_bf16 v[2:5], v[174:177], v[206:209], v[2:5]
	v_mfma_f32_16x16x32_bf16 v[54:57], v[170:173], v[186:189], v[54:57]
	v_mfma_f32_16x16x32_bf16 v[50:53], v[178:181], v[186:189], v[50:53]
	v_mfma_f32_16x16x32_bf16 v[38:41], v[170:173], v[194:197], v[38:41]
	v_mfma_f32_16x16x32_bf16 v[34:37], v[178:181], v[194:197], v[34:37]
	v_mfma_f32_16x16x32_bf16 v[22:25], v[170:173], v[202:205], v[22:25]
	v_mfma_f32_16x16x32_bf16 v[18:21], v[178:181], v[202:205], v[18:21]
	v_mfma_f32_16x16x32_bf16 v[6:9], v[170:173], v[210:213], v[6:9]
	v_mfma_f32_16x16x32_bf16 v[2:5], v[178:181], v[210:213], v[2:5]
	s_setprio 2
	s_barrier
	s_movk_i32 s38, 0x100
	s_andn2_b64 vcc, exec, s[4:5]
	s_mov_b64 s[10:11], -1
	s_mov_b64 s[4:5], 0
	s_cbranch_vccz .LBB0_390
	s_and_b64 vcc, exec, s[44:45]
	s_cbranch_vccz .LBB0_393
	s_barrier

; #define PG8_STAGE(bufoff, gbase, voff) do { _Pragma("unroll") for (int _i = 0; _i < 2; ++_i) \
;         __builtin_amdgcn_global_load_lds((const unsigned*)((const char*)(gbase) + (voff)[_i]), (LAS unsigned*)(lds + (bufoff) + ldsw + _i * 8192), 16, 0, 0); } while (0)
; #define PG8_LDA(dst, b, h) do { _Pragma("unroll") for (int m = 0; m < 4; ++m) _Pragma("unroll") for (int k = 0; k < 2; ++k) dst[m][k] = *(const LAS bf16x8*)(lds + PG8_SA(b, h) + aoff + m * 2048 + k * 1024); } while (0)
; #define PG8_LDB(dst, b, h) do { _Pragma("unroll") for (int n = 0; n < 2; ++n) _Pragma("unroll") for (int k = 0; k < 2; ++k) dst[n][k] = *(const LAS bf16x8*)(lds + PG8_SB(b, h) + boff + n * 2048 + k * 1024); } while (0)
; #define PG8_MMA(ai, bj, At, Bt) do { __builtin_amdgcn_s_setprio(1); _Pragma("unroll") for (int m = 0; m < 4; ++m) _Pragma("unroll") for (int n = 0; n < 2; ++n) _Pragma("unroll") for (int k = 0; k < 2; ++k) \
;         acc[ai][bj][m][n] = __builtin_amdgcn_mfma_f32_16x16x32_bf16(Bt[n][k], At[m][k], acc[ai][bj][m][n], 0, 0, 0); __builtin_amdgcn_s_setprio(0); } while (0)
; #define PG8_WAIT_V(n) asm volatile("s_waitcnt vmcnt(" #n ")" ::: "memory")
; #define PG8_WAIT_L(n) asm volatile("s_waitcnt lgkmcnt(" #n ")" ::: "memory")
; #define PG8_BAR __builtin_amdgcn_s_barrier()
; #define PG8_SCHED __builtin_amdgcn_sched_barrier(0)
; template <class Epi>
; __device__ __forceinline__ void gemm_phase(LAS unsigned char* lds, const Gemm g, int G, int c, const Epi& E) {
;     ...
;             const bool last = (t == nt - 2);
;             const char* a1 = cA + (size_t)(t + 1) * kstep;
;             const char* a2 = last ? nA : cA + (size_t)(t + 2) * kstep; const char* b2 = last ? nB : cB + (size_t)(t + 2) * kstep;
;             const char* a3 = a2 + kstep; const char* b3 = b2 + kstep;
;             PG8_LDB(B0, 0, 0); PG8_LDB(B1, 0, 1); PG8_SCHED; PG8_LDA(At, 0, 0); PG8_STAGE(PG8_SA(1, 1), a1 + hstepA, voffA);
;             PG8_WAIT_V(8); PG8_WAIT_L(0); PG8_BAR; PG8_MMA(0, 0, At, B0); PG8_MMA(0, 1, At, B1); PG8_BAR; PG8_SCHED;
;             PG8_LDA(At, 0, 1); PG8_STAGE(PG8_SB(0, 0), b2, voffB); PG8_STAGE(PG8_SB(0, 1), b2 + hstepB, voffB); PG8_STAGE(PG8_SA(0, 0), a2, voffA);
;             PG8_WAIT_V(8); PG8_WAIT_L(0); PG8_BAR; PG8_MMA(1, 0, At, B0); PG8_MMA(1, 1, At, B1); PG8_BAR; PG8_SCHED;
.LBB0_476:
	s_add_u32 s33, s8, s38
	s_addc_u32 s39, s9, 0
	s_add_u32 s56, s33, 0x100
	s_addc_u32 s57, s39, 0
	s_and_b64 s[54:55], s[10:11], exec
	s_cselect_b32 s57, s47, s57
	s_cselect_b32 s56, s46, s56
	s_add_u32 s38, s6, s38
	s_addc_u32 s54, s7, 0
	s_add_u32 s38, s38, 0x100
	s_addc_u32 s54, s54, 0
	s_and_b64 s[10:11], s[10:11], exec
	s_cselect_b32 s59, s53, s54
	s_cselect_b32 s58, s52, s38
	s_add_u32 s66, s33, 0xb0080
	ds_read_b128 v[130:133], v166
	ds_read_b128 v[134:137], v166 offset:1024
	ds_read_b128 v[150:153], v166 offset:2048
	ds_read_b128 v[154:157], v166 offset:3072
	ds_read_b128 v[158:161], v167
	ds_read_b128 v[172:175], v167 offset:1024
	ds_read_b128 v[176:179], v167 offset:2048
	ds_read_b128 v[180:183], v167 offset:3072
	s_addc_u32 s67, s39, 0
	s_add_i32 s63, s95, s83
	s_add_i32 m0, s86, 0xc000
	s_add_i32 s64, s86, 0xe000
	s_add_i32 s74, s63, 0x2000
	s_add_u32 s60, s58, 0xb0000
	s_addc_u32 s61, s59, 0
	s_add_i32 s75, s96, s83
	s_add_i32 s62, s75, 0x2000
	s_add_i32 vcc_hi, 0, 0x18000
	s_add_i32 vcc_lo, 0, 0x1c000
	s_add_u32 s54, s56, 0xb0000
	s_addc_u32 s55, s57, 0
	s_add_i32 s39, vcc_hi, s83
	s_add_i32 s73, s39, 0x2000
	s_add_u32 s10, s58, 0xb0080
	s_addc_u32 s11, s59, 0
	s_add_i32 s38, vcc_lo, s83
	s_add_i32 s33, s38, 0x2000
	v_lshl_add_u64 v[162:163], s[66:67], 0, v[138:139]
	ds_read_b128 v[184:187], v168
	ds_read_b128 v[188:191], v168 offset:1024
	ds_read_b128 v[192:195], v168 offset:2048
	ds_read_b128 v[196:199], v168 offset:3072
	ds_read_b128 v[200:203], v168 offset:4096
	ds_read_b128 v[204:207], v168 offset:5120
	ds_read_b128 v[208:211], v168 offset:6144
	ds_read_b128 v[212:215], v168 offset:7168
	global_load_lds_dwordx4 v[162:163], off
	v_lshl_add_u64 v[162:163], s[66:67], 0, v[142:143]
	s_mov_b32 m0, s64
	s_nop 0
	global_load_lds_dwordx4 v[162:163], off
	s_waitcnt vmcnt(8)
	s_waitcnt lgkmcnt(0)
	s_barrier
	s_setprio 0
	s_waitcnt lgkmcnt(0)
	v_mfma_f32_16x16x32_bf16 v[126:129], v[130:133], v[184:187], v[126:129]
	v_mfma_f32_16x16x32_bf16 v[122:125], v[150:153], v[184:187], v[122:125]
	v_mfma_f32_16x16x32_bf16 v[110:113], v[130:133], v[192:195], v[110:113]
	v_mfma_f32_16x16x32_bf16 v[106:109], v[150:153], v[192:195], v[106:109]
	v_mfma_f32_16x16x32_bf16 v[94:97], v[130:133], v[200:203], v[94:97]
	v_mfma_f32_16x16x32_bf16 v[90:93], v[150:153], v[200:203], v[90:93]
	v_mfma_f32_16x16x32_bf16 v[78:81], v[130:133], v[208:211], v[78:81]
	v_mfma_f32_16x16x32_bf16 v[74:77], v[150:153], v[208:211], v[74:77]
	v_mfma_f32_16x16x32_bf16 v[126:129], v[134:137], v[188:191], v[126:129]
	v_mfma_f32_16x16x32_bf16 v[122:125], v[154:157], v[188:191], v[122:125]
	v_mfma_f32_16x16x32_bf16 v[110:113], v[134:137], v[196:199], v[110:113]
	v_mfma_f32_16x16x32_bf16 v[106:109], v[154:157], v[196:199], v[106:109]
	v_mfma_f32_16x16x32_bf16 v[94:97], v[134:137], v[204:207], v[94:97]
	v_mfma_f32_16x16x32_bf16 v[90:93], v[154:157], v[204:207], v[90:93]
	v_mfma_f32_16x16x32_bf16 v[78:81], v[134:137], v[212:215], v[78:81]
	v_mfma_f32_16x16x32_bf16 v[74:77], v[154:157], v[212:215], v[74:77]
	s_setprio 2
	s_setprio 0
	v_mfma_f32_16x16x32_bf16 v[118:121], v[158:161], v[184:187], v[118:121]
	v_mfma_f32_16x16x32_bf16 v[114:117], v[176:179], v[184:187], v[114:117]
	v_mfma_f32_16x16x32_bf16 v[102:105], v[158:161], v[192:195], v[102:105]
	v_mfma_f32_16x16x32_bf16 v[98:101], v[176:179], v[192:195], v[98:101]
	v_mfma_f32_16x16x32_bf16 v[86:89], v[158:161], v[200:203], v[86:89]
	v_mfma_f32_16x16x32_bf16 v[82:85], v[176:179], v[200:203], v[82:85]
	v_mfma_f32_16x16x32_bf16 v[70:73], v[158:161], v[208:211], v[70:73]
	v_mfma_f32_16x16x32_bf16 v[66:69], v[176:179], v[208:211], v[66:69]
	v_mfma_f32_16x16x32_bf16 v[118:121], v[172:175], v[188:191], v[118:121]
	v_mfma_f32_16x16x32_bf16 v[114:117], v[180:183], v[188:191], v[114:117]
	v_mfma_f32_16x16x32_bf16 v[102:105], v[172:175], v[196:199], v[102:105]
	v_mfma_f32_16x16x32_bf16 v[98:101], v[180:183], v[196:199], v[98:101]
	v_mfma_f32_16x16x32_bf16 v[86:89], v[172:175], v[204:207], v[86:89]
	v_mfma_f32_16x16x32_bf16 v[82:85], v[180:183], v[204:207], v[82:85]
	v_mfma_f32_16x16x32_bf16 v[70:73], v[172:175], v[212:215], v[70:73]
	v_mfma_f32_16x16x32_bf16 v[66:69], v[180:183], v[212:215], v[66:69]
	s_setprio 2
	s_barrier
	s_mov_b32 m0, s63
	v_lshl_add_u64 v[162:163], s[58:59], 0, v[140:141]
	ds_read_b128 v[184:187], v168 offset:16384
	ds_read_b128 v[188:191], v168 offset:17408
	ds_read_b128 v[192:195], v168 offset:18432
	ds_read_b128 v[196:199], v168 offset:19456
	ds_read_b128 v[200:203], v168 offset:20480
	ds_read_b128 v[204:207], v168 offset:21504
	ds_read_b128 v[208:211], v168 offset:22528
	ds_read_b128 v[212:215], v168 offset:23552
	global_load_lds_dwordx4 v[162:163], off
	v_lshl_add_u64 v[216:217], s[58:59], 0, v[144:145]
	s_mov_b32 m0, s74
	v_lshl_add_u64 v[218:219], s[60:61], 0, v[140:141]
	global_load_lds_dwordx4 v[216:217], off
	s_mov_b32 m0, s75
	v_lshl_add_u64 v[220:221], s[56:57], 0, v[142:143]
	global_load_lds_dwordx4 v[218:219], off
	v_lshl_add_u64 v[218:219], s[60:61], 0, v[144:145]
	s_mov_b32 m0, s62
	s_nop 0
	global_load_lds_dwordx4 v[218:219], off
	v_lshl_add_u64 v[218:219], s[56:57], 0, v[138:139]
	s_mov_b32 m0, s86
	s_nop 0
	global_load_lds_dwordx4 v[218:219], off
	s_mov_b32 m0, s87
	s_nop 0
	global_load_lds_dwordx4 v[220:221], off
	s_waitcnt vmcnt(8)
	s_waitcnt lgkmcnt(0)
	s_barrier
; #define PG8_STAGE(bufoff, gbase, voff) do { _Pragma("unroll") for (int _i = 0; _i < 2; ++_i) \
;         __builtin_amdgcn_global_load_lds((const unsigned*)((const char*)(gbase) + (voff)[_i]), (LAS unsigned*)(lds + (bufoff) + ldsw + _i * 8192), 16, 0, 0); } while (0)
; #define PG8_LDA(dst, b, h) do { _Pragma("unroll") for (int m = 0; m < 4; ++m) _Pragma("unroll") for (int k = 0; k < 2; ++k) dst[m][k] = *(const LAS bf16x8*)(lds + PG8_SA(b, h) + aoff + m * 2048 + k * 1024); } while (0)
; #define PG8_LDB(dst, b, h) do { _Pragma("unroll") for (int n = 0; n < 2; ++n) _Pragma("unroll") for (int k = 0; k < 2; ++k) dst[n][k] = *(const LAS bf16x8*)(lds + PG8_SB(b, h) + boff + n * 2048 + k * 1024); } while (0)
; #define PG8_MMA(ai, bj, At, Bt) do { __builtin_amdgcn_s_setprio(1); _Pragma("unroll") for (int m = 0; m < 4; ++m) _Pragma("unroll") for (int n = 0; n < 2; ++n) _Pragma("unroll") for (int k = 0; k < 2; ++k) \
;         acc[ai][bj][m][n] = __builtin_amdgcn_mfma_f32_16x16x32_bf16(Bt[n][k], At[m][k], acc[ai][bj][m][n], 0, 0, 0); __builtin_amdgcn_s_setprio(0); } while (0)
; #define PG8_WAIT_V(n) asm volatile("s_waitcnt vmcnt(" #n ")" ::: "memory")
; #define PG8_WAIT_L(n) asm volatile("s_waitcnt lgkmcnt(" #n ")" ::: "memory")
; #define PG8_BAR __builtin_amdgcn_s_barrier()
; #define PG8_SCHED __builtin_amdgcn_sched_barrier(0)
; template <class Epi>
; __device__ __forceinline__ void gemm_phase(LAS unsigned char* lds, const Gemm g, int G, int c, const Epi& E) {
;     ...
;             PG8_WAIT_V(8); PG8_WAIT_L(0); PG8_BAR; PG8_MMA(1, 0, At, B0); PG8_MMA(1, 1, At, B1); PG8_BAR; PG8_SCHED;
;             PG8_LDB(B0, 1, 0); PG8_LDB(B1, 1, 1); PG8_SCHED; PG8_LDA(At, 1, 0); PG8_STAGE(PG8_SA(0, 1), a2 + hstepA, voffA);
;             PG8_WAIT_V(8); PG8_WAIT_L(0); PG8_BAR; PG8_MMA(0, 0, At, B0); PG8_MMA(0, 1, At, B1); PG8_BAR; PG8_SCHED;
	s_setprio 0
	s_waitcnt lgkmcnt(0)
	v_mfma_f32_16x16x32_bf16 v[62:65], v[130:133], v[184:187], v[62:65]
	v_mfma_f32_16x16x32_bf16 v[58:61], v[150:153], v[184:187], v[58:61]
	v_mfma_f32_16x16x32_bf16 v[46:49], v[130:133], v[192:195], v[46:49]
	v_mfma_f32_16x16x32_bf16 v[42:45], v[150:153], v[192:195], v[42:45]
	v_mfma_f32_16x16x32_bf16 v[30:33], v[130:133], v[200:203], v[30:33]
	v_mfma_f32_16x16x32_bf16 v[26:29], v[150:153], v[200:203], v[26:29]
	v_mfma_f32_16x16x32_bf16 v[14:17], v[130:133], v[208:211], v[14:17]
	v_mfma_f32_16x16x32_bf16 v[10:13], v[150:153], v[208:211], v[10:13]
	v_mfma_f32_16x16x32_bf16 v[62:65], v[134:137], v[188:191], v[62:65]
	v_mfma_f32_16x16x32_bf16 v[58:61], v[154:157], v[188:191], v[58:61]
	v_mfma_f32_16x16x32_bf16 v[46:49], v[134:137], v[196:199], v[46:49]
	v_mfma_f32_16x16x32_bf16 v[42:45], v[154:157], v[196:199], v[42:45]
	v_mfma_f32_16x16x32_bf16 v[30:33], v[134:137], v[204:207], v[30:33]
	v_mfma_f32_16x16x32_bf16 v[26:29], v[154:157], v[204:207], v[26:29]
	v_mfma_f32_16x16x32_bf16 v[14:17], v[134:137], v[212:215], v[14:17]
	v_mfma_f32_16x16x32_bf16 v[10:13], v[154:157], v[212:215], v[10:13]
	s_setprio 2
	s_setprio 0
	v_mfma_f32_16x16x32_bf16 v[54:57], v[158:161], v[184:187], v[54:57]
	v_mfma_f32_16x16x32_bf16 v[50:53], v[176:179], v[184:187], v[50:53]
	v_mfma_f32_16x16x32_bf16 v[38:41], v[158:161], v[192:195], v[38:41]
	v_mfma_f32_16x16x32_bf16 v[34:37], v[176:179], v[192:195], v[34:37]
	v_mfma_f32_16x16x32_bf16 v[22:25], v[158:161], v[200:203], v[22:25]
	v_mfma_f32_16x16x32_bf16 v[18:21], v[176:179], v[200:203], v[18:21]
	v_mfma_f32_16x16x32_bf16 v[6:9], v[158:161], v[208:211], v[6:9]
	v_mfma_f32_16x16x32_bf16 v[2:5], v[176:179], v[208:211], v[2:5]
	v_mfma_f32_16x16x32_bf16 v[54:57], v[172:175], v[188:191], v[54:57]
	v_mfma_f32_16x16x32_bf16 v[50:53], v[180:183], v[188:191], v[50:53]
	v_mfma_f32_16x16x32_bf16 v[38:41], v[172:175], v[196:199], v[38:41]
	v_mfma_f32_16x16x32_bf16 v[34:37], v[180:183], v[196:199], v[34:37]
	v_mfma_f32_16x16x32_bf16 v[22:25], v[172:175], v[204:207], v[22:25]
	v_mfma_f32_16x16x32_bf16 v[18:21], v[180:183], v[204:207], v[18:21]
	v_mfma_f32_16x16x32_bf16 v[6:9], v[172:175], v[212:215], v[6:9]
	v_mfma_f32_16x16x32_bf16 v[2:5], v[180:183], v[212:215], v[2:5]
	s_setprio 2
	s_barrier
	v_add_u32_e32 v154, vcc_hi, v165
	v_add_u32_e32 v180, vcc_lo, v165
	ds_read_b128 v[130:133], v154
	ds_read_b128 v[134:137], v154 offset:1024
	ds_read_b128 v[150:153], v154 offset:2048
	ds_read_b128 v[154:157], v154 offset:3072
	ds_read_b128 v[158:161], v180
	ds_read_b128 v[172:175], v180 offset:1024
	ds_read_b128 v[176:179], v180 offset:2048
	ds_read_b128 v[180:183], v180 offset:3072
	s_mov_b32 m0, s88
	v_lshl_add_u64 v[222:223], s[54:55], 0, v[138:139]
	ds_read_b128 v[184:187], v168 offset:32768
	ds_read_b128 v[188:191], v168 offset:33792
	ds_read_b128 v[192:195], v168 offset:34816
	ds_read_b128 v[196:199], v168 offset:35840
	ds_read_b128 v[200:203], v168 offset:36864
	ds_read_b128 v[204:207], v168 offset:37888
	ds_read_b128 v[208:211], v168 offset:38912
	ds_read_b128 v[212:215], v168 offset:39936
	global_load_lds_dwordx4 v[222:223], off
	v_lshl_add_u64 v[222:223], s[54:55], 0, v[142:143]
	s_mov_b32 m0, s89
	s_nop 0
	global_load_lds_dwordx4 v[222:223], off
	s_waitcnt vmcnt(8)
	s_waitcnt lgkmcnt(0)
	s_barrier
	s_setprio 0
	s_waitcnt lgkmcnt(0)
	v_mfma_f32_16x16x32_bf16 v[126:129], v[130:133], v[184:187], v[126:129]
	v_mfma_f32_16x16x32_bf16 v[122:125], v[150:153], v[184:187], v[122:125]
	v_mfma_f32_16x16x32_bf16 v[110:113], v[130:133], v[192:195], v[110:113]
	v_mfma_f32_16x16x32_bf16 v[106:109], v[150:153], v[192:195], v[106:109]
	v_mfma_f32_16x16x32_bf16 v[94:97], v[130:133], v[200:203], v[94:97]
	v_mfma_f32_16x16x32_bf16 v[90:93], v[150:153], v[200:203], v[90:93]
	v_mfma_f32_16x16x32_bf16 v[78:81], v[130:133], v[208:211], v[78:81]
	v_mfma_f32_16x16x32_bf16 v[74:77], v[150:153], v[208:211], v[74:77]
	v_mfma_f32_16x16x32_bf16 v[126:129], v[134:137], v[188:191], v[126:129]
	v_mfma_f32_16x16x32_bf16 v[122:125], v[154:157], v[188:191], v[122:125]
	v_mfma_f32_16x16x32_bf16 v[110:113], v[134:137], v[196:199], v[110:113]
	v_mfma_f32_16x16x32_bf16 v[106:109], v[154:157], v[196:199], v[106:109]
	v_mfma_f32_16x16x32_bf16 v[94:97], v[134:137], v[204:207], v[94:97]
	v_mfma_f32_16x16x32_bf16 v[90:93], v[154:157], v[204:207], v[90:93]
	v_mfma_f32_16x16x32_bf16 v[78:81], v[134:137], v[212:215], v[78:81]
	v_mfma_f32_16x16x32_bf16 v[74:77], v[154:157], v[212:215], v[74:77]
	s_setprio 2
	s_setprio 0
	v_mfma_f32_16x16x32_bf16 v[118:121], v[158:161], v[184:187], v[118:121]
	v_mfma_f32_16x16x32_bf16 v[114:117], v[176:179], v[184:187], v[114:117]
	v_mfma_f32_16x16x32_bf16 v[102:105], v[158:161], v[192:195], v[102:105]
	v_mfma_f32_16x16x32_bf16 v[98:101], v[176:179], v[192:195], v[98:101]
	v_mfma_f32_16x16x32_bf16 v[86:89], v[158:161], v[200:203], v[86:89]
	v_mfma_f32_16x16x32_bf16 v[82:85], v[176:179], v[200:203], v[82:85]
	v_mfma_f32_16x16x32_bf16 v[70:73], v[158:161], v[208:211], v[70:73]
	v_mfma_f32_16x16x32_bf16 v[66:69], v[176:179], v[208:211], v[66:69]
	v_mfma_f32_16x16x32_bf16 v[118:121], v[172:175], v[188:191], v[118:121]
	v_mfma_f32_16x16x32_bf16 v[114:117], v[180:183], v[188:191], v[114:117]
	v_mfma_f32_16x16x32_bf16 v[102:105], v[172:175], v[196:199], v[102:105]
	v_mfma_f32_16x16x32_bf16 v[98:101], v[180:183], v[196:199], v[98:101]
	v_mfma_f32_16x16x32_bf16 v[86:89], v[172:175], v[204:207], v[86:89]
	v_mfma_f32_16x16x32_bf16 v[82:85], v[180:183], v[204:207], v[82:85]
	v_mfma_f32_16x16x32_bf16 v[70:73], v[172:175], v[212:215], v[70:73]
	v_mfma_f32_16x16x32_bf16 v[66:69], v[180:183], v[212:215], v[66:69]
	s_setprio 2
	s_barrier
; #define PG8_STAGE(bufoff, gbase, voff) do { _Pragma("unroll") for (int _i = 0; _i < 2; ++_i) \
;         __builtin_amdgcn_global_load_lds((const unsigned*)((const char*)(gbase) + (voff)[_i]), (LAS unsigned*)(lds + (bufoff) + ldsw + _i * 8192), 16, 0, 0); } while (0)
; #define PG8_LDA(dst, b, h) do { _Pragma("unroll") for (int m = 0; m < 4; ++m) _Pragma("unroll") for (int k = 0; k < 2; ++k) dst[m][k] = *(const LAS bf16x8*)(lds + PG8_SA(b, h) + aoff + m * 2048 + k * 1024); } while (0)
; #define PG8_MMA(ai, bj, At, Bt) do { __builtin_amdgcn_s_setprio(1); _Pragma("unroll") for (int m = 0; m < 4; ++m) _Pragma("unroll") for (int n = 0; n < 2; ++n) _Pragma("unroll") for (int k = 0; k < 2; ++k) \
;         acc[ai][bj][m][n] = __builtin_amdgcn_mfma_f32_16x16x32_bf16(Bt[n][k], At[m][k], acc[ai][bj][m][n], 0, 0, 0); __builtin_amdgcn_s_setprio(0); } while (0)
; #define PG8_WAIT_V(n) asm volatile("s_waitcnt vmcnt(" #n ")" ::: "memory")
; #define PG8_WAIT_L(n) asm volatile("s_waitcnt lgkmcnt(" #n ")" ::: "memory")
; #define PG8_BAR __builtin_amdgcn_s_barrier()
; #define PG8_SCHED __builtin_amdgcn_sched_barrier(0)
; template <class Epi>
; __device__ __forceinline__ void gemm_phase(LAS unsigned char* lds, const Gemm g, int G, int c, const Epi& E) {
;     ...
;             PG8_LDA(At, 1, 1); PG8_STAGE(PG8_SB(1, 0), b3, voffB); PG8_STAGE(PG8_SB(1, 1), b3 + hstepB, voffB); PG8_STAGE(PG8_SA(1, 0), a3, voffA);
;             PG8_WAIT_V(8); PG8_WAIT_L(0); PG8_BAR; PG8_MMA(1, 0, At, B0); PG8_MMA(1, 1, At, B1); PG8_BAR; PG8_SCHED;
;         }
;         if (wr == 0) PG8_BAR;
	s_mov_b32 m0, s39
	v_lshl_add_u64 v[162:163], v[162:163], 0, s[24:25]
	ds_read_b128 v[184:187], v168 offset:49152
	ds_read_b128 v[188:191], v168 offset:50176
	ds_read_b128 v[192:195], v168 offset:51200
	ds_read_b128 v[196:199], v168 offset:52224
	ds_read_b128 v[200:203], v168 offset:53248
	ds_read_b128 v[204:207], v168 offset:54272
	ds_read_b128 v[208:211], v168 offset:55296
	ds_read_b128 v[212:215], v168 offset:56320
	global_load_lds_dwordx4 v[162:163], off
	v_lshl_add_u64 v[162:163], v[216:217], 0, s[24:25]
	s_mov_b32 m0, s73
	s_nop 0
	global_load_lds_dwordx4 v[162:163], off
	v_lshl_add_u64 v[162:163], s[10:11], 0, v[140:141]
	s_mov_b32 m0, s38
	s_nop 0
	global_load_lds_dwordx4 v[162:163], off
	v_lshl_add_u64 v[162:163], s[10:11], 0, v[144:145]
	s_mov_b32 m0, s33
	s_nop 0
	global_load_lds_dwordx4 v[162:163], off
	v_lshl_add_u64 v[162:163], v[218:219], 0, s[24:25]
	s_mov_b32 m0, s93
	s_nop 0
	global_load_lds_dwordx4 v[162:163], off
	v_lshl_add_u64 v[162:163], v[220:221], 0, s[24:25]
	s_mov_b32 m0, s94
	s_nop 0
	global_load_lds_dwordx4 v[162:163], off
	s_waitcnt vmcnt(8)
	s_waitcnt lgkmcnt(0)
	s_barrier
	s_setprio 0
	s_waitcnt lgkmcnt(0)
	v_mfma_f32_16x16x32_bf16 v[62:65], v[130:133], v[184:187], v[62:65]
	v_mfma_f32_16x16x32_bf16 v[58:61], v[150:153], v[184:187], v[58:61]
	v_mfma_f32_16x16x32_bf16 v[46:49], v[130:133], v[192:195], v[46:49]
	v_mfma_f32_16x16x32_bf16 v[42:45], v[150:153], v[192:195], v[42:45]
	v_mfma_f32_16x16x32_bf16 v[30:33], v[130:133], v[200:203], v[30:33]
	v_mfma_f32_16x16x32_bf16 v[26:29], v[150:153], v[200:203], v[26:29]
	v_mfma_f32_16x16x32_bf16 v[14:17], v[130:133], v[208:211], v[14:17]
	v_mfma_f32_16x16x32_bf16 v[10:13], v[150:153], v[208:211], v[10:13]
	v_mfma_f32_16x16x32_bf16 v[62:65], v[134:137], v[188:191], v[62:65]
	v_mfma_f32_16x16x32_bf16 v[58:61], v[154:157], v[188:191], v[58:61]
	v_mfma_f32_16x16x32_bf16 v[46:49], v[134:137], v[196:199], v[46:49]
	v_mfma_f32_16x16x32_bf16 v[42:45], v[154:157], v[196:199], v[42:45]
	v_mfma_f32_16x16x32_bf16 v[30:33], v[134:137], v[204:207], v[30:33]
	v_mfma_f32_16x16x32_bf16 v[26:29], v[154:157], v[204:207], v[26:29]
	v_mfma_f32_16x16x32_bf16 v[14:17], v[134:137], v[212:215], v[14:17]
	v_mfma_f32_16x16x32_bf16 v[10:13], v[154:157], v[212:215], v[10:13]
	s_setprio 2
	s_setprio 0
	v_mfma_f32_16x16x32_bf16 v[54:57], v[158:161], v[184:187], v[54:57]
	v_mfma_f32_16x16x32_bf16 v[50:53], v[176:179], v[184:187], v[50:53]
	v_mfma_f32_16x16x32_bf16 v[38:41], v[158:161], v[192:195], v[38:41]
	v_mfma_f32_16x16x32_bf16 v[34:37], v[176:179], v[192:195], v[34:37]
	v_mfma_f32_16x16x32_bf16 v[22:25], v[158:161], v[200:203], v[22:25]
	v_mfma_f32_16x16x32_bf16 v[18:21], v[176:179], v[200:203], v[18:21]
	v_mfma_f32_16x16x32_bf16 v[6:9], v[158:161], v[208:211], v[6:9]
	v_mfma_f32_16x16x32_bf16 v[2:5], v[176:179], v[208:211], v[2:5]
	v_mfma_f32_16x16x32_bf16 v[54:57], v[172:175], v[188:191], v[54:57]
	v_mfma_f32_16x16x32_bf16 v[50:53], v[180:183], v[188:191], v[50:53]
	v_mfma_f32_16x16x32_bf16 v[38:41], v[172:175], v[196:199], v[38:41]
	v_mfma_f32_16x16x32_bf16 v[34:37], v[180:183], v[196:199], v[34:37]
	v_mfma_f32_16x16x32_bf16 v[22:25], v[172:175], v[204:207], v[22:25]
	v_mfma_f32_16x16x32_bf16 v[18:21], v[180:183], v[204:207], v[18:21]
	v_mfma_f32_16x16x32_bf16 v[6:9], v[172:175], v[212:215], v[6:9]
	v_mfma_f32_16x16x32_bf16 v[2:5], v[180:183], v[212:215], v[2:5]
	s_setprio 2
	s_barrier
	s_movk_i32 s38, 0x100
	s_andn2_b64 vcc, exec, s[4:5]
	s_mov_b64 s[10:11], -1
	s_mov_b64 s[4:5], 0
	s_cbranch_vccz .LBB0_476
	s_and_b64 vcc, exec, s[44:45]
	s_cbranch_vccz .LBB0_479
	s_barrier

; #define PG8_STAGE(bufoff, gbase, voff) do { _Pragma("unroll") for (int _i = 0; _i < 2; ++_i) \
;         __builtin_amdgcn_global_load_lds((const unsigned*)((const char*)(gbase) + (voff)[_i]), (LAS unsigned*)(lds + (bufoff) + ldsw + _i * 8192), 16, 0, 0); } while (0)
; #define PG8_LDA(dst, b, h) do { _Pragma("unroll") for (int m = 0; m < 4; ++m) _Pragma("unroll") for (int k = 0; k < 2; ++k) dst[m][k] = *(const LAS bf16x8*)(lds + PG8_SA(b, h) + aoff + m * 2048 + k * 1024); } while (0)
; #define PG8_LDB(dst, b, h) do { _Pragma("unroll") for (int n = 0; n < 2; ++n) _Pragma("unroll") for (int k = 0; k < 2; ++k) dst[n][k] = *(const LAS bf16x8*)(lds + PG8_SB(b, h) + boff + n * 2048 + k * 1024); } while (0)
; #define PG8_MMA(ai, bj, At, Bt) do { __builtin_amdgcn_s_setprio(1); _Pragma("unroll") for (int m = 0; m < 4; ++m) _Pragma("unroll") for (int n = 0; n < 2; ++n) _Pragma("unroll") for (int k = 0; k < 2; ++k) \
;         acc[ai][bj][m][n] = __builtin_amdgcn_mfma_f32_16x16x32_bf16(Bt[n][k], At[m][k], acc[ai][bj][m][n], 0, 0, 0); __builtin_amdgcn_s_setprio(0); } while (0)
; #define PG8_WAIT_V(n) asm volatile("s_waitcnt vmcnt(" #n ")" ::: "memory")
; #define PG8_WAIT_L(n) asm volatile("s_waitcnt lgkmcnt(" #n ")" ::: "memory")
; #define PG8_BAR __builtin_amdgcn_s_barrier()
; #define PG8_SCHED __builtin_amdgcn_sched_barrier(0)
; template <class Epi>
; __device__ __forceinline__ void gemm_phase(LAS unsigned char* lds, const Gemm g, int G, int c, const Epi& E) {
;     ...
;             const bool last = (t == nt - 2);
;             const char* a1 = cA + (size_t)(t + 1) * kstep;
;             const char* a2 = last ? nA : cA + (size_t)(t + 2) * kstep; const char* b2 = last ? nB : cB + (size_t)(t + 2) * kstep;
;             const char* a3 = a2 + kstep; const char* b3 = b2 + kstep;
;             PG8_LDB(B0, 0, 0); PG8_LDB(B1, 0, 1); PG8_SCHED; PG8_LDA(At, 0, 0); PG8_STAGE(PG8_SA(1, 1), a1 + hstepA, voffA);
;             PG8_WAIT_V(8); PG8_WAIT_L(0); PG8_BAR; PG8_MMA(0, 0, At, B0); PG8_MMA(0, 1, At, B1); PG8_BAR; PG8_SCHED;
;             PG8_LDA(At, 0, 1); PG8_STAGE(PG8_SB(0, 0), b2, voffB); PG8_STAGE(PG8_SB(0, 1), b2 + hstepB, voffB); PG8_STAGE(PG8_SA(0, 0), a2, voffA);
;             PG8_WAIT_V(8); PG8_WAIT_L(0); PG8_BAR; PG8_MMA(1, 0, At, B0); PG8_MMA(1, 1, At, B1); PG8_BAR; PG8_SCHED;
.LBB0_594:
	s_add_u32 s33, s8, s38
	s_addc_u32 s62, s9, 0
	s_add_u32 s39, s33, 0x100
	s_addc_u32 s58, s62, 0
	s_and_b64 s[56:57], s[54:55], exec
	s_cselect_b32 s59, s45, s58
	s_cselect_b32 s58, s44, s39
	s_add_u32 s38, s6, s38
	s_addc_u32 s39, s7, 0
	s_add_u32 s56, s38, 0x100
	s_addc_u32 s57, s39, 0
	s_and_b64 s[38:39], s[54:55], exec
	s_cselect_b32 s61, s47, s57
	s_cselect_b32 s60, s46, s56
	s_add_u32 s68, s33, 0xb0080
	s_addc_u32 s69, s62, 0
	s_add_i32 s63, s86, s23
	ds_read_b128 v[142:145], v166
	ds_read_b128 v[146:149], v166 offset:1024
	ds_read_b128 v[150:153], v166 offset:2048
	ds_read_b128 v[154:157], v166 offset:3072
	ds_read_b128 v[158:161], v167
	ds_read_b128 v[170:173], v167 offset:1024
	ds_read_b128 v[174:177], v167 offset:2048
	ds_read_b128 v[178:181], v167 offset:3072
	s_add_i32 m0, s72, 0xc000
	s_add_i32 s64, s72, 0xe000
	s_add_i32 s74, s63, 0x2000
	s_add_u32 s66, s60, 0xb0000
	s_addc_u32 s67, s61, 0
	s_add_i32 s62, s87, s23
	s_add_i32 s75, s62, 0x2000
	s_add_i32 s97, 0, 0x18000
	s_add_i32 s33, 0, 0x1c000
	s_add_u32 s56, s58, 0xb0000
	s_addc_u32 s57, s59, 0
	s_add_i32 s96, s97, s23
	s_add_i32 s39, s96, 0x2000
	s_add_u32 s54, s60, 0xb0080
	s_addc_u32 s55, s61, 0
	s_add_i32 s95, s33, s23
	s_add_i32 s38, s95, 0x2000
	v_lshl_add_u64 v[162:163], s[68:69], 0, v[136:137]
	ds_read_b128 v[182:185], v168
	ds_read_b128 v[186:189], v168 offset:1024
	ds_read_b128 v[190:193], v168 offset:2048
	ds_read_b128 v[194:197], v168 offset:3072
	ds_read_b128 v[198:201], v168 offset:4096
	ds_read_b128 v[202:205], v168 offset:5120
	ds_read_b128 v[206:209], v168 offset:6144
	ds_read_b128 v[210:213], v168 offset:7168
	global_load_lds_dwordx4 v[162:163], off
	v_lshl_add_u64 v[162:163], s[68:69], 0, v[132:133]
	s_mov_b32 m0, s64
	s_nop 0
	global_load_lds_dwordx4 v[162:163], off
	s_waitcnt vmcnt(8)
	s_waitcnt lgkmcnt(0)
	s_barrier
	s_setprio 0
	s_waitcnt lgkmcnt(0)
	v_mfma_f32_16x16x32_bf16 v[126:129], v[142:145], v[182:185], v[126:129]
	v_mfma_f32_16x16x32_bf16 v[122:125], v[150:153], v[182:185], v[122:125]
	v_mfma_f32_16x16x32_bf16 v[110:113], v[142:145], v[190:193], v[110:113]
	v_mfma_f32_16x16x32_bf16 v[106:109], v[150:153], v[190:193], v[106:109]
	v_mfma_f32_16x16x32_bf16 v[94:97], v[142:145], v[198:201], v[94:97]
	v_mfma_f32_16x16x32_bf16 v[90:93], v[150:153], v[198:201], v[90:93]
	v_mfma_f32_16x16x32_bf16 v[78:81], v[142:145], v[206:209], v[78:81]
	v_mfma_f32_16x16x32_bf16 v[74:77], v[150:153], v[206:209], v[74:77]
	v_mfma_f32_16x16x32_bf16 v[126:129], v[146:149], v[186:189], v[126:129]
	v_mfma_f32_16x16x32_bf16 v[122:125], v[154:157], v[186:189], v[122:125]
	v_mfma_f32_16x16x32_bf16 v[110:113], v[146:149], v[194:197], v[110:113]
	v_mfma_f32_16x16x32_bf16 v[106:109], v[154:157], v[194:197], v[106:109]
	v_mfma_f32_16x16x32_bf16 v[94:97], v[146:149], v[202:205], v[94:97]
	v_mfma_f32_16x16x32_bf16 v[90:93], v[154:157], v[202:205], v[90:93]
	v_mfma_f32_16x16x32_bf16 v[78:81], v[146:149], v[210:213], v[78:81]
	v_mfma_f32_16x16x32_bf16 v[74:77], v[154:157], v[210:213], v[74:77]
	s_setprio 2
	s_setprio 0
	v_mfma_f32_16x16x32_bf16 v[118:121], v[158:161], v[182:185], v[118:121]
	v_mfma_f32_16x16x32_bf16 v[114:117], v[174:177], v[182:185], v[114:117]
	v_mfma_f32_16x16x32_bf16 v[102:105], v[158:161], v[190:193], v[102:105]
	v_mfma_f32_16x16x32_bf16 v[98:101], v[174:177], v[190:193], v[98:101]
	v_mfma_f32_16x16x32_bf16 v[86:89], v[158:161], v[198:201], v[86:89]
	v_mfma_f32_16x16x32_bf16 v[82:85], v[174:177], v[198:201], v[82:85]
	v_mfma_f32_16x16x32_bf16 v[70:73], v[158:161], v[206:209], v[70:73]
	v_mfma_f32_16x16x32_bf16 v[66:69], v[174:177], v[206:209], v[66:69]
	v_mfma_f32_16x16x32_bf16 v[118:121], v[170:173], v[186:189], v[118:121]
	v_mfma_f32_16x16x32_bf16 v[114:117], v[178:181], v[186:189], v[114:117]
	v_mfma_f32_16x16x32_bf16 v[102:105], v[170:173], v[194:197], v[102:105]
	v_mfma_f32_16x16x32_bf16 v[98:101], v[178:181], v[194:197], v[98:101]
	v_mfma_f32_16x16x32_bf16 v[86:89], v[170:173], v[202:205], v[86:89]
	v_mfma_f32_16x16x32_bf16 v[82:85], v[178:181], v[202:205], v[82:85]
	v_mfma_f32_16x16x32_bf16 v[70:73], v[170:173], v[210:213], v[70:73]
	v_mfma_f32_16x16x32_bf16 v[66:69], v[178:181], v[210:213], v[66:69]
	s_setprio 2
	s_barrier
	s_mov_b32 m0, s63
	v_lshl_add_u64 v[162:163], s[60:61], 0, v[134:135]
	ds_read_b128 v[182:185], v168 offset:16384
	ds_read_b128 v[186:189], v168 offset:17408
	ds_read_b128 v[190:193], v168 offset:18432
	ds_read_b128 v[194:197], v168 offset:19456
	ds_read_b128 v[198:201], v168 offset:20480
	ds_read_b128 v[202:205], v168 offset:21504
	ds_read_b128 v[206:209], v168 offset:22528
	ds_read_b128 v[210:213], v168 offset:23552
	global_load_lds_dwordx4 v[162:163], off
	v_lshl_add_u64 v[214:215], s[60:61], 0, v[130:131]
	s_mov_b32 m0, s74
	v_lshl_add_u64 v[216:217], s[66:67], 0, v[134:135]
	global_load_lds_dwordx4 v[214:215], off
	s_mov_b32 m0, s62
	v_lshl_add_u64 v[218:219], s[58:59], 0, v[132:133]
	global_load_lds_dwordx4 v[216:217], off
	v_lshl_add_u64 v[216:217], s[66:67], 0, v[130:131]
	s_mov_b32 m0, s75
	s_nop 0
	global_load_lds_dwordx4 v[216:217], off
	v_lshl_add_u64 v[216:217], s[58:59], 0, v[136:137]
	s_mov_b32 m0, s72
	s_nop 0
	global_load_lds_dwordx4 v[216:217], off
	s_mov_b32 m0, s73
	s_nop 0
	global_load_lds_dwordx4 v[218:219], off
	s_waitcnt vmcnt(8)
	s_waitcnt lgkmcnt(0)
	s_barrier
; #define PG8_STAGE(bufoff, gbase, voff) do { _Pragma("unroll") for (int _i = 0; _i < 2; ++_i) \
;         __builtin_amdgcn_global_load_lds((const unsigned*)((const char*)(gbase) + (voff)[_i]), (LAS unsigned*)(lds + (bufoff) + ldsw + _i * 8192), 16, 0, 0); } while (0)
; #define PG8_LDA(dst, b, h) do { _Pragma("unroll") for (int m = 0; m < 4; ++m) _Pragma("unroll") for (int k = 0; k < 2; ++k) dst[m][k] = *(const LAS bf16x8*)(lds + PG8_SA(b, h) + aoff + m * 2048 + k * 1024); } while (0)
; #define PG8_LDB(dst, b, h) do { _Pragma("unroll") for (int n = 0; n < 2; ++n) _Pragma("unroll") for (int k = 0; k < 2; ++k) dst[n][k] = *(const LAS bf16x8*)(lds + PG8_SB(b, h) + boff + n * 2048 + k * 1024); } while (0)
; #define PG8_MMA(ai, bj, At, Bt) do { __builtin_amdgcn_s_setprio(1); _Pragma("unroll") for (int m = 0; m < 4; ++m) _Pragma("unroll") for (int n = 0; n < 2; ++n) _Pragma("unroll") for (int k = 0; k < 2; ++k) \
;         acc[ai][bj][m][n] = __builtin_amdgcn_mfma_f32_16x16x32_bf16(Bt[n][k], At[m][k], acc[ai][bj][m][n], 0, 0, 0); __builtin_amdgcn_s_setprio(0); } while (0)
; #define PG8_WAIT_V(n) asm volatile("s_waitcnt vmcnt(" #n ")" ::: "memory")
; #define PG8_WAIT_L(n) asm volatile("s_waitcnt lgkmcnt(" #n ")" ::: "memory")
; #define PG8_BAR __builtin_amdgcn_s_barrier()
; #define PG8_SCHED __builtin_amdgcn_sched_barrier(0)
; template <class Epi>
; __device__ __forceinline__ void gemm_phase(LAS unsigned char* lds, const Gemm g, int G, int c, const Epi& E) {
;     ...
;             PG8_WAIT_V(8); PG8_WAIT_L(0); PG8_BAR; PG8_MMA(1, 0, At, B0); PG8_MMA(1, 1, At, B1); PG8_BAR; PG8_SCHED;
;             PG8_LDB(B0, 1, 0); PG8_LDB(B1, 1, 1); PG8_SCHED; PG8_LDA(At, 1, 0); PG8_STAGE(PG8_SA(0, 1), a2 + hstepA, voffA);
;             PG8_WAIT_V(8); PG8_WAIT_L(0); PG8_BAR; PG8_MMA(0, 0, At, B0); PG8_MMA(0, 1, At, B1); PG8_BAR; PG8_SCHED;
	s_setprio 0
	s_waitcnt lgkmcnt(0)
	v_mfma_f32_16x16x32_bf16 v[62:65], v[142:145], v[182:185], v[62:65]
	v_mfma_f32_16x16x32_bf16 v[58:61], v[150:153], v[182:185], v[58:61]
	v_mfma_f32_16x16x32_bf16 v[46:49], v[142:145], v[190:193], v[46:49]
	v_mfma_f32_16x16x32_bf16 v[42:45], v[150:153], v[190:193], v[42:45]
	v_mfma_f32_16x16x32_bf16 v[30:33], v[142:145], v[198:201], v[30:33]
	v_mfma_f32_16x16x32_bf16 v[26:29], v[150:153], v[198:201], v[26:29]
	v_mfma_f32_16x16x32_bf16 v[14:17], v[142:145], v[206:209], v[14:17]
	v_mfma_f32_16x16x32_bf16 v[10:13], v[150:153], v[206:209], v[10:13]
	v_mfma_f32_16x16x32_bf16 v[62:65], v[146:149], v[186:189], v[62:65]
	v_mfma_f32_16x16x32_bf16 v[58:61], v[154:157], v[186:189], v[58:61]
	v_mfma_f32_16x16x32_bf16 v[46:49], v[146:149], v[194:197], v[46:49]
	v_mfma_f32_16x16x32_bf16 v[42:45], v[154:157], v[194:197], v[42:45]
	v_mfma_f32_16x16x32_bf16 v[30:33], v[146:149], v[202:205], v[30:33]
	v_mfma_f32_16x16x32_bf16 v[26:29], v[154:157], v[202:205], v[26:29]
	v_mfma_f32_16x16x32_bf16 v[14:17], v[146:149], v[210:213], v[14:17]
	v_mfma_f32_16x16x32_bf16 v[10:13], v[154:157], v[210:213], v[10:13]
	s_setprio 2
	s_setprio 0
	v_mfma_f32_16x16x32_bf16 v[54:57], v[158:161], v[182:185], v[54:57]
	v_mfma_f32_16x16x32_bf16 v[50:53], v[174:177], v[182:185], v[50:53]
	v_mfma_f32_16x16x32_bf16 v[38:41], v[158:161], v[190:193], v[38:41]
	v_mfma_f32_16x16x32_bf16 v[34:37], v[174:177], v[190:193], v[34:37]
	v_mfma_f32_16x16x32_bf16 v[22:25], v[158:161], v[198:201], v[22:25]
	v_mfma_f32_16x16x32_bf16 v[18:21], v[174:177], v[198:201], v[18:21]
	v_mfma_f32_16x16x32_bf16 v[6:9], v[158:161], v[206:209], v[6:9]
	v_mfma_f32_16x16x32_bf16 v[2:5], v[174:177], v[206:209], v[2:5]
	v_mfma_f32_16x16x32_bf16 v[54:57], v[170:173], v[186:189], v[54:57]
	v_mfma_f32_16x16x32_bf16 v[50:53], v[178:181], v[186:189], v[50:53]
	v_mfma_f32_16x16x32_bf16 v[38:41], v[170:173], v[194:197], v[38:41]
	v_mfma_f32_16x16x32_bf16 v[34:37], v[178:181], v[194:197], v[34:37]
	v_mfma_f32_16x16x32_bf16 v[22:25], v[170:173], v[202:205], v[22:25]
	v_mfma_f32_16x16x32_bf16 v[18:21], v[178:181], v[202:205], v[18:21]
	v_mfma_f32_16x16x32_bf16 v[6:9], v[170:173], v[210:213], v[6:9]
	v_mfma_f32_16x16x32_bf16 v[2:5], v[178:181], v[210:213], v[2:5]
	s_setprio 2
	s_barrier
	v_add_u32_e32 v154, s97, v165
	v_add_u32_e32 v178, s33, v165
	ds_read_b128 v[142:145], v154
	ds_read_b128 v[146:149], v154 offset:1024
	ds_read_b128 v[150:153], v154 offset:2048
	ds_read_b128 v[154:157], v154 offset:3072
	ds_read_b128 v[158:161], v178
	ds_read_b128 v[170:173], v178 offset:1024
	ds_read_b128 v[174:177], v178 offset:2048
	ds_read_b128 v[178:181], v178 offset:3072
	s_mov_b32 m0, s78
	v_lshl_add_u64 v[220:221], s[56:57], 0, v[136:137]
	ds_read_b128 v[182:185], v168 offset:32768
	ds_read_b128 v[186:189], v168 offset:33792
	ds_read_b128 v[190:193], v168 offset:34816
	ds_read_b128 v[194:197], v168 offset:35840
	ds_read_b128 v[198:201], v168 offset:36864
	ds_read_b128 v[202:205], v168 offset:37888
	ds_read_b128 v[206:209], v168 offset:38912
	ds_read_b128 v[210:213], v168 offset:39936
	global_load_lds_dwordx4 v[220:221], off
	v_lshl_add_u64 v[220:221], s[56:57], 0, v[132:133]
	s_mov_b32 m0, s81
	s_nop 0
	global_load_lds_dwordx4 v[220:221], off
	s_waitcnt vmcnt(8)
	s_waitcnt lgkmcnt(0)
	s_barrier
	s_setprio 0
	s_waitcnt lgkmcnt(0)
	v_mfma_f32_16x16x32_bf16 v[126:129], v[142:145], v[182:185], v[126:129]
	v_mfma_f32_16x16x32_bf16 v[122:125], v[150:153], v[182:185], v[122:125]
	v_mfma_f32_16x16x32_bf16 v[110:113], v[142:145], v[190:193], v[110:113]
	v_mfma_f32_16x16x32_bf16 v[106:109], v[150:153], v[190:193], v[106:109]
	v_mfma_f32_16x16x32_bf16 v[94:97], v[142:145], v[198:201], v[94:97]
	v_mfma_f32_16x16x32_bf16 v[90:93], v[150:153], v[198:201], v[90:93]
	v_mfma_f32_16x16x32_bf16 v[78:81], v[142:145], v[206:209], v[78:81]
	v_mfma_f32_16x16x32_bf16 v[74:77], v[150:153], v[206:209], v[74:77]
	v_mfma_f32_16x16x32_bf16 v[126:129], v[146:149], v[186:189], v[126:129]
	v_mfma_f32_16x16x32_bf16 v[122:125], v[154:157], v[186:189], v[122:125]
	v_mfma_f32_16x16x32_bf16 v[110:113], v[146:149], v[194:197], v[110:113]
	v_mfma_f32_16x16x32_bf16 v[106:109], v[154:157], v[194:197], v[106:109]
	v_mfma_f32_16x16x32_bf16 v[94:97], v[146:149], v[202:205], v[94:97]
	v_mfma_f32_16x16x32_bf16 v[90:93], v[154:157], v[202:205], v[90:93]
	v_mfma_f32_16x16x32_bf16 v[78:81], v[146:149], v[210:213], v[78:81]
	v_mfma_f32_16x16x32_bf16 v[74:77], v[154:157], v[210:213], v[74:77]
	s_setprio 2
	s_setprio 0
	v_mfma_f32_16x16x32_bf16 v[118:121], v[158:161], v[182:185], v[118:121]
	v_mfma_f32_16x16x32_bf16 v[114:117], v[174:177], v[182:185], v[114:117]
	v_mfma_f32_16x16x32_bf16 v[102:105], v[158:161], v[190:193], v[102:105]
	v_mfma_f32_16x16x32_bf16 v[98:101], v[174:177], v[190:193], v[98:101]
	v_mfma_f32_16x16x32_bf16 v[86:89], v[158:161], v[198:201], v[86:89]
	v_mfma_f32_16x16x32_bf16 v[82:85], v[174:177], v[198:201], v[82:85]
	v_mfma_f32_16x16x32_bf16 v[70:73], v[158:161], v[206:209], v[70:73]
	v_mfma_f32_16x16x32_bf16 v[66:69], v[174:177], v[206:209], v[66:69]
	v_mfma_f32_16x16x32_bf16 v[118:121], v[170:173], v[186:189], v[118:121]
	v_mfma_f32_16x16x32_bf16 v[114:117], v[178:181], v[186:189], v[114:117]
	v_mfma_f32_16x16x32_bf16 v[102:105], v[170:173], v[194:197], v[102:105]
	v_mfma_f32_16x16x32_bf16 v[98:101], v[178:181], v[194:197], v[98:101]
	v_mfma_f32_16x16x32_bf16 v[86:89], v[170:173], v[202:205], v[86:89]
	v_mfma_f32_16x16x32_bf16 v[82:85], v[178:181], v[202:205], v[82:85]
	v_mfma_f32_16x16x32_bf16 v[70:73], v[170:173], v[210:213], v[70:73]
	v_mfma_f32_16x16x32_bf16 v[66:69], v[178:181], v[210:213], v[66:69]
	s_setprio 2
	s_barrier
; #define PG8_STAGE(bufoff, gbase, voff) do { _Pragma("unroll") for (int _i = 0; _i < 2; ++_i) \
;         __builtin_amdgcn_global_load_lds((const unsigned*)((const char*)(gbase) + (voff)[_i]), (LAS unsigned*)(lds + (bufoff) + ldsw + _i * 8192), 16, 0, 0); } while (0)
; #define PG8_LDA(dst, b, h) do { _Pragma("unroll") for (int m = 0; m < 4; ++m) _Pragma("unroll") for (int k = 0; k < 2; ++k) dst[m][k] = *(const LAS bf16x8*)(lds + PG8_SA(b, h) + aoff + m * 2048 + k * 1024); } while (0)
; #define PG8_MMA(ai, bj, At, Bt) do { __builtin_amdgcn_s_setprio(1); _Pragma("unroll") for (int m = 0; m < 4; ++m) _Pragma("unroll") for (int n = 0; n < 2; ++n) _Pragma("unroll") for (int k = 0; k < 2; ++k) \
;         acc[ai][bj][m][n] = __builtin_amdgcn_mfma_f32_16x16x32_bf16(Bt[n][k], At[m][k], acc[ai][bj][m][n], 0, 0, 0); __builtin_amdgcn_s_setprio(0); } while (0)
; #define PG8_WAIT_V(n) asm volatile("s_waitcnt vmcnt(" #n ")" ::: "memory")
; #define PG8_WAIT_L(n) asm volatile("s_waitcnt lgkmcnt(" #n ")" ::: "memory")
; #define PG8_BAR __builtin_amdgcn_s_barrier()
; #define PG8_SCHED __builtin_amdgcn_sched_barrier(0)
; template <class Epi>
; __device__ __forceinline__ void gemm_phase(LAS unsigned char* lds, const Gemm g, int G, int c, const Epi& E) {
;     ...
;             PG8_LDA(At, 1, 1); PG8_STAGE(PG8_SB(1, 0), b3, voffB); PG8_STAGE(PG8_SB(1, 1), b3 + hstepB, voffB); PG8_STAGE(PG8_SA(1, 0), a3, voffA);
;             PG8_WAIT_V(8); PG8_WAIT_L(0); PG8_BAR; PG8_MMA(1, 0, At, B0); PG8_MMA(1, 1, At, B1); PG8_BAR; PG8_SCHED;
;         }
;         if (wr == 0) PG8_BAR;
	s_mov_b32 m0, s96
	v_lshl_add_u64 v[162:163], v[162:163], 0, s[18:19]
	ds_read_b128 v[182:185], v168 offset:49152
	ds_read_b128 v[186:189], v168 offset:50176
	ds_read_b128 v[190:193], v168 offset:51200
	ds_read_b128 v[194:197], v168 offset:52224
	ds_read_b128 v[198:201], v168 offset:53248
	ds_read_b128 v[202:205], v168 offset:54272
	ds_read_b128 v[206:209], v168 offset:55296
	ds_read_b128 v[210:213], v168 offset:56320
	global_load_lds_dwordx4 v[162:163], off
	v_lshl_add_u64 v[162:163], v[214:215], 0, s[18:19]
	s_mov_b32 m0, s39
	s_nop 0
	global_load_lds_dwordx4 v[162:163], off
	v_lshl_add_u64 v[162:163], s[54:55], 0, v[134:135]
	s_mov_b32 m0, s95
	s_nop 0
	global_load_lds_dwordx4 v[162:163], off
	v_lshl_add_u64 v[162:163], s[54:55], 0, v[130:131]
	s_mov_b32 m0, s38
	s_nop 0
	global_load_lds_dwordx4 v[162:163], off
	v_lshl_add_u64 v[162:163], v[216:217], 0, s[18:19]
	s_mov_b32 m0, s84
	s_nop 0
	global_load_lds_dwordx4 v[162:163], off
	v_lshl_add_u64 v[162:163], v[218:219], 0, s[18:19]
	s_mov_b32 m0, s85
	s_nop 0
	global_load_lds_dwordx4 v[162:163], off
	s_waitcnt vmcnt(8)
	s_waitcnt lgkmcnt(0)
	s_barrier
	s_setprio 0
	s_waitcnt lgkmcnt(0)
	v_mfma_f32_16x16x32_bf16 v[62:65], v[142:145], v[182:185], v[62:65]
	v_mfma_f32_16x16x32_bf16 v[58:61], v[150:153], v[182:185], v[58:61]
	v_mfma_f32_16x16x32_bf16 v[46:49], v[142:145], v[190:193], v[46:49]
	v_mfma_f32_16x16x32_bf16 v[42:45], v[150:153], v[190:193], v[42:45]
	v_mfma_f32_16x16x32_bf16 v[30:33], v[142:145], v[198:201], v[30:33]
	v_mfma_f32_16x16x32_bf16 v[26:29], v[150:153], v[198:201], v[26:29]
	v_mfma_f32_16x16x32_bf16 v[14:17], v[142:145], v[206:209], v[14:17]
	v_mfma_f32_16x16x32_bf16 v[10:13], v[150:153], v[206:209], v[10:13]
	v_mfma_f32_16x16x32_bf16 v[62:65], v[146:149], v[186:189], v[62:65]
	v_mfma_f32_16x16x32_bf16 v[58:61], v[154:157], v[186:189], v[58:61]
	v_mfma_f32_16x16x32_bf16 v[46:49], v[146:149], v[194:197], v[46:49]
	v_mfma_f32_16x16x32_bf16 v[42:45], v[154:157], v[194:197], v[42:45]
	v_mfma_f32_16x16x32_bf16 v[30:33], v[146:149], v[202:205], v[30:33]
	v_mfma_f32_16x16x32_bf16 v[26:29], v[154:157], v[202:205], v[26:29]
	v_mfma_f32_16x16x32_bf16 v[14:17], v[146:149], v[210:213], v[14:17]
	v_mfma_f32_16x16x32_bf16 v[10:13], v[154:157], v[210:213], v[10:13]
	s_setprio 2
	s_setprio 0
	v_mfma_f32_16x16x32_bf16 v[54:57], v[158:161], v[182:185], v[54:57]
	v_mfma_f32_16x16x32_bf16 v[50:53], v[174:177], v[182:185], v[50:53]
	v_mfma_f32_16x16x32_bf16 v[38:41], v[158:161], v[190:193], v[38:41]
	v_mfma_f32_16x16x32_bf16 v[34:37], v[174:177], v[190:193], v[34:37]
	v_mfma_f32_16x16x32_bf16 v[22:25], v[158:161], v[198:201], v[22:25]
	v_mfma_f32_16x16x32_bf16 v[18:21], v[174:177], v[198:201], v[18:21]
	v_mfma_f32_16x16x32_bf16 v[6:9], v[158:161], v[206:209], v[6:9]
	v_mfma_f32_16x16x32_bf16 v[2:5], v[174:177], v[206:209], v[2:5]
	v_mfma_f32_16x16x32_bf16 v[54:57], v[170:173], v[186:189], v[54:57]
	v_mfma_f32_16x16x32_bf16 v[50:53], v[178:181], v[186:189], v[50:53]
	v_mfma_f32_16x16x32_bf16 v[38:41], v[170:173], v[194:197], v[38:41]
	v_mfma_f32_16x16x32_bf16 v[34:37], v[178:181], v[194:197], v[34:37]
	v_mfma_f32_16x16x32_bf16 v[22:25], v[170:173], v[202:205], v[22:25]
	v_mfma_f32_16x16x32_bf16 v[18:21], v[178:181], v[202:205], v[18:21]
	v_mfma_f32_16x16x32_bf16 v[6:9], v[170:173], v[210:213], v[6:9]
	v_mfma_f32_16x16x32_bf16 v[2:5], v[178:181], v[210:213], v[2:5]
	s_setprio 2
	s_barrier
	s_movk_i32 s38, 0x100
	s_andn2_b64 vcc, exec, s[4:5]
	s_mov_b64 s[54:55], -1
	s_mov_b64 s[4:5], 0
	s_cbranch_vccz .LBB0_594
	s_and_b64 vcc, exec, s[20:21]
	s_cbranch_vccz .LBB0_597
	s_barrier

; #define PG8_STAGE(bufoff, gbase, voff) do { _Pragma("unroll") for (int _i = 0; _i < 2; ++_i) \
;         __builtin_amdgcn_global_load_lds((const unsigned*)((const char*)(gbase) + (voff)[_i]), (LAS unsigned*)(lds + (bufoff) + ldsw + _i * 8192), 16, 0, 0); } while (0)
; #define PG8_LDA(dst, b, h) do { _Pragma("unroll") for (int m = 0; m < 4; ++m) _Pragma("unroll") for (int k = 0; k < 2; ++k) dst[m][k] = *(const LAS bf16x8*)(lds + PG8_SA(b, h) + aoff + m * 2048 + k * 1024); } while (0)
; #define PG8_LDB(dst, b, h) do { _Pragma("unroll") for (int n = 0; n < 2; ++n) _Pragma("unroll") for (int k = 0; k < 2; ++k) dst[n][k] = *(const LAS bf16x8*)(lds + PG8_SB(b, h) + boff + n * 2048 + k * 1024); } while (0)
; #define PG8_MMA(ai, bj, At, Bt) do { __builtin_amdgcn_s_setprio(1); _Pragma("unroll") for (int m = 0; m < 4; ++m) _Pragma("unroll") for (int n = 0; n < 2; ++n) _Pragma("unroll") for (int k = 0; k < 2; ++k) \
;         acc[ai][bj][m][n] = __builtin_amdgcn_mfma_f32_16x16x32_bf16(Bt[n][k], At[m][k], acc[ai][bj][m][n], 0, 0, 0); __builtin_amdgcn_s_setprio(0); } while (0)
; #define PG8_WAIT_V(n) asm volatile("s_waitcnt vmcnt(" #n ")" ::: "memory")
; #define PG8_WAIT_L(n) asm volatile("s_waitcnt lgkmcnt(" #n ")" ::: "memory")
; #define PG8_BAR __builtin_amdgcn_s_barrier()
; #define PG8_SCHED __builtin_amdgcn_sched_barrier(0)
; template <class Epi>
; __device__ __forceinline__ void gemm_phase(LAS unsigned char* lds, const Gemm g, int G, int c, const Epi& E) {
;     ...
;             const bool last = (t == nt - 2);
;             const char* a1 = cA + (size_t)(t + 1) * kstep;
;             const char* a2 = last ? nA : cA + (size_t)(t + 2) * kstep; const char* b2 = last ? nB : cB + (size_t)(t + 2) * kstep;
;             const char* a3 = a2 + kstep; const char* b3 = b2 + kstep;
;             PG8_LDB(B0, 0, 0); PG8_LDB(B1, 0, 1); PG8_SCHED; PG8_LDA(At, 0, 0); PG8_STAGE(PG8_SA(1, 1), a1 + hstepA, voffA);
;             PG8_WAIT_V(8); PG8_WAIT_L(0); PG8_BAR; PG8_MMA(0, 0, At, B0); PG8_MMA(0, 1, At, B1); PG8_BAR; PG8_SCHED;
;             PG8_LDA(At, 0, 1); PG8_STAGE(PG8_SB(0, 0), b2, voffB); PG8_STAGE(PG8_SB(0, 1), b2 + hstepB, voffB); PG8_STAGE(PG8_SA(0, 0), a2, voffA);
;             PG8_WAIT_V(8); PG8_WAIT_L(0); PG8_BAR; PG8_MMA(1, 0, At, B0); PG8_MMA(1, 1, At, B1); PG8_BAR; PG8_SCHED;
.LBB0_765:
	ds_read_b128 v[146:149], v152
	ds_read_b128 v[156:159], v152 offset:1024
	ds_read_b128 v[160:163], v152 offset:2048
	ds_read_b128 v[164:167], v152 offset:3072
	ds_read_b128 v[168:171], v153
	ds_read_b128 v[172:175], v153 offset:1024
	ds_read_b128 v[176:179], v153 offset:2048
	ds_read_b128 v[180:183], v153 offset:3072
	s_add_u32 s33, s44, 0xfff00080
	s_addc_u32 s46, s45, -1
	s_cmp_eq_u32 s83, 60
	s_cselect_b32 s53, s15, s46
	s_cselect_b32 s52, s78, s33
	s_cselect_b32 s47, s11, s82
	s_cselect_b32 s46, s13, s81
	v_lshl_add_u64 v[216:217], s[44:45], 0, v[138:139]
	s_add_i32 m0, s17, 0xc000
	ds_read_b128 v[184:187], v154
	ds_read_b128 v[188:191], v154 offset:1024
	ds_read_b128 v[192:195], v154 offset:2048
	ds_read_b128 v[196:199], v154 offset:3072
	ds_read_b128 v[200:203], v154 offset:4096
	ds_read_b128 v[204:207], v154 offset:5120
	ds_read_b128 v[208:211], v154 offset:6144
	ds_read_b128 v[212:215], v154 offset:7168
	global_load_lds_dwordx4 v[216:217], off
	v_lshl_add_u64 v[216:217], s[44:45], 0, v[140:141]
	s_add_i32 m0, s17, 0xe000
	s_nop 0
	global_load_lds_dwordx4 v[216:217], off
	s_waitcnt vmcnt(8)
	s_waitcnt lgkmcnt(0)
	s_barrier
	s_setprio 0
	s_waitcnt lgkmcnt(0)
	v_mfma_f32_16x16x32_bf16 v[126:129], v[146:149], v[184:187], v[126:129]
	v_mfma_f32_16x16x32_bf16 v[122:125], v[160:163], v[184:187], v[122:125]
	v_mfma_f32_16x16x32_bf16 v[118:121], v[146:149], v[192:195], v[118:121]
	v_mfma_f32_16x16x32_bf16 v[110:113], v[160:163], v[192:195], v[110:113]
	v_mfma_f32_16x16x32_bf16 v[102:105], v[146:149], v[200:203], v[102:105]
	v_mfma_f32_16x16x32_bf16 v[94:97], v[160:163], v[200:203], v[94:97]
	v_mfma_f32_16x16x32_bf16 v[86:89], v[146:149], v[208:211], v[86:89]
	v_mfma_f32_16x16x32_bf16 v[78:81], v[160:163], v[208:211], v[78:81]
	v_mfma_f32_16x16x32_bf16 v[126:129], v[156:159], v[188:191], v[126:129]
	v_mfma_f32_16x16x32_bf16 v[122:125], v[164:167], v[188:191], v[122:125]
	v_mfma_f32_16x16x32_bf16 v[118:121], v[156:159], v[196:199], v[118:121]
	v_mfma_f32_16x16x32_bf16 v[110:113], v[164:167], v[196:199], v[110:113]
	v_mfma_f32_16x16x32_bf16 v[102:105], v[156:159], v[204:207], v[102:105]
	v_mfma_f32_16x16x32_bf16 v[94:97], v[164:167], v[204:207], v[94:97]
	v_mfma_f32_16x16x32_bf16 v[86:89], v[156:159], v[212:215], v[86:89]
	v_mfma_f32_16x16x32_bf16 v[78:81], v[164:167], v[212:215], v[78:81]
	s_setprio 2
	s_setprio 0
	v_mfma_f32_16x16x32_bf16 v[114:117], v[168:171], v[184:187], v[114:117]
	v_mfma_f32_16x16x32_bf16 v[106:109], v[176:179], v[184:187], v[106:109]
	v_mfma_f32_16x16x32_bf16 v[98:101], v[168:171], v[192:195], v[98:101]
	v_mfma_f32_16x16x32_bf16 v[90:93], v[176:179], v[192:195], v[90:93]
	v_mfma_f32_16x16x32_bf16 v[82:85], v[168:171], v[200:203], v[82:85]
	v_mfma_f32_16x16x32_bf16 v[74:77], v[176:179], v[200:203], v[74:77]
	v_mfma_f32_16x16x32_bf16 v[70:73], v[168:171], v[208:211], v[70:73]
	v_mfma_f32_16x16x32_bf16 v[66:69], v[176:179], v[208:211], v[66:69]
	v_mfma_f32_16x16x32_bf16 v[114:117], v[172:175], v[188:191], v[114:117]
	v_mfma_f32_16x16x32_bf16 v[106:109], v[180:183], v[188:191], v[106:109]
	v_mfma_f32_16x16x32_bf16 v[98:101], v[172:175], v[196:199], v[98:101]
	v_mfma_f32_16x16x32_bf16 v[90:93], v[180:183], v[196:199], v[90:93]
	v_mfma_f32_16x16x32_bf16 v[82:85], v[172:175], v[204:207], v[82:85]
	v_mfma_f32_16x16x32_bf16 v[74:77], v[180:183], v[204:207], v[74:77]
	v_mfma_f32_16x16x32_bf16 v[70:73], v[172:175], v[212:215], v[70:73]
	v_mfma_f32_16x16x32_bf16 v[66:69], v[180:183], v[212:215], v[66:69]
	s_setprio 2
	s_barrier
	s_add_i32 s33, s72, s61
	v_lshl_add_u64 v[216:217], s[46:47], 0, v[134:135]
	s_mov_b32 m0, s33
	ds_read_b128 v[184:187], v154 offset:16384
	ds_read_b128 v[188:191], v154 offset:17408
	ds_read_b128 v[192:195], v154 offset:18432
	ds_read_b128 v[196:199], v154 offset:19456
	ds_read_b128 v[200:203], v154 offset:20480
	ds_read_b128 v[204:207], v154 offset:21504
	ds_read_b128 v[208:211], v154 offset:22528
	ds_read_b128 v[212:215], v154 offset:23552
	global_load_lds_dwordx4 v[216:217], off
	s_add_i32 m0, s33, 0x2000
	s_add_u32 s62, s46, 0x100000
	v_lshl_add_u64 v[218:219], s[46:47], 0, v[130:131]
	s_addc_u32 s63, s47, 0
	s_add_i32 s33, s73, s61
	global_load_lds_dwordx4 v[218:219], off
	v_lshl_add_u64 v[220:221], s[62:63], 0, v[134:135]
	s_mov_b32 m0, s33
	v_lshl_add_u64 v[224:225], s[52:53], 0, v[132:133]
	global_load_lds_dwordx4 v[220:221], off
	v_lshl_add_u64 v[220:221], s[62:63], 0, v[130:131]
	s_add_i32 m0, s33, 0x2000
	s_nop 0
	global_load_lds_dwordx4 v[220:221], off
	v_lshl_add_u64 v[220:221], s[52:53], 0, v[136:137]
	s_mov_b32 m0, s17
	s_nop 0
	global_load_lds_dwordx4 v[220:221], off
	s_mov_b32 m0, s39
	s_nop 0
	global_load_lds_dwordx4 v[224:225], off
	s_waitcnt vmcnt(8)
	s_waitcnt lgkmcnt(0)
	s_barrier
; #define PG8_STAGE(bufoff, gbase, voff) do { _Pragma("unroll") for (int _i = 0; _i < 2; ++_i) \
;         __builtin_amdgcn_global_load_lds((const unsigned*)((const char*)(gbase) + (voff)[_i]), (LAS unsigned*)(lds + (bufoff) + ldsw + _i * 8192), 16, 0, 0); } while (0)
; #define PG8_LDA(dst, b, h) do { _Pragma("unroll") for (int m = 0; m < 4; ++m) _Pragma("unroll") for (int k = 0; k < 2; ++k) dst[m][k] = *(const LAS bf16x8*)(lds + PG8_SA(b, h) + aoff + m * 2048 + k * 1024); } while (0)
; #define PG8_LDB(dst, b, h) do { _Pragma("unroll") for (int n = 0; n < 2; ++n) _Pragma("unroll") for (int k = 0; k < 2; ++k) dst[n][k] = *(const LAS bf16x8*)(lds + PG8_SB(b, h) + boff + n * 2048 + k * 1024); } while (0)
; #define PG8_MMA(ai, bj, At, Bt) do { __builtin_amdgcn_s_setprio(1); _Pragma("unroll") for (int m = 0; m < 4; ++m) _Pragma("unroll") for (int n = 0; n < 2; ++n) _Pragma("unroll") for (int k = 0; k < 2; ++k) \
;         acc[ai][bj][m][n] = __builtin_amdgcn_mfma_f32_16x16x32_bf16(Bt[n][k], At[m][k], acc[ai][bj][m][n], 0, 0, 0); __builtin_amdgcn_s_setprio(0); } while (0)
; #define PG8_WAIT_V(n) asm volatile("s_waitcnt vmcnt(" #n ")" ::: "memory")
; #define PG8_WAIT_L(n) asm volatile("s_waitcnt lgkmcnt(" #n ")" ::: "memory")
; #define PG8_BAR __builtin_amdgcn_s_barrier()
; #define PG8_SCHED __builtin_amdgcn_sched_barrier(0)
; template <class Epi>
; __device__ __forceinline__ void gemm_phase(LAS unsigned char* lds, const Gemm g, int G, int c, const Epi& E) {
;     ...
;             PG8_WAIT_V(8); PG8_WAIT_L(0); PG8_BAR; PG8_MMA(1, 0, At, B0); PG8_MMA(1, 1, At, B1); PG8_BAR; PG8_SCHED;
;             PG8_LDB(B0, 1, 0); PG8_LDB(B1, 1, 1); PG8_SCHED; PG8_LDA(At, 1, 0); PG8_STAGE(PG8_SA(0, 1), a2 + hstepA, voffA);
;             PG8_WAIT_V(8); PG8_WAIT_L(0); PG8_BAR; PG8_MMA(0, 0, At, B0); PG8_MMA(0, 1, At, B1); PG8_BAR; PG8_SCHED;
	s_setprio 0
	s_waitcnt lgkmcnt(0)
	v_mfma_f32_16x16x32_bf16 v[62:65], v[146:149], v[184:187], v[62:65]
	v_mfma_f32_16x16x32_bf16 v[58:61], v[160:163], v[184:187], v[58:61]
	v_mfma_f32_16x16x32_bf16 v[54:57], v[146:149], v[192:195], v[54:57]
	v_mfma_f32_16x16x32_bf16 v[46:49], v[160:163], v[192:195], v[46:49]
	v_mfma_f32_16x16x32_bf16 v[38:41], v[146:149], v[200:203], v[38:41]
	v_mfma_f32_16x16x32_bf16 v[30:33], v[160:163], v[200:203], v[30:33]
	v_mfma_f32_16x16x32_bf16 v[22:25], v[146:149], v[208:211], v[22:25]
	v_mfma_f32_16x16x32_bf16 v[14:17], v[160:163], v[208:211], v[14:17]
	v_mfma_f32_16x16x32_bf16 v[62:65], v[156:159], v[188:191], v[62:65]
	v_mfma_f32_16x16x32_bf16 v[58:61], v[164:167], v[188:191], v[58:61]
	v_mfma_f32_16x16x32_bf16 v[54:57], v[156:159], v[196:199], v[54:57]
	v_mfma_f32_16x16x32_bf16 v[46:49], v[164:167], v[196:199], v[46:49]
	v_mfma_f32_16x16x32_bf16 v[38:41], v[156:159], v[204:207], v[38:41]
	v_mfma_f32_16x16x32_bf16 v[30:33], v[164:167], v[204:207], v[30:33]
	v_mfma_f32_16x16x32_bf16 v[22:25], v[156:159], v[212:215], v[22:25]
	v_mfma_f32_16x16x32_bf16 v[14:17], v[164:167], v[212:215], v[14:17]
	s_setprio 2
	s_setprio 0
	v_mfma_f32_16x16x32_bf16 v[50:53], v[168:171], v[184:187], v[50:53]
	v_mfma_f32_16x16x32_bf16 v[42:45], v[176:179], v[184:187], v[42:45]
	v_mfma_f32_16x16x32_bf16 v[34:37], v[168:171], v[192:195], v[34:37]
	v_mfma_f32_16x16x32_bf16 v[26:29], v[176:179], v[192:195], v[26:29]
	v_mfma_f32_16x16x32_bf16 v[18:21], v[168:171], v[200:203], v[18:21]
	v_mfma_f32_16x16x32_bf16 v[10:13], v[176:179], v[200:203], v[10:13]
	v_mfma_f32_16x16x32_bf16 v[6:9], v[168:171], v[208:211], v[6:9]
	v_mfma_f32_16x16x32_bf16 v[2:5], v[176:179], v[208:211], v[2:5]
	v_mfma_f32_16x16x32_bf16 v[50:53], v[172:175], v[188:191], v[50:53]
	v_mfma_f32_16x16x32_bf16 v[42:45], v[180:183], v[188:191], v[42:45]
	v_mfma_f32_16x16x32_bf16 v[34:37], v[172:175], v[196:199], v[34:37]
	v_mfma_f32_16x16x32_bf16 v[26:29], v[180:183], v[196:199], v[26:29]
	v_mfma_f32_16x16x32_bf16 v[18:21], v[172:175], v[204:207], v[18:21]
	v_mfma_f32_16x16x32_bf16 v[10:13], v[180:183], v[204:207], v[10:13]
	v_mfma_f32_16x16x32_bf16 v[6:9], v[172:175], v[212:215], v[6:9]
	v_mfma_f32_16x16x32_bf16 v[2:5], v[180:183], v[212:215], v[2:5]
	s_setprio 2
	s_barrier
	s_add_i32 s33, 0, 0x18000
	v_add_u32_e32 v155, s33, v151
	s_add_i32 s62, 0, 0x1c000
	ds_read_b128 v[146:149], v155
	ds_read_b128 v[156:159], v155 offset:1024
	ds_read_b128 v[160:163], v155 offset:2048
	ds_read_b128 v[164:167], v155 offset:3072
	v_add_u32_e32 v155, s62, v151
	ds_read_b128 v[168:171], v155
	ds_read_b128 v[172:175], v155 offset:1024
	ds_read_b128 v[176:179], v155 offset:2048
	ds_read_b128 v[180:183], v155 offset:3072
	s_add_u32 s52, s52, 0x100000
	s_addc_u32 s53, s53, 0
	s_mov_b32 m0, s43
	v_lshl_add_u64 v[226:227], s[52:53], 0, v[136:137]
	ds_read_b128 v[184:187], v154 offset:32768
	ds_read_b128 v[188:191], v154 offset:33792
	ds_read_b128 v[192:195], v154 offset:34816
	ds_read_b128 v[196:199], v154 offset:35840
	ds_read_b128 v[200:203], v154 offset:36864
	ds_read_b128 v[204:207], v154 offset:37888
	ds_read_b128 v[208:211], v154 offset:38912
	ds_read_b128 v[212:215], v154 offset:39936
	global_load_lds_dwordx4 v[226:227], off
	v_lshl_add_u64 v[226:227], s[52:53], 0, v[132:133]
	s_mov_b32 m0, s66
	s_nop 0
	global_load_lds_dwordx4 v[226:227], off
	s_waitcnt vmcnt(8)
	s_waitcnt lgkmcnt(0)
	s_barrier
	s_setprio 0
	s_waitcnt lgkmcnt(0)
	v_mfma_f32_16x16x32_bf16 v[126:129], v[146:149], v[184:187], v[126:129]
	v_mfma_f32_16x16x32_bf16 v[122:125], v[160:163], v[184:187], v[122:125]
	v_mfma_f32_16x16x32_bf16 v[118:121], v[146:149], v[192:195], v[118:121]
	v_mfma_f32_16x16x32_bf16 v[110:113], v[160:163], v[192:195], v[110:113]
	v_mfma_f32_16x16x32_bf16 v[102:105], v[146:149], v[200:203], v[102:105]
	v_mfma_f32_16x16x32_bf16 v[94:97], v[160:163], v[200:203], v[94:97]
	v_mfma_f32_16x16x32_bf16 v[86:89], v[146:149], v[208:211], v[86:89]
	v_mfma_f32_16x16x32_bf16 v[78:81], v[160:163], v[208:211], v[78:81]
	v_mfma_f32_16x16x32_bf16 v[126:129], v[156:159], v[188:191], v[126:129]
	v_mfma_f32_16x16x32_bf16 v[122:125], v[164:167], v[188:191], v[122:125]
	v_mfma_f32_16x16x32_bf16 v[118:121], v[156:159], v[196:199], v[118:121]
	v_mfma_f32_16x16x32_bf16 v[110:113], v[164:167], v[196:199], v[110:113]
	v_mfma_f32_16x16x32_bf16 v[102:105], v[156:159], v[204:207], v[102:105]
	v_mfma_f32_16x16x32_bf16 v[94:97], v[164:167], v[204:207], v[94:97]
	v_mfma_f32_16x16x32_bf16 v[86:89], v[156:159], v[212:215], v[86:89]
	v_mfma_f32_16x16x32_bf16 v[78:81], v[164:167], v[212:215], v[78:81]
	s_setprio 2
	s_setprio 0
	v_mfma_f32_16x16x32_bf16 v[114:117], v[168:171], v[184:187], v[114:117]
	v_mfma_f32_16x16x32_bf16 v[106:109], v[176:179], v[184:187], v[106:109]
	v_mfma_f32_16x16x32_bf16 v[98:101], v[168:171], v[192:195], v[98:101]
	v_mfma_f32_16x16x32_bf16 v[90:93], v[176:179], v[192:195], v[90:93]
	v_mfma_f32_16x16x32_bf16 v[82:85], v[168:171], v[200:203], v[82:85]
	v_mfma_f32_16x16x32_bf16 v[74:77], v[176:179], v[200:203], v[74:77]
	v_mfma_f32_16x16x32_bf16 v[70:73], v[168:171], v[208:211], v[70:73]
	v_mfma_f32_16x16x32_bf16 v[66:69], v[176:179], v[208:211], v[66:69]
	v_mfma_f32_16x16x32_bf16 v[114:117], v[172:175], v[188:191], v[114:117]
	v_mfma_f32_16x16x32_bf16 v[106:109], v[180:183], v[188:191], v[106:109]
	v_mfma_f32_16x16x32_bf16 v[98:101], v[172:175], v[196:199], v[98:101]
	v_mfma_f32_16x16x32_bf16 v[90:93], v[180:183], v[196:199], v[90:93]
	v_mfma_f32_16x16x32_bf16 v[82:85], v[172:175], v[204:207], v[82:85]
	v_mfma_f32_16x16x32_bf16 v[74:77], v[180:183], v[204:207], v[74:77]
	v_mfma_f32_16x16x32_bf16 v[70:73], v[172:175], v[212:215], v[70:73]
	v_mfma_f32_16x16x32_bf16 v[66:69], v[180:183], v[212:215], v[66:69]
	s_setprio 2
	s_barrier
; #define PG8_STAGE(bufoff, gbase, voff) do { _Pragma("unroll") for (int _i = 0; _i < 2; ++_i) \
;         __builtin_amdgcn_global_load_lds((const unsigned*)((const char*)(gbase) + (voff)[_i]), (LAS unsigned*)(lds + (bufoff) + ldsw + _i * 8192), 16, 0, 0); } while (0)
; #define PG8_LDA(dst, b, h) do { _Pragma("unroll") for (int m = 0; m < 4; ++m) _Pragma("unroll") for (int k = 0; k < 2; ++k) dst[m][k] = *(const LAS bf16x8*)(lds + PG8_SA(b, h) + aoff + m * 2048 + k * 1024); } while (0)
; #define PG8_MMA(ai, bj, At, Bt) do { __builtin_amdgcn_s_setprio(1); _Pragma("unroll") for (int m = 0; m < 4; ++m) _Pragma("unroll") for (int n = 0; n < 2; ++n) _Pragma("unroll") for (int k = 0; k < 2; ++k) \
;         acc[ai][bj][m][n] = __builtin_amdgcn_mfma_f32_16x16x32_bf16(Bt[n][k], At[m][k], acc[ai][bj][m][n], 0, 0, 0); __builtin_amdgcn_s_setprio(0); } while (0)
; #define PG8_WAIT_V(n) asm volatile("s_waitcnt vmcnt(" #n ")" ::: "memory")
; #define PG8_WAIT_L(n) asm volatile("s_waitcnt lgkmcnt(" #n ")" ::: "memory")
; #define PG8_BAR __builtin_amdgcn_s_barrier()
; #define PG8_SCHED __builtin_amdgcn_sched_barrier(0)
; template <class Epi>
; __device__ __forceinline__ void gemm_phase(LAS unsigned char* lds, const Gemm g, int G, int c, const Epi& E) {
;     ...
;             PG8_LDA(At, 1, 1); PG8_STAGE(PG8_SB(1, 0), b3, voffB); PG8_STAGE(PG8_SB(1, 1), b3 + hstepB, voffB); PG8_STAGE(PG8_SA(1, 0), a3, voffA);
;             PG8_WAIT_V(8); PG8_WAIT_L(0); PG8_BAR; PG8_MMA(1, 0, At, B0); PG8_MMA(1, 1, At, B1); PG8_BAR; PG8_SCHED;
;         }
;         if (wr == 0) PG8_BAR;
	s_add_i32 s33, s33, s61
	v_lshl_add_u64 v[216:217], v[216:217], 0, s[6:7]
	s_mov_b32 m0, s33
	ds_read_b128 v[184:187], v154 offset:49152
	ds_read_b128 v[188:191], v154 offset:50176
	ds_read_b128 v[192:195], v154 offset:51200
	ds_read_b128 v[196:199], v154 offset:52224
	ds_read_b128 v[200:203], v154 offset:53248
	ds_read_b128 v[204:207], v154 offset:54272
	ds_read_b128 v[208:211], v154 offset:55296
	ds_read_b128 v[212:215], v154 offset:56320
	global_load_lds_dwordx4 v[216:217], off
	s_add_i32 m0, s33, 0x2000
	s_add_u32 s46, s46, 0x100080
	v_lshl_add_u64 v[216:217], v[218:219], 0, s[6:7]
	s_addc_u32 s47, s47, 0
	s_add_i32 s33, s62, s61
	global_load_lds_dwordx4 v[216:217], off
	v_lshl_add_u64 v[216:217], s[46:47], 0, v[134:135]
	s_mov_b32 m0, s33
	s_nop 0
	global_load_lds_dwordx4 v[216:217], off
	v_lshl_add_u64 v[216:217], s[46:47], 0, v[130:131]
	s_add_i32 m0, s33, 0x2000
	s_nop 0
	global_load_lds_dwordx4 v[216:217], off
	v_lshl_add_u64 v[216:217], v[220:221], 0, s[6:7]
	s_mov_b32 m0, s70
	s_nop 0
	global_load_lds_dwordx4 v[216:217], off
	v_lshl_add_u64 v[216:217], v[224:225], 0, s[6:7]
	s_mov_b32 m0, s71
	s_nop 0
	global_load_lds_dwordx4 v[216:217], off
	s_waitcnt vmcnt(8)
	s_waitcnt lgkmcnt(0)
	s_barrier
	s_setprio 0
	s_waitcnt lgkmcnt(0)
	v_mfma_f32_16x16x32_bf16 v[62:65], v[146:149], v[184:187], v[62:65]
	v_mfma_f32_16x16x32_bf16 v[58:61], v[160:163], v[184:187], v[58:61]
	v_mfma_f32_16x16x32_bf16 v[54:57], v[146:149], v[192:195], v[54:57]
	v_mfma_f32_16x16x32_bf16 v[46:49], v[160:163], v[192:195], v[46:49]
	v_mfma_f32_16x16x32_bf16 v[38:41], v[146:149], v[200:203], v[38:41]
	v_mfma_f32_16x16x32_bf16 v[30:33], v[160:163], v[200:203], v[30:33]
	v_mfma_f32_16x16x32_bf16 v[22:25], v[146:149], v[208:211], v[22:25]
	v_mfma_f32_16x16x32_bf16 v[14:17], v[160:163], v[208:211], v[14:17]
	v_mfma_f32_16x16x32_bf16 v[62:65], v[156:159], v[188:191], v[62:65]
	v_mfma_f32_16x16x32_bf16 v[58:61], v[164:167], v[188:191], v[58:61]
	v_mfma_f32_16x16x32_bf16 v[54:57], v[156:159], v[196:199], v[54:57]
	v_mfma_f32_16x16x32_bf16 v[46:49], v[164:167], v[196:199], v[46:49]
	v_mfma_f32_16x16x32_bf16 v[38:41], v[156:159], v[204:207], v[38:41]
	v_mfma_f32_16x16x32_bf16 v[30:33], v[164:167], v[204:207], v[30:33]
	v_mfma_f32_16x16x32_bf16 v[22:25], v[156:159], v[212:215], v[22:25]
	v_mfma_f32_16x16x32_bf16 v[14:17], v[164:167], v[212:215], v[14:17]
	s_setprio 2
	s_setprio 0
	v_mfma_f32_16x16x32_bf16 v[50:53], v[168:171], v[184:187], v[50:53]
	v_mfma_f32_16x16x32_bf16 v[42:45], v[176:179], v[184:187], v[42:45]
	v_mfma_f32_16x16x32_bf16 v[34:37], v[168:171], v[192:195], v[34:37]
	v_mfma_f32_16x16x32_bf16 v[26:29], v[176:179], v[192:195], v[26:29]
	v_mfma_f32_16x16x32_bf16 v[18:21], v[168:171], v[200:203], v[18:21]
	v_mfma_f32_16x16x32_bf16 v[10:13], v[176:179], v[200:203], v[10:13]
	v_mfma_f32_16x16x32_bf16 v[6:9], v[168:171], v[208:211], v[6:9]
	v_mfma_f32_16x16x32_bf16 v[2:5], v[176:179], v[208:211], v[2:5]
	v_mfma_f32_16x16x32_bf16 v[50:53], v[172:175], v[188:191], v[50:53]
	v_mfma_f32_16x16x32_bf16 v[42:45], v[180:183], v[188:191], v[42:45]
	v_mfma_f32_16x16x32_bf16 v[34:37], v[172:175], v[196:199], v[34:37]
	v_mfma_f32_16x16x32_bf16 v[26:29], v[180:183], v[196:199], v[26:29]
	v_mfma_f32_16x16x32_bf16 v[18:21], v[172:175], v[204:207], v[18:21]
	v_mfma_f32_16x16x32_bf16 v[10:13], v[180:183], v[204:207], v[10:13]
	v_mfma_f32_16x16x32_bf16 v[6:9], v[172:175], v[212:215], v[6:9]
	v_mfma_f32_16x16x32_bf16 v[2:5], v[180:183], v[212:215], v[2:5]
	s_setprio 2
	s_barrier
	s_add_i32 s83, s83, 2
	s_add_u32 s44, s44, 0x100
	s_addc_u32 s45, s45, 0
	s_add_u32 s81, s81, 0x100
	s_addc_u32 s82, s82, 0
	s_cmp_gt_u32 s83, 61
	s_cbranch_scc0 .LBB0_765
	s_and_b64 vcc, exec, s[8:9]
	s_cbranch_vccz .LBB0_768
	s_barrier

; #define PG8_STAGE(bufoff, gbase, voff) do { _Pragma("unroll") for (int _i = 0; _i < 2; ++_i) \
;         __builtin_amdgcn_global_load_lds((const unsigned*)((const char*)(gbase) + (voff)[_i]), (LAS unsigned*)(lds + (bufoff) + ldsw + _i * 8192), 16, 0, 0); } while (0)
; #define PG8_LDA(dst, b, h) do { _Pragma("unroll") for (int m = 0; m < 4; ++m) _Pragma("unroll") for (int k = 0; k < 2; ++k) dst[m][k] = *(const LAS bf16x8*)(lds + PG8_SA(b, h) + aoff + m * 2048 + k * 1024); } while (0)
; #define PG8_LDB(dst, b, h) do { _Pragma("unroll") for (int n = 0; n < 2; ++n) _Pragma("unroll") for (int k = 0; k < 2; ++k) dst[n][k] = *(const LAS bf16x8*)(lds + PG8_SB(b, h) + boff + n * 2048 + k * 1024); } while (0)
; #define PG8_MMA(ai, bj, At, Bt) do { __builtin_amdgcn_s_setprio(1); _Pragma("unroll") for (int m = 0; m < 4; ++m) _Pragma("unroll") for (int n = 0; n < 2; ++n) _Pragma("unroll") for (int k = 0; k < 2; ++k) \
;         acc[ai][bj][m][n] = __builtin_amdgcn_mfma_f32_16x16x32_bf16(Bt[n][k], At[m][k], acc[ai][bj][m][n], 0, 0, 0); __builtin_amdgcn_s_setprio(0); } while (0)
; #define PG8_WAIT_V(n) asm volatile("s_waitcnt vmcnt(" #n ")" ::: "memory")
; #define PG8_WAIT_L(n) asm volatile("s_waitcnt lgkmcnt(" #n ")" ::: "memory")
; #define PG8_BAR __builtin_amdgcn_s_barrier()
; #define PG8_SCHED __builtin_amdgcn_sched_barrier(0)
; template <class Epi>
; __device__ __forceinline__ void gemm_phase(LAS unsigned char* lds, const Gemm g, int G, int c, const Epi& E) {
;     ...
;             const bool last = (t == nt - 2);
;             const char* a1 = cA + (size_t)(t + 1) * kstep;
;             const char* a2 = last ? nA : cA + (size_t)(t + 2) * kstep; const char* b2 = last ? nB : cB + (size_t)(t + 2) * kstep;
;             const char* a3 = a2 + kstep; const char* b3 = b2 + kstep;
;             PG8_LDB(B0, 0, 0); PG8_LDB(B1, 0, 1); PG8_SCHED; PG8_LDA(At, 0, 0); PG8_STAGE(PG8_SA(1, 1), a1 + hstepA, voffA);
;             PG8_WAIT_V(8); PG8_WAIT_L(0); PG8_BAR; PG8_MMA(0, 0, At, B0); PG8_MMA(0, 1, At, B1); PG8_BAR; PG8_SCHED;
;             PG8_LDA(At, 0, 1); PG8_STAGE(PG8_SB(0, 0), b2, voffB); PG8_STAGE(PG8_SB(0, 1), b2 + hstepB, voffB); PG8_STAGE(PG8_SA(0, 0), a2, voffA);
;             PG8_WAIT_V(8); PG8_WAIT_L(0); PG8_BAR; PG8_MMA(1, 0, At, B0); PG8_MMA(1, 1, At, B1); PG8_BAR; PG8_SCHED;
.LBB0_781:
	ds_read_b128 v[150:153], v146
	ds_read_b128 v[154:157], v146 offset:1024
	ds_read_b128 v[158:161], v146 offset:2048
	ds_read_b128 v[162:165], v146 offset:3072
	ds_read_b128 v[166:169], v147
	ds_read_b128 v[170:173], v147 offset:1024
	ds_read_b128 v[174:177], v147 offset:2048
	ds_read_b128 v[178:181], v147 offset:3072
	s_add_u32 s52, s46, 0x100
	s_addc_u32 s53, s47, 0
	s_add_u32 s33, s90, s46
	s_addc_u32 s55, s91, s47
	s_cmp_eq_u32 s92, 4
	s_cselect_b32 s56, 0, s52
	s_cselect_b32 s57, 0, s53
	s_cselect_b32 s54, s89, s33
	s_cselect_b32 s55, s25, s55
	s_add_u32 s56, s2, s56
	s_addc_u32 s57, s3, s57
	s_mov_b32 m0, s83
	v_lshl_add_u64 v[142:143], v[138:139], 0, s[46:47]
	ds_read_b128 v[182:185], v148
	ds_read_b128 v[186:189], v148 offset:1024
	ds_read_b128 v[190:193], v148 offset:2048
	ds_read_b128 v[194:197], v148 offset:3072
	ds_read_b128 v[198:201], v148 offset:4096
	ds_read_b128 v[202:205], v148 offset:5120
	ds_read_b128 v[206:209], v148 offset:6144
	ds_read_b128 v[210:213], v148 offset:7168
	global_load_lds_dwordx4 v[142:143], off
	v_lshl_add_u64 v[142:143], v[140:141], 0, s[46:47]
	s_mov_b32 m0, s84
	s_nop 0
	global_load_lds_dwordx4 v[142:143], off
	s_waitcnt vmcnt(8)
	s_waitcnt lgkmcnt(0)
	s_barrier
	s_setprio 0
	s_waitcnt lgkmcnt(0)
	v_mfma_f32_16x16x32_bf16 v[126:129], v[150:153], v[182:185], v[126:129]
	v_mfma_f32_16x16x32_bf16 v[122:125], v[158:161], v[182:185], v[122:125]
	v_mfma_f32_16x16x32_bf16 v[118:121], v[150:153], v[190:193], v[118:121]
	v_mfma_f32_16x16x32_bf16 v[110:113], v[158:161], v[190:193], v[110:113]
	v_mfma_f32_16x16x32_bf16 v[102:105], v[150:153], v[198:201], v[102:105]
	v_mfma_f32_16x16x32_bf16 v[94:97], v[158:161], v[198:201], v[94:97]
	v_mfma_f32_16x16x32_bf16 v[86:89], v[150:153], v[206:209], v[86:89]
	v_mfma_f32_16x16x32_bf16 v[78:81], v[158:161], v[206:209], v[78:81]
	v_mfma_f32_16x16x32_bf16 v[126:129], v[154:157], v[186:189], v[126:129]
	v_mfma_f32_16x16x32_bf16 v[122:125], v[162:165], v[186:189], v[122:125]
	v_mfma_f32_16x16x32_bf16 v[118:121], v[154:157], v[194:197], v[118:121]
	v_mfma_f32_16x16x32_bf16 v[110:113], v[162:165], v[194:197], v[110:113]
	v_mfma_f32_16x16x32_bf16 v[102:105], v[154:157], v[202:205], v[102:105]
	v_mfma_f32_16x16x32_bf16 v[94:97], v[162:165], v[202:205], v[94:97]
	v_mfma_f32_16x16x32_bf16 v[86:89], v[154:157], v[210:213], v[86:89]
	v_mfma_f32_16x16x32_bf16 v[78:81], v[162:165], v[210:213], v[78:81]
	s_setprio 2
	s_setprio 0
	v_mfma_f32_16x16x32_bf16 v[114:117], v[166:169], v[182:185], v[114:117]
	v_mfma_f32_16x16x32_bf16 v[106:109], v[174:177], v[182:185], v[106:109]
	v_mfma_f32_16x16x32_bf16 v[98:101], v[166:169], v[190:193], v[98:101]
	v_mfma_f32_16x16x32_bf16 v[90:93], v[174:177], v[190:193], v[90:93]
	v_mfma_f32_16x16x32_bf16 v[82:85], v[166:169], v[198:201], v[82:85]
	v_mfma_f32_16x16x32_bf16 v[74:77], v[174:177], v[198:201], v[74:77]
	v_mfma_f32_16x16x32_bf16 v[70:73], v[166:169], v[206:209], v[70:73]
	v_mfma_f32_16x16x32_bf16 v[66:69], v[174:177], v[206:209], v[66:69]
	v_mfma_f32_16x16x32_bf16 v[114:117], v[170:173], v[186:189], v[114:117]
	v_mfma_f32_16x16x32_bf16 v[106:109], v[178:181], v[186:189], v[106:109]
	v_mfma_f32_16x16x32_bf16 v[98:101], v[170:173], v[194:197], v[98:101]
	v_mfma_f32_16x16x32_bf16 v[90:93], v[178:181], v[194:197], v[90:93]
	v_mfma_f32_16x16x32_bf16 v[82:85], v[170:173], v[202:205], v[82:85]
	v_mfma_f32_16x16x32_bf16 v[74:77], v[178:181], v[202:205], v[74:77]
	v_mfma_f32_16x16x32_bf16 v[70:73], v[170:173], v[210:213], v[70:73]
	v_mfma_f32_16x16x32_bf16 v[66:69], v[178:181], v[210:213], v[66:69]
	s_setprio 2
	s_barrier
	s_mov_b32 m0, s85
	v_lshl_add_u64 v[142:143], s[54:55], 0, v[134:135]
	s_add_u32 s46, s54, 0x20000
	ds_read_b128 v[182:185], v148 offset:16384
	ds_read_b128 v[186:189], v148 offset:17408
	ds_read_b128 v[190:193], v148 offset:18432
	ds_read_b128 v[194:197], v148 offset:19456
	ds_read_b128 v[198:201], v148 offset:20480
	ds_read_b128 v[202:205], v148 offset:21504
	ds_read_b128 v[206:209], v148 offset:22528
	ds_read_b128 v[210:213], v148 offset:23552
	global_load_lds_dwordx4 v[142:143], off
	v_lshl_add_u64 v[214:215], s[54:55], 0, v[130:131]
	s_mov_b32 m0, s86
	s_addc_u32 s47, s55, 0
	global_load_lds_dwordx4 v[214:215], off
	v_lshl_add_u64 v[216:217], s[46:47], 0, v[134:135]
	s_mov_b32 m0, s87
	v_lshl_add_u64 v[218:219], s[56:57], 0, v[132:133]
	global_load_lds_dwordx4 v[216:217], off
	v_lshl_add_u64 v[216:217], s[46:47], 0, v[130:131]
	s_mov_b32 m0, s88
	s_nop 0
	global_load_lds_dwordx4 v[216:217], off
	v_lshl_add_u64 v[216:217], s[56:57], 0, v[136:137]
	s_mov_b32 m0, s45
	s_nop 0
	global_load_lds_dwordx4 v[216:217], off
	s_mov_b32 m0, s61
	s_nop 0
	global_load_lds_dwordx4 v[218:219], off
	s_waitcnt vmcnt(8)
	s_waitcnt lgkmcnt(0)
	s_barrier
; #define PG8_STAGE(bufoff, gbase, voff) do { _Pragma("unroll") for (int _i = 0; _i < 2; ++_i) \
;         __builtin_amdgcn_global_load_lds((const unsigned*)((const char*)(gbase) + (voff)[_i]), (LAS unsigned*)(lds + (bufoff) + ldsw + _i * 8192), 16, 0, 0); } while (0)
; #define PG8_LDA(dst, b, h) do { _Pragma("unroll") for (int m = 0; m < 4; ++m) _Pragma("unroll") for (int k = 0; k < 2; ++k) dst[m][k] = *(const LAS bf16x8*)(lds + PG8_SA(b, h) + aoff + m * 2048 + k * 1024); } while (0)
; #define PG8_LDB(dst, b, h) do { _Pragma("unroll") for (int n = 0; n < 2; ++n) _Pragma("unroll") for (int k = 0; k < 2; ++k) dst[n][k] = *(const LAS bf16x8*)(lds + PG8_SB(b, h) + boff + n * 2048 + k * 1024); } while (0)
; #define PG8_MMA(ai, bj, At, Bt) do { __builtin_amdgcn_s_setprio(1); _Pragma("unroll") for (int m = 0; m < 4; ++m) _Pragma("unroll") for (int n = 0; n < 2; ++n) _Pragma("unroll") for (int k = 0; k < 2; ++k) \
;         acc[ai][bj][m][n] = __builtin_amdgcn_mfma_f32_16x16x32_bf16(Bt[n][k], At[m][k], acc[ai][bj][m][n], 0, 0, 0); __builtin_amdgcn_s_setprio(0); } while (0)
; #define PG8_WAIT_V(n) asm volatile("s_waitcnt vmcnt(" #n ")" ::: "memory")
; #define PG8_WAIT_L(n) asm volatile("s_waitcnt lgkmcnt(" #n ")" ::: "memory")
; #define PG8_BAR __builtin_amdgcn_s_barrier()
; #define PG8_SCHED __builtin_amdgcn_sched_barrier(0)
; template <class Epi>
; __device__ __forceinline__ void gemm_phase(LAS unsigned char* lds, const Gemm g, int G, int c, const Epi& E) {
;     ...
;             PG8_WAIT_V(8); PG8_WAIT_L(0); PG8_BAR; PG8_MMA(1, 0, At, B0); PG8_MMA(1, 1, At, B1); PG8_BAR; PG8_SCHED;
;             PG8_LDB(B0, 1, 0); PG8_LDB(B1, 1, 1); PG8_SCHED; PG8_LDA(At, 1, 0); PG8_STAGE(PG8_SA(0, 1), a2 + hstepA, voffA);
;             PG8_WAIT_V(8); PG8_WAIT_L(0); PG8_BAR; PG8_MMA(0, 0, At, B0); PG8_MMA(0, 1, At, B1); PG8_BAR; PG8_SCHED;
	s_setprio 0
	s_waitcnt lgkmcnt(0)
	v_mfma_f32_16x16x32_bf16 v[62:65], v[150:153], v[182:185], v[62:65]
	v_mfma_f32_16x16x32_bf16 v[58:61], v[158:161], v[182:185], v[58:61]
	v_mfma_f32_16x16x32_bf16 v[54:57], v[150:153], v[190:193], v[54:57]
	v_mfma_f32_16x16x32_bf16 v[46:49], v[158:161], v[190:193], v[46:49]
	v_mfma_f32_16x16x32_bf16 v[38:41], v[150:153], v[198:201], v[38:41]
	v_mfma_f32_16x16x32_bf16 v[30:33], v[158:161], v[198:201], v[30:33]
	v_mfma_f32_16x16x32_bf16 v[22:25], v[150:153], v[206:209], v[22:25]
	v_mfma_f32_16x16x32_bf16 v[14:17], v[158:161], v[206:209], v[14:17]
	v_mfma_f32_16x16x32_bf16 v[62:65], v[154:157], v[186:189], v[62:65]
	v_mfma_f32_16x16x32_bf16 v[58:61], v[162:165], v[186:189], v[58:61]
	v_mfma_f32_16x16x32_bf16 v[54:57], v[154:157], v[194:197], v[54:57]
	v_mfma_f32_16x16x32_bf16 v[46:49], v[162:165], v[194:197], v[46:49]
	v_mfma_f32_16x16x32_bf16 v[38:41], v[154:157], v[202:205], v[38:41]
	v_mfma_f32_16x16x32_bf16 v[30:33], v[162:165], v[202:205], v[30:33]
	v_mfma_f32_16x16x32_bf16 v[22:25], v[154:157], v[210:213], v[22:25]
	v_mfma_f32_16x16x32_bf16 v[14:17], v[162:165], v[210:213], v[14:17]
	s_setprio 2
	s_setprio 0
	v_mfma_f32_16x16x32_bf16 v[50:53], v[166:169], v[182:185], v[50:53]
	v_mfma_f32_16x16x32_bf16 v[42:45], v[174:177], v[182:185], v[42:45]
	v_mfma_f32_16x16x32_bf16 v[34:37], v[166:169], v[190:193], v[34:37]
	v_mfma_f32_16x16x32_bf16 v[26:29], v[174:177], v[190:193], v[26:29]
	v_mfma_f32_16x16x32_bf16 v[18:21], v[166:169], v[198:201], v[18:21]
	v_mfma_f32_16x16x32_bf16 v[10:13], v[174:177], v[198:201], v[10:13]
	v_mfma_f32_16x16x32_bf16 v[6:9], v[166:169], v[206:209], v[6:9]
	v_mfma_f32_16x16x32_bf16 v[2:5], v[174:177], v[206:209], v[2:5]
	v_mfma_f32_16x16x32_bf16 v[50:53], v[170:173], v[186:189], v[50:53]
	v_mfma_f32_16x16x32_bf16 v[42:45], v[178:181], v[186:189], v[42:45]
	v_mfma_f32_16x16x32_bf16 v[34:37], v[170:173], v[194:197], v[34:37]
	v_mfma_f32_16x16x32_bf16 v[26:29], v[178:181], v[194:197], v[26:29]
	v_mfma_f32_16x16x32_bf16 v[18:21], v[170:173], v[202:205], v[18:21]
	v_mfma_f32_16x16x32_bf16 v[10:13], v[178:181], v[202:205], v[10:13]
	v_mfma_f32_16x16x32_bf16 v[6:9], v[170:173], v[210:213], v[6:9]
	v_mfma_f32_16x16x32_bf16 v[2:5], v[178:181], v[210:213], v[2:5]
	s_setprio 2
	s_barrier
	s_add_i32 s33, 0, 0x18000
	v_add_u32_e32 v149, s33, v145
	s_add_i32 s62, 0, 0x1c000
	ds_read_b128 v[150:153], v149
	ds_read_b128 v[154:157], v149 offset:1024
	ds_read_b128 v[158:161], v149 offset:2048
	ds_read_b128 v[162:165], v149 offset:3072
	v_add_u32_e32 v149, s62, v145
	ds_read_b128 v[166:169], v149
	ds_read_b128 v[170:173], v149 offset:1024
	ds_read_b128 v[174:177], v149 offset:2048
	ds_read_b128 v[178:181], v149 offset:3072
	s_add_u32 s46, s56, 0x20000
	s_addc_u32 s47, s57, 0
	s_mov_b32 m0, s66
	v_lshl_add_u64 v[220:221], s[46:47], 0, v[136:137]
	ds_read_b128 v[182:185], v148 offset:32768
	ds_read_b128 v[186:189], v148 offset:33792
	ds_read_b128 v[190:193], v148 offset:34816
	ds_read_b128 v[194:197], v148 offset:35840
	ds_read_b128 v[198:201], v148 offset:36864
	ds_read_b128 v[202:205], v148 offset:37888
	ds_read_b128 v[206:209], v148 offset:38912
	ds_read_b128 v[210:213], v148 offset:39936
	global_load_lds_dwordx4 v[220:221], off
	v_lshl_add_u64 v[220:221], s[46:47], 0, v[132:133]
	s_mov_b32 m0, s67
	s_nop 0
	global_load_lds_dwordx4 v[220:221], off
	s_waitcnt vmcnt(8)
	s_waitcnt lgkmcnt(0)
	s_barrier
	s_setprio 0
	s_waitcnt lgkmcnt(0)
	v_mfma_f32_16x16x32_bf16 v[126:129], v[150:153], v[182:185], v[126:129]
	v_mfma_f32_16x16x32_bf16 v[122:125], v[158:161], v[182:185], v[122:125]
	v_mfma_f32_16x16x32_bf16 v[118:121], v[150:153], v[190:193], v[118:121]
	v_mfma_f32_16x16x32_bf16 v[110:113], v[158:161], v[190:193], v[110:113]
	v_mfma_f32_16x16x32_bf16 v[102:105], v[150:153], v[198:201], v[102:105]
	v_mfma_f32_16x16x32_bf16 v[94:97], v[158:161], v[198:201], v[94:97]
	v_mfma_f32_16x16x32_bf16 v[86:89], v[150:153], v[206:209], v[86:89]
	v_mfma_f32_16x16x32_bf16 v[78:81], v[158:161], v[206:209], v[78:81]
	v_mfma_f32_16x16x32_bf16 v[126:129], v[154:157], v[186:189], v[126:129]
	v_mfma_f32_16x16x32_bf16 v[122:125], v[162:165], v[186:189], v[122:125]
	v_mfma_f32_16x16x32_bf16 v[118:121], v[154:157], v[194:197], v[118:121]
	v_mfma_f32_16x16x32_bf16 v[110:113], v[162:165], v[194:197], v[110:113]
	v_mfma_f32_16x16x32_bf16 v[102:105], v[154:157], v[202:205], v[102:105]
	v_mfma_f32_16x16x32_bf16 v[94:97], v[162:165], v[202:205], v[94:97]
	v_mfma_f32_16x16x32_bf16 v[86:89], v[154:157], v[210:213], v[86:89]
	v_mfma_f32_16x16x32_bf16 v[78:81], v[162:165], v[210:213], v[78:81]
	s_setprio 2
	s_setprio 0
	v_mfma_f32_16x16x32_bf16 v[114:117], v[166:169], v[182:185], v[114:117]
	v_mfma_f32_16x16x32_bf16 v[106:109], v[174:177], v[182:185], v[106:109]
	v_mfma_f32_16x16x32_bf16 v[98:101], v[166:169], v[190:193], v[98:101]
	v_mfma_f32_16x16x32_bf16 v[90:93], v[174:177], v[190:193], v[90:93]
	v_mfma_f32_16x16x32_bf16 v[82:85], v[166:169], v[198:201], v[82:85]
	v_mfma_f32_16x16x32_bf16 v[74:77], v[174:177], v[198:201], v[74:77]
	v_mfma_f32_16x16x32_bf16 v[70:73], v[166:169], v[206:209], v[70:73]
	v_mfma_f32_16x16x32_bf16 v[66:69], v[174:177], v[206:209], v[66:69]
	v_mfma_f32_16x16x32_bf16 v[114:117], v[170:173], v[186:189], v[114:117]
	v_mfma_f32_16x16x32_bf16 v[106:109], v[178:181], v[186:189], v[106:109]
	v_mfma_f32_16x16x32_bf16 v[98:101], v[170:173], v[194:197], v[98:101]
	v_mfma_f32_16x16x32_bf16 v[90:93], v[178:181], v[194:197], v[90:93]
	v_mfma_f32_16x16x32_bf16 v[82:85], v[170:173], v[202:205], v[82:85]
	v_mfma_f32_16x16x32_bf16 v[74:77], v[178:181], v[202:205], v[74:77]
	v_mfma_f32_16x16x32_bf16 v[70:73], v[170:173], v[210:213], v[70:73]
	v_mfma_f32_16x16x32_bf16 v[66:69], v[178:181], v[210:213], v[66:69]
	s_setprio 2
	s_barrier
; #define PG8_STAGE(bufoff, gbase, voff) do { _Pragma("unroll") for (int _i = 0; _i < 2; ++_i) \
;         __builtin_amdgcn_global_load_lds((const unsigned*)((const char*)(gbase) + (voff)[_i]), (LAS unsigned*)(lds + (bufoff) + ldsw + _i * 8192), 16, 0, 0); } while (0)
; #define PG8_LDA(dst, b, h) do { _Pragma("unroll") for (int m = 0; m < 4; ++m) _Pragma("unroll") for (int k = 0; k < 2; ++k) dst[m][k] = *(const LAS bf16x8*)(lds + PG8_SA(b, h) + aoff + m * 2048 + k * 1024); } while (0)
; #define PG8_MMA(ai, bj, At, Bt) do { __builtin_amdgcn_s_setprio(1); _Pragma("unroll") for (int m = 0; m < 4; ++m) _Pragma("unroll") for (int n = 0; n < 2; ++n) _Pragma("unroll") for (int k = 0; k < 2; ++k) \
;         acc[ai][bj][m][n] = __builtin_amdgcn_mfma_f32_16x16x32_bf16(Bt[n][k], At[m][k], acc[ai][bj][m][n], 0, 0, 0); __builtin_amdgcn_s_setprio(0); } while (0)
; #define PG8_WAIT_V(n) asm volatile("s_waitcnt vmcnt(" #n ")" ::: "memory")
; #define PG8_WAIT_L(n) asm volatile("s_waitcnt lgkmcnt(" #n ")" ::: "memory")
; #define PG8_BAR __builtin_amdgcn_s_barrier()
; #define PG8_SCHED __builtin_amdgcn_sched_barrier(0)
; template <class Epi>
; __device__ __forceinline__ void gemm_phase(LAS unsigned char* lds, const Gemm g, int G, int c, const Epi& E) {
;     ...
;             PG8_LDA(At, 1, 1); PG8_STAGE(PG8_SB(1, 0), b3, voffB); PG8_STAGE(PG8_SB(1, 1), b3 + hstepB, voffB); PG8_STAGE(PG8_SA(1, 0), a3, voffA);
;             PG8_WAIT_V(8); PG8_WAIT_L(0); PG8_BAR; PG8_MMA(1, 0, At, B0); PG8_MMA(1, 1, At, B1); PG8_BAR; PG8_SCHED;
;         }
;         if (wr == 0) PG8_BAR;
	s_add_i32 s33, s33, s58
	v_lshl_add_u64 v[142:143], v[142:143], 0, s[6:7]
	s_mov_b32 m0, s33
	ds_read_b128 v[182:185], v148 offset:49152
	ds_read_b128 v[186:189], v148 offset:50176
	ds_read_b128 v[190:193], v148 offset:51200
	ds_read_b128 v[194:197], v148 offset:52224
	ds_read_b128 v[198:201], v148 offset:53248
	ds_read_b128 v[202:205], v148 offset:54272
	ds_read_b128 v[206:209], v148 offset:55296
	ds_read_b128 v[210:213], v148 offset:56320
	global_load_lds_dwordx4 v[142:143], off
	s_add_i32 m0, s33, 0x2000
	s_add_u32 s46, s54, 0x20080
	v_lshl_add_u64 v[142:143], v[214:215], 0, s[6:7]
	s_addc_u32 s47, s55, 0
	s_add_i32 s33, s62, s58
	global_load_lds_dwordx4 v[142:143], off
	v_lshl_add_u64 v[142:143], s[46:47], 0, v[134:135]
	s_mov_b32 m0, s33
	s_nop 0
	global_load_lds_dwordx4 v[142:143], off
	v_lshl_add_u64 v[142:143], s[46:47], 0, v[130:131]
	s_add_i32 m0, s33, 0x2000
	s_nop 0
	global_load_lds_dwordx4 v[142:143], off
	v_lshl_add_u64 v[142:143], v[216:217], 0, s[6:7]
	s_mov_b32 m0, s71
	s_nop 0
	global_load_lds_dwordx4 v[142:143], off
	v_lshl_add_u64 v[142:143], v[218:219], 0, s[6:7]
	s_mov_b32 m0, s72
	s_nop 0
	global_load_lds_dwordx4 v[142:143], off
	s_waitcnt vmcnt(8)
	s_waitcnt lgkmcnt(0)
	s_barrier
	s_setprio 0
	s_waitcnt lgkmcnt(0)
	v_mfma_f32_16x16x32_bf16 v[62:65], v[150:153], v[182:185], v[62:65]
	v_mfma_f32_16x16x32_bf16 v[58:61], v[158:161], v[182:185], v[58:61]
	v_mfma_f32_16x16x32_bf16 v[54:57], v[150:153], v[190:193], v[54:57]
	v_mfma_f32_16x16x32_bf16 v[46:49], v[158:161], v[190:193], v[46:49]
	v_mfma_f32_16x16x32_bf16 v[38:41], v[150:153], v[198:201], v[38:41]
	v_mfma_f32_16x16x32_bf16 v[30:33], v[158:161], v[198:201], v[30:33]
	v_mfma_f32_16x16x32_bf16 v[22:25], v[150:153], v[206:209], v[22:25]
	v_mfma_f32_16x16x32_bf16 v[14:17], v[158:161], v[206:209], v[14:17]
	v_mfma_f32_16x16x32_bf16 v[62:65], v[154:157], v[186:189], v[62:65]
	v_mfma_f32_16x16x32_bf16 v[58:61], v[162:165], v[186:189], v[58:61]
	v_mfma_f32_16x16x32_bf16 v[54:57], v[154:157], v[194:197], v[54:57]
	v_mfma_f32_16x16x32_bf16 v[46:49], v[162:165], v[194:197], v[46:49]
	v_mfma_f32_16x16x32_bf16 v[38:41], v[154:157], v[202:205], v[38:41]
	v_mfma_f32_16x16x32_bf16 v[30:33], v[162:165], v[202:205], v[30:33]
	v_mfma_f32_16x16x32_bf16 v[22:25], v[154:157], v[210:213], v[22:25]
	v_mfma_f32_16x16x32_bf16 v[14:17], v[162:165], v[210:213], v[14:17]
	s_setprio 2
	s_setprio 0
	v_mfma_f32_16x16x32_bf16 v[50:53], v[166:169], v[182:185], v[50:53]
	v_mfma_f32_16x16x32_bf16 v[42:45], v[174:177], v[182:185], v[42:45]
	v_mfma_f32_16x16x32_bf16 v[34:37], v[166:169], v[190:193], v[34:37]
	v_mfma_f32_16x16x32_bf16 v[26:29], v[174:177], v[190:193], v[26:29]
	v_mfma_f32_16x16x32_bf16 v[18:21], v[166:169], v[198:201], v[18:21]
	v_mfma_f32_16x16x32_bf16 v[10:13], v[174:177], v[198:201], v[10:13]
	v_mfma_f32_16x16x32_bf16 v[6:9], v[166:169], v[206:209], v[6:9]
	v_mfma_f32_16x16x32_bf16 v[2:5], v[174:177], v[206:209], v[2:5]
	v_mfma_f32_16x16x32_bf16 v[50:53], v[170:173], v[186:189], v[50:53]
	v_mfma_f32_16x16x32_bf16 v[42:45], v[178:181], v[186:189], v[42:45]
	v_mfma_f32_16x16x32_bf16 v[34:37], v[170:173], v[194:197], v[34:37]
	v_mfma_f32_16x16x32_bf16 v[26:29], v[178:181], v[194:197], v[26:29]
	v_mfma_f32_16x16x32_bf16 v[18:21], v[170:173], v[202:205], v[18:21]
	v_mfma_f32_16x16x32_bf16 v[10:13], v[178:181], v[202:205], v[10:13]
	v_mfma_f32_16x16x32_bf16 v[6:9], v[170:173], v[210:213], v[6:9]
	v_mfma_f32_16x16x32_bf16 v[2:5], v[178:181], v[210:213], v[2:5]
	s_setprio 2
	s_barrier
	s_add_i32 s92, s92, 2
	s_cmp_gt_u32 s92, 5
	s_mov_b64 s[46:47], s[52:53]
	s_cbranch_scc0 .LBB0_781
	s_and_b64 vcc, exec, s[8:9]
	s_cbranch_vccz .LBB0_784
	s_barrier

; #define PG8_STAGE(bufoff, gbase, voff) do { _Pragma("unroll") for (int _i = 0; _i < 2; ++_i) \
;         __builtin_amdgcn_global_load_lds((const unsigned*)((const char*)(gbase) + (voff)[_i]), (LAS unsigned*)(lds + (bufoff) + ldsw + _i * 8192), 16, 0, 0); } while (0)
; #define PG8_LDA(dst, b, h) do { _Pragma("unroll") for (int m = 0; m < 4; ++m) _Pragma("unroll") for (int k = 0; k < 2; ++k) dst[m][k] = *(const LAS bf16x8*)(lds + PG8_SA(b, h) + aoff + m * 2048 + k * 1024); } while (0)
; #define PG8_LDB(dst, b, h) do { _Pragma("unroll") for (int n = 0; n < 2; ++n) _Pragma("unroll") for (int k = 0; k < 2; ++k) dst[n][k] = *(const LAS bf16x8*)(lds + PG8_SB(b, h) + boff + n * 2048 + k * 1024); } while (0)
; #define PG8_MMA(ai, bj, At, Bt) do { __builtin_amdgcn_s_setprio(1); _Pragma("unroll") for (int m = 0; m < 4; ++m) _Pragma("unroll") for (int n = 0; n < 2; ++n) _Pragma("unroll") for (int k = 0; k < 2; ++k) \
;         acc[ai][bj][m][n] = __builtin_amdgcn_mfma_f32_16x16x32_bf16(Bt[n][k], At[m][k], acc[ai][bj][m][n], 0, 0, 0); __builtin_amdgcn_s_setprio(0); } while (0)
; #define PG8_WAIT_V(n) asm volatile("s_waitcnt vmcnt(" #n ")" ::: "memory")
; #define PG8_WAIT_L(n) asm volatile("s_waitcnt lgkmcnt(" #n ")" ::: "memory")
; #define PG8_BAR __builtin_amdgcn_s_barrier()
; #define PG8_SCHED __builtin_amdgcn_sched_barrier(0)
; template <class Epi>
; __device__ __forceinline__ void gemm_phase(LAS unsigned char* lds, const Gemm g, int G, int c, const Epi& E) {
;     ...
;             const bool last = (t == nt - 2);
;             const char* a1 = cA + (size_t)(t + 1) * kstep;
;             const char* a2 = last ? nA : cA + (size_t)(t + 2) * kstep; const char* b2 = last ? nB : cB + (size_t)(t + 2) * kstep;
;             const char* a3 = a2 + kstep; const char* b3 = b2 + kstep;
;             PG8_LDB(B0, 0, 0); PG8_LDB(B1, 0, 1); PG8_SCHED; PG8_LDA(At, 0, 0); PG8_STAGE(PG8_SA(1, 1), a1 + hstepA, voffA);
;             PG8_WAIT_V(8); PG8_WAIT_L(0); PG8_BAR; PG8_MMA(0, 0, At, B0); PG8_MMA(0, 1, At, B1); PG8_BAR; PG8_SCHED;
;             PG8_LDA(At, 0, 1); PG8_STAGE(PG8_SB(0, 0), b2, voffB); PG8_STAGE(PG8_SB(0, 1), b2 + hstepB, voffB); PG8_STAGE(PG8_SA(0, 0), a2, voffA);
;             PG8_WAIT_V(8); PG8_WAIT_L(0); PG8_BAR; PG8_MMA(1, 0, At, B0); PG8_MMA(1, 1, At, B1); PG8_BAR; PG8_SCHED;
.LBB0_903:
	ds_read_b128 v[130:133], v170
	ds_read_b128 v[134:137], v170 offset:1024
	ds_read_b128 v[138:141], v170 offset:2048
	ds_read_b128 v[142:145], v170 offset:3072
	ds_read_b128 v[162:165], v171
	ds_read_b128 v[174:177], v171 offset:1024
	ds_read_b128 v[178:181], v171 offset:2048
	ds_read_b128 v[182:185], v171 offset:3072
	s_add_u32 s33, s4, 0xfffc0080
	s_addc_u32 s42, s5, -1
	s_cmp_eq_u32 s46, 12
	s_cselect_b32 s45, s19, s42
	s_cselect_b32 s44, s18, s33
	s_cselect_b32 s43, s15, s39
	s_cselect_b32 s42, s17, s23
	v_lshl_add_u64 v[166:167], s[4:5], 0, v[154:155]
	s_add_i32 m0, s25, 0xc000
	ds_read_b128 v[186:189], v172
	ds_read_b128 v[190:193], v172 offset:1024
	ds_read_b128 v[194:197], v172 offset:2048
	ds_read_b128 v[198:201], v172 offset:3072
	ds_read_b128 v[202:205], v172 offset:4096
	ds_read_b128 v[206:209], v172 offset:5120
	ds_read_b128 v[210:213], v172 offset:6144
	ds_read_b128 v[214:217], v172 offset:7168
	global_load_lds_dwordx4 v[166:167], off
	v_lshl_add_u64 v[166:167], s[4:5], 0, v[156:157]
	s_add_i32 m0, s25, 0xe000
	s_nop 0
	global_load_lds_dwordx4 v[166:167], off
	s_waitcnt vmcnt(8)
	s_waitcnt lgkmcnt(0)
	s_barrier
	s_setprio 0
	s_waitcnt lgkmcnt(0)
	v_mfma_f32_16x16x32_bf16 v[126:129], v[130:133], v[186:189], v[126:129]
	v_mfma_f32_16x16x32_bf16 v[122:125], v[138:141], v[186:189], v[122:125]
	v_mfma_f32_16x16x32_bf16 v[110:113], v[130:133], v[194:197], v[110:113]
	v_mfma_f32_16x16x32_bf16 v[106:109], v[138:141], v[194:197], v[106:109]
	v_mfma_f32_16x16x32_bf16 v[94:97], v[130:133], v[202:205], v[94:97]
	v_mfma_f32_16x16x32_bf16 v[90:93], v[138:141], v[202:205], v[90:93]
	v_mfma_f32_16x16x32_bf16 v[78:81], v[130:133], v[210:213], v[78:81]
	v_mfma_f32_16x16x32_bf16 v[74:77], v[138:141], v[210:213], v[74:77]
	v_mfma_f32_16x16x32_bf16 v[126:129], v[134:137], v[190:193], v[126:129]
	v_mfma_f32_16x16x32_bf16 v[122:125], v[142:145], v[190:193], v[122:125]
	v_mfma_f32_16x16x32_bf16 v[110:113], v[134:137], v[198:201], v[110:113]
	v_mfma_f32_16x16x32_bf16 v[106:109], v[142:145], v[198:201], v[106:109]
	v_mfma_f32_16x16x32_bf16 v[94:97], v[134:137], v[206:209], v[94:97]
	v_mfma_f32_16x16x32_bf16 v[90:93], v[142:145], v[206:209], v[90:93]
	v_mfma_f32_16x16x32_bf16 v[78:81], v[134:137], v[214:217], v[78:81]
	v_mfma_f32_16x16x32_bf16 v[74:77], v[142:145], v[214:217], v[74:77]
	s_setprio 2
	s_setprio 0
	v_mfma_f32_16x16x32_bf16 v[118:121], v[162:165], v[186:189], v[118:121]
	v_mfma_f32_16x16x32_bf16 v[114:117], v[178:181], v[186:189], v[114:117]
	v_mfma_f32_16x16x32_bf16 v[102:105], v[162:165], v[194:197], v[102:105]
	v_mfma_f32_16x16x32_bf16 v[98:101], v[178:181], v[194:197], v[98:101]
	v_mfma_f32_16x16x32_bf16 v[86:89], v[162:165], v[202:205], v[86:89]
	v_mfma_f32_16x16x32_bf16 v[82:85], v[178:181], v[202:205], v[82:85]
	v_mfma_f32_16x16x32_bf16 v[70:73], v[162:165], v[210:213], v[70:73]
	v_mfma_f32_16x16x32_bf16 v[66:69], v[178:181], v[210:213], v[66:69]
	v_mfma_f32_16x16x32_bf16 v[118:121], v[174:177], v[190:193], v[118:121]
	v_mfma_f32_16x16x32_bf16 v[114:117], v[182:185], v[190:193], v[114:117]
	v_mfma_f32_16x16x32_bf16 v[102:105], v[174:177], v[198:201], v[102:105]
	v_mfma_f32_16x16x32_bf16 v[98:101], v[182:185], v[198:201], v[98:101]
	v_mfma_f32_16x16x32_bf16 v[86:89], v[174:177], v[206:209], v[86:89]
	v_mfma_f32_16x16x32_bf16 v[82:85], v[182:185], v[206:209], v[82:85]
	v_mfma_f32_16x16x32_bf16 v[70:73], v[174:177], v[214:217], v[70:73]
	v_mfma_f32_16x16x32_bf16 v[66:69], v[182:185], v[214:217], v[66:69]
	s_setprio 2
	s_barrier
	s_add_i32 s33, s72, s54
	v_lshl_add_u64 v[166:167], s[42:43], 0, v[150:151]
	s_mov_b32 m0, s33
	ds_read_b128 v[186:189], v172 offset:16384
	ds_read_b128 v[190:193], v172 offset:17408
	ds_read_b128 v[194:197], v172 offset:18432
	ds_read_b128 v[198:201], v172 offset:19456
	ds_read_b128 v[202:205], v172 offset:20480
	ds_read_b128 v[206:209], v172 offset:21504
	ds_read_b128 v[210:213], v172 offset:22528
	ds_read_b128 v[214:217], v172 offset:23552
	global_load_lds_dwordx4 v[166:167], off
	s_add_i32 m0, s33, 0x2000
	s_add_u32 s62, s42, 0x40000
	v_lshl_add_u64 v[218:219], s[42:43], 0, v[146:147]
	s_addc_u32 s63, s43, 0
	s_add_i32 s33, s73, s54
	global_load_lds_dwordx4 v[218:219], off
	v_lshl_add_u64 v[220:221], s[62:63], 0, v[150:151]
	s_mov_b32 m0, s33
	v_lshl_add_u64 v[222:223], s[44:45], 0, v[148:149]
	global_load_lds_dwordx4 v[220:221], off
	v_lshl_add_u64 v[220:221], s[62:63], 0, v[146:147]
	s_add_i32 m0, s33, 0x2000
	s_nop 0
	global_load_lds_dwordx4 v[220:221], off
	v_lshl_add_u64 v[220:221], s[44:45], 0, v[152:153]
	s_mov_b32 m0, s25
	s_nop 0
	global_load_lds_dwordx4 v[220:221], off
	s_mov_b32 m0, s57
	s_nop 0
	global_load_lds_dwordx4 v[222:223], off
	s_waitcnt vmcnt(8)
	s_waitcnt lgkmcnt(0)
	s_barrier
; #define PG8_STAGE(bufoff, gbase, voff) do { _Pragma("unroll") for (int _i = 0; _i < 2; ++_i) \
;         __builtin_amdgcn_global_load_lds((const unsigned*)((const char*)(gbase) + (voff)[_i]), (LAS unsigned*)(lds + (bufoff) + ldsw + _i * 8192), 16, 0, 0); } while (0)
; #define PG8_LDA(dst, b, h) do { _Pragma("unroll") for (int m = 0; m < 4; ++m) _Pragma("unroll") for (int k = 0; k < 2; ++k) dst[m][k] = *(const LAS bf16x8*)(lds + PG8_SA(b, h) + aoff + m * 2048 + k * 1024); } while (0)
; #define PG8_LDB(dst, b, h) do { _Pragma("unroll") for (int n = 0; n < 2; ++n) _Pragma("unroll") for (int k = 0; k < 2; ++k) dst[n][k] = *(const LAS bf16x8*)(lds + PG8_SB(b, h) + boff + n * 2048 + k * 1024); } while (0)
; #define PG8_MMA(ai, bj, At, Bt) do { __builtin_amdgcn_s_setprio(1); _Pragma("unroll") for (int m = 0; m < 4; ++m) _Pragma("unroll") for (int n = 0; n < 2; ++n) _Pragma("unroll") for (int k = 0; k < 2; ++k) \
;         acc[ai][bj][m][n] = __builtin_amdgcn_mfma_f32_16x16x32_bf16(Bt[n][k], At[m][k], acc[ai][bj][m][n], 0, 0, 0); __builtin_amdgcn_s_setprio(0); } while (0)
; #define PG8_WAIT_V(n) asm volatile("s_waitcnt vmcnt(" #n ")" ::: "memory")
; #define PG8_WAIT_L(n) asm volatile("s_waitcnt lgkmcnt(" #n ")" ::: "memory")
; #define PG8_BAR __builtin_amdgcn_s_barrier()
; #define PG8_SCHED __builtin_amdgcn_sched_barrier(0)
; template <class Epi>
; __device__ __forceinline__ void gemm_phase(LAS unsigned char* lds, const Gemm g, int G, int c, const Epi& E) {
;     ...
;             PG8_WAIT_V(8); PG8_WAIT_L(0); PG8_BAR; PG8_MMA(1, 0, At, B0); PG8_MMA(1, 1, At, B1); PG8_BAR; PG8_SCHED;
;             PG8_LDB(B0, 1, 0); PG8_LDB(B1, 1, 1); PG8_SCHED; PG8_LDA(At, 1, 0); PG8_STAGE(PG8_SA(0, 1), a2 + hstepA, voffA);
;             PG8_WAIT_V(8); PG8_WAIT_L(0); PG8_BAR; PG8_MMA(0, 0, At, B0); PG8_MMA(0, 1, At, B1); PG8_BAR; PG8_SCHED;
	s_setprio 0
	s_waitcnt lgkmcnt(0)
	v_mfma_f32_16x16x32_bf16 v[62:65], v[130:133], v[186:189], v[62:65]
	v_mfma_f32_16x16x32_bf16 v[58:61], v[138:141], v[186:189], v[58:61]
	v_mfma_f32_16x16x32_bf16 v[46:49], v[130:133], v[194:197], v[46:49]
	v_mfma_f32_16x16x32_bf16 v[42:45], v[138:141], v[194:197], v[42:45]
	v_mfma_f32_16x16x32_bf16 v[30:33], v[130:133], v[202:205], v[30:33]
	v_mfma_f32_16x16x32_bf16 v[26:29], v[138:141], v[202:205], v[26:29]
	v_mfma_f32_16x16x32_bf16 v[14:17], v[130:133], v[210:213], v[14:17]
	v_mfma_f32_16x16x32_bf16 v[10:13], v[138:141], v[210:213], v[10:13]
	v_mfma_f32_16x16x32_bf16 v[62:65], v[134:137], v[190:193], v[62:65]
	v_mfma_f32_16x16x32_bf16 v[58:61], v[142:145], v[190:193], v[58:61]
	v_mfma_f32_16x16x32_bf16 v[46:49], v[134:137], v[198:201], v[46:49]
	v_mfma_f32_16x16x32_bf16 v[42:45], v[142:145], v[198:201], v[42:45]
	v_mfma_f32_16x16x32_bf16 v[30:33], v[134:137], v[206:209], v[30:33]
	v_mfma_f32_16x16x32_bf16 v[26:29], v[142:145], v[206:209], v[26:29]
	v_mfma_f32_16x16x32_bf16 v[14:17], v[134:137], v[214:217], v[14:17]
	v_mfma_f32_16x16x32_bf16 v[10:13], v[142:145], v[214:217], v[10:13]
	s_setprio 2
	s_setprio 0
	v_mfma_f32_16x16x32_bf16 v[54:57], v[162:165], v[186:189], v[54:57]
	v_mfma_f32_16x16x32_bf16 v[50:53], v[178:181], v[186:189], v[50:53]
	v_mfma_f32_16x16x32_bf16 v[38:41], v[162:165], v[194:197], v[38:41]
	v_mfma_f32_16x16x32_bf16 v[34:37], v[178:181], v[194:197], v[34:37]
	v_mfma_f32_16x16x32_bf16 v[22:25], v[162:165], v[202:205], v[22:25]
	v_mfma_f32_16x16x32_bf16 v[18:21], v[178:181], v[202:205], v[18:21]
	v_mfma_f32_16x16x32_bf16 v[6:9], v[162:165], v[210:213], v[6:9]
	v_mfma_f32_16x16x32_bf16 v[2:5], v[178:181], v[210:213], v[2:5]
	v_mfma_f32_16x16x32_bf16 v[54:57], v[174:177], v[190:193], v[54:57]
	v_mfma_f32_16x16x32_bf16 v[50:53], v[182:185], v[190:193], v[50:53]
	v_mfma_f32_16x16x32_bf16 v[38:41], v[174:177], v[198:201], v[38:41]
	v_mfma_f32_16x16x32_bf16 v[34:37], v[182:185], v[198:201], v[34:37]
	v_mfma_f32_16x16x32_bf16 v[22:25], v[174:177], v[206:209], v[22:25]
	v_mfma_f32_16x16x32_bf16 v[18:21], v[182:185], v[206:209], v[18:21]
	v_mfma_f32_16x16x32_bf16 v[6:9], v[174:177], v[214:217], v[6:9]
	v_mfma_f32_16x16x32_bf16 v[2:5], v[182:185], v[214:217], v[2:5]
	s_setprio 2
	s_barrier
	s_add_i32 s33, 0, 0x18000
	s_add_i32 s47, 0, 0x1c000
	v_add_u32_e32 v142, s33, v169
	v_add_u32_e32 v173, s47, v169
	ds_read_b128 v[130:133], v142
	ds_read_b128 v[134:137], v142 offset:1024
	ds_read_b128 v[138:141], v142 offset:2048
	ds_read_b128 v[142:145], v142 offset:3072
	ds_read_b128 v[162:165], v173
	ds_read_b128 v[174:177], v173 offset:1024
	ds_read_b128 v[178:181], v173 offset:2048
	ds_read_b128 v[182:185], v173 offset:3072
	s_add_u32 s44, s44, 0x40000
	s_addc_u32 s45, s45, 0
	s_mov_b32 m0, s58
	v_lshl_add_u64 v[224:225], s[44:45], 0, v[152:153]
	ds_read_b128 v[186:189], v172 offset:32768
	ds_read_b128 v[190:193], v172 offset:33792
	ds_read_b128 v[194:197], v172 offset:34816
	ds_read_b128 v[198:201], v172 offset:35840
	ds_read_b128 v[202:205], v172 offset:36864
	ds_read_b128 v[206:209], v172 offset:37888
	ds_read_b128 v[210:213], v172 offset:38912
	ds_read_b128 v[214:217], v172 offset:39936
	global_load_lds_dwordx4 v[224:225], off
	v_lshl_add_u64 v[224:225], s[44:45], 0, v[148:149]
	s_mov_b32 m0, s59
	s_nop 0
	global_load_lds_dwordx4 v[224:225], off
	s_waitcnt vmcnt(8)
	s_waitcnt lgkmcnt(0)
	s_barrier
	s_setprio 0
	s_waitcnt lgkmcnt(0)
	v_mfma_f32_16x16x32_bf16 v[126:129], v[130:133], v[186:189], v[126:129]
	v_mfma_f32_16x16x32_bf16 v[122:125], v[138:141], v[186:189], v[122:125]
	v_mfma_f32_16x16x32_bf16 v[110:113], v[130:133], v[194:197], v[110:113]
	v_mfma_f32_16x16x32_bf16 v[106:109], v[138:141], v[194:197], v[106:109]
	v_mfma_f32_16x16x32_bf16 v[94:97], v[130:133], v[202:205], v[94:97]
	v_mfma_f32_16x16x32_bf16 v[90:93], v[138:141], v[202:205], v[90:93]
	v_mfma_f32_16x16x32_bf16 v[78:81], v[130:133], v[210:213], v[78:81]
	v_mfma_f32_16x16x32_bf16 v[74:77], v[138:141], v[210:213], v[74:77]
	v_mfma_f32_16x16x32_bf16 v[126:129], v[134:137], v[190:193], v[126:129]
	v_mfma_f32_16x16x32_bf16 v[122:125], v[142:145], v[190:193], v[122:125]
	v_mfma_f32_16x16x32_bf16 v[110:113], v[134:137], v[198:201], v[110:113]
	v_mfma_f32_16x16x32_bf16 v[106:109], v[142:145], v[198:201], v[106:109]
	v_mfma_f32_16x16x32_bf16 v[94:97], v[134:137], v[206:209], v[94:97]
	v_mfma_f32_16x16x32_bf16 v[90:93], v[142:145], v[206:209], v[90:93]
	v_mfma_f32_16x16x32_bf16 v[78:81], v[134:137], v[214:217], v[78:81]
	v_mfma_f32_16x16x32_bf16 v[74:77], v[142:145], v[214:217], v[74:77]
	s_setprio 2
	s_setprio 0
	v_mfma_f32_16x16x32_bf16 v[118:121], v[162:165], v[186:189], v[118:121]
	v_mfma_f32_16x16x32_bf16 v[114:117], v[178:181], v[186:189], v[114:117]
	v_mfma_f32_16x16x32_bf16 v[102:105], v[162:165], v[194:197], v[102:105]
	v_mfma_f32_16x16x32_bf16 v[98:101], v[178:181], v[194:197], v[98:101]
	v_mfma_f32_16x16x32_bf16 v[86:89], v[162:165], v[202:205], v[86:89]
	v_mfma_f32_16x16x32_bf16 v[82:85], v[178:181], v[202:205], v[82:85]
	v_mfma_f32_16x16x32_bf16 v[70:73], v[162:165], v[210:213], v[70:73]
	v_mfma_f32_16x16x32_bf16 v[66:69], v[178:181], v[210:213], v[66:69]
	v_mfma_f32_16x16x32_bf16 v[118:121], v[174:177], v[190:193], v[118:121]
	v_mfma_f32_16x16x32_bf16 v[114:117], v[182:185], v[190:193], v[114:117]
	v_mfma_f32_16x16x32_bf16 v[102:105], v[174:177], v[198:201], v[102:105]
	v_mfma_f32_16x16x32_bf16 v[98:101], v[182:185], v[198:201], v[98:101]
	v_mfma_f32_16x16x32_bf16 v[86:89], v[174:177], v[206:209], v[86:89]
	v_mfma_f32_16x16x32_bf16 v[82:85], v[182:185], v[206:209], v[82:85]
	v_mfma_f32_16x16x32_bf16 v[70:73], v[174:177], v[214:217], v[70:73]
	v_mfma_f32_16x16x32_bf16 v[66:69], v[182:185], v[214:217], v[66:69]
	s_setprio 2
	s_barrier
; #define PG8_STAGE(bufoff, gbase, voff) do { _Pragma("unroll") for (int _i = 0; _i < 2; ++_i) \
;         __builtin_amdgcn_global_load_lds((const unsigned*)((const char*)(gbase) + (voff)[_i]), (LAS unsigned*)(lds + (bufoff) + ldsw + _i * 8192), 16, 0, 0); } while (0)
; #define PG8_LDA(dst, b, h) do { _Pragma("unroll") for (int m = 0; m < 4; ++m) _Pragma("unroll") for (int k = 0; k < 2; ++k) dst[m][k] = *(const LAS bf16x8*)(lds + PG8_SA(b, h) + aoff + m * 2048 + k * 1024); } while (0)
; #define PG8_MMA(ai, bj, At, Bt) do { __builtin_amdgcn_s_setprio(1); _Pragma("unroll") for (int m = 0; m < 4; ++m) _Pragma("unroll") for (int n = 0; n < 2; ++n) _Pragma("unroll") for (int k = 0; k < 2; ++k) \
;         acc[ai][bj][m][n] = __builtin_amdgcn_mfma_f32_16x16x32_bf16(Bt[n][k], At[m][k], acc[ai][bj][m][n], 0, 0, 0); __builtin_amdgcn_s_setprio(0); } while (0)
; #define PG8_WAIT_V(n) asm volatile("s_waitcnt vmcnt(" #n ")" ::: "memory")
; #define PG8_WAIT_L(n) asm volatile("s_waitcnt lgkmcnt(" #n ")" ::: "memory")
; #define PG8_BAR __builtin_amdgcn_s_barrier()
; #define PG8_SCHED __builtin_amdgcn_sched_barrier(0)
; template <class Epi>
; __device__ __forceinline__ void gemm_phase(LAS unsigned char* lds, const Gemm g, int G, int c, const Epi& E) {
;     ...
;             PG8_LDA(At, 1, 1); PG8_STAGE(PG8_SB(1, 0), b3, voffB); PG8_STAGE(PG8_SB(1, 1), b3 + hstepB, voffB); PG8_STAGE(PG8_SA(1, 0), a3, voffA);
;             PG8_WAIT_V(8); PG8_WAIT_L(0); PG8_BAR; PG8_MMA(1, 0, At, B0); PG8_MMA(1, 1, At, B1); PG8_BAR; PG8_SCHED;
;         }
;         if (wr == 0) PG8_BAR;
	s_add_i32 s33, s33, s54
	v_lshl_add_u64 v[166:167], v[166:167], 0, s[10:11]
	s_mov_b32 m0, s33
	ds_read_b128 v[186:189], v172 offset:49152
	ds_read_b128 v[190:193], v172 offset:50176
	ds_read_b128 v[194:197], v172 offset:51200
	ds_read_b128 v[198:201], v172 offset:52224
	ds_read_b128 v[202:205], v172 offset:53248
	ds_read_b128 v[206:209], v172 offset:54272
	ds_read_b128 v[210:213], v172 offset:55296
	ds_read_b128 v[214:217], v172 offset:56320
	global_load_lds_dwordx4 v[166:167], off
	s_add_i32 m0, s33, 0x2000
	s_add_u32 s42, s42, 0x40080
	v_lshl_add_u64 v[166:167], v[218:219], 0, s[10:11]
	s_addc_u32 s43, s43, 0
	s_add_i32 s33, s47, s54
	global_load_lds_dwordx4 v[166:167], off
	v_lshl_add_u64 v[166:167], s[42:43], 0, v[150:151]
	s_mov_b32 m0, s33
	s_nop 0
	global_load_lds_dwordx4 v[166:167], off
	v_lshl_add_u64 v[166:167], s[42:43], 0, v[146:147]
	s_add_i32 m0, s33, 0x2000
	s_nop 0
	global_load_lds_dwordx4 v[166:167], off
	v_lshl_add_u64 v[166:167], v[220:221], 0, s[10:11]
	s_mov_b32 m0, s69
	s_nop 0
	global_load_lds_dwordx4 v[166:167], off
	v_lshl_add_u64 v[166:167], v[222:223], 0, s[10:11]
	s_mov_b32 m0, s70
	s_nop 0
	global_load_lds_dwordx4 v[166:167], off
	s_waitcnt vmcnt(8)
	s_waitcnt lgkmcnt(0)
	s_barrier
	s_setprio 0
	s_waitcnt lgkmcnt(0)
	v_mfma_f32_16x16x32_bf16 v[62:65], v[130:133], v[186:189], v[62:65]
	v_mfma_f32_16x16x32_bf16 v[58:61], v[138:141], v[186:189], v[58:61]
	v_mfma_f32_16x16x32_bf16 v[46:49], v[130:133], v[194:197], v[46:49]
	v_mfma_f32_16x16x32_bf16 v[42:45], v[138:141], v[194:197], v[42:45]
	v_mfma_f32_16x16x32_bf16 v[30:33], v[130:133], v[202:205], v[30:33]
	v_mfma_f32_16x16x32_bf16 v[26:29], v[138:141], v[202:205], v[26:29]
	v_mfma_f32_16x16x32_bf16 v[14:17], v[130:133], v[210:213], v[14:17]
	v_mfma_f32_16x16x32_bf16 v[10:13], v[138:141], v[210:213], v[10:13]
	v_mfma_f32_16x16x32_bf16 v[62:65], v[134:137], v[190:193], v[62:65]
	v_mfma_f32_16x16x32_bf16 v[58:61], v[142:145], v[190:193], v[58:61]
	v_mfma_f32_16x16x32_bf16 v[46:49], v[134:137], v[198:201], v[46:49]
	v_mfma_f32_16x16x32_bf16 v[42:45], v[142:145], v[198:201], v[42:45]
	v_mfma_f32_16x16x32_bf16 v[30:33], v[134:137], v[206:209], v[30:33]
	v_mfma_f32_16x16x32_bf16 v[26:29], v[142:145], v[206:209], v[26:29]
	v_mfma_f32_16x16x32_bf16 v[14:17], v[134:137], v[214:217], v[14:17]
	v_mfma_f32_16x16x32_bf16 v[10:13], v[142:145], v[214:217], v[10:13]
	s_setprio 2
	s_setprio 0
	v_mfma_f32_16x16x32_bf16 v[54:57], v[162:165], v[186:189], v[54:57]
	v_mfma_f32_16x16x32_bf16 v[50:53], v[178:181], v[186:189], v[50:53]
	v_mfma_f32_16x16x32_bf16 v[38:41], v[162:165], v[194:197], v[38:41]
	v_mfma_f32_16x16x32_bf16 v[34:37], v[178:181], v[194:197], v[34:37]
	v_mfma_f32_16x16x32_bf16 v[22:25], v[162:165], v[202:205], v[22:25]
	v_mfma_f32_16x16x32_bf16 v[18:21], v[178:181], v[202:205], v[18:21]
	v_mfma_f32_16x16x32_bf16 v[6:9], v[162:165], v[210:213], v[6:9]
	v_mfma_f32_16x16x32_bf16 v[2:5], v[178:181], v[210:213], v[2:5]
	v_mfma_f32_16x16x32_bf16 v[54:57], v[174:177], v[190:193], v[54:57]
	v_mfma_f32_16x16x32_bf16 v[50:53], v[182:185], v[190:193], v[50:53]
	v_mfma_f32_16x16x32_bf16 v[38:41], v[174:177], v[198:201], v[38:41]
	v_mfma_f32_16x16x32_bf16 v[34:37], v[182:185], v[198:201], v[34:37]
	v_mfma_f32_16x16x32_bf16 v[22:25], v[174:177], v[206:209], v[22:25]
	v_mfma_f32_16x16x32_bf16 v[18:21], v[182:185], v[206:209], v[18:21]
	v_mfma_f32_16x16x32_bf16 v[6:9], v[174:177], v[214:217], v[6:9]
	v_mfma_f32_16x16x32_bf16 v[2:5], v[182:185], v[214:217], v[2:5]
	s_setprio 2
	s_barrier
	s_add_i32 s46, s46, 2
	s_add_u32 s4, s4, 0x100
	s_addc_u32 s5, s5, 0
	s_add_u32 s23, s23, 0x100
	s_addc_u32 s39, s39, 0
	s_cmp_gt_u32 s46, 13
	s_cbranch_scc0 .LBB0_903
	s_and_b64 vcc, exec, s[12:13]
	s_cbranch_vccz .LBB0_906
	s_barrier

; #define PG8_STAGE(bufoff, gbase, voff) do { _Pragma("unroll") for (int _i = 0; _i < 2; ++_i) \
;         __builtin_amdgcn_global_load_lds((const unsigned*)((const char*)(gbase) + (voff)[_i]), (LAS unsigned*)(lds + (bufoff) + ldsw + _i * 8192), 16, 0, 0); } while (0)
; #define PG8_LDA(dst, b, h) do { _Pragma("unroll") for (int m = 0; m < 4; ++m) _Pragma("unroll") for (int k = 0; k < 2; ++k) dst[m][k] = *(const LAS bf16x8*)(lds + PG8_SA(b, h) + aoff + m * 2048 + k * 1024); } while (0)
; #define PG8_LDB(dst, b, h) do { _Pragma("unroll") for (int n = 0; n < 2; ++n) _Pragma("unroll") for (int k = 0; k < 2; ++k) dst[n][k] = *(const LAS bf16x8*)(lds + PG8_SB(b, h) + boff + n * 2048 + k * 1024); } while (0)
; #define PG8_MMA(ai, bj, At, Bt) do { __builtin_amdgcn_s_setprio(1); _Pragma("unroll") for (int m = 0; m < 4; ++m) _Pragma("unroll") for (int n = 0; n < 2; ++n) _Pragma("unroll") for (int k = 0; k < 2; ++k) \
;         acc[ai][bj][m][n] = __builtin_amdgcn_mfma_f32_16x16x32_bf16(Bt[n][k], At[m][k], acc[ai][bj][m][n], 0, 0, 0); __builtin_amdgcn_s_setprio(0); } while (0)
; #define PG8_WAIT_V(n) asm volatile("s_waitcnt vmcnt(" #n ")" ::: "memory")
; #define PG8_WAIT_L(n) asm volatile("s_waitcnt lgkmcnt(" #n ")" ::: "memory")
; #define PG8_BAR __builtin_amdgcn_s_barrier()
; #define PG8_SCHED __builtin_amdgcn_sched_barrier(0)
; template <class Epi>
; __device__ __forceinline__ void gemm_phase(LAS unsigned char* lds, const Gemm g, int G, int c, const Epi& E) {
;     ...
;             const bool last = (t == nt - 2);
;             const char* a1 = cA + (size_t)(t + 1) * kstep;
;             const char* a2 = last ? nA : cA + (size_t)(t + 2) * kstep; const char* b2 = last ? nB : cB + (size_t)(t + 2) * kstep;
;             const char* a3 = a2 + kstep; const char* b3 = b2 + kstep;
;             PG8_LDB(B0, 0, 0); PG8_LDB(B1, 0, 1); PG8_SCHED; PG8_LDA(At, 0, 0); PG8_STAGE(PG8_SA(1, 1), a1 + hstepA, voffA);
;             PG8_WAIT_V(8); PG8_WAIT_L(0); PG8_BAR; PG8_MMA(0, 0, At, B0); PG8_MMA(0, 1, At, B1); PG8_BAR; PG8_SCHED;
;             PG8_LDA(At, 0, 1); PG8_STAGE(PG8_SB(0, 0), b2, voffB); PG8_STAGE(PG8_SB(0, 1), b2 + hstepB, voffB); PG8_STAGE(PG8_SA(0, 0), a2, voffA);
;             PG8_WAIT_V(8); PG8_WAIT_L(0); PG8_BAR; PG8_MMA(1, 0, At, B0); PG8_MMA(1, 1, At, B1); PG8_BAR; PG8_SCHED;
.LBB0_1058:
	ds_read_b128 v[152:155], v148
	ds_read_b128 v[156:159], v148 offset:1024
	ds_read_b128 v[160:163], v148 offset:2048
	ds_read_b128 v[164:167], v148 offset:3072
	ds_read_b128 v[168:171], v149
	ds_read_b128 v[172:175], v149 offset:1024
	ds_read_b128 v[176:179], v149 offset:2048
	ds_read_b128 v[180:183], v149 offset:3072
	s_add_u32 s33, s4, 0xfffc0080
	s_addc_u32 s38, s5, -1
	s_cmp_eq_u32 s80, 12
	s_cselect_b32 s41, s21, s38
	s_cselect_b32 s40, s20, s33
	s_cselect_b32 s39, s17, s79
	s_cselect_b32 s38, s19, s78
	v_lshl_add_u64 v[216:217], s[4:5], 0, v[138:139]
	s_add_i32 m0, s25, 0xc000
	ds_read_b128 v[184:187], v150
	ds_read_b128 v[188:191], v150 offset:1024
	ds_read_b128 v[192:195], v150 offset:2048
	ds_read_b128 v[196:199], v150 offset:3072
	ds_read_b128 v[200:203], v150 offset:4096
	ds_read_b128 v[204:207], v150 offset:5120
	ds_read_b128 v[208:211], v150 offset:6144
	ds_read_b128 v[212:215], v150 offset:7168
	global_load_lds_dwordx4 v[216:217], off
	v_lshl_add_u64 v[216:217], s[4:5], 0, v[140:141]
	s_add_i32 m0, s25, 0xe000
	s_nop 0
	global_load_lds_dwordx4 v[216:217], off
	s_waitcnt vmcnt(8)
	s_waitcnt lgkmcnt(0)
	s_barrier
	s_setprio 0
	s_waitcnt lgkmcnt(0)
	v_mfma_f32_16x16x32_bf16 v[126:129], v[152:155], v[184:187], v[126:129]
	v_mfma_f32_16x16x32_bf16 v[122:125], v[160:163], v[184:187], v[122:125]
	v_mfma_f32_16x16x32_bf16 v[110:113], v[152:155], v[192:195], v[110:113]
	v_mfma_f32_16x16x32_bf16 v[106:109], v[160:163], v[192:195], v[106:109]
	v_mfma_f32_16x16x32_bf16 v[94:97], v[152:155], v[200:203], v[94:97]
	v_mfma_f32_16x16x32_bf16 v[90:93], v[160:163], v[200:203], v[90:93]
	v_mfma_f32_16x16x32_bf16 v[78:81], v[152:155], v[208:211], v[78:81]
	v_mfma_f32_16x16x32_bf16 v[74:77], v[160:163], v[208:211], v[74:77]
	v_mfma_f32_16x16x32_bf16 v[126:129], v[156:159], v[188:191], v[126:129]
	v_mfma_f32_16x16x32_bf16 v[122:125], v[164:167], v[188:191], v[122:125]
	v_mfma_f32_16x16x32_bf16 v[110:113], v[156:159], v[196:199], v[110:113]
	v_mfma_f32_16x16x32_bf16 v[106:109], v[164:167], v[196:199], v[106:109]
	v_mfma_f32_16x16x32_bf16 v[94:97], v[156:159], v[204:207], v[94:97]
	v_mfma_f32_16x16x32_bf16 v[90:93], v[164:167], v[204:207], v[90:93]
	v_mfma_f32_16x16x32_bf16 v[78:81], v[156:159], v[212:215], v[78:81]
	v_mfma_f32_16x16x32_bf16 v[74:77], v[164:167], v[212:215], v[74:77]
	s_setprio 2
	s_setprio 0
	v_mfma_f32_16x16x32_bf16 v[118:121], v[168:171], v[184:187], v[118:121]
	v_mfma_f32_16x16x32_bf16 v[114:117], v[176:179], v[184:187], v[114:117]
	v_mfma_f32_16x16x32_bf16 v[102:105], v[168:171], v[192:195], v[102:105]
	v_mfma_f32_16x16x32_bf16 v[98:101], v[176:179], v[192:195], v[98:101]
	v_mfma_f32_16x16x32_bf16 v[86:89], v[168:171], v[200:203], v[86:89]
	v_mfma_f32_16x16x32_bf16 v[82:85], v[176:179], v[200:203], v[82:85]
	v_mfma_f32_16x16x32_bf16 v[70:73], v[168:171], v[208:211], v[70:73]
	v_mfma_f32_16x16x32_bf16 v[66:69], v[176:179], v[208:211], v[66:69]
	v_mfma_f32_16x16x32_bf16 v[118:121], v[172:175], v[188:191], v[118:121]
	v_mfma_f32_16x16x32_bf16 v[114:117], v[180:183], v[188:191], v[114:117]
	v_mfma_f32_16x16x32_bf16 v[102:105], v[172:175], v[196:199], v[102:105]
	v_mfma_f32_16x16x32_bf16 v[98:101], v[180:183], v[196:199], v[98:101]
	v_mfma_f32_16x16x32_bf16 v[86:89], v[172:175], v[204:207], v[86:89]
	v_mfma_f32_16x16x32_bf16 v[82:85], v[180:183], v[204:207], v[82:85]
	v_mfma_f32_16x16x32_bf16 v[70:73], v[172:175], v[212:215], v[70:73]
	v_mfma_f32_16x16x32_bf16 v[66:69], v[180:183], v[212:215], v[66:69]
	s_setprio 2
	s_barrier
	s_add_i32 s33, s60, s46
	v_lshl_add_u64 v[216:217], s[38:39], 0, v[134:135]
	s_mov_b32 m0, s33
	ds_read_b128 v[184:187], v150 offset:16384
	ds_read_b128 v[188:191], v150 offset:17408
	ds_read_b128 v[192:195], v150 offset:18432
	ds_read_b128 v[196:199], v150 offset:19456
	ds_read_b128 v[200:203], v150 offset:20480
	ds_read_b128 v[204:207], v150 offset:21504
	ds_read_b128 v[208:211], v150 offset:22528
	ds_read_b128 v[212:215], v150 offset:23552
	global_load_lds_dwordx4 v[216:217], off
	s_add_i32 m0, s33, 0x2000
	s_add_u32 s62, s38, 0x40000
	v_lshl_add_u64 v[218:219], s[38:39], 0, v[130:131]
	s_addc_u32 s63, s39, 0
	s_add_i32 s33, s61, s46
	global_load_lds_dwordx4 v[218:219], off
	v_lshl_add_u64 v[220:221], s[62:63], 0, v[134:135]
	s_mov_b32 m0, s33
	v_lshl_add_u64 v[222:223], s[40:41], 0, v[132:133]
	global_load_lds_dwordx4 v[220:221], off
	v_lshl_add_u64 v[220:221], s[62:63], 0, v[130:131]
	s_add_i32 m0, s33, 0x2000
	s_nop 0
	global_load_lds_dwordx4 v[220:221], off
	v_lshl_add_u64 v[220:221], s[40:41], 0, v[136:137]
	s_mov_b32 m0, s25
	s_nop 0
	global_load_lds_dwordx4 v[220:221], off
	s_mov_b32 m0, s37
	s_nop 0
	global_load_lds_dwordx4 v[222:223], off
	s_waitcnt vmcnt(8)
	s_waitcnt lgkmcnt(0)
	s_barrier
; #define PG8_STAGE(bufoff, gbase, voff) do { _Pragma("unroll") for (int _i = 0; _i < 2; ++_i) \
;         __builtin_amdgcn_global_load_lds((const unsigned*)((const char*)(gbase) + (voff)[_i]), (LAS unsigned*)(lds + (bufoff) + ldsw + _i * 8192), 16, 0, 0); } while (0)
; #define PG8_LDA(dst, b, h) do { _Pragma("unroll") for (int m = 0; m < 4; ++m) _Pragma("unroll") for (int k = 0; k < 2; ++k) dst[m][k] = *(const LAS bf16x8*)(lds + PG8_SA(b, h) + aoff + m * 2048 + k * 1024); } while (0)
; #define PG8_LDB(dst, b, h) do { _Pragma("unroll") for (int n = 0; n < 2; ++n) _Pragma("unroll") for (int k = 0; k < 2; ++k) dst[n][k] = *(const LAS bf16x8*)(lds + PG8_SB(b, h) + boff + n * 2048 + k * 1024); } while (0)
; #define PG8_MMA(ai, bj, At, Bt) do { __builtin_amdgcn_s_setprio(1); _Pragma("unroll") for (int m = 0; m < 4; ++m) _Pragma("unroll") for (int n = 0; n < 2; ++n) _Pragma("unroll") for (int k = 0; k < 2; ++k) \
;         acc[ai][bj][m][n] = __builtin_amdgcn_mfma_f32_16x16x32_bf16(Bt[n][k], At[m][k], acc[ai][bj][m][n], 0, 0, 0); __builtin_amdgcn_s_setprio(0); } while (0)
; #define PG8_WAIT_V(n) asm volatile("s_waitcnt vmcnt(" #n ")" ::: "memory")
; #define PG8_WAIT_L(n) asm volatile("s_waitcnt lgkmcnt(" #n ")" ::: "memory")
; #define PG8_BAR __builtin_amdgcn_s_barrier()
; #define PG8_SCHED __builtin_amdgcn_sched_barrier(0)
; template <class Epi>
; __device__ __forceinline__ void gemm_phase(LAS unsigned char* lds, const Gemm g, int G, int c, const Epi& E) {
;     ...
;             PG8_WAIT_V(8); PG8_WAIT_L(0); PG8_BAR; PG8_MMA(1, 0, At, B0); PG8_MMA(1, 1, At, B1); PG8_BAR; PG8_SCHED;
;             PG8_LDB(B0, 1, 0); PG8_LDB(B1, 1, 1); PG8_SCHED; PG8_LDA(At, 1, 0); PG8_STAGE(PG8_SA(0, 1), a2 + hstepA, voffA);
;             PG8_WAIT_V(8); PG8_WAIT_L(0); PG8_BAR; PG8_MMA(0, 0, At, B0); PG8_MMA(0, 1, At, B1); PG8_BAR; PG8_SCHED;
	s_setprio 0
	s_waitcnt lgkmcnt(0)
	v_mfma_f32_16x16x32_bf16 v[62:65], v[152:155], v[184:187], v[62:65]
	v_mfma_f32_16x16x32_bf16 v[58:61], v[160:163], v[184:187], v[58:61]
	v_mfma_f32_16x16x32_bf16 v[46:49], v[152:155], v[192:195], v[46:49]
	v_mfma_f32_16x16x32_bf16 v[42:45], v[160:163], v[192:195], v[42:45]
	v_mfma_f32_16x16x32_bf16 v[30:33], v[152:155], v[200:203], v[30:33]
	v_mfma_f32_16x16x32_bf16 v[26:29], v[160:163], v[200:203], v[26:29]
	v_mfma_f32_16x16x32_bf16 v[14:17], v[152:155], v[208:211], v[14:17]
	v_mfma_f32_16x16x32_bf16 v[10:13], v[160:163], v[208:211], v[10:13]
	v_mfma_f32_16x16x32_bf16 v[62:65], v[156:159], v[188:191], v[62:65]
	v_mfma_f32_16x16x32_bf16 v[58:61], v[164:167], v[188:191], v[58:61]
	v_mfma_f32_16x16x32_bf16 v[46:49], v[156:159], v[196:199], v[46:49]
	v_mfma_f32_16x16x32_bf16 v[42:45], v[164:167], v[196:199], v[42:45]
	v_mfma_f32_16x16x32_bf16 v[30:33], v[156:159], v[204:207], v[30:33]
	v_mfma_f32_16x16x32_bf16 v[26:29], v[164:167], v[204:207], v[26:29]
	v_mfma_f32_16x16x32_bf16 v[14:17], v[156:159], v[212:215], v[14:17]
	v_mfma_f32_16x16x32_bf16 v[10:13], v[164:167], v[212:215], v[10:13]
	s_setprio 2
	s_setprio 0
	v_mfma_f32_16x16x32_bf16 v[54:57], v[168:171], v[184:187], v[54:57]
	v_mfma_f32_16x16x32_bf16 v[50:53], v[176:179], v[184:187], v[50:53]
	v_mfma_f32_16x16x32_bf16 v[38:41], v[168:171], v[192:195], v[38:41]
	v_mfma_f32_16x16x32_bf16 v[34:37], v[176:179], v[192:195], v[34:37]
	v_mfma_f32_16x16x32_bf16 v[22:25], v[168:171], v[200:203], v[22:25]
	v_mfma_f32_16x16x32_bf16 v[18:21], v[176:179], v[200:203], v[18:21]
	v_mfma_f32_16x16x32_bf16 v[6:9], v[168:171], v[208:211], v[6:9]
	v_mfma_f32_16x16x32_bf16 v[2:5], v[176:179], v[208:211], v[2:5]
	v_mfma_f32_16x16x32_bf16 v[54:57], v[172:175], v[188:191], v[54:57]
	v_mfma_f32_16x16x32_bf16 v[50:53], v[180:183], v[188:191], v[50:53]
	v_mfma_f32_16x16x32_bf16 v[38:41], v[172:175], v[196:199], v[38:41]
	v_mfma_f32_16x16x32_bf16 v[34:37], v[180:183], v[196:199], v[34:37]
	v_mfma_f32_16x16x32_bf16 v[22:25], v[172:175], v[204:207], v[22:25]
	v_mfma_f32_16x16x32_bf16 v[18:21], v[180:183], v[204:207], v[18:21]
	v_mfma_f32_16x16x32_bf16 v[6:9], v[172:175], v[212:215], v[6:9]
	v_mfma_f32_16x16x32_bf16 v[2:5], v[180:183], v[212:215], v[2:5]
	s_setprio 2
	s_barrier
	s_add_i32 s33, 0, 0x18000
	s_add_i32 s62, 0, 0x1c000
	v_add_u32_e32 v164, s33, v147
	v_add_u32_e32 v180, s62, v147
	ds_read_b128 v[152:155], v164
	ds_read_b128 v[156:159], v164 offset:1024
	ds_read_b128 v[160:163], v164 offset:2048
	ds_read_b128 v[164:167], v164 offset:3072
	ds_read_b128 v[168:171], v180
	ds_read_b128 v[172:175], v180 offset:1024
	ds_read_b128 v[176:179], v180 offset:2048
	ds_read_b128 v[180:183], v180 offset:3072
	s_add_u32 s40, s40, 0x40000
	s_addc_u32 s41, s41, 0
	s_mov_b32 m0, s47
	v_lshl_add_u64 v[224:225], s[40:41], 0, v[136:137]
	ds_read_b128 v[184:187], v150 offset:32768
	ds_read_b128 v[188:191], v150 offset:33792
	ds_read_b128 v[192:195], v150 offset:34816
	ds_read_b128 v[196:199], v150 offset:35840
	ds_read_b128 v[200:203], v150 offset:36864
	ds_read_b128 v[204:207], v150 offset:37888
	ds_read_b128 v[208:211], v150 offset:38912
	ds_read_b128 v[212:215], v150 offset:39936
	global_load_lds_dwordx4 v[224:225], off
	v_lshl_add_u64 v[224:225], s[40:41], 0, v[132:133]
	s_mov_b32 m0, s52
	s_nop 0
	global_load_lds_dwordx4 v[224:225], off
	s_waitcnt vmcnt(8)
	s_waitcnt lgkmcnt(0)
	s_barrier
	s_setprio 0
	s_waitcnt lgkmcnt(0)
	v_mfma_f32_16x16x32_bf16 v[126:129], v[152:155], v[184:187], v[126:129]
	v_mfma_f32_16x16x32_bf16 v[122:125], v[160:163], v[184:187], v[122:125]
	v_mfma_f32_16x16x32_bf16 v[110:113], v[152:155], v[192:195], v[110:113]
	v_mfma_f32_16x16x32_bf16 v[106:109], v[160:163], v[192:195], v[106:109]
	v_mfma_f32_16x16x32_bf16 v[94:97], v[152:155], v[200:203], v[94:97]
	v_mfma_f32_16x16x32_bf16 v[90:93], v[160:163], v[200:203], v[90:93]
	v_mfma_f32_16x16x32_bf16 v[78:81], v[152:155], v[208:211], v[78:81]
	v_mfma_f32_16x16x32_bf16 v[74:77], v[160:163], v[208:211], v[74:77]
	v_mfma_f32_16x16x32_bf16 v[126:129], v[156:159], v[188:191], v[126:129]
	v_mfma_f32_16x16x32_bf16 v[122:125], v[164:167], v[188:191], v[122:125]
	v_mfma_f32_16x16x32_bf16 v[110:113], v[156:159], v[196:199], v[110:113]
	v_mfma_f32_16x16x32_bf16 v[106:109], v[164:167], v[196:199], v[106:109]
	v_mfma_f32_16x16x32_bf16 v[94:97], v[156:159], v[204:207], v[94:97]
	v_mfma_f32_16x16x32_bf16 v[90:93], v[164:167], v[204:207], v[90:93]
	v_mfma_f32_16x16x32_bf16 v[78:81], v[156:159], v[212:215], v[78:81]
	v_mfma_f32_16x16x32_bf16 v[74:77], v[164:167], v[212:215], v[74:77]
	s_setprio 2
	s_setprio 0
	v_mfma_f32_16x16x32_bf16 v[118:121], v[168:171], v[184:187], v[118:121]
	v_mfma_f32_16x16x32_bf16 v[114:117], v[176:179], v[184:187], v[114:117]
	v_mfma_f32_16x16x32_bf16 v[102:105], v[168:171], v[192:195], v[102:105]
	v_mfma_f32_16x16x32_bf16 v[98:101], v[176:179], v[192:195], v[98:101]
	v_mfma_f32_16x16x32_bf16 v[86:89], v[168:171], v[200:203], v[86:89]
	v_mfma_f32_16x16x32_bf16 v[82:85], v[176:179], v[200:203], v[82:85]
	v_mfma_f32_16x16x32_bf16 v[70:73], v[168:171], v[208:211], v[70:73]
	v_mfma_f32_16x16x32_bf16 v[66:69], v[176:179], v[208:211], v[66:69]
	v_mfma_f32_16x16x32_bf16 v[118:121], v[172:175], v[188:191], v[118:121]
	v_mfma_f32_16x16x32_bf16 v[114:117], v[180:183], v[188:191], v[114:117]
	v_mfma_f32_16x16x32_bf16 v[102:105], v[172:175], v[196:199], v[102:105]
	v_mfma_f32_16x16x32_bf16 v[98:101], v[180:183], v[196:199], v[98:101]
	v_mfma_f32_16x16x32_bf16 v[86:89], v[172:175], v[204:207], v[86:89]
	v_mfma_f32_16x16x32_bf16 v[82:85], v[180:183], v[204:207], v[82:85]
	v_mfma_f32_16x16x32_bf16 v[70:73], v[172:175], v[212:215], v[70:73]
	v_mfma_f32_16x16x32_bf16 v[66:69], v[180:183], v[212:215], v[66:69]
	s_setprio 2
	s_barrier
; #define PG8_STAGE(bufoff, gbase, voff) do { _Pragma("unroll") for (int _i = 0; _i < 2; ++_i) \
;         __builtin_amdgcn_global_load_lds((const unsigned*)((const char*)(gbase) + (voff)[_i]), (LAS unsigned*)(lds + (bufoff) + ldsw + _i * 8192), 16, 0, 0); } while (0)
; #define PG8_LDA(dst, b, h) do { _Pragma("unroll") for (int m = 0; m < 4; ++m) _Pragma("unroll") for (int k = 0; k < 2; ++k) dst[m][k] = *(const LAS bf16x8*)(lds + PG8_SA(b, h) + aoff + m * 2048 + k * 1024); } while (0)
; #define PG8_MMA(ai, bj, At, Bt) do { __builtin_amdgcn_s_setprio(1); _Pragma("unroll") for (int m = 0; m < 4; ++m) _Pragma("unroll") for (int n = 0; n < 2; ++n) _Pragma("unroll") for (int k = 0; k < 2; ++k) \
;         acc[ai][bj][m][n] = __builtin_amdgcn_mfma_f32_16x16x32_bf16(Bt[n][k], At[m][k], acc[ai][bj][m][n], 0, 0, 0); __builtin_amdgcn_s_setprio(0); } while (0)
; #define PG8_WAIT_V(n) asm volatile("s_waitcnt vmcnt(" #n ")" ::: "memory")
; #define PG8_WAIT_L(n) asm volatile("s_waitcnt lgkmcnt(" #n ")" ::: "memory")
; #define PG8_BAR __builtin_amdgcn_s_barrier()
; #define PG8_SCHED __builtin_amdgcn_sched_barrier(0)
; template <class Epi>
; __device__ __forceinline__ void gemm_phase(LAS unsigned char* lds, const Gemm g, int G, int c, const Epi& E) {
;     ...
;             PG8_LDA(At, 1, 1); PG8_STAGE(PG8_SB(1, 0), b3, voffB); PG8_STAGE(PG8_SB(1, 1), b3 + hstepB, voffB); PG8_STAGE(PG8_SA(1, 0), a3, voffA);
;             PG8_WAIT_V(8); PG8_WAIT_L(0); PG8_BAR; PG8_MMA(1, 0, At, B0); PG8_MMA(1, 1, At, B1); PG8_BAR; PG8_SCHED;
;         }
;         if (wr == 0) PG8_BAR;
	s_add_i32 s33, s33, s46
	v_lshl_add_u64 v[216:217], v[216:217], 0, s[12:13]
	s_mov_b32 m0, s33
	ds_read_b128 v[184:187], v150 offset:49152
	ds_read_b128 v[188:191], v150 offset:50176
	ds_read_b128 v[192:195], v150 offset:51200
	ds_read_b128 v[196:199], v150 offset:52224
	ds_read_b128 v[200:203], v150 offset:53248
	ds_read_b128 v[204:207], v150 offset:54272
	ds_read_b128 v[208:211], v150 offset:55296
	ds_read_b128 v[212:215], v150 offset:56320
	global_load_lds_dwordx4 v[216:217], off
	s_add_i32 m0, s33, 0x2000
	s_add_u32 s38, s38, 0x40080
	v_lshl_add_u64 v[216:217], v[218:219], 0, s[12:13]
	s_addc_u32 s39, s39, 0
	s_add_i32 s33, s62, s46
	global_load_lds_dwordx4 v[216:217], off
	v_lshl_add_u64 v[216:217], s[38:39], 0, v[134:135]
	s_mov_b32 m0, s33
	s_nop 0
	global_load_lds_dwordx4 v[216:217], off
	v_lshl_add_u64 v[216:217], s[38:39], 0, v[130:131]
	s_add_i32 m0, s33, 0x2000
	s_nop 0
	global_load_lds_dwordx4 v[216:217], off
	v_lshl_add_u64 v[216:217], v[220:221], 0, s[12:13]
	s_mov_b32 m0, s57
	s_nop 0
	global_load_lds_dwordx4 v[216:217], off
	v_lshl_add_u64 v[216:217], v[222:223], 0, s[12:13]
	s_mov_b32 m0, s58
	s_nop 0
	global_load_lds_dwordx4 v[216:217], off
	s_waitcnt vmcnt(8)
	s_waitcnt lgkmcnt(0)
	s_barrier
	s_setprio 0
	s_waitcnt lgkmcnt(0)
	v_mfma_f32_16x16x32_bf16 v[62:65], v[152:155], v[184:187], v[62:65]
	v_mfma_f32_16x16x32_bf16 v[58:61], v[160:163], v[184:187], v[58:61]
	v_mfma_f32_16x16x32_bf16 v[46:49], v[152:155], v[192:195], v[46:49]
	v_mfma_f32_16x16x32_bf16 v[42:45], v[160:163], v[192:195], v[42:45]
	v_mfma_f32_16x16x32_bf16 v[30:33], v[152:155], v[200:203], v[30:33]
	v_mfma_f32_16x16x32_bf16 v[26:29], v[160:163], v[200:203], v[26:29]
	v_mfma_f32_16x16x32_bf16 v[14:17], v[152:155], v[208:211], v[14:17]
	v_mfma_f32_16x16x32_bf16 v[10:13], v[160:163], v[208:211], v[10:13]
	v_mfma_f32_16x16x32_bf16 v[62:65], v[156:159], v[188:191], v[62:65]
	v_mfma_f32_16x16x32_bf16 v[58:61], v[164:167], v[188:191], v[58:61]
	v_mfma_f32_16x16x32_bf16 v[46:49], v[156:159], v[196:199], v[46:49]
	v_mfma_f32_16x16x32_bf16 v[42:45], v[164:167], v[196:199], v[42:45]
	v_mfma_f32_16x16x32_bf16 v[30:33], v[156:159], v[204:207], v[30:33]
	v_mfma_f32_16x16x32_bf16 v[26:29], v[164:167], v[204:207], v[26:29]
	v_mfma_f32_16x16x32_bf16 v[14:17], v[156:159], v[212:215], v[14:17]
	v_mfma_f32_16x16x32_bf16 v[10:13], v[164:167], v[212:215], v[10:13]
	s_setprio 2
	s_setprio 0
	v_mfma_f32_16x16x32_bf16 v[54:57], v[168:171], v[184:187], v[54:57]
	v_mfma_f32_16x16x32_bf16 v[50:53], v[176:179], v[184:187], v[50:53]
	v_mfma_f32_16x16x32_bf16 v[38:41], v[168:171], v[192:195], v[38:41]
	v_mfma_f32_16x16x32_bf16 v[34:37], v[176:179], v[192:195], v[34:37]
	v_mfma_f32_16x16x32_bf16 v[22:25], v[168:171], v[200:203], v[22:25]
	v_mfma_f32_16x16x32_bf16 v[18:21], v[176:179], v[200:203], v[18:21]
	v_mfma_f32_16x16x32_bf16 v[6:9], v[168:171], v[208:211], v[6:9]
	v_mfma_f32_16x16x32_bf16 v[2:5], v[176:179], v[208:211], v[2:5]
	v_mfma_f32_16x16x32_bf16 v[54:57], v[172:175], v[188:191], v[54:57]
	v_mfma_f32_16x16x32_bf16 v[50:53], v[180:183], v[188:191], v[50:53]
	v_mfma_f32_16x16x32_bf16 v[38:41], v[172:175], v[196:199], v[38:41]
	v_mfma_f32_16x16x32_bf16 v[34:37], v[180:183], v[196:199], v[34:37]
	v_mfma_f32_16x16x32_bf16 v[22:25], v[172:175], v[204:207], v[22:25]
	v_mfma_f32_16x16x32_bf16 v[18:21], v[180:183], v[204:207], v[18:21]
	v_mfma_f32_16x16x32_bf16 v[6:9], v[172:175], v[212:215], v[6:9]
	v_mfma_f32_16x16x32_bf16 v[2:5], v[180:183], v[212:215], v[2:5]
	s_setprio 2
	s_barrier
	s_add_i32 s80, s80, 2
	s_add_u32 s4, s4, 0x100
	s_addc_u32 s5, s5, 0
	s_add_u32 s78, s78, 0x100
	s_addc_u32 s79, s79, 0
	s_cmp_gt_u32 s80, 13
	s_cbranch_scc0 .LBB0_1058
	s_and_b64 vcc, exec, s[14:15]
	s_cbranch_vccz .LBB0_1061
	s_barrier

; #define PG8_STAGE(bufoff, gbase, voff) do { _Pragma("unroll") for (int _i = 0; _i < 2; ++_i) \
;         __builtin_amdgcn_global_load_lds((const unsigned*)((const char*)(gbase) + (voff)[_i]), (LAS unsigned*)(lds + (bufoff) + ldsw + _i * 8192), 16, 0, 0); } while (0)
; #define PG8_LDA(dst, b, h) do { _Pragma("unroll") for (int m = 0; m < 4; ++m) _Pragma("unroll") for (int k = 0; k < 2; ++k) dst[m][k] = *(const LAS bf16x8*)(lds + PG8_SA(b, h) + aoff + m * 2048 + k * 1024); } while (0)
; #define PG8_LDB(dst, b, h) do { _Pragma("unroll") for (int n = 0; n < 2; ++n) _Pragma("unroll") for (int k = 0; k < 2; ++k) dst[n][k] = *(const LAS bf16x8*)(lds + PG8_SB(b, h) + boff + n * 2048 + k * 1024); } while (0)
; #define PG8_MMA(ai, bj, At, Bt) do { __builtin_amdgcn_s_setprio(1); _Pragma("unroll") for (int m = 0; m < 4; ++m) _Pragma("unroll") for (int n = 0; n < 2; ++n) _Pragma("unroll") for (int k = 0; k < 2; ++k) \
;         acc[ai][bj][m][n] = __builtin_amdgcn_mfma_f32_16x16x32_bf16(Bt[n][k], At[m][k], acc[ai][bj][m][n], 0, 0, 0); __builtin_amdgcn_s_setprio(0); } while (0)
; #define PG8_WAIT_V(n) asm volatile("s_waitcnt vmcnt(" #n ")" ::: "memory")
; #define PG8_WAIT_L(n) asm volatile("s_waitcnt lgkmcnt(" #n ")" ::: "memory")
; #define PG8_BAR __builtin_amdgcn_s_barrier()
; #define PG8_SCHED __builtin_amdgcn_sched_barrier(0)
; template <class Epi>
; __device__ __forceinline__ void gemm_phase(LAS unsigned char* lds, const Gemm g, int G, int c, const Epi& E) {
;     ...
;             const bool last = (t == nt - 2);
;             const char* a1 = cA + (size_t)(t + 1) * kstep;
;             const char* a2 = last ? nA : cA + (size_t)(t + 2) * kstep; const char* b2 = last ? nB : cB + (size_t)(t + 2) * kstep;
;             const char* a3 = a2 + kstep; const char* b3 = b2 + kstep;
;             PG8_LDB(B0, 0, 0); PG8_LDB(B1, 0, 1); PG8_SCHED; PG8_LDA(At, 0, 0); PG8_STAGE(PG8_SA(1, 1), a1 + hstepA, voffA);
;             PG8_WAIT_V(8); PG8_WAIT_L(0); PG8_BAR; PG8_MMA(0, 0, At, B0); PG8_MMA(0, 1, At, B1); PG8_BAR; PG8_SCHED;
;             PG8_LDA(At, 0, 1); PG8_STAGE(PG8_SB(0, 0), b2, voffB); PG8_STAGE(PG8_SB(0, 1), b2 + hstepB, voffB); PG8_STAGE(PG8_SA(0, 0), a2, voffA);
;             PG8_WAIT_V(8); PG8_WAIT_L(0); PG8_BAR; PG8_MMA(1, 0, At, B0); PG8_MMA(1, 1, At, B1); PG8_BAR; PG8_SCHED;
.LBB0_1143:
	ds_read_b128 v[122:125], v168
	ds_read_b128 v[126:129], v168 offset:1024
	ds_read_b128 v[130:133], v168 offset:2048
	ds_read_b128 v[134:137], v168 offset:3072
	ds_read_b128 v[162:165], v169
	ds_read_b128 v[172:175], v169 offset:1024
	ds_read_b128 v[176:179], v169 offset:2048
	ds_read_b128 v[180:183], v169 offset:3072
	s_add_u32 s18, s16, 0x100
	s_addc_u32 s19, s17, 0
	s_cmp_eq_u32 s68, 40
	s_cselect_b32 s23, s5, s19
	s_cselect_b32 s22, s4, s18
	s_cselect_b32 s21, s15, s67
	s_cselect_b32 s20, s14, s66
	v_lshl_add_u64 v[216:217], s[16:17], 0, v[154:155]
	s_add_i32 m0, s38, 0xc000
	ds_read_b128 v[184:187], v170
	ds_read_b128 v[188:191], v170 offset:1024
	ds_read_b128 v[192:195], v170 offset:2048
	ds_read_b128 v[196:199], v170 offset:3072
	ds_read_b128 v[200:203], v170 offset:4096
	ds_read_b128 v[204:207], v170 offset:5120
	ds_read_b128 v[208:211], v170 offset:6144
	ds_read_b128 v[212:215], v170 offset:7168
	global_load_lds_dwordx4 v[216:217], off
	v_lshl_add_u64 v[216:217], s[16:17], 0, v[156:157]
	s_add_i32 m0, s38, 0xe000
	s_nop 0
	global_load_lds_dwordx4 v[216:217], off
	s_waitcnt vmcnt(8)
	s_waitcnt lgkmcnt(0)
	s_barrier
	s_setprio 0
	s_waitcnt lgkmcnt(0)
	v_mfma_f32_16x16x32_bf16 v[142:145], v[122:125], v[184:187], v[142:145]
	v_mfma_f32_16x16x32_bf16 v[138:141], v[130:133], v[184:187], v[138:141]
	v_mfma_f32_16x16x32_bf16 v[118:121], v[122:125], v[192:195], v[118:121]
	v_mfma_f32_16x16x32_bf16 v[106:109], v[130:133], v[192:195], v[106:109]
	v_mfma_f32_16x16x32_bf16 v[102:105], v[122:125], v[200:203], v[102:105]
	v_mfma_f32_16x16x32_bf16 v[90:93], v[130:133], v[200:203], v[90:93]
	v_mfma_f32_16x16x32_bf16 v[86:89], v[122:125], v[208:211], v[86:89]
	v_mfma_f32_16x16x32_bf16 v[74:77], v[130:133], v[208:211], v[74:77]
	v_mfma_f32_16x16x32_bf16 v[142:145], v[126:129], v[188:191], v[142:145]
	v_mfma_f32_16x16x32_bf16 v[138:141], v[134:137], v[188:191], v[138:141]
	v_mfma_f32_16x16x32_bf16 v[118:121], v[126:129], v[196:199], v[118:121]
	v_mfma_f32_16x16x32_bf16 v[106:109], v[134:137], v[196:199], v[106:109]
	v_mfma_f32_16x16x32_bf16 v[102:105], v[126:129], v[204:207], v[102:105]
	v_mfma_f32_16x16x32_bf16 v[90:93], v[134:137], v[204:207], v[90:93]
	v_mfma_f32_16x16x32_bf16 v[86:89], v[126:129], v[212:215], v[86:89]
	v_mfma_f32_16x16x32_bf16 v[74:77], v[134:137], v[212:215], v[74:77]
	s_setprio 2
	s_setprio 0
	v_mfma_f32_16x16x32_bf16 v[114:117], v[162:165], v[184:187], v[114:117]
	v_mfma_f32_16x16x32_bf16 v[110:113], v[176:179], v[184:187], v[110:113]
	v_mfma_f32_16x16x32_bf16 v[98:101], v[162:165], v[192:195], v[98:101]
	v_mfma_f32_16x16x32_bf16 v[94:97], v[176:179], v[192:195], v[94:97]
	v_mfma_f32_16x16x32_bf16 v[82:85], v[162:165], v[200:203], v[82:85]
	v_mfma_f32_16x16x32_bf16 v[78:81], v[176:179], v[200:203], v[78:81]
	v_mfma_f32_16x16x32_bf16 v[70:73], v[162:165], v[208:211], v[70:73]
	v_mfma_f32_16x16x32_bf16 v[66:69], v[176:179], v[208:211], v[66:69]
	v_mfma_f32_16x16x32_bf16 v[114:117], v[172:175], v[188:191], v[114:117]
	v_mfma_f32_16x16x32_bf16 v[110:113], v[180:183], v[188:191], v[110:113]
	v_mfma_f32_16x16x32_bf16 v[98:101], v[172:175], v[196:199], v[98:101]
	v_mfma_f32_16x16x32_bf16 v[94:97], v[180:183], v[196:199], v[94:97]
	v_mfma_f32_16x16x32_bf16 v[82:85], v[172:175], v[204:207], v[82:85]
	v_mfma_f32_16x16x32_bf16 v[78:81], v[180:183], v[204:207], v[78:81]
	v_mfma_f32_16x16x32_bf16 v[70:73], v[172:175], v[212:215], v[70:73]
	v_mfma_f32_16x16x32_bf16 v[66:69], v[180:183], v[212:215], v[66:69]
	s_setprio 2
	s_barrier
	s_add_i32 s16, s54, s36
	v_lshl_add_u64 v[216:217], s[20:21], 0, v[150:151]
	s_mov_b32 m0, s16
	ds_read_b128 v[184:187], v170 offset:16384
	ds_read_b128 v[188:191], v170 offset:17408
	ds_read_b128 v[192:195], v170 offset:18432
	ds_read_b128 v[196:199], v170 offset:19456
	ds_read_b128 v[200:203], v170 offset:20480
	ds_read_b128 v[204:207], v170 offset:21504
	ds_read_b128 v[208:211], v170 offset:22528
	ds_read_b128 v[212:215], v170 offset:23552
	global_load_lds_dwordx4 v[216:217], off
	s_add_i32 m0, s16, 0x2000
	s_add_u32 s16, s20, 0xb0000
	v_lshl_add_u64 v[218:219], s[20:21], 0, v[146:147]
	s_addc_u32 s17, s21, 0
	s_add_i32 s33, s55, s36
	global_load_lds_dwordx4 v[218:219], off
	v_lshl_add_u64 v[220:221], s[16:17], 0, v[150:151]
	s_mov_b32 m0, s33
	v_lshl_add_u64 v[222:223], s[22:23], 0, v[148:149]
	global_load_lds_dwordx4 v[220:221], off
	v_lshl_add_u64 v[220:221], s[16:17], 0, v[146:147]
	s_add_i32 m0, s33, 0x2000
	s_nop 0
	global_load_lds_dwordx4 v[220:221], off
	v_lshl_add_u64 v[220:221], s[22:23], 0, v[152:153]
	s_mov_b32 m0, s38
	s_nop 0
	global_load_lds_dwordx4 v[220:221], off
	s_mov_b32 m0, s39
	s_nop 0
	global_load_lds_dwordx4 v[222:223], off
	s_waitcnt vmcnt(8)
	s_waitcnt lgkmcnt(0)
	s_barrier
; #define PG8_STAGE(bufoff, gbase, voff) do { _Pragma("unroll") for (int _i = 0; _i < 2; ++_i) \
;         __builtin_amdgcn_global_load_lds((const unsigned*)((const char*)(gbase) + (voff)[_i]), (LAS unsigned*)(lds + (bufoff) + ldsw + _i * 8192), 16, 0, 0); } while (0)
; #define PG8_LDA(dst, b, h) do { _Pragma("unroll") for (int m = 0; m < 4; ++m) _Pragma("unroll") for (int k = 0; k < 2; ++k) dst[m][k] = *(const LAS bf16x8*)(lds + PG8_SA(b, h) + aoff + m * 2048 + k * 1024); } while (0)
; #define PG8_LDB(dst, b, h) do { _Pragma("unroll") for (int n = 0; n < 2; ++n) _Pragma("unroll") for (int k = 0; k < 2; ++k) dst[n][k] = *(const LAS bf16x8*)(lds + PG8_SB(b, h) + boff + n * 2048 + k * 1024); } while (0)
; #define PG8_MMA(ai, bj, At, Bt) do { __builtin_amdgcn_s_setprio(1); _Pragma("unroll") for (int m = 0; m < 4; ++m) _Pragma("unroll") for (int n = 0; n < 2; ++n) _Pragma("unroll") for (int k = 0; k < 2; ++k) \
;         acc[ai][bj][m][n] = __builtin_amdgcn_mfma_f32_16x16x32_bf16(Bt[n][k], At[m][k], acc[ai][bj][m][n], 0, 0, 0); __builtin_amdgcn_s_setprio(0); } while (0)
; #define PG8_WAIT_V(n) asm volatile("s_waitcnt vmcnt(" #n ")" ::: "memory")
; #define PG8_WAIT_L(n) asm volatile("s_waitcnt lgkmcnt(" #n ")" ::: "memory")
; #define PG8_BAR __builtin_amdgcn_s_barrier()
; #define PG8_SCHED __builtin_amdgcn_sched_barrier(0)
; template <class Epi>
; __device__ __forceinline__ void gemm_phase(LAS unsigned char* lds, const Gemm g, int G, int c, const Epi& E) {
;     ...
;             PG8_WAIT_V(8); PG8_WAIT_L(0); PG8_BAR; PG8_MMA(1, 0, At, B0); PG8_MMA(1, 1, At, B1); PG8_BAR; PG8_SCHED;
;             PG8_LDB(B0, 1, 0); PG8_LDB(B1, 1, 1); PG8_SCHED; PG8_LDA(At, 1, 0); PG8_STAGE(PG8_SA(0, 1), a2 + hstepA, voffA);
;             PG8_WAIT_V(8); PG8_WAIT_L(0); PG8_BAR; PG8_MMA(0, 0, At, B0); PG8_MMA(0, 1, At, B1); PG8_BAR; PG8_SCHED;
	s_setprio 0
	s_waitcnt lgkmcnt(0)
	v_mfma_f32_16x16x32_bf16 v[62:65], v[122:125], v[184:187], v[62:65]
	v_mfma_f32_16x16x32_bf16 v[58:61], v[130:133], v[184:187], v[58:61]
	v_mfma_f32_16x16x32_bf16 v[54:57], v[122:125], v[192:195], v[54:57]
	v_mfma_f32_16x16x32_bf16 v[42:45], v[130:133], v[192:195], v[42:45]
	v_mfma_f32_16x16x32_bf16 v[38:41], v[122:125], v[200:203], v[38:41]
	v_mfma_f32_16x16x32_bf16 v[26:29], v[130:133], v[200:203], v[26:29]
	v_mfma_f32_16x16x32_bf16 v[22:25], v[122:125], v[208:211], v[22:25]
	v_mfma_f32_16x16x32_bf16 v[10:13], v[130:133], v[208:211], v[10:13]
	v_mfma_f32_16x16x32_bf16 v[62:65], v[126:129], v[188:191], v[62:65]
	v_mfma_f32_16x16x32_bf16 v[58:61], v[134:137], v[188:191], v[58:61]
	v_mfma_f32_16x16x32_bf16 v[54:57], v[126:129], v[196:199], v[54:57]
	v_mfma_f32_16x16x32_bf16 v[42:45], v[134:137], v[196:199], v[42:45]
	v_mfma_f32_16x16x32_bf16 v[38:41], v[126:129], v[204:207], v[38:41]
	v_mfma_f32_16x16x32_bf16 v[26:29], v[134:137], v[204:207], v[26:29]
	v_mfma_f32_16x16x32_bf16 v[22:25], v[126:129], v[212:215], v[22:25]
	v_mfma_f32_16x16x32_bf16 v[10:13], v[134:137], v[212:215], v[10:13]
	s_setprio 2
	s_setprio 0
	v_mfma_f32_16x16x32_bf16 v[50:53], v[162:165], v[184:187], v[50:53]
	v_mfma_f32_16x16x32_bf16 v[46:49], v[176:179], v[184:187], v[46:49]
	v_mfma_f32_16x16x32_bf16 v[34:37], v[162:165], v[192:195], v[34:37]
	v_mfma_f32_16x16x32_bf16 v[30:33], v[176:179], v[192:195], v[30:33]
	v_mfma_f32_16x16x32_bf16 v[18:21], v[162:165], v[200:203], v[18:21]
	v_mfma_f32_16x16x32_bf16 v[14:17], v[176:179], v[200:203], v[14:17]
	v_mfma_f32_16x16x32_bf16 v[6:9], v[162:165], v[208:211], v[6:9]
	v_mfma_f32_16x16x32_bf16 v[2:5], v[176:179], v[208:211], v[2:5]
	v_mfma_f32_16x16x32_bf16 v[50:53], v[172:175], v[188:191], v[50:53]
	v_mfma_f32_16x16x32_bf16 v[46:49], v[180:183], v[188:191], v[46:49]
	v_mfma_f32_16x16x32_bf16 v[34:37], v[172:175], v[196:199], v[34:37]
	v_mfma_f32_16x16x32_bf16 v[30:33], v[180:183], v[196:199], v[30:33]
	v_mfma_f32_16x16x32_bf16 v[18:21], v[172:175], v[204:207], v[18:21]
	v_mfma_f32_16x16x32_bf16 v[14:17], v[180:183], v[204:207], v[14:17]
	v_mfma_f32_16x16x32_bf16 v[6:9], v[172:175], v[212:215], v[6:9]
	v_mfma_f32_16x16x32_bf16 v[2:5], v[180:183], v[212:215], v[2:5]
	s_setprio 2
	s_barrier
	s_add_i32 s33, 0, 0x18000
	s_add_i32 s62, 0, 0x1c000
	v_add_u32_e32 v134, s33, v167
	v_add_u32_e32 v171, s62, v167
	ds_read_b128 v[122:125], v134
	ds_read_b128 v[126:129], v134 offset:1024
	ds_read_b128 v[130:133], v134 offset:2048
	ds_read_b128 v[134:137], v134 offset:3072
	ds_read_b128 v[162:165], v171
	ds_read_b128 v[172:175], v171 offset:1024
	ds_read_b128 v[176:179], v171 offset:2048
	ds_read_b128 v[180:183], v171 offset:3072
	s_add_u32 s16, s22, 0xb0000
	s_addc_u32 s17, s23, 0
	s_mov_b32 m0, s40
	v_lshl_add_u64 v[224:225], s[16:17], 0, v[152:153]
	ds_read_b128 v[184:187], v170 offset:32768
	ds_read_b128 v[188:191], v170 offset:33792
	ds_read_b128 v[192:195], v170 offset:34816
	ds_read_b128 v[196:199], v170 offset:35840
	ds_read_b128 v[200:203], v170 offset:36864
	ds_read_b128 v[204:207], v170 offset:37888
	ds_read_b128 v[208:211], v170 offset:38912
	ds_read_b128 v[212:215], v170 offset:39936
	global_load_lds_dwordx4 v[224:225], off
	v_lshl_add_u64 v[224:225], s[16:17], 0, v[148:149]
	s_mov_b32 m0, s41
	s_nop 0
	global_load_lds_dwordx4 v[224:225], off
	s_waitcnt vmcnt(8)
	s_waitcnt lgkmcnt(0)
	s_barrier
	s_setprio 0
	s_waitcnt lgkmcnt(0)
	v_mfma_f32_16x16x32_bf16 v[142:145], v[122:125], v[184:187], v[142:145]
	v_mfma_f32_16x16x32_bf16 v[138:141], v[130:133], v[184:187], v[138:141]
	v_mfma_f32_16x16x32_bf16 v[118:121], v[122:125], v[192:195], v[118:121]
	v_mfma_f32_16x16x32_bf16 v[106:109], v[130:133], v[192:195], v[106:109]
	v_mfma_f32_16x16x32_bf16 v[102:105], v[122:125], v[200:203], v[102:105]
	v_mfma_f32_16x16x32_bf16 v[90:93], v[130:133], v[200:203], v[90:93]
	v_mfma_f32_16x16x32_bf16 v[86:89], v[122:125], v[208:211], v[86:89]
	v_mfma_f32_16x16x32_bf16 v[74:77], v[130:133], v[208:211], v[74:77]
	v_mfma_f32_16x16x32_bf16 v[142:145], v[126:129], v[188:191], v[142:145]
	v_mfma_f32_16x16x32_bf16 v[138:141], v[134:137], v[188:191], v[138:141]
	v_mfma_f32_16x16x32_bf16 v[118:121], v[126:129], v[196:199], v[118:121]
	v_mfma_f32_16x16x32_bf16 v[106:109], v[134:137], v[196:199], v[106:109]
	v_mfma_f32_16x16x32_bf16 v[102:105], v[126:129], v[204:207], v[102:105]
	v_mfma_f32_16x16x32_bf16 v[90:93], v[134:137], v[204:207], v[90:93]
	v_mfma_f32_16x16x32_bf16 v[86:89], v[126:129], v[212:215], v[86:89]
	v_mfma_f32_16x16x32_bf16 v[74:77], v[134:137], v[212:215], v[74:77]
	s_setprio 2
	s_setprio 0
	v_mfma_f32_16x16x32_bf16 v[114:117], v[162:165], v[184:187], v[114:117]
	v_mfma_f32_16x16x32_bf16 v[110:113], v[176:179], v[184:187], v[110:113]
	v_mfma_f32_16x16x32_bf16 v[98:101], v[162:165], v[192:195], v[98:101]
	v_mfma_f32_16x16x32_bf16 v[94:97], v[176:179], v[192:195], v[94:97]
	v_mfma_f32_16x16x32_bf16 v[82:85], v[162:165], v[200:203], v[82:85]
	v_mfma_f32_16x16x32_bf16 v[78:81], v[176:179], v[200:203], v[78:81]
	v_mfma_f32_16x16x32_bf16 v[70:73], v[162:165], v[208:211], v[70:73]
	v_mfma_f32_16x16x32_bf16 v[66:69], v[176:179], v[208:211], v[66:69]
	v_mfma_f32_16x16x32_bf16 v[114:117], v[172:175], v[188:191], v[114:117]
	v_mfma_f32_16x16x32_bf16 v[110:113], v[180:183], v[188:191], v[110:113]
	v_mfma_f32_16x16x32_bf16 v[98:101], v[172:175], v[196:199], v[98:101]
	v_mfma_f32_16x16x32_bf16 v[94:97], v[180:183], v[196:199], v[94:97]
	v_mfma_f32_16x16x32_bf16 v[82:85], v[172:175], v[204:207], v[82:85]
	v_mfma_f32_16x16x32_bf16 v[78:81], v[180:183], v[204:207], v[78:81]
	v_mfma_f32_16x16x32_bf16 v[70:73], v[172:175], v[212:215], v[70:73]
	v_mfma_f32_16x16x32_bf16 v[66:69], v[180:183], v[212:215], v[66:69]
	s_setprio 2
	s_barrier
; #define PG8_STAGE(bufoff, gbase, voff) do { _Pragma("unroll") for (int _i = 0; _i < 2; ++_i) \
;         __builtin_amdgcn_global_load_lds((const unsigned*)((const char*)(gbase) + (voff)[_i]), (LAS unsigned*)(lds + (bufoff) + ldsw + _i * 8192), 16, 0, 0); } while (0)
; #define PG8_LDA(dst, b, h) do { _Pragma("unroll") for (int m = 0; m < 4; ++m) _Pragma("unroll") for (int k = 0; k < 2; ++k) dst[m][k] = *(const LAS bf16x8*)(lds + PG8_SA(b, h) + aoff + m * 2048 + k * 1024); } while (0)
; #define PG8_MMA(ai, bj, At, Bt) do { __builtin_amdgcn_s_setprio(1); _Pragma("unroll") for (int m = 0; m < 4; ++m) _Pragma("unroll") for (int n = 0; n < 2; ++n) _Pragma("unroll") for (int k = 0; k < 2; ++k) \
;         acc[ai][bj][m][n] = __builtin_amdgcn_mfma_f32_16x16x32_bf16(Bt[n][k], At[m][k], acc[ai][bj][m][n], 0, 0, 0); __builtin_amdgcn_s_setprio(0); } while (0)
; #define PG8_WAIT_V(n) asm volatile("s_waitcnt vmcnt(" #n ")" ::: "memory")
; #define PG8_WAIT_L(n) asm volatile("s_waitcnt lgkmcnt(" #n ")" ::: "memory")
; #define PG8_BAR __builtin_amdgcn_s_barrier()
; #define PG8_SCHED __builtin_amdgcn_sched_barrier(0)
; template <class Epi>
; __device__ __forceinline__ void gemm_phase(LAS unsigned char* lds, const Gemm g, int G, int c, const Epi& E) {
;     ...
;             PG8_LDA(At, 1, 1); PG8_STAGE(PG8_SB(1, 0), b3, voffB); PG8_STAGE(PG8_SB(1, 1), b3 + hstepB, voffB); PG8_STAGE(PG8_SA(1, 0), a3, voffA);
;             PG8_WAIT_V(8); PG8_WAIT_L(0); PG8_BAR; PG8_MMA(1, 0, At, B0); PG8_MMA(1, 1, At, B1); PG8_BAR; PG8_SCHED;
;         }
;         if (wr == 0) PG8_BAR;
	s_add_i32 s16, s33, s36
	v_lshl_add_u64 v[216:217], v[216:217], 0, s[10:11]
	s_mov_b32 m0, s16
	ds_read_b128 v[184:187], v170 offset:49152
	ds_read_b128 v[188:191], v170 offset:50176
	ds_read_b128 v[192:195], v170 offset:51200
	ds_read_b128 v[196:199], v170 offset:52224
	ds_read_b128 v[200:203], v170 offset:53248
	ds_read_b128 v[204:207], v170 offset:54272
	ds_read_b128 v[208:211], v170 offset:55296
	ds_read_b128 v[212:215], v170 offset:56320
	global_load_lds_dwordx4 v[216:217], off
	s_add_i32 m0, s16, 0x2000
	s_add_u32 s16, s20, 0xb0080
	v_lshl_add_u64 v[216:217], v[218:219], 0, s[10:11]
	s_addc_u32 s17, s21, 0
	s_add_i32 s20, s62, s36
	global_load_lds_dwordx4 v[216:217], off
	v_lshl_add_u64 v[216:217], s[16:17], 0, v[150:151]
	s_mov_b32 m0, s20
	s_nop 0
	global_load_lds_dwordx4 v[216:217], off
	v_lshl_add_u64 v[216:217], s[16:17], 0, v[146:147]
	s_add_i32 m0, s20, 0x2000
	s_nop 0
	global_load_lds_dwordx4 v[216:217], off
	v_lshl_add_u64 v[216:217], v[220:221], 0, s[10:11]
	s_mov_b32 m0, s47
	s_nop 0
	global_load_lds_dwordx4 v[216:217], off
	v_lshl_add_u64 v[216:217], v[222:223], 0, s[10:11]
	s_mov_b32 m0, s52
	s_nop 0
	global_load_lds_dwordx4 v[216:217], off
	s_waitcnt vmcnt(8)
	s_waitcnt lgkmcnt(0)
	s_barrier
	s_setprio 0
	s_waitcnt lgkmcnt(0)
	v_mfma_f32_16x16x32_bf16 v[62:65], v[122:125], v[184:187], v[62:65]
	v_mfma_f32_16x16x32_bf16 v[58:61], v[130:133], v[184:187], v[58:61]
	v_mfma_f32_16x16x32_bf16 v[54:57], v[122:125], v[192:195], v[54:57]
	v_mfma_f32_16x16x32_bf16 v[42:45], v[130:133], v[192:195], v[42:45]
	v_mfma_f32_16x16x32_bf16 v[38:41], v[122:125], v[200:203], v[38:41]
	v_mfma_f32_16x16x32_bf16 v[26:29], v[130:133], v[200:203], v[26:29]
	v_mfma_f32_16x16x32_bf16 v[22:25], v[122:125], v[208:211], v[22:25]
	v_mfma_f32_16x16x32_bf16 v[10:13], v[130:133], v[208:211], v[10:13]
	v_mfma_f32_16x16x32_bf16 v[62:65], v[126:129], v[188:191], v[62:65]
	v_mfma_f32_16x16x32_bf16 v[58:61], v[134:137], v[188:191], v[58:61]
	v_mfma_f32_16x16x32_bf16 v[54:57], v[126:129], v[196:199], v[54:57]
	v_mfma_f32_16x16x32_bf16 v[42:45], v[134:137], v[196:199], v[42:45]
	v_mfma_f32_16x16x32_bf16 v[38:41], v[126:129], v[204:207], v[38:41]
	v_mfma_f32_16x16x32_bf16 v[26:29], v[134:137], v[204:207], v[26:29]
	v_mfma_f32_16x16x32_bf16 v[22:25], v[126:129], v[212:215], v[22:25]
	v_mfma_f32_16x16x32_bf16 v[10:13], v[134:137], v[212:215], v[10:13]
	s_setprio 2
	s_setprio 0
	v_mfma_f32_16x16x32_bf16 v[50:53], v[162:165], v[184:187], v[50:53]
	v_mfma_f32_16x16x32_bf16 v[46:49], v[176:179], v[184:187], v[46:49]
	v_mfma_f32_16x16x32_bf16 v[34:37], v[162:165], v[192:195], v[34:37]
	v_mfma_f32_16x16x32_bf16 v[30:33], v[176:179], v[192:195], v[30:33]
	v_mfma_f32_16x16x32_bf16 v[18:21], v[162:165], v[200:203], v[18:21]
	v_mfma_f32_16x16x32_bf16 v[14:17], v[176:179], v[200:203], v[14:17]
	v_mfma_f32_16x16x32_bf16 v[6:9], v[162:165], v[208:211], v[6:9]
	v_mfma_f32_16x16x32_bf16 v[2:5], v[176:179], v[208:211], v[2:5]
	v_mfma_f32_16x16x32_bf16 v[50:53], v[172:175], v[188:191], v[50:53]
	v_mfma_f32_16x16x32_bf16 v[46:49], v[180:183], v[188:191], v[46:49]
	v_mfma_f32_16x16x32_bf16 v[34:37], v[172:175], v[196:199], v[34:37]
	v_mfma_f32_16x16x32_bf16 v[30:33], v[180:183], v[196:199], v[30:33]
	v_mfma_f32_16x16x32_bf16 v[18:21], v[172:175], v[204:207], v[18:21]
	v_mfma_f32_16x16x32_bf16 v[14:17], v[180:183], v[204:207], v[14:17]
	v_mfma_f32_16x16x32_bf16 v[6:9], v[172:175], v[212:215], v[6:9]
	v_mfma_f32_16x16x32_bf16 v[2:5], v[180:183], v[212:215], v[2:5]
	s_setprio 2
	s_barrier
	s_add_i32 s68, s68, 2
	s_add_u32 s66, s66, 0x100
	s_addc_u32 s67, s67, 0
	s_cmp_gt_u32 s68, 41
	s_mov_b64 s[16:17], s[18:19]
	s_cbranch_scc0 .LBB0_1143
	s_and_b64 vcc, exec, s[12:13]
	s_cbranch_vccz .LBB0_1146
	s_barrier

; #define PG8_STAGE(bufoff, gbase, voff) do { _Pragma("unroll") for (int _i = 0; _i < 2; ++_i) \
;         __builtin_amdgcn_global_load_lds((const unsigned*)((const char*)(gbase) + (voff)[_i]), (LAS unsigned*)(lds + (bufoff) + ldsw + _i * 8192), 16, 0, 0); } while (0)
; #define PG8_LDA(dst, b, h) do { _Pragma("unroll") for (int m = 0; m < 4; ++m) _Pragma("unroll") for (int k = 0; k < 2; ++k) dst[m][k] = *(const LAS bf16x8*)(lds + PG8_SA(b, h) + aoff + m * 2048 + k * 1024); } while (0)
; #define PG8_LDB(dst, b, h) do { _Pragma("unroll") for (int n = 0; n < 2; ++n) _Pragma("unroll") for (int k = 0; k < 2; ++k) dst[n][k] = *(const LAS bf16x8*)(lds + PG8_SB(b, h) + boff + n * 2048 + k * 1024); } while (0)
; #define PG8_MMA(ai, bj, At, Bt) do { __builtin_amdgcn_s_setprio(1); _Pragma("unroll") for (int m = 0; m < 4; ++m) _Pragma("unroll") for (int n = 0; n < 2; ++n) _Pragma("unroll") for (int k = 0; k < 2; ++k) \
;         acc[ai][bj][m][n] = __builtin_amdgcn_mfma_f32_16x16x32_bf16(Bt[n][k], At[m][k], acc[ai][bj][m][n], 0, 0, 0); __builtin_amdgcn_s_setprio(0); } while (0)
; #define PG8_WAIT_V(n) asm volatile("s_waitcnt vmcnt(" #n ")" ::: "memory")
; #define PG8_WAIT_L(n) asm volatile("s_waitcnt lgkmcnt(" #n ")" ::: "memory")
; #define PG8_BAR __builtin_amdgcn_s_barrier()
; #define PG8_SCHED __builtin_amdgcn_sched_barrier(0)
; template <class Epi>
; __device__ __forceinline__ void gemm_phase(LAS unsigned char* lds, const Gemm g, int G, int c, const Epi& E) {
;     ...
;             const bool last = (t == nt - 2);
;             const char* a1 = cA + (size_t)(t + 1) * kstep;
;             const char* a2 = last ? nA : cA + (size_t)(t + 2) * kstep; const char* b2 = last ? nB : cB + (size_t)(t + 2) * kstep;
;             const char* a3 = a2 + kstep; const char* b3 = b2 + kstep;
;             PG8_LDB(B0, 0, 0); PG8_LDB(B1, 0, 1); PG8_SCHED; PG8_LDA(At, 0, 0); PG8_STAGE(PG8_SA(1, 1), a1 + hstepA, voffA);
;             PG8_WAIT_V(8); PG8_WAIT_L(0); PG8_BAR; PG8_MMA(0, 0, At, B0); PG8_MMA(0, 1, At, B1); PG8_BAR; PG8_SCHED;
;             PG8_LDA(At, 0, 1); PG8_STAGE(PG8_SB(0, 0), b2, voffB); PG8_STAGE(PG8_SB(0, 1), b2 + hstepB, voffB); PG8_STAGE(PG8_SA(0, 0), a2, voffA);
;             PG8_WAIT_V(8); PG8_WAIT_L(0); PG8_BAR; PG8_MMA(1, 0, At, B0); PG8_MMA(1, 1, At, B1); PG8_BAR; PG8_SCHED;
.LBB0_1297:
	ds_read_b128 v[146:149], v152
	ds_read_b128 v[158:161], v152 offset:1024
	ds_read_b128 v[162:165], v152 offset:2048
	ds_read_b128 v[166:169], v152 offset:3072
	ds_read_b128 v[170:173], v153
	ds_read_b128 v[174:177], v153 offset:1024
	ds_read_b128 v[178:181], v153 offset:2048
	ds_read_b128 v[182:185], v153 offset:3072
	s_add_u32 s33, s4, 0xfffc0080
	s_addc_u32 s46, s5, -1
	s_cmp_eq_u32 s81, 12
	s_cselect_b32 s49, s43, s46
	s_cselect_b32 s48, s42, s33
	s_cselect_b32 s47, s7, s80
	s_cselect_b32 s46, s39, s41
	v_lshl_add_u64 v[218:219], s[4:5], 0, v[138:139]
	s_add_i32 m0, s11, 0xc000
	ds_read_b128 v[186:189], v154
	ds_read_b128 v[190:193], v154 offset:1024
	ds_read_b128 v[194:197], v154 offset:2048
	ds_read_b128 v[198:201], v154 offset:3072
	ds_read_b128 v[202:205], v154 offset:4096
	ds_read_b128 v[206:209], v154 offset:5120
	ds_read_b128 v[210:213], v154 offset:6144
	ds_read_b128 v[214:217], v154 offset:7168
	global_load_lds_dwordx4 v[218:219], off
	v_lshl_add_u64 v[218:219], s[4:5], 0, v[140:141]
	s_add_i32 m0, s11, 0xe000
	s_nop 0
	global_load_lds_dwordx4 v[218:219], off
	s_waitcnt vmcnt(8)
	s_waitcnt lgkmcnt(0)
	s_barrier
	s_setprio 0
	s_waitcnt lgkmcnt(0)
	v_mfma_f32_16x16x32_bf16 v[126:129], v[146:149], v[186:189], v[126:129]
	v_mfma_f32_16x16x32_bf16 v[122:125], v[162:165], v[186:189], v[122:125]
	v_mfma_f32_16x16x32_bf16 v[110:113], v[146:149], v[194:197], v[110:113]
	v_mfma_f32_16x16x32_bf16 v[106:109], v[162:165], v[194:197], v[106:109]
	v_mfma_f32_16x16x32_bf16 v[94:97], v[146:149], v[202:205], v[94:97]
	v_mfma_f32_16x16x32_bf16 v[90:93], v[162:165], v[202:205], v[90:93]
	v_mfma_f32_16x16x32_bf16 v[78:81], v[146:149], v[210:213], v[78:81]
	v_mfma_f32_16x16x32_bf16 v[74:77], v[162:165], v[210:213], v[74:77]
	v_mfma_f32_16x16x32_bf16 v[126:129], v[158:161], v[190:193], v[126:129]
	v_mfma_f32_16x16x32_bf16 v[122:125], v[166:169], v[190:193], v[122:125]
	v_mfma_f32_16x16x32_bf16 v[110:113], v[158:161], v[198:201], v[110:113]
	v_mfma_f32_16x16x32_bf16 v[106:109], v[166:169], v[198:201], v[106:109]
	v_mfma_f32_16x16x32_bf16 v[94:97], v[158:161], v[206:209], v[94:97]
	v_mfma_f32_16x16x32_bf16 v[90:93], v[166:169], v[206:209], v[90:93]
	v_mfma_f32_16x16x32_bf16 v[78:81], v[158:161], v[214:217], v[78:81]
	v_mfma_f32_16x16x32_bf16 v[74:77], v[166:169], v[214:217], v[74:77]
	s_setprio 2
	s_setprio 0
	v_mfma_f32_16x16x32_bf16 v[118:121], v[170:173], v[186:189], v[118:121]
	v_mfma_f32_16x16x32_bf16 v[114:117], v[178:181], v[186:189], v[114:117]
	v_mfma_f32_16x16x32_bf16 v[102:105], v[170:173], v[194:197], v[102:105]
	v_mfma_f32_16x16x32_bf16 v[98:101], v[178:181], v[194:197], v[98:101]
	v_mfma_f32_16x16x32_bf16 v[86:89], v[170:173], v[202:205], v[86:89]
	v_mfma_f32_16x16x32_bf16 v[82:85], v[178:181], v[202:205], v[82:85]
	v_mfma_f32_16x16x32_bf16 v[70:73], v[170:173], v[210:213], v[70:73]
	v_mfma_f32_16x16x32_bf16 v[66:69], v[178:181], v[210:213], v[66:69]
	v_mfma_f32_16x16x32_bf16 v[118:121], v[174:177], v[190:193], v[118:121]
	v_mfma_f32_16x16x32_bf16 v[114:117], v[182:185], v[190:193], v[114:117]
	v_mfma_f32_16x16x32_bf16 v[102:105], v[174:177], v[198:201], v[102:105]
	v_mfma_f32_16x16x32_bf16 v[98:101], v[182:185], v[198:201], v[98:101]
	v_mfma_f32_16x16x32_bf16 v[86:89], v[174:177], v[206:209], v[86:89]
	v_mfma_f32_16x16x32_bf16 v[82:85], v[182:185], v[206:209], v[82:85]
	v_mfma_f32_16x16x32_bf16 v[70:73], v[174:177], v[214:217], v[70:73]
	v_mfma_f32_16x16x32_bf16 v[66:69], v[182:185], v[214:217], v[66:69]
	s_setprio 2
	s_barrier
	s_add_i32 s33, s71, s56
	v_lshl_add_u64 v[218:219], s[46:47], 0, v[132:133]
	s_mov_b32 m0, s33
	ds_read_b128 v[186:189], v154 offset:16384
	ds_read_b128 v[190:193], v154 offset:17408
	ds_read_b128 v[194:197], v154 offset:18432
	ds_read_b128 v[198:201], v154 offset:19456
	ds_read_b128 v[202:205], v154 offset:20480
	ds_read_b128 v[206:209], v154 offset:21504
	ds_read_b128 v[210:213], v154 offset:22528
	ds_read_b128 v[214:217], v154 offset:23552
	global_load_lds_dwordx4 v[218:219], off
	s_add_i32 m0, s33, 0x2000
	s_add_u32 s62, s46, 0x40000
	v_lshl_add_u64 v[220:221], s[46:47], 0, v[136:137]
	s_addc_u32 s63, s47, 0
	s_add_i32 s33, s72, s56
	global_load_lds_dwordx4 v[220:221], off
	v_lshl_add_u64 v[222:223], s[62:63], 0, v[132:133]
	s_mov_b32 m0, s33
	v_lshl_add_u64 v[224:225], s[48:49], 0, v[134:135]
	global_load_lds_dwordx4 v[222:223], off
	v_lshl_add_u64 v[222:223], s[62:63], 0, v[136:137]
	s_add_i32 m0, s33, 0x2000
	s_nop 0
	global_load_lds_dwordx4 v[222:223], off
	v_lshl_add_u64 v[222:223], s[48:49], 0, v[130:131]
	s_mov_b32 m0, s11
	s_nop 0
	global_load_lds_dwordx4 v[222:223], off
	s_mov_b32 m0, s57
	s_nop 0
	global_load_lds_dwordx4 v[224:225], off
	s_waitcnt vmcnt(8)
	s_waitcnt lgkmcnt(0)
	s_barrier
; #define PG8_STAGE(bufoff, gbase, voff) do { _Pragma("unroll") for (int _i = 0; _i < 2; ++_i) \
;         __builtin_amdgcn_global_load_lds((const unsigned*)((const char*)(gbase) + (voff)[_i]), (LAS unsigned*)(lds + (bufoff) + ldsw + _i * 8192), 16, 0, 0); } while (0)
; #define PG8_LDA(dst, b, h) do { _Pragma("unroll") for (int m = 0; m < 4; ++m) _Pragma("unroll") for (int k = 0; k < 2; ++k) dst[m][k] = *(const LAS bf16x8*)(lds + PG8_SA(b, h) + aoff + m * 2048 + k * 1024); } while (0)
; #define PG8_LDB(dst, b, h) do { _Pragma("unroll") for (int n = 0; n < 2; ++n) _Pragma("unroll") for (int k = 0; k < 2; ++k) dst[n][k] = *(const LAS bf16x8*)(lds + PG8_SB(b, h) + boff + n * 2048 + k * 1024); } while (0)
; #define PG8_MMA(ai, bj, At, Bt) do { __builtin_amdgcn_s_setprio(1); _Pragma("unroll") for (int m = 0; m < 4; ++m) _Pragma("unroll") for (int n = 0; n < 2; ++n) _Pragma("unroll") for (int k = 0; k < 2; ++k) \
;         acc[ai][bj][m][n] = __builtin_amdgcn_mfma_f32_16x16x32_bf16(Bt[n][k], At[m][k], acc[ai][bj][m][n], 0, 0, 0); __builtin_amdgcn_s_setprio(0); } while (0)
; #define PG8_WAIT_V(n) asm volatile("s_waitcnt vmcnt(" #n ")" ::: "memory")
; #define PG8_WAIT_L(n) asm volatile("s_waitcnt lgkmcnt(" #n ")" ::: "memory")
; #define PG8_BAR __builtin_amdgcn_s_barrier()
; #define PG8_SCHED __builtin_amdgcn_sched_barrier(0)
; template <class Epi>
; __device__ __forceinline__ void gemm_phase(LAS unsigned char* lds, const Gemm g, int G, int c, const Epi& E) {
;     ...
;             PG8_WAIT_V(8); PG8_WAIT_L(0); PG8_BAR; PG8_MMA(1, 0, At, B0); PG8_MMA(1, 1, At, B1); PG8_BAR; PG8_SCHED;
;             PG8_LDB(B0, 1, 0); PG8_LDB(B1, 1, 1); PG8_SCHED; PG8_LDA(At, 1, 0); PG8_STAGE(PG8_SA(0, 1), a2 + hstepA, voffA);
;             PG8_WAIT_V(8); PG8_WAIT_L(0); PG8_BAR; PG8_MMA(0, 0, At, B0); PG8_MMA(0, 1, At, B1); PG8_BAR; PG8_SCHED;
	s_setprio 0
	s_waitcnt lgkmcnt(0)
	v_mfma_f32_16x16x32_bf16 v[62:65], v[146:149], v[186:189], v[62:65]
	v_mfma_f32_16x16x32_bf16 v[58:61], v[162:165], v[186:189], v[58:61]
	v_mfma_f32_16x16x32_bf16 v[46:49], v[146:149], v[194:197], v[46:49]
	v_mfma_f32_16x16x32_bf16 v[42:45], v[162:165], v[194:197], v[42:45]
	v_mfma_f32_16x16x32_bf16 v[30:33], v[146:149], v[202:205], v[30:33]
	v_mfma_f32_16x16x32_bf16 v[26:29], v[162:165], v[202:205], v[26:29]
	v_mfma_f32_16x16x32_bf16 v[14:17], v[146:149], v[210:213], v[14:17]
	v_mfma_f32_16x16x32_bf16 v[10:13], v[162:165], v[210:213], v[10:13]
	v_mfma_f32_16x16x32_bf16 v[62:65], v[158:161], v[190:193], v[62:65]
	v_mfma_f32_16x16x32_bf16 v[58:61], v[166:169], v[190:193], v[58:61]
	v_mfma_f32_16x16x32_bf16 v[46:49], v[158:161], v[198:201], v[46:49]
	v_mfma_f32_16x16x32_bf16 v[42:45], v[166:169], v[198:201], v[42:45]
	v_mfma_f32_16x16x32_bf16 v[30:33], v[158:161], v[206:209], v[30:33]
	v_mfma_f32_16x16x32_bf16 v[26:29], v[166:169], v[206:209], v[26:29]
	v_mfma_f32_16x16x32_bf16 v[14:17], v[158:161], v[214:217], v[14:17]
	v_mfma_f32_16x16x32_bf16 v[10:13], v[166:169], v[214:217], v[10:13]
	s_setprio 2
	s_setprio 0
	v_mfma_f32_16x16x32_bf16 v[54:57], v[170:173], v[186:189], v[54:57]
	v_mfma_f32_16x16x32_bf16 v[50:53], v[178:181], v[186:189], v[50:53]
	v_mfma_f32_16x16x32_bf16 v[38:41], v[170:173], v[194:197], v[38:41]
	v_mfma_f32_16x16x32_bf16 v[34:37], v[178:181], v[194:197], v[34:37]
	v_mfma_f32_16x16x32_bf16 v[22:25], v[170:173], v[202:205], v[22:25]
	v_mfma_f32_16x16x32_bf16 v[18:21], v[178:181], v[202:205], v[18:21]
	v_mfma_f32_16x16x32_bf16 v[6:9], v[170:173], v[210:213], v[6:9]
	v_mfma_f32_16x16x32_bf16 v[2:5], v[178:181], v[210:213], v[2:5]
	v_mfma_f32_16x16x32_bf16 v[54:57], v[174:177], v[190:193], v[54:57]
	v_mfma_f32_16x16x32_bf16 v[50:53], v[182:185], v[190:193], v[50:53]
	v_mfma_f32_16x16x32_bf16 v[38:41], v[174:177], v[198:201], v[38:41]
	v_mfma_f32_16x16x32_bf16 v[34:37], v[182:185], v[198:201], v[34:37]
	v_mfma_f32_16x16x32_bf16 v[22:25], v[174:177], v[206:209], v[22:25]
	v_mfma_f32_16x16x32_bf16 v[18:21], v[182:185], v[206:209], v[18:21]
	v_mfma_f32_16x16x32_bf16 v[6:9], v[174:177], v[214:217], v[6:9]
	v_mfma_f32_16x16x32_bf16 v[2:5], v[182:185], v[214:217], v[2:5]
	s_setprio 2
	s_barrier
	s_add_i32 s33, 0, 0x18000
	v_add_u32_e32 v157, s33, v151
	s_add_i32 s62, 0, 0x1c000
	ds_read_b128 v[146:149], v157
	ds_read_b128 v[158:161], v157 offset:1024
	ds_read_b128 v[162:165], v157 offset:2048
	ds_read_b128 v[166:169], v157 offset:3072
	v_add_u32_e32 v157, s62, v151
	ds_read_b128 v[170:173], v157
	ds_read_b128 v[174:177], v157 offset:1024
	ds_read_b128 v[178:181], v157 offset:2048
	ds_read_b128 v[182:185], v157 offset:3072
	s_add_u32 s48, s48, 0x40000
	s_addc_u32 s49, s49, 0
	s_mov_b32 m0, s58
	v_lshl_add_u64 v[226:227], s[48:49], 0, v[130:131]
	ds_read_b128 v[186:189], v154 offset:32768
	ds_read_b128 v[190:193], v154 offset:33792
	ds_read_b128 v[194:197], v154 offset:34816
	ds_read_b128 v[198:201], v154 offset:35840
	ds_read_b128 v[202:205], v154 offset:36864
	ds_read_b128 v[206:209], v154 offset:37888
	ds_read_b128 v[210:213], v154 offset:38912
	ds_read_b128 v[214:217], v154 offset:39936
	global_load_lds_dwordx4 v[226:227], off
	v_lshl_add_u64 v[226:227], s[48:49], 0, v[134:135]
	s_mov_b32 m0, s59
	s_nop 0
	global_load_lds_dwordx4 v[226:227], off
	s_waitcnt vmcnt(8)
	s_waitcnt lgkmcnt(0)
	s_barrier
	s_setprio 0
	s_waitcnt lgkmcnt(0)
	v_mfma_f32_16x16x32_bf16 v[126:129], v[146:149], v[186:189], v[126:129]
	v_mfma_f32_16x16x32_bf16 v[122:125], v[162:165], v[186:189], v[122:125]
	v_mfma_f32_16x16x32_bf16 v[110:113], v[146:149], v[194:197], v[110:113]
	v_mfma_f32_16x16x32_bf16 v[106:109], v[162:165], v[194:197], v[106:109]
	v_mfma_f32_16x16x32_bf16 v[94:97], v[146:149], v[202:205], v[94:97]
	v_mfma_f32_16x16x32_bf16 v[90:93], v[162:165], v[202:205], v[90:93]
	v_mfma_f32_16x16x32_bf16 v[78:81], v[146:149], v[210:213], v[78:81]
	v_mfma_f32_16x16x32_bf16 v[74:77], v[162:165], v[210:213], v[74:77]
	v_mfma_f32_16x16x32_bf16 v[126:129], v[158:161], v[190:193], v[126:129]
	v_mfma_f32_16x16x32_bf16 v[122:125], v[166:169], v[190:193], v[122:125]
	v_mfma_f32_16x16x32_bf16 v[110:113], v[158:161], v[198:201], v[110:113]
	v_mfma_f32_16x16x32_bf16 v[106:109], v[166:169], v[198:201], v[106:109]
	v_mfma_f32_16x16x32_bf16 v[94:97], v[158:161], v[206:209], v[94:97]
	v_mfma_f32_16x16x32_bf16 v[90:93], v[166:169], v[206:209], v[90:93]
	v_mfma_f32_16x16x32_bf16 v[78:81], v[158:161], v[214:217], v[78:81]
	v_mfma_f32_16x16x32_bf16 v[74:77], v[166:169], v[214:217], v[74:77]
	s_setprio 2
	s_setprio 0
	v_mfma_f32_16x16x32_bf16 v[118:121], v[170:173], v[186:189], v[118:121]
	v_mfma_f32_16x16x32_bf16 v[114:117], v[178:181], v[186:189], v[114:117]
	v_mfma_f32_16x16x32_bf16 v[102:105], v[170:173], v[194:197], v[102:105]
	v_mfma_f32_16x16x32_bf16 v[98:101], v[178:181], v[194:197], v[98:101]
	v_mfma_f32_16x16x32_bf16 v[86:89], v[170:173], v[202:205], v[86:89]
	v_mfma_f32_16x16x32_bf16 v[82:85], v[178:181], v[202:205], v[82:85]
	v_mfma_f32_16x16x32_bf16 v[70:73], v[170:173], v[210:213], v[70:73]
	v_mfma_f32_16x16x32_bf16 v[66:69], v[178:181], v[210:213], v[66:69]
	v_mfma_f32_16x16x32_bf16 v[118:121], v[174:177], v[190:193], v[118:121]
	v_mfma_f32_16x16x32_bf16 v[114:117], v[182:185], v[190:193], v[114:117]
	v_mfma_f32_16x16x32_bf16 v[102:105], v[174:177], v[198:201], v[102:105]
	v_mfma_f32_16x16x32_bf16 v[98:101], v[182:185], v[198:201], v[98:101]
	v_mfma_f32_16x16x32_bf16 v[86:89], v[174:177], v[206:209], v[86:89]
	v_mfma_f32_16x16x32_bf16 v[82:85], v[182:185], v[206:209], v[82:85]
	v_mfma_f32_16x16x32_bf16 v[70:73], v[174:177], v[214:217], v[70:73]
	v_mfma_f32_16x16x32_bf16 v[66:69], v[182:185], v[214:217], v[66:69]
	s_setprio 2
	s_barrier
; #define PG8_STAGE(bufoff, gbase, voff) do { _Pragma("unroll") for (int _i = 0; _i < 2; ++_i) \
;         __builtin_amdgcn_global_load_lds((const unsigned*)((const char*)(gbase) + (voff)[_i]), (LAS unsigned*)(lds + (bufoff) + ldsw + _i * 8192), 16, 0, 0); } while (0)
; #define PG8_LDA(dst, b, h) do { _Pragma("unroll") for (int m = 0; m < 4; ++m) _Pragma("unroll") for (int k = 0; k < 2; ++k) dst[m][k] = *(const LAS bf16x8*)(lds + PG8_SA(b, h) + aoff + m * 2048 + k * 1024); } while (0)
; #define PG8_MMA(ai, bj, At, Bt) do { __builtin_amdgcn_s_setprio(1); _Pragma("unroll") for (int m = 0; m < 4; ++m) _Pragma("unroll") for (int n = 0; n < 2; ++n) _Pragma("unroll") for (int k = 0; k < 2; ++k) \
;         acc[ai][bj][m][n] = __builtin_amdgcn_mfma_f32_16x16x32_bf16(Bt[n][k], At[m][k], acc[ai][bj][m][n], 0, 0, 0); __builtin_amdgcn_s_setprio(0); } while (0)
; #define PG8_WAIT_V(n) asm volatile("s_waitcnt vmcnt(" #n ")" ::: "memory")
; #define PG8_WAIT_L(n) asm volatile("s_waitcnt lgkmcnt(" #n ")" ::: "memory")
; #define PG8_BAR __builtin_amdgcn_s_barrier()
; #define PG8_SCHED __builtin_amdgcn_sched_barrier(0)
; template <class Epi>
; __device__ __forceinline__ void gemm_phase(LAS unsigned char* lds, const Gemm g, int G, int c, const Epi& E) {
;     ...
;             PG8_LDA(At, 1, 1); PG8_STAGE(PG8_SB(1, 0), b3, voffB); PG8_STAGE(PG8_SB(1, 1), b3 + hstepB, voffB); PG8_STAGE(PG8_SA(1, 0), a3, voffA);
;             PG8_WAIT_V(8); PG8_WAIT_L(0); PG8_BAR; PG8_MMA(1, 0, At, B0); PG8_MMA(1, 1, At, B1); PG8_BAR; PG8_SCHED;
;         }
;         if (wr == 0) PG8_BAR;
	s_add_i32 s33, s33, s56
	v_lshl_add_u64 v[218:219], v[218:219], 0, s[20:21]
	s_mov_b32 m0, s33
	ds_read_b128 v[186:189], v154 offset:49152
	ds_read_b128 v[190:193], v154 offset:50176
	ds_read_b128 v[194:197], v154 offset:51200
	ds_read_b128 v[198:201], v154 offset:52224
	ds_read_b128 v[202:205], v154 offset:53248
	ds_read_b128 v[206:209], v154 offset:54272
	ds_read_b128 v[210:213], v154 offset:55296
	ds_read_b128 v[214:217], v154 offset:56320
	global_load_lds_dwordx4 v[218:219], off
	s_add_i32 m0, s33, 0x2000
	s_add_u32 s46, s46, 0x40080
	v_lshl_add_u64 v[218:219], v[220:221], 0, s[20:21]
	s_addc_u32 s47, s47, 0
	s_add_i32 s33, s62, s56
	global_load_lds_dwordx4 v[218:219], off
	v_lshl_add_u64 v[218:219], s[46:47], 0, v[132:133]
	s_mov_b32 m0, s33
	s_nop 0
	global_load_lds_dwordx4 v[218:219], off
	v_lshl_add_u64 v[218:219], s[46:47], 0, v[136:137]
	s_add_i32 m0, s33, 0x2000
	s_nop 0
	global_load_lds_dwordx4 v[218:219], off
	v_lshl_add_u64 v[218:219], v[222:223], 0, s[20:21]
	s_mov_b32 m0, s67
	s_nop 0
	global_load_lds_dwordx4 v[218:219], off
	v_lshl_add_u64 v[218:219], v[224:225], 0, s[20:21]
	s_mov_b32 m0, s68
	s_nop 0
	global_load_lds_dwordx4 v[218:219], off
	s_waitcnt vmcnt(8)
	s_waitcnt lgkmcnt(0)
	s_barrier
	s_setprio 0
	s_waitcnt lgkmcnt(0)
	v_mfma_f32_16x16x32_bf16 v[62:65], v[146:149], v[186:189], v[62:65]
	v_mfma_f32_16x16x32_bf16 v[58:61], v[162:165], v[186:189], v[58:61]
	v_mfma_f32_16x16x32_bf16 v[46:49], v[146:149], v[194:197], v[46:49]
	v_mfma_f32_16x16x32_bf16 v[42:45], v[162:165], v[194:197], v[42:45]
	v_mfma_f32_16x16x32_bf16 v[30:33], v[146:149], v[202:205], v[30:33]
	v_mfma_f32_16x16x32_bf16 v[26:29], v[162:165], v[202:205], v[26:29]
	v_mfma_f32_16x16x32_bf16 v[14:17], v[146:149], v[210:213], v[14:17]
	v_mfma_f32_16x16x32_bf16 v[10:13], v[162:165], v[210:213], v[10:13]
	v_mfma_f32_16x16x32_bf16 v[62:65], v[158:161], v[190:193], v[62:65]
	v_mfma_f32_16x16x32_bf16 v[58:61], v[166:169], v[190:193], v[58:61]
	v_mfma_f32_16x16x32_bf16 v[46:49], v[158:161], v[198:201], v[46:49]
	v_mfma_f32_16x16x32_bf16 v[42:45], v[166:169], v[198:201], v[42:45]
	v_mfma_f32_16x16x32_bf16 v[30:33], v[158:161], v[206:209], v[30:33]
	v_mfma_f32_16x16x32_bf16 v[26:29], v[166:169], v[206:209], v[26:29]
	v_mfma_f32_16x16x32_bf16 v[14:17], v[158:161], v[214:217], v[14:17]
	v_mfma_f32_16x16x32_bf16 v[10:13], v[166:169], v[214:217], v[10:13]
	s_setprio 2
	s_setprio 0
	v_mfma_f32_16x16x32_bf16 v[54:57], v[170:173], v[186:189], v[54:57]
	v_mfma_f32_16x16x32_bf16 v[50:53], v[178:181], v[186:189], v[50:53]
	v_mfma_f32_16x16x32_bf16 v[38:41], v[170:173], v[194:197], v[38:41]
	v_mfma_f32_16x16x32_bf16 v[34:37], v[178:181], v[194:197], v[34:37]
	v_mfma_f32_16x16x32_bf16 v[22:25], v[170:173], v[202:205], v[22:25]
	v_mfma_f32_16x16x32_bf16 v[18:21], v[178:181], v[202:205], v[18:21]
	v_mfma_f32_16x16x32_bf16 v[6:9], v[170:173], v[210:213], v[6:9]
	v_mfma_f32_16x16x32_bf16 v[2:5], v[178:181], v[210:213], v[2:5]
	v_mfma_f32_16x16x32_bf16 v[54:57], v[174:177], v[190:193], v[54:57]
	v_mfma_f32_16x16x32_bf16 v[50:53], v[182:185], v[190:193], v[50:53]
	v_mfma_f32_16x16x32_bf16 v[38:41], v[174:177], v[198:201], v[38:41]
	v_mfma_f32_16x16x32_bf16 v[34:37], v[182:185], v[198:201], v[34:37]
	v_mfma_f32_16x16x32_bf16 v[22:25], v[174:177], v[206:209], v[22:25]
	v_mfma_f32_16x16x32_bf16 v[18:21], v[182:185], v[206:209], v[18:21]
	v_mfma_f32_16x16x32_bf16 v[6:9], v[174:177], v[214:217], v[6:9]
	v_mfma_f32_16x16x32_bf16 v[2:5], v[182:185], v[214:217], v[2:5]
	s_setprio 2
	s_barrier
	s_add_i32 s81, s81, 2
	s_add_u32 s4, s4, 0x100
	s_addc_u32 s5, s5, 0
	s_add_u32 s41, s41, 0x100
	s_addc_u32 s80, s80, 0
	s_cmp_gt_u32 s81, 13
	s_cbranch_scc0 .LBB0_1297
	s_and_b64 vcc, exec, s[22:23]
	s_cbranch_vccz .LBB0_1300
	s_barrier

; #define PG8_STAGE(bufoff, gbase, voff) do { _Pragma("unroll") for (int _i = 0; _i < 2; ++_i) \
;         __builtin_amdgcn_global_load_lds((const unsigned*)((const char*)(gbase) + (voff)[_i]), (LAS unsigned*)(lds + (bufoff) + ldsw + _i * 8192), 16, 0, 0); } while (0)
; #define PG8_LDA(dst, b, h) do { _Pragma("unroll") for (int m = 0; m < 4; ++m) _Pragma("unroll") for (int k = 0; k < 2; ++k) dst[m][k] = *(const LAS bf16x8*)(lds + PG8_SA(b, h) + aoff + m * 2048 + k * 1024); } while (0)
; #define PG8_LDB(dst, b, h) do { _Pragma("unroll") for (int n = 0; n < 2; ++n) _Pragma("unroll") for (int k = 0; k < 2; ++k) dst[n][k] = *(const LAS bf16x8*)(lds + PG8_SB(b, h) + boff + n * 2048 + k * 1024); } while (0)
; #define PG8_MMA(ai, bj, At, Bt) do { __builtin_amdgcn_s_setprio(1); _Pragma("unroll") for (int m = 0; m < 4; ++m) _Pragma("unroll") for (int n = 0; n < 2; ++n) _Pragma("unroll") for (int k = 0; k < 2; ++k) \
;         acc[ai][bj][m][n] = __builtin_amdgcn_mfma_f32_16x16x32_bf16(Bt[n][k], At[m][k], acc[ai][bj][m][n], 0, 0, 0); __builtin_amdgcn_s_setprio(0); } while (0)
; #define PG8_WAIT_V(n) asm volatile("s_waitcnt vmcnt(" #n ")" ::: "memory")
; #define PG8_WAIT_L(n) asm volatile("s_waitcnt lgkmcnt(" #n ")" ::: "memory")
; #define PG8_BAR __builtin_amdgcn_s_barrier()
; #define PG8_SCHED __builtin_amdgcn_sched_barrier(0)
; template <class Epi>
; __device__ __forceinline__ void gemm_phase(LAS unsigned char* lds, const Gemm g, int G, int c, const Epi& E) {
;     ...
;         for (int t = 0; t < nt; t += 2) {
;             const bool last = (t == nt - 2);
;             const char* a1 = cA + (size_t)(t + 1) * kstep;
;             const char* a2 = last ? nA : cA + (size_t)(t + 2) * kstep; const char* b2 = last ? nB : cB + (size_t)(t + 2) * kstep;
;             const char* a3 = a2 + kstep; const char* b3 = b2 + kstep;
;             PG8_LDB(B0, 0, 0); PG8_LDB(B1, 0, 1); PG8_SCHED; PG8_LDA(At, 0, 0); PG8_STAGE(PG8_SA(1, 1), a1 + hstepA, voffA);
;             PG8_WAIT_V(8); PG8_WAIT_L(0); PG8_BAR; PG8_MMA(0, 0, At, B0); PG8_MMA(0, 1, At, B1); PG8_BAR; PG8_SCHED;
;             PG8_LDA(At, 0, 1); PG8_STAGE(PG8_SB(0, 0), b2, voffB); PG8_STAGE(PG8_SB(0, 1), b2 + hstepB, voffB); PG8_STAGE(PG8_SA(0, 0), a2, voffA);
.LBB0_1429:
	s_add_u32 s33, s18, s13
	s_addc_u32 s42, s19, 0
	s_add_u32 s38, s33, 0x100
	s_addc_u32 s39, s42, 0
	s_and_b64 s[24:25], s[22:23], exec
	s_cselect_b32 s39, s5, s39
	s_cselect_b32 s38, s4, s38
	s_add_u32 s13, s16, s13
	s_addc_u32 s24, s17, 0
	s_add_u32 s13, s13, 0x100
	s_addc_u32 s24, s24, 0
	s_and_b64 s[22:23], s[22:23], exec
	s_cselect_b32 s41, s15, s24
	s_cselect_b32 s40, s14, s13
	s_add_u32 s44, s33, 0xb0080
	ds_read_b128 v[142:145], v148
	ds_read_b128 v[152:155], v148 offset:1024
	ds_read_b128 v[156:159], v148 offset:2048
	ds_read_b128 v[160:163], v148 offset:3072
	ds_read_b128 v[164:167], v149
	ds_read_b128 v[168:171], v149 offset:1024
	ds_read_b128 v[172:175], v149 offset:2048
	ds_read_b128 v[176:179], v149 offset:3072
	s_addc_u32 s45, s42, 0
	s_add_i32 s65, s72, s48
	s_add_i32 m0, s49, 0xc000
	s_add_i32 s85, s49, 0xe000
	s_add_i32 s62, s65, 0x2000
	s_add_u32 s42, s40, 0xb0000
	s_addc_u32 s43, s41, 0
	s_add_i32 s64, s73, s48
	s_add_i32 s63, s64, 0x2000
	s_add_i32 s84, 0, 0x18000
	s_add_i32 s33, 0, 0x1c000
	s_add_u32 s24, s38, 0xb0000
	s_addc_u32 s25, s39, 0
	s_add_i32 s83, s84, s48
	s_add_i32 s13, s83, 0x2000
	s_add_u32 s22, s40, 0xb0080
	s_addc_u32 s23, s41, 0
	s_add_i32 s75, s33, s48
	s_add_i32 s74, s75, 0x2000
	v_lshl_add_u64 v[212:213], s[44:45], 0, v[136:137]
	ds_read_b128 v[180:183], v150
	ds_read_b128 v[184:187], v150 offset:1024
	ds_read_b128 v[188:191], v150 offset:2048
	ds_read_b128 v[192:195], v150 offset:3072
	ds_read_b128 v[196:199], v150 offset:4096
	ds_read_b128 v[200:203], v150 offset:5120
	ds_read_b128 v[204:207], v150 offset:6144
	ds_read_b128 v[208:211], v150 offset:7168
	global_load_lds_dwordx4 v[212:213], off
	v_lshl_add_u64 v[212:213], s[44:45], 0, v[132:133]
	s_mov_b32 m0, s85
	s_nop 0
	global_load_lds_dwordx4 v[212:213], off
	s_waitcnt vmcnt(8)
	s_waitcnt lgkmcnt(0)
	s_barrier
	s_setprio 0
	s_waitcnt lgkmcnt(0)
	v_mfma_f32_16x16x32_bf16 v[126:129], v[142:145], v[180:183], v[126:129]
	v_mfma_f32_16x16x32_bf16 v[122:125], v[156:159], v[180:183], v[122:125]
	v_mfma_f32_16x16x32_bf16 v[118:121], v[142:145], v[188:191], v[118:121]
	v_mfma_f32_16x16x32_bf16 v[110:113], v[156:159], v[188:191], v[110:113]
	v_mfma_f32_16x16x32_bf16 v[102:105], v[142:145], v[196:199], v[102:105]
	v_mfma_f32_16x16x32_bf16 v[94:97], v[156:159], v[196:199], v[94:97]
	v_mfma_f32_16x16x32_bf16 v[86:89], v[142:145], v[204:207], v[86:89]
	v_mfma_f32_16x16x32_bf16 v[78:81], v[156:159], v[204:207], v[78:81]
	v_mfma_f32_16x16x32_bf16 v[126:129], v[152:155], v[184:187], v[126:129]
	v_mfma_f32_16x16x32_bf16 v[122:125], v[160:163], v[184:187], v[122:125]
	v_mfma_f32_16x16x32_bf16 v[118:121], v[152:155], v[192:195], v[118:121]
	v_mfma_f32_16x16x32_bf16 v[110:113], v[160:163], v[192:195], v[110:113]
	v_mfma_f32_16x16x32_bf16 v[102:105], v[152:155], v[200:203], v[102:105]
	v_mfma_f32_16x16x32_bf16 v[94:97], v[160:163], v[200:203], v[94:97]
	v_mfma_f32_16x16x32_bf16 v[86:89], v[152:155], v[208:211], v[86:89]
	v_mfma_f32_16x16x32_bf16 v[78:81], v[160:163], v[208:211], v[78:81]
	s_setprio 2
	s_setprio 0
	v_mfma_f32_16x16x32_bf16 v[114:117], v[164:167], v[180:183], v[114:117]
	v_mfma_f32_16x16x32_bf16 v[106:109], v[172:175], v[180:183], v[106:109]
	v_mfma_f32_16x16x32_bf16 v[98:101], v[164:167], v[188:191], v[98:101]
	v_mfma_f32_16x16x32_bf16 v[90:93], v[172:175], v[188:191], v[90:93]
	v_mfma_f32_16x16x32_bf16 v[82:85], v[164:167], v[196:199], v[82:85]
	v_mfma_f32_16x16x32_bf16 v[74:77], v[172:175], v[196:199], v[74:77]
	v_mfma_f32_16x16x32_bf16 v[70:73], v[164:167], v[204:207], v[70:73]
	v_mfma_f32_16x16x32_bf16 v[66:69], v[172:175], v[204:207], v[66:69]
	v_mfma_f32_16x16x32_bf16 v[114:117], v[168:171], v[184:187], v[114:117]
	v_mfma_f32_16x16x32_bf16 v[106:109], v[176:179], v[184:187], v[106:109]
	v_mfma_f32_16x16x32_bf16 v[98:101], v[168:171], v[192:195], v[98:101]
	v_mfma_f32_16x16x32_bf16 v[90:93], v[176:179], v[192:195], v[90:93]
	v_mfma_f32_16x16x32_bf16 v[82:85], v[168:171], v[200:203], v[82:85]
	v_mfma_f32_16x16x32_bf16 v[74:77], v[176:179], v[200:203], v[74:77]
	v_mfma_f32_16x16x32_bf16 v[70:73], v[168:171], v[208:211], v[70:73]
	v_mfma_f32_16x16x32_bf16 v[66:69], v[176:179], v[208:211], v[66:69]
	s_setprio 2
	s_barrier
	s_mov_b32 m0, s65
	v_lshl_add_u64 v[212:213], s[40:41], 0, v[134:135]
	ds_read_b128 v[180:183], v150 offset:16384
	ds_read_b128 v[184:187], v150 offset:17408
	ds_read_b128 v[188:191], v150 offset:18432
	ds_read_b128 v[192:195], v150 offset:19456
	ds_read_b128 v[196:199], v150 offset:20480
	ds_read_b128 v[200:203], v150 offset:21504
	ds_read_b128 v[204:207], v150 offset:22528
	ds_read_b128 v[208:211], v150 offset:23552
	global_load_lds_dwordx4 v[212:213], off
	v_lshl_add_u64 v[214:215], s[40:41], 0, v[130:131]
	s_mov_b32 m0, s62
	v_lshl_add_u64 v[216:217], s[42:43], 0, v[134:135]
	global_load_lds_dwordx4 v[214:215], off
	s_mov_b32 m0, s64
	v_lshl_add_u64 v[218:219], s[38:39], 0, v[132:133]
	global_load_lds_dwordx4 v[216:217], off
	v_lshl_add_u64 v[216:217], s[42:43], 0, v[130:131]
	s_mov_b32 m0, s63
	s_nop 0
	global_load_lds_dwordx4 v[216:217], off
	v_lshl_add_u64 v[216:217], s[38:39], 0, v[136:137]
	s_mov_b32 m0, s49
	s_nop 0
	global_load_lds_dwordx4 v[216:217], off
	s_mov_b32 m0, s52
	s_nop 0
	global_load_lds_dwordx4 v[218:219], off
	s_waitcnt vmcnt(8)
	s_waitcnt lgkmcnt(0)
	s_barrier
; #define PG8_STAGE(bufoff, gbase, voff) do { _Pragma("unroll") for (int _i = 0; _i < 2; ++_i) \
;         __builtin_amdgcn_global_load_lds((const unsigned*)((const char*)(gbase) + (voff)[_i]), (LAS unsigned*)(lds + (bufoff) + ldsw + _i * 8192), 16, 0, 0); } while (0)
; #define PG8_LDA(dst, b, h) do { _Pragma("unroll") for (int m = 0; m < 4; ++m) _Pragma("unroll") for (int k = 0; k < 2; ++k) dst[m][k] = *(const LAS bf16x8*)(lds + PG8_SA(b, h) + aoff + m * 2048 + k * 1024); } while (0)
; #define PG8_LDB(dst, b, h) do { _Pragma("unroll") for (int n = 0; n < 2; ++n) _Pragma("unroll") for (int k = 0; k < 2; ++k) dst[n][k] = *(const LAS bf16x8*)(lds + PG8_SB(b, h) + boff + n * 2048 + k * 1024); } while (0)
; #define PG8_MMA(ai, bj, At, Bt) do { __builtin_amdgcn_s_setprio(1); _Pragma("unroll") for (int m = 0; m < 4; ++m) _Pragma("unroll") for (int n = 0; n < 2; ++n) _Pragma("unroll") for (int k = 0; k < 2; ++k) \
;         acc[ai][bj][m][n] = __builtin_amdgcn_mfma_f32_16x16x32_bf16(Bt[n][k], At[m][k], acc[ai][bj][m][n], 0, 0, 0); __builtin_amdgcn_s_setprio(0); } while (0)
; #define PG8_WAIT_V(n) asm volatile("s_waitcnt vmcnt(" #n ")" ::: "memory")
; #define PG8_WAIT_L(n) asm volatile("s_waitcnt lgkmcnt(" #n ")" ::: "memory")
; #define PG8_BAR __builtin_amdgcn_s_barrier()
; #define PG8_SCHED __builtin_amdgcn_sched_barrier(0)
; template <class Epi>
; __device__ __forceinline__ void gemm_phase(LAS unsigned char* lds, const Gemm g, int G, int c, const Epi& E) {
;     ...
;             PG8_WAIT_V(8); PG8_WAIT_L(0); PG8_BAR; PG8_MMA(1, 0, At, B0); PG8_MMA(1, 1, At, B1); PG8_BAR; PG8_SCHED;
;             PG8_LDB(B0, 1, 0); PG8_LDB(B1, 1, 1); PG8_SCHED; PG8_LDA(At, 1, 0); PG8_STAGE(PG8_SA(0, 1), a2 + hstepA, voffA);
;             PG8_WAIT_V(8); PG8_WAIT_L(0); PG8_BAR; PG8_MMA(0, 0, At, B0); PG8_MMA(0, 1, At, B1); PG8_BAR; PG8_SCHED;
	s_setprio 0
	s_waitcnt lgkmcnt(0)
	v_mfma_f32_16x16x32_bf16 v[62:65], v[142:145], v[180:183], v[62:65]
	v_mfma_f32_16x16x32_bf16 v[58:61], v[156:159], v[180:183], v[58:61]
	v_mfma_f32_16x16x32_bf16 v[54:57], v[142:145], v[188:191], v[54:57]
	v_mfma_f32_16x16x32_bf16 v[46:49], v[156:159], v[188:191], v[46:49]
	v_mfma_f32_16x16x32_bf16 v[38:41], v[142:145], v[196:199], v[38:41]
	v_mfma_f32_16x16x32_bf16 v[30:33], v[156:159], v[196:199], v[30:33]
	v_mfma_f32_16x16x32_bf16 v[22:25], v[142:145], v[204:207], v[22:25]
	v_mfma_f32_16x16x32_bf16 v[14:17], v[156:159], v[204:207], v[14:17]
	v_mfma_f32_16x16x32_bf16 v[62:65], v[152:155], v[184:187], v[62:65]
	v_mfma_f32_16x16x32_bf16 v[58:61], v[160:163], v[184:187], v[58:61]
	v_mfma_f32_16x16x32_bf16 v[54:57], v[152:155], v[192:195], v[54:57]
	v_mfma_f32_16x16x32_bf16 v[46:49], v[160:163], v[192:195], v[46:49]
	v_mfma_f32_16x16x32_bf16 v[38:41], v[152:155], v[200:203], v[38:41]
	v_mfma_f32_16x16x32_bf16 v[30:33], v[160:163], v[200:203], v[30:33]
	v_mfma_f32_16x16x32_bf16 v[22:25], v[152:155], v[208:211], v[22:25]
	v_mfma_f32_16x16x32_bf16 v[14:17], v[160:163], v[208:211], v[14:17]
	s_setprio 2
	s_setprio 0
	v_mfma_f32_16x16x32_bf16 v[50:53], v[164:167], v[180:183], v[50:53]
	v_mfma_f32_16x16x32_bf16 v[42:45], v[172:175], v[180:183], v[42:45]
	v_mfma_f32_16x16x32_bf16 v[34:37], v[164:167], v[188:191], v[34:37]
	v_mfma_f32_16x16x32_bf16 v[26:29], v[172:175], v[188:191], v[26:29]
	v_mfma_f32_16x16x32_bf16 v[18:21], v[164:167], v[196:199], v[18:21]
	v_mfma_f32_16x16x32_bf16 v[10:13], v[172:175], v[196:199], v[10:13]
	v_mfma_f32_16x16x32_bf16 v[6:9], v[164:167], v[204:207], v[6:9]
	v_mfma_f32_16x16x32_bf16 v[2:5], v[172:175], v[204:207], v[2:5]
	v_mfma_f32_16x16x32_bf16 v[50:53], v[168:171], v[184:187], v[50:53]
	v_mfma_f32_16x16x32_bf16 v[42:45], v[176:179], v[184:187], v[42:45]
	v_mfma_f32_16x16x32_bf16 v[34:37], v[168:171], v[192:195], v[34:37]
	v_mfma_f32_16x16x32_bf16 v[26:29], v[176:179], v[192:195], v[26:29]
	v_mfma_f32_16x16x32_bf16 v[18:21], v[168:171], v[200:203], v[18:21]
	v_mfma_f32_16x16x32_bf16 v[10:13], v[176:179], v[200:203], v[10:13]
	v_mfma_f32_16x16x32_bf16 v[6:9], v[168:171], v[208:211], v[6:9]
	v_mfma_f32_16x16x32_bf16 v[2:5], v[176:179], v[208:211], v[2:5]
	s_setprio 2
	s_barrier
	v_add_u32_e32 v151, s84, v147
	ds_read_b128 v[142:145], v151
	ds_read_b128 v[152:155], v151 offset:1024
	ds_read_b128 v[156:159], v151 offset:2048
	ds_read_b128 v[160:163], v151 offset:3072
	v_add_u32_e32 v151, s33, v147
	ds_read_b128 v[164:167], v151
	ds_read_b128 v[168:171], v151 offset:1024
	ds_read_b128 v[172:175], v151 offset:2048
	ds_read_b128 v[176:179], v151 offset:3072
	s_mov_b32 m0, s53
	v_lshl_add_u64 v[220:221], s[24:25], 0, v[136:137]
	ds_read_b128 v[180:183], v150 offset:32768
	ds_read_b128 v[184:187], v150 offset:33792
	ds_read_b128 v[188:191], v150 offset:34816
	ds_read_b128 v[192:195], v150 offset:35840
	ds_read_b128 v[196:199], v150 offset:36864
	ds_read_b128 v[200:203], v150 offset:37888
	ds_read_b128 v[204:207], v150 offset:38912
	ds_read_b128 v[208:211], v150 offset:39936
	global_load_lds_dwordx4 v[220:221], off
	v_lshl_add_u64 v[220:221], s[24:25], 0, v[132:133]
	s_mov_b32 m0, s54
	s_nop 0
	global_load_lds_dwordx4 v[220:221], off
	s_waitcnt vmcnt(8)
	s_waitcnt lgkmcnt(0)
	s_barrier
	s_setprio 0
	s_waitcnt lgkmcnt(0)
	v_mfma_f32_16x16x32_bf16 v[126:129], v[142:145], v[180:183], v[126:129]
	v_mfma_f32_16x16x32_bf16 v[122:125], v[156:159], v[180:183], v[122:125]
	v_mfma_f32_16x16x32_bf16 v[118:121], v[142:145], v[188:191], v[118:121]
	v_mfma_f32_16x16x32_bf16 v[110:113], v[156:159], v[188:191], v[110:113]
	v_mfma_f32_16x16x32_bf16 v[102:105], v[142:145], v[196:199], v[102:105]
	v_mfma_f32_16x16x32_bf16 v[94:97], v[156:159], v[196:199], v[94:97]
	v_mfma_f32_16x16x32_bf16 v[86:89], v[142:145], v[204:207], v[86:89]
	v_mfma_f32_16x16x32_bf16 v[78:81], v[156:159], v[204:207], v[78:81]
	v_mfma_f32_16x16x32_bf16 v[126:129], v[152:155], v[184:187], v[126:129]
	v_mfma_f32_16x16x32_bf16 v[122:125], v[160:163], v[184:187], v[122:125]
	v_mfma_f32_16x16x32_bf16 v[118:121], v[152:155], v[192:195], v[118:121]
	v_mfma_f32_16x16x32_bf16 v[110:113], v[160:163], v[192:195], v[110:113]
	v_mfma_f32_16x16x32_bf16 v[102:105], v[152:155], v[200:203], v[102:105]
	v_mfma_f32_16x16x32_bf16 v[94:97], v[160:163], v[200:203], v[94:97]
	v_mfma_f32_16x16x32_bf16 v[86:89], v[152:155], v[208:211], v[86:89]
	v_mfma_f32_16x16x32_bf16 v[78:81], v[160:163], v[208:211], v[78:81]
	s_setprio 2
	s_setprio 0
	v_mfma_f32_16x16x32_bf16 v[114:117], v[164:167], v[180:183], v[114:117]
	v_mfma_f32_16x16x32_bf16 v[106:109], v[172:175], v[180:183], v[106:109]
	v_mfma_f32_16x16x32_bf16 v[98:101], v[164:167], v[188:191], v[98:101]
	v_mfma_f32_16x16x32_bf16 v[90:93], v[172:175], v[188:191], v[90:93]
	v_mfma_f32_16x16x32_bf16 v[82:85], v[164:167], v[196:199], v[82:85]
	v_mfma_f32_16x16x32_bf16 v[74:77], v[172:175], v[196:199], v[74:77]
	v_mfma_f32_16x16x32_bf16 v[70:73], v[164:167], v[204:207], v[70:73]
	v_mfma_f32_16x16x32_bf16 v[66:69], v[172:175], v[204:207], v[66:69]
	v_mfma_f32_16x16x32_bf16 v[114:117], v[168:171], v[184:187], v[114:117]
	v_mfma_f32_16x16x32_bf16 v[106:109], v[176:179], v[184:187], v[106:109]
	v_mfma_f32_16x16x32_bf16 v[98:101], v[168:171], v[192:195], v[98:101]
	v_mfma_f32_16x16x32_bf16 v[90:93], v[176:179], v[192:195], v[90:93]
	v_mfma_f32_16x16x32_bf16 v[82:85], v[168:171], v[200:203], v[82:85]
	v_mfma_f32_16x16x32_bf16 v[74:77], v[176:179], v[200:203], v[74:77]
	v_mfma_f32_16x16x32_bf16 v[70:73], v[168:171], v[208:211], v[70:73]
	v_mfma_f32_16x16x32_bf16 v[66:69], v[176:179], v[208:211], v[66:69]
	s_setprio 2
	s_barrier
; #define PG8_STAGE(bufoff, gbase, voff) do { _Pragma("unroll") for (int _i = 0; _i < 2; ++_i) \
;         __builtin_amdgcn_global_load_lds((const unsigned*)((const char*)(gbase) + (voff)[_i]), (LAS unsigned*)(lds + (bufoff) + ldsw + _i * 8192), 16, 0, 0); } while (0)
; #define PG8_LDA(dst, b, h) do { _Pragma("unroll") for (int m = 0; m < 4; ++m) _Pragma("unroll") for (int k = 0; k < 2; ++k) dst[m][k] = *(const LAS bf16x8*)(lds + PG8_SA(b, h) + aoff + m * 2048 + k * 1024); } while (0)
; #define PG8_MMA(ai, bj, At, Bt) do { __builtin_amdgcn_s_setprio(1); _Pragma("unroll") for (int m = 0; m < 4; ++m) _Pragma("unroll") for (int n = 0; n < 2; ++n) _Pragma("unroll") for (int k = 0; k < 2; ++k) \
;         acc[ai][bj][m][n] = __builtin_amdgcn_mfma_f32_16x16x32_bf16(Bt[n][k], At[m][k], acc[ai][bj][m][n], 0, 0, 0); __builtin_amdgcn_s_setprio(0); } while (0)
; #define PG8_WAIT_V(n) asm volatile("s_waitcnt vmcnt(" #n ")" ::: "memory")
; #define PG8_WAIT_L(n) asm volatile("s_waitcnt lgkmcnt(" #n ")" ::: "memory")
; #define PG8_BAR __builtin_amdgcn_s_barrier()
; #define PG8_SCHED __builtin_amdgcn_sched_barrier(0)
; template <class Epi>
; __device__ __forceinline__ void gemm_phase(LAS unsigned char* lds, const Gemm g, int G, int c, const Epi& E) {
;     ...
;             PG8_LDA(At, 1, 1); PG8_STAGE(PG8_SB(1, 0), b3, voffB); PG8_STAGE(PG8_SB(1, 1), b3 + hstepB, voffB); PG8_STAGE(PG8_SA(1, 0), a3, voffA);
;             PG8_WAIT_V(8); PG8_WAIT_L(0); PG8_BAR; PG8_MMA(1, 0, At, B0); PG8_MMA(1, 1, At, B1); PG8_BAR; PG8_SCHED;
;         }
;         if (wr == 0) PG8_BAR;
	s_mov_b32 m0, s83
	v_lshl_add_u64 v[212:213], v[212:213], 0, s[8:9]
	ds_read_b128 v[180:183], v150 offset:49152
	ds_read_b128 v[184:187], v150 offset:50176
	ds_read_b128 v[188:191], v150 offset:51200
	ds_read_b128 v[192:195], v150 offset:52224
	ds_read_b128 v[196:199], v150 offset:53248
	ds_read_b128 v[200:203], v150 offset:54272
	ds_read_b128 v[204:207], v150 offset:55296
	ds_read_b128 v[208:211], v150 offset:56320
	global_load_lds_dwordx4 v[212:213], off
	v_lshl_add_u64 v[212:213], v[214:215], 0, s[8:9]
	s_mov_b32 m0, s13
	s_nop 0
	global_load_lds_dwordx4 v[212:213], off
	v_lshl_add_u64 v[212:213], s[22:23], 0, v[134:135]
	s_mov_b32 m0, s75
	s_nop 0
	global_load_lds_dwordx4 v[212:213], off
	v_lshl_add_u64 v[212:213], s[22:23], 0, v[130:131]
	s_mov_b32 m0, s74
	s_nop 0
	global_load_lds_dwordx4 v[212:213], off
	v_lshl_add_u64 v[212:213], v[216:217], 0, s[8:9]
	s_mov_b32 m0, s70
	s_nop 0
	global_load_lds_dwordx4 v[212:213], off
	v_lshl_add_u64 v[212:213], v[218:219], 0, s[8:9]
	s_mov_b32 m0, s71
	s_nop 0
	global_load_lds_dwordx4 v[212:213], off
	s_waitcnt vmcnt(8)
	s_waitcnt lgkmcnt(0)
	s_barrier
	s_setprio 0
	s_waitcnt lgkmcnt(0)
	v_mfma_f32_16x16x32_bf16 v[62:65], v[142:145], v[180:183], v[62:65]
	v_mfma_f32_16x16x32_bf16 v[58:61], v[156:159], v[180:183], v[58:61]
	v_mfma_f32_16x16x32_bf16 v[54:57], v[142:145], v[188:191], v[54:57]
	v_mfma_f32_16x16x32_bf16 v[46:49], v[156:159], v[188:191], v[46:49]
	v_mfma_f32_16x16x32_bf16 v[38:41], v[142:145], v[196:199], v[38:41]
	v_mfma_f32_16x16x32_bf16 v[30:33], v[156:159], v[196:199], v[30:33]
	v_mfma_f32_16x16x32_bf16 v[22:25], v[142:145], v[204:207], v[22:25]
	v_mfma_f32_16x16x32_bf16 v[14:17], v[156:159], v[204:207], v[14:17]
	v_mfma_f32_16x16x32_bf16 v[62:65], v[152:155], v[184:187], v[62:65]
	v_mfma_f32_16x16x32_bf16 v[58:61], v[160:163], v[184:187], v[58:61]
	v_mfma_f32_16x16x32_bf16 v[54:57], v[152:155], v[192:195], v[54:57]
	v_mfma_f32_16x16x32_bf16 v[46:49], v[160:163], v[192:195], v[46:49]
	v_mfma_f32_16x16x32_bf16 v[38:41], v[152:155], v[200:203], v[38:41]
	v_mfma_f32_16x16x32_bf16 v[30:33], v[160:163], v[200:203], v[30:33]
	v_mfma_f32_16x16x32_bf16 v[22:25], v[152:155], v[208:211], v[22:25]
	v_mfma_f32_16x16x32_bf16 v[14:17], v[160:163], v[208:211], v[14:17]
	s_setprio 2
	s_setprio 0
	v_mfma_f32_16x16x32_bf16 v[50:53], v[164:167], v[180:183], v[50:53]
	v_mfma_f32_16x16x32_bf16 v[42:45], v[172:175], v[180:183], v[42:45]
	v_mfma_f32_16x16x32_bf16 v[34:37], v[164:167], v[188:191], v[34:37]
	v_mfma_f32_16x16x32_bf16 v[26:29], v[172:175], v[188:191], v[26:29]
	v_mfma_f32_16x16x32_bf16 v[18:21], v[164:167], v[196:199], v[18:21]
	v_mfma_f32_16x16x32_bf16 v[10:13], v[172:175], v[196:199], v[10:13]
	v_mfma_f32_16x16x32_bf16 v[6:9], v[164:167], v[204:207], v[6:9]
	v_mfma_f32_16x16x32_bf16 v[2:5], v[172:175], v[204:207], v[2:5]
	v_mfma_f32_16x16x32_bf16 v[50:53], v[168:171], v[184:187], v[50:53]
	v_mfma_f32_16x16x32_bf16 v[42:45], v[176:179], v[184:187], v[42:45]
	v_mfma_f32_16x16x32_bf16 v[34:37], v[168:171], v[192:195], v[34:37]
	v_mfma_f32_16x16x32_bf16 v[26:29], v[176:179], v[192:195], v[26:29]
	v_mfma_f32_16x16x32_bf16 v[18:21], v[168:171], v[200:203], v[18:21]
	v_mfma_f32_16x16x32_bf16 v[10:13], v[176:179], v[200:203], v[10:13]
	v_mfma_f32_16x16x32_bf16 v[6:9], v[168:171], v[208:211], v[6:9]
	v_mfma_f32_16x16x32_bf16 v[2:5], v[176:179], v[208:211], v[2:5]
	s_setprio 2
	s_barrier
	s_movk_i32 s13, 0x100
	s_andn2_b64 vcc, exec, s[20:21]
	s_mov_b64 s[22:23], -1
	s_mov_b64 s[20:21], 0
	s_cbranch_vccz .LBB0_1429
	s_and_b64 vcc, exec, s[10:11]
	s_cbranch_vccz .LBB0_1432
	s_barrier

; #define PG8_STAGE(bufoff, gbase, voff) do { _Pragma("unroll") for (int _i = 0; _i < 2; ++_i) \
;         __builtin_amdgcn_global_load_lds((const unsigned*)((const char*)(gbase) + (voff)[_i]), (LAS unsigned*)(lds + (bufoff) + ldsw + _i * 8192), 16, 0, 0); } while (0)
; #define PG8_LDA(dst, b, h) do { _Pragma("unroll") for (int m = 0; m < 4; ++m) _Pragma("unroll") for (int k = 0; k < 2; ++k) dst[m][k] = *(const LAS bf16x8*)(lds + PG8_SA(b, h) + aoff + m * 2048 + k * 1024); } while (0)
; #define PG8_LDB(dst, b, h) do { _Pragma("unroll") for (int n = 0; n < 2; ++n) _Pragma("unroll") for (int k = 0; k < 2; ++k) dst[n][k] = *(const LAS bf16x8*)(lds + PG8_SB(b, h) + boff + n * 2048 + k * 1024); } while (0)
; #define PG8_MMA(ai, bj, At, Bt) do { __builtin_amdgcn_s_setprio(1); _Pragma("unroll") for (int m = 0; m < 4; ++m) _Pragma("unroll") for (int n = 0; n < 2; ++n) _Pragma("unroll") for (int k = 0; k < 2; ++k) \
;         acc[ai][bj][m][n] = __builtin_amdgcn_mfma_f32_16x16x32_bf16(Bt[n][k], At[m][k], acc[ai][bj][m][n], 0, 0, 0); __builtin_amdgcn_s_setprio(0); } while (0)
; #define PG8_WAIT_V(n) asm volatile("s_waitcnt vmcnt(" #n ")" ::: "memory")
; #define PG8_WAIT_L(n) asm volatile("s_waitcnt lgkmcnt(" #n ")" ::: "memory")
; #define PG8_BAR __builtin_amdgcn_s_barrier()
; #define PG8_SCHED __builtin_amdgcn_sched_barrier(0)
; template <class Epi>
; __device__ __forceinline__ void gemm_phase(LAS unsigned char* lds, const Gemm g, int G, int c, const Epi& E) {
;     ...
;         for (int t = 0; t < nt; t += 2) {
;             const bool last = (t == nt - 2);
;             const char* a1 = cA + (size_t)(t + 1) * kstep;
;             const char* a2 = last ? nA : cA + (size_t)(t + 2) * kstep; const char* b2 = last ? nB : cB + (size_t)(t + 2) * kstep;
;             const char* a3 = a2 + kstep; const char* b3 = b2 + kstep;
;             PG8_LDB(B0, 0, 0); PG8_LDB(B1, 0, 1); PG8_SCHED; PG8_LDA(At, 0, 0); PG8_STAGE(PG8_SA(1, 1), a1 + hstepA, voffA);
;             PG8_WAIT_V(8); PG8_WAIT_L(0); PG8_BAR; PG8_MMA(0, 0, At, B0); PG8_MMA(0, 1, At, B1); PG8_BAR; PG8_SCHED;
;             PG8_LDA(At, 0, 1); PG8_STAGE(PG8_SB(0, 0), b2, voffB); PG8_STAGE(PG8_SB(0, 1), b2 + hstepB, voffB); PG8_STAGE(PG8_SA(0, 0), a2, voffA);
.LBB0_1451:
	s_add_u32 s33, s8, s44
	s_addc_u32 s45, s9, 0
	s_add_u32 s48, s33, 0x100
	s_addc_u32 s49, s45, 0
	s_and_b64 s[46:47], s[10:11], exec
	s_cselect_b32 s47, s41, s49
	s_cselect_b32 s46, s40, s48
	s_add_u32 s44, s6, s44
	s_addc_u32 s48, s7, 0
	s_add_u32 s44, s44, 0x100
	s_addc_u32 s48, s48, 0
	s_and_b64 s[10:11], s[10:11], exec
	s_cselect_b32 s49, s43, s48
	s_cselect_b32 s48, s42, s44
	s_add_u32 s54, s33, 0xb0080
	ds_read_b128 v[142:145], v160
	ds_read_b128 v[146:149], v160 offset:1024
	ds_read_b128 v[150:153], v160 offset:2048
	ds_read_b128 v[154:157], v160 offset:3072
	ds_read_b128 v[166:169], v161
	ds_read_b128 v[170:173], v161 offset:1024
	ds_read_b128 v[174:177], v161 offset:2048
	ds_read_b128 v[178:181], v161 offset:3072
	s_addc_u32 s55, s45, 0
	s_add_i32 s65, s82, s66
	s_add_i32 m0, s69, 0xc000
	s_add_i32 s74, s69, 0xe000
	s_add_i32 s62, s65, 0x2000
	s_add_u32 s52, s48, 0xb0000
	s_addc_u32 s53, s49, 0
	s_add_i32 s64, s83, s66
	s_add_i32 s63, s64, 0x2000
	s_add_i32 s97, 0, 0x18000
	s_add_i32 s33, 0, 0x1c000
	s_add_u32 s44, s46, 0xb0000
	s_addc_u32 s45, s47, 0
	s_add_i32 s96, s97, s66
	s_add_i32 s94, s96, 0x2000
	s_add_u32 s10, s48, 0xb0080
	s_addc_u32 s11, s49, 0
	s_add_i32 s95, s33, s66
	s_add_i32 s93, s95, 0x2000
	v_lshl_add_u64 v[214:215], s[54:55], 0, v[130:131]
	ds_read_b128 v[182:185], v162
	ds_read_b128 v[186:189], v162 offset:1024
	ds_read_b128 v[190:193], v162 offset:2048
	ds_read_b128 v[194:197], v162 offset:3072
	ds_read_b128 v[198:201], v162 offset:4096
	ds_read_b128 v[202:205], v162 offset:5120
	ds_read_b128 v[206:209], v162 offset:6144
	ds_read_b128 v[210:213], v162 offset:7168
	global_load_lds_dwordx4 v[214:215], off
	v_lshl_add_u64 v[214:215], s[54:55], 0, v[134:135]
	s_mov_b32 m0, s74
	s_nop 0
	global_load_lds_dwordx4 v[214:215], off
	s_waitcnt vmcnt(8)
	s_waitcnt lgkmcnt(0)
	s_barrier
	s_setprio 0
	s_waitcnt lgkmcnt(0)
	v_mfma_f32_16x16x32_bf16 v[126:129], v[142:145], v[182:185], v[126:129]
	v_mfma_f32_16x16x32_bf16 v[122:125], v[150:153], v[182:185], v[122:125]
	v_mfma_f32_16x16x32_bf16 v[110:113], v[142:145], v[190:193], v[110:113]
	v_mfma_f32_16x16x32_bf16 v[106:109], v[150:153], v[190:193], v[106:109]
	v_mfma_f32_16x16x32_bf16 v[94:97], v[142:145], v[198:201], v[94:97]
	v_mfma_f32_16x16x32_bf16 v[90:93], v[150:153], v[198:201], v[90:93]
	v_mfma_f32_16x16x32_bf16 v[78:81], v[142:145], v[206:209], v[78:81]
	v_mfma_f32_16x16x32_bf16 v[74:77], v[150:153], v[206:209], v[74:77]
	v_mfma_f32_16x16x32_bf16 v[126:129], v[146:149], v[186:189], v[126:129]
	v_mfma_f32_16x16x32_bf16 v[122:125], v[154:157], v[186:189], v[122:125]
	v_mfma_f32_16x16x32_bf16 v[110:113], v[146:149], v[194:197], v[110:113]
	v_mfma_f32_16x16x32_bf16 v[106:109], v[154:157], v[194:197], v[106:109]
	v_mfma_f32_16x16x32_bf16 v[94:97], v[146:149], v[202:205], v[94:97]
	v_mfma_f32_16x16x32_bf16 v[90:93], v[154:157], v[202:205], v[90:93]
	v_mfma_f32_16x16x32_bf16 v[78:81], v[146:149], v[210:213], v[78:81]
	v_mfma_f32_16x16x32_bf16 v[74:77], v[154:157], v[210:213], v[74:77]
	s_setprio 2
	s_setprio 0
	v_mfma_f32_16x16x32_bf16 v[118:121], v[166:169], v[182:185], v[118:121]
	v_mfma_f32_16x16x32_bf16 v[114:117], v[174:177], v[182:185], v[114:117]
	v_mfma_f32_16x16x32_bf16 v[102:105], v[166:169], v[190:193], v[102:105]
	v_mfma_f32_16x16x32_bf16 v[98:101], v[174:177], v[190:193], v[98:101]
	v_mfma_f32_16x16x32_bf16 v[86:89], v[166:169], v[198:201], v[86:89]
	v_mfma_f32_16x16x32_bf16 v[82:85], v[174:177], v[198:201], v[82:85]
	v_mfma_f32_16x16x32_bf16 v[70:73], v[166:169], v[206:209], v[70:73]
	v_mfma_f32_16x16x32_bf16 v[66:69], v[174:177], v[206:209], v[66:69]
	v_mfma_f32_16x16x32_bf16 v[118:121], v[170:173], v[186:189], v[118:121]
	v_mfma_f32_16x16x32_bf16 v[114:117], v[178:181], v[186:189], v[114:117]
	v_mfma_f32_16x16x32_bf16 v[102:105], v[170:173], v[194:197], v[102:105]
	v_mfma_f32_16x16x32_bf16 v[98:101], v[178:181], v[194:197], v[98:101]
	v_mfma_f32_16x16x32_bf16 v[86:89], v[170:173], v[202:205], v[86:89]
	v_mfma_f32_16x16x32_bf16 v[82:85], v[178:181], v[202:205], v[82:85]
	v_mfma_f32_16x16x32_bf16 v[70:73], v[170:173], v[210:213], v[70:73]
	v_mfma_f32_16x16x32_bf16 v[66:69], v[178:181], v[210:213], v[66:69]
	s_setprio 2
	s_barrier
	s_mov_b32 m0, s65
	v_lshl_add_u64 v[214:215], s[48:49], 0, v[132:133]
	ds_read_b128 v[182:185], v162 offset:16384
	ds_read_b128 v[186:189], v162 offset:17408
	ds_read_b128 v[190:193], v162 offset:18432
	ds_read_b128 v[194:197], v162 offset:19456
	ds_read_b128 v[198:201], v162 offset:20480
	ds_read_b128 v[202:205], v162 offset:21504
	ds_read_b128 v[206:209], v162 offset:22528
	ds_read_b128 v[210:213], v162 offset:23552
	global_load_lds_dwordx4 v[214:215], off
	v_lshl_add_u64 v[216:217], s[48:49], 0, v[136:137]
	s_mov_b32 m0, s62
	v_lshl_add_u64 v[218:219], s[52:53], 0, v[132:133]
	global_load_lds_dwordx4 v[216:217], off
	s_mov_b32 m0, s64
	v_lshl_add_u64 v[220:221], s[46:47], 0, v[134:135]
	global_load_lds_dwordx4 v[218:219], off
	v_lshl_add_u64 v[218:219], s[52:53], 0, v[136:137]
	s_mov_b32 m0, s63
	s_nop 0
	global_load_lds_dwordx4 v[218:219], off
	v_lshl_add_u64 v[218:219], s[46:47], 0, v[130:131]
	s_mov_b32 m0, s69
	s_nop 0
	global_load_lds_dwordx4 v[218:219], off
	s_mov_b32 m0, s70
	s_nop 0
	global_load_lds_dwordx4 v[220:221], off
	s_waitcnt vmcnt(8)
	s_waitcnt lgkmcnt(0)
	s_barrier
; #define PG8_STAGE(bufoff, gbase, voff) do { _Pragma("unroll") for (int _i = 0; _i < 2; ++_i) \
;         __builtin_amdgcn_global_load_lds((const unsigned*)((const char*)(gbase) + (voff)[_i]), (LAS unsigned*)(lds + (bufoff) + ldsw + _i * 8192), 16, 0, 0); } while (0)
; #define PG8_LDA(dst, b, h) do { _Pragma("unroll") for (int m = 0; m < 4; ++m) _Pragma("unroll") for (int k = 0; k < 2; ++k) dst[m][k] = *(const LAS bf16x8*)(lds + PG8_SA(b, h) + aoff + m * 2048 + k * 1024); } while (0)
; #define PG8_LDB(dst, b, h) do { _Pragma("unroll") for (int n = 0; n < 2; ++n) _Pragma("unroll") for (int k = 0; k < 2; ++k) dst[n][k] = *(const LAS bf16x8*)(lds + PG8_SB(b, h) + boff + n * 2048 + k * 1024); } while (0)
; #define PG8_MMA(ai, bj, At, Bt) do { __builtin_amdgcn_s_setprio(1); _Pragma("unroll") for (int m = 0; m < 4; ++m) _Pragma("unroll") for (int n = 0; n < 2; ++n) _Pragma("unroll") for (int k = 0; k < 2; ++k) \
;         acc[ai][bj][m][n] = __builtin_amdgcn_mfma_f32_16x16x32_bf16(Bt[n][k], At[m][k], acc[ai][bj][m][n], 0, 0, 0); __builtin_amdgcn_s_setprio(0); } while (0)
; #define PG8_WAIT_V(n) asm volatile("s_waitcnt vmcnt(" #n ")" ::: "memory")
; #define PG8_WAIT_L(n) asm volatile("s_waitcnt lgkmcnt(" #n ")" ::: "memory")
; #define PG8_BAR __builtin_amdgcn_s_barrier()
; #define PG8_SCHED __builtin_amdgcn_sched_barrier(0)
; template <class Epi>
; __device__ __forceinline__ void gemm_phase(LAS unsigned char* lds, const Gemm g, int G, int c, const Epi& E) {
;     ...
;             PG8_WAIT_V(8); PG8_WAIT_L(0); PG8_BAR; PG8_MMA(1, 0, At, B0); PG8_MMA(1, 1, At, B1); PG8_BAR; PG8_SCHED;
;             PG8_LDB(B0, 1, 0); PG8_LDB(B1, 1, 1); PG8_SCHED; PG8_LDA(At, 1, 0); PG8_STAGE(PG8_SA(0, 1), a2 + hstepA, voffA);
;             PG8_WAIT_V(8); PG8_WAIT_L(0); PG8_BAR; PG8_MMA(0, 0, At, B0); PG8_MMA(0, 1, At, B1); PG8_BAR; PG8_SCHED;
	s_setprio 0
	s_waitcnt lgkmcnt(0)
	v_mfma_f32_16x16x32_bf16 v[62:65], v[142:145], v[182:185], v[62:65]
	v_mfma_f32_16x16x32_bf16 v[58:61], v[150:153], v[182:185], v[58:61]
	v_mfma_f32_16x16x32_bf16 v[46:49], v[142:145], v[190:193], v[46:49]
	v_mfma_f32_16x16x32_bf16 v[42:45], v[150:153], v[190:193], v[42:45]
	v_mfma_f32_16x16x32_bf16 v[30:33], v[142:145], v[198:201], v[30:33]
	v_mfma_f32_16x16x32_bf16 v[26:29], v[150:153], v[198:201], v[26:29]
	v_mfma_f32_16x16x32_bf16 v[14:17], v[142:145], v[206:209], v[14:17]
	v_mfma_f32_16x16x32_bf16 v[10:13], v[150:153], v[206:209], v[10:13]
	v_mfma_f32_16x16x32_bf16 v[62:65], v[146:149], v[186:189], v[62:65]
	v_mfma_f32_16x16x32_bf16 v[58:61], v[154:157], v[186:189], v[58:61]
	v_mfma_f32_16x16x32_bf16 v[46:49], v[146:149], v[194:197], v[46:49]
	v_mfma_f32_16x16x32_bf16 v[42:45], v[154:157], v[194:197], v[42:45]
	v_mfma_f32_16x16x32_bf16 v[30:33], v[146:149], v[202:205], v[30:33]
	v_mfma_f32_16x16x32_bf16 v[26:29], v[154:157], v[202:205], v[26:29]
	v_mfma_f32_16x16x32_bf16 v[14:17], v[146:149], v[210:213], v[14:17]
	v_mfma_f32_16x16x32_bf16 v[10:13], v[154:157], v[210:213], v[10:13]
	s_setprio 2
	s_setprio 0
	v_mfma_f32_16x16x32_bf16 v[54:57], v[166:169], v[182:185], v[54:57]
	v_mfma_f32_16x16x32_bf16 v[50:53], v[174:177], v[182:185], v[50:53]
	v_mfma_f32_16x16x32_bf16 v[38:41], v[166:169], v[190:193], v[38:41]
	v_mfma_f32_16x16x32_bf16 v[34:37], v[174:177], v[190:193], v[34:37]
	v_mfma_f32_16x16x32_bf16 v[22:25], v[166:169], v[198:201], v[22:25]
	v_mfma_f32_16x16x32_bf16 v[18:21], v[174:177], v[198:201], v[18:21]
	v_mfma_f32_16x16x32_bf16 v[6:9], v[166:169], v[206:209], v[6:9]
	v_mfma_f32_16x16x32_bf16 v[2:5], v[174:177], v[206:209], v[2:5]
	v_mfma_f32_16x16x32_bf16 v[54:57], v[170:173], v[186:189], v[54:57]
	v_mfma_f32_16x16x32_bf16 v[50:53], v[178:181], v[186:189], v[50:53]
	v_mfma_f32_16x16x32_bf16 v[38:41], v[170:173], v[194:197], v[38:41]
	v_mfma_f32_16x16x32_bf16 v[34:37], v[178:181], v[194:197], v[34:37]
	v_mfma_f32_16x16x32_bf16 v[22:25], v[170:173], v[202:205], v[22:25]
	v_mfma_f32_16x16x32_bf16 v[18:21], v[178:181], v[202:205], v[18:21]
	v_mfma_f32_16x16x32_bf16 v[6:9], v[170:173], v[210:213], v[6:9]
	v_mfma_f32_16x16x32_bf16 v[2:5], v[178:181], v[210:213], v[2:5]
	s_setprio 2
	s_barrier
	v_add_u32_e32 v154, s97, v159
	v_add_u32_e32 v178, s33, v159
	ds_read_b128 v[142:145], v154
	ds_read_b128 v[146:149], v154 offset:1024
	ds_read_b128 v[150:153], v154 offset:2048
	ds_read_b128 v[154:157], v154 offset:3072
	ds_read_b128 v[166:169], v178
	ds_read_b128 v[170:173], v178 offset:1024
	ds_read_b128 v[174:177], v178 offset:2048
	ds_read_b128 v[178:181], v178 offset:3072
	s_mov_b32 m0, s71
	v_lshl_add_u64 v[222:223], s[44:45], 0, v[130:131]
	ds_read_b128 v[182:185], v162 offset:32768
	ds_read_b128 v[186:189], v162 offset:33792
	ds_read_b128 v[190:193], v162 offset:34816
	ds_read_b128 v[194:197], v162 offset:35840
	ds_read_b128 v[198:201], v162 offset:36864
	ds_read_b128 v[202:205], v162 offset:37888
	ds_read_b128 v[206:209], v162 offset:38912
	ds_read_b128 v[210:213], v162 offset:39936
	global_load_lds_dwordx4 v[222:223], off
	v_lshl_add_u64 v[222:223], s[44:45], 0, v[134:135]
	s_mov_b32 m0, s72
	s_nop 0
	global_load_lds_dwordx4 v[222:223], off
	s_waitcnt vmcnt(8)
	s_waitcnt lgkmcnt(0)
	s_barrier
	s_setprio 0
	s_waitcnt lgkmcnt(0)
	v_mfma_f32_16x16x32_bf16 v[126:129], v[142:145], v[182:185], v[126:129]
	v_mfma_f32_16x16x32_bf16 v[122:125], v[150:153], v[182:185], v[122:125]
	v_mfma_f32_16x16x32_bf16 v[110:113], v[142:145], v[190:193], v[110:113]
	v_mfma_f32_16x16x32_bf16 v[106:109], v[150:153], v[190:193], v[106:109]
	v_mfma_f32_16x16x32_bf16 v[94:97], v[142:145], v[198:201], v[94:97]
	v_mfma_f32_16x16x32_bf16 v[90:93], v[150:153], v[198:201], v[90:93]
	v_mfma_f32_16x16x32_bf16 v[78:81], v[142:145], v[206:209], v[78:81]
	v_mfma_f32_16x16x32_bf16 v[74:77], v[150:153], v[206:209], v[74:77]
	v_mfma_f32_16x16x32_bf16 v[126:129], v[146:149], v[186:189], v[126:129]
	v_mfma_f32_16x16x32_bf16 v[122:125], v[154:157], v[186:189], v[122:125]
	v_mfma_f32_16x16x32_bf16 v[110:113], v[146:149], v[194:197], v[110:113]
	v_mfma_f32_16x16x32_bf16 v[106:109], v[154:157], v[194:197], v[106:109]
	v_mfma_f32_16x16x32_bf16 v[94:97], v[146:149], v[202:205], v[94:97]
	v_mfma_f32_16x16x32_bf16 v[90:93], v[154:157], v[202:205], v[90:93]
	v_mfma_f32_16x16x32_bf16 v[78:81], v[146:149], v[210:213], v[78:81]
	v_mfma_f32_16x16x32_bf16 v[74:77], v[154:157], v[210:213], v[74:77]
	s_setprio 2
	s_setprio 0
	v_mfma_f32_16x16x32_bf16 v[118:121], v[166:169], v[182:185], v[118:121]
	v_mfma_f32_16x16x32_bf16 v[114:117], v[174:177], v[182:185], v[114:117]
	v_mfma_f32_16x16x32_bf16 v[102:105], v[166:169], v[190:193], v[102:105]
	v_mfma_f32_16x16x32_bf16 v[98:101], v[174:177], v[190:193], v[98:101]
	v_mfma_f32_16x16x32_bf16 v[86:89], v[166:169], v[198:201], v[86:89]
	v_mfma_f32_16x16x32_bf16 v[82:85], v[174:177], v[198:201], v[82:85]
	v_mfma_f32_16x16x32_bf16 v[70:73], v[166:169], v[206:209], v[70:73]
	v_mfma_f32_16x16x32_bf16 v[66:69], v[174:177], v[206:209], v[66:69]
	v_mfma_f32_16x16x32_bf16 v[118:121], v[170:173], v[186:189], v[118:121]
	v_mfma_f32_16x16x32_bf16 v[114:117], v[178:181], v[186:189], v[114:117]
	v_mfma_f32_16x16x32_bf16 v[102:105], v[170:173], v[194:197], v[102:105]
	v_mfma_f32_16x16x32_bf16 v[98:101], v[178:181], v[194:197], v[98:101]
	v_mfma_f32_16x16x32_bf16 v[86:89], v[170:173], v[202:205], v[86:89]
	v_mfma_f32_16x16x32_bf16 v[82:85], v[178:181], v[202:205], v[82:85]
	v_mfma_f32_16x16x32_bf16 v[70:73], v[170:173], v[210:213], v[70:73]
	v_mfma_f32_16x16x32_bf16 v[66:69], v[178:181], v[210:213], v[66:69]
	s_setprio 2
	s_barrier
; #define PG8_STAGE(bufoff, gbase, voff) do { _Pragma("unroll") for (int _i = 0; _i < 2; ++_i) \
;         __builtin_amdgcn_global_load_lds((const unsigned*)((const char*)(gbase) + (voff)[_i]), (LAS unsigned*)(lds + (bufoff) + ldsw + _i * 8192), 16, 0, 0); } while (0)
; #define PG8_LDA(dst, b, h) do { _Pragma("unroll") for (int m = 0; m < 4; ++m) _Pragma("unroll") for (int k = 0; k < 2; ++k) dst[m][k] = *(const LAS bf16x8*)(lds + PG8_SA(b, h) + aoff + m * 2048 + k * 1024); } while (0)
; #define PG8_MMA(ai, bj, At, Bt) do { __builtin_amdgcn_s_setprio(1); _Pragma("unroll") for (int m = 0; m < 4; ++m) _Pragma("unroll") for (int n = 0; n < 2; ++n) _Pragma("unroll") for (int k = 0; k < 2; ++k) \
;         acc[ai][bj][m][n] = __builtin_amdgcn_mfma_f32_16x16x32_bf16(Bt[n][k], At[m][k], acc[ai][bj][m][n], 0, 0, 0); __builtin_amdgcn_s_setprio(0); } while (0)
; #define PG8_WAIT_V(n) asm volatile("s_waitcnt vmcnt(" #n ")" ::: "memory")
; #define PG8_WAIT_L(n) asm volatile("s_waitcnt lgkmcnt(" #n ")" ::: "memory")
; #define PG8_BAR __builtin_amdgcn_s_barrier()
; #define PG8_SCHED __builtin_amdgcn_sched_barrier(0)
; template <class Epi>
; __device__ __forceinline__ void gemm_phase(LAS unsigned char* lds, const Gemm g, int G, int c, const Epi& E) {
;     ...
;             PG8_LDA(At, 1, 1); PG8_STAGE(PG8_SB(1, 0), b3, voffB); PG8_STAGE(PG8_SB(1, 1), b3 + hstepB, voffB); PG8_STAGE(PG8_SA(1, 0), a3, voffA);
;             PG8_WAIT_V(8); PG8_WAIT_L(0); PG8_BAR; PG8_MMA(1, 0, At, B0); PG8_MMA(1, 1, At, B1); PG8_BAR; PG8_SCHED;
;         }
;         if (wr == 0) PG8_BAR;
	s_mov_b32 m0, s96
	v_lshl_add_u64 v[214:215], v[214:215], 0, s[22:23]
	ds_read_b128 v[182:185], v162 offset:49152
	ds_read_b128 v[186:189], v162 offset:50176
	ds_read_b128 v[190:193], v162 offset:51200
	ds_read_b128 v[194:197], v162 offset:52224
	ds_read_b128 v[198:201], v162 offset:53248
	ds_read_b128 v[202:205], v162 offset:54272
	ds_read_b128 v[206:209], v162 offset:55296
	ds_read_b128 v[210:213], v162 offset:56320
	global_load_lds_dwordx4 v[214:215], off
	v_lshl_add_u64 v[214:215], v[216:217], 0, s[22:23]
	s_mov_b32 m0, s94
	s_nop 0
	global_load_lds_dwordx4 v[214:215], off
	v_lshl_add_u64 v[214:215], s[10:11], 0, v[132:133]
	s_mov_b32 m0, s95
	s_nop 0
	global_load_lds_dwordx4 v[214:215], off
	v_lshl_add_u64 v[214:215], s[10:11], 0, v[136:137]
	s_mov_b32 m0, s93
	s_nop 0
	global_load_lds_dwordx4 v[214:215], off
	v_lshl_add_u64 v[214:215], v[218:219], 0, s[22:23]
	s_mov_b32 m0, s80
	s_nop 0
	global_load_lds_dwordx4 v[214:215], off
	v_lshl_add_u64 v[214:215], v[220:221], 0, s[22:23]
	s_mov_b32 m0, s81
	s_nop 0
	global_load_lds_dwordx4 v[214:215], off
	s_waitcnt vmcnt(8)
	s_waitcnt lgkmcnt(0)
	s_barrier
	s_setprio 0
	s_waitcnt lgkmcnt(0)
	v_mfma_f32_16x16x32_bf16 v[62:65], v[142:145], v[182:185], v[62:65]
	v_mfma_f32_16x16x32_bf16 v[58:61], v[150:153], v[182:185], v[58:61]
	v_mfma_f32_16x16x32_bf16 v[46:49], v[142:145], v[190:193], v[46:49]
	v_mfma_f32_16x16x32_bf16 v[42:45], v[150:153], v[190:193], v[42:45]
	v_mfma_f32_16x16x32_bf16 v[30:33], v[142:145], v[198:201], v[30:33]
	v_mfma_f32_16x16x32_bf16 v[26:29], v[150:153], v[198:201], v[26:29]
	v_mfma_f32_16x16x32_bf16 v[14:17], v[142:145], v[206:209], v[14:17]
	v_mfma_f32_16x16x32_bf16 v[10:13], v[150:153], v[206:209], v[10:13]
	v_mfma_f32_16x16x32_bf16 v[62:65], v[146:149], v[186:189], v[62:65]
	v_mfma_f32_16x16x32_bf16 v[58:61], v[154:157], v[186:189], v[58:61]
	v_mfma_f32_16x16x32_bf16 v[46:49], v[146:149], v[194:197], v[46:49]
	v_mfma_f32_16x16x32_bf16 v[42:45], v[154:157], v[194:197], v[42:45]
	v_mfma_f32_16x16x32_bf16 v[30:33], v[146:149], v[202:205], v[30:33]
	v_mfma_f32_16x16x32_bf16 v[26:29], v[154:157], v[202:205], v[26:29]
	v_mfma_f32_16x16x32_bf16 v[14:17], v[146:149], v[210:213], v[14:17]
	v_mfma_f32_16x16x32_bf16 v[10:13], v[154:157], v[210:213], v[10:13]
	s_setprio 2
	s_setprio 0
	v_mfma_f32_16x16x32_bf16 v[54:57], v[166:169], v[182:185], v[54:57]
	v_mfma_f32_16x16x32_bf16 v[50:53], v[174:177], v[182:185], v[50:53]
	v_mfma_f32_16x16x32_bf16 v[38:41], v[166:169], v[190:193], v[38:41]
	v_mfma_f32_16x16x32_bf16 v[34:37], v[174:177], v[190:193], v[34:37]
	v_mfma_f32_16x16x32_bf16 v[22:25], v[166:169], v[198:201], v[22:25]
	v_mfma_f32_16x16x32_bf16 v[18:21], v[174:177], v[198:201], v[18:21]
	v_mfma_f32_16x16x32_bf16 v[6:9], v[166:169], v[206:209], v[6:9]
	v_mfma_f32_16x16x32_bf16 v[2:5], v[174:177], v[206:209], v[2:5]
	v_mfma_f32_16x16x32_bf16 v[54:57], v[170:173], v[186:189], v[54:57]
	v_mfma_f32_16x16x32_bf16 v[50:53], v[178:181], v[186:189], v[50:53]
	v_mfma_f32_16x16x32_bf16 v[38:41], v[170:173], v[194:197], v[38:41]
	v_mfma_f32_16x16x32_bf16 v[34:37], v[178:181], v[194:197], v[34:37]
	v_mfma_f32_16x16x32_bf16 v[22:25], v[170:173], v[202:205], v[22:25]
	v_mfma_f32_16x16x32_bf16 v[18:21], v[178:181], v[202:205], v[18:21]
	v_mfma_f32_16x16x32_bf16 v[6:9], v[170:173], v[210:213], v[6:9]
	v_mfma_f32_16x16x32_bf16 v[2:5], v[178:181], v[210:213], v[2:5]
	s_setprio 2
	s_barrier
	s_movk_i32 s44, 0x100
	s_andn2_b64 vcc, exec, s[4:5]
	s_mov_b64 s[10:11], -1
	s_mov_b64 s[4:5], 0
	s_cbranch_vccz .LBB0_1451
	s_and_b64 vcc, exec, s[24:25]
	s_cbranch_vccz .LBB0_1454
	s_barrier

; #define PG8_STAGE(bufoff, gbase, voff) do { _Pragma("unroll") for (int _i = 0; _i < 2; ++_i) \
;         __builtin_amdgcn_global_load_lds((const unsigned*)((const char*)(gbase) + (voff)[_i]), (LAS unsigned*)(lds + (bufoff) + ldsw + _i * 8192), 16, 0, 0); } while (0)
; #define PG8_LDA(dst, b, h) do { _Pragma("unroll") for (int m = 0; m < 4; ++m) _Pragma("unroll") for (int k = 0; k < 2; ++k) dst[m][k] = *(const LAS bf16x8*)(lds + PG8_SA(b, h) + aoff + m * 2048 + k * 1024); } while (0)
; #define PG8_LDB(dst, b, h) do { _Pragma("unroll") for (int n = 0; n < 2; ++n) _Pragma("unroll") for (int k = 0; k < 2; ++k) dst[n][k] = *(const LAS bf16x8*)(lds + PG8_SB(b, h) + boff + n * 2048 + k * 1024); } while (0)
; #define PG8_MMA(ai, bj, At, Bt) do { __builtin_amdgcn_s_setprio(1); _Pragma("unroll") for (int m = 0; m < 4; ++m) _Pragma("unroll") for (int n = 0; n < 2; ++n) _Pragma("unroll") for (int k = 0; k < 2; ++k) \
;         acc[ai][bj][m][n] = __builtin_amdgcn_mfma_f32_16x16x32_bf16(Bt[n][k], At[m][k], acc[ai][bj][m][n], 0, 0, 0); __builtin_amdgcn_s_setprio(0); } while (0)
; #define PG8_WAIT_V(n) asm volatile("s_waitcnt vmcnt(" #n ")" ::: "memory")
; #define PG8_WAIT_L(n) asm volatile("s_waitcnt lgkmcnt(" #n ")" ::: "memory")
; #define PG8_BAR __builtin_amdgcn_s_barrier()
; #define PG8_SCHED __builtin_amdgcn_sched_barrier(0)
; template <class Epi>
; __device__ __forceinline__ void gemm_phase(LAS unsigned char* lds, const Gemm g, int G, int c, const Epi& E) {
;     ...
;         for (int t = 0; t < nt; t += 2) {
;             const bool last = (t == nt - 2);
;             const char* a1 = cA + (size_t)(t + 1) * kstep;
;             const char* a2 = last ? nA : cA + (size_t)(t + 2) * kstep; const char* b2 = last ? nB : cB + (size_t)(t + 2) * kstep;
;             const char* a3 = a2 + kstep; const char* b3 = b2 + kstep;
;             PG8_LDB(B0, 0, 0); PG8_LDB(B1, 0, 1); PG8_SCHED; PG8_LDA(At, 0, 0); PG8_STAGE(PG8_SA(1, 1), a1 + hstepA, voffA);
;             PG8_WAIT_V(8); PG8_WAIT_L(0); PG8_BAR; PG8_MMA(0, 0, At, B0); PG8_MMA(0, 1, At, B1); PG8_BAR; PG8_SCHED;
;             PG8_LDA(At, 0, 1); PG8_STAGE(PG8_SB(0, 0), b2, voffB); PG8_STAGE(PG8_SB(0, 1), b2 + hstepB, voffB); PG8_STAGE(PG8_SA(0, 0), a2, voffA);
.LBB0_1537:
	s_add_u32 s33, s8, s44
	s_addc_u32 s45, s9, 0
	s_add_u32 s48, s33, 0x100
	s_addc_u32 s49, s45, 0
	s_and_b64 s[46:47], s[10:11], exec
	s_cselect_b32 s47, s41, s49
	s_cselect_b32 s46, s40, s48
	s_add_u32 s44, s6, s44
	s_addc_u32 s48, s7, 0
	s_add_u32 s44, s44, 0x100
	s_addc_u32 s48, s48, 0
	s_and_b64 s[10:11], s[10:11], exec
	s_cselect_b32 s49, s43, s48
	s_cselect_b32 s48, s42, s44
	s_add_u32 s54, s33, 0xb0080
	ds_read_b128 v[130:133], v166
	ds_read_b128 v[134:137], v166 offset:1024
	ds_read_b128 v[150:153], v166 offset:2048
	ds_read_b128 v[154:157], v166 offset:3072
	ds_read_b128 v[158:161], v167
	ds_read_b128 v[172:175], v167 offset:1024
	ds_read_b128 v[176:179], v167 offset:2048
	ds_read_b128 v[180:183], v167 offset:3072
	s_addc_u32 s55, s45, 0
	s_add_i32 s63, s87, s70
	s_add_i32 m0, s73, 0xc000
	s_add_i32 s64, s73, 0xe000
	s_add_i32 s74, s63, 0x2000
	s_add_u32 s52, s48, 0xb0000
	s_addc_u32 s53, s49, 0
	s_add_i32 s62, s88, s70
	s_add_i32 s75, s62, 0x2000
	s_add_i32 s97, 0, 0x18000
	s_add_i32 s33, 0, 0x1c000
	s_add_u32 s44, s46, 0xb0000
	s_addc_u32 s45, s47, 0
	s_add_i32 s96, s97, s70
	s_add_i32 s94, s96, 0x2000
	s_add_u32 s10, s48, 0xb0080
	s_addc_u32 s11, s49, 0
	s_add_i32 s95, s33, s70
	s_add_i32 s93, s95, 0x2000
	v_lshl_add_u64 v[162:163], s[54:55], 0, v[138:139]
	ds_read_b128 v[184:187], v168
	ds_read_b128 v[188:191], v168 offset:1024
	ds_read_b128 v[192:195], v168 offset:2048
	ds_read_b128 v[196:199], v168 offset:3072
	ds_read_b128 v[200:203], v168 offset:4096
	ds_read_b128 v[204:207], v168 offset:5120
	ds_read_b128 v[208:211], v168 offset:6144
	ds_read_b128 v[212:215], v168 offset:7168
	global_load_lds_dwordx4 v[162:163], off
	v_lshl_add_u64 v[162:163], s[54:55], 0, v[142:143]
	s_mov_b32 m0, s64
	s_nop 0
	global_load_lds_dwordx4 v[162:163], off
	s_waitcnt vmcnt(8)
	s_waitcnt lgkmcnt(0)
	s_barrier
	s_setprio 0
	s_waitcnt lgkmcnt(0)
	v_mfma_f32_16x16x32_bf16 v[126:129], v[130:133], v[184:187], v[126:129]
	v_mfma_f32_16x16x32_bf16 v[122:125], v[150:153], v[184:187], v[122:125]
	v_mfma_f32_16x16x32_bf16 v[110:113], v[130:133], v[192:195], v[110:113]
	v_mfma_f32_16x16x32_bf16 v[106:109], v[150:153], v[192:195], v[106:109]
	v_mfma_f32_16x16x32_bf16 v[94:97], v[130:133], v[200:203], v[94:97]
	v_mfma_f32_16x16x32_bf16 v[90:93], v[150:153], v[200:203], v[90:93]
	v_mfma_f32_16x16x32_bf16 v[78:81], v[130:133], v[208:211], v[78:81]
	v_mfma_f32_16x16x32_bf16 v[74:77], v[150:153], v[208:211], v[74:77]
	v_mfma_f32_16x16x32_bf16 v[126:129], v[134:137], v[188:191], v[126:129]
	v_mfma_f32_16x16x32_bf16 v[122:125], v[154:157], v[188:191], v[122:125]
	v_mfma_f32_16x16x32_bf16 v[110:113], v[134:137], v[196:199], v[110:113]
	v_mfma_f32_16x16x32_bf16 v[106:109], v[154:157], v[196:199], v[106:109]
	v_mfma_f32_16x16x32_bf16 v[94:97], v[134:137], v[204:207], v[94:97]
	v_mfma_f32_16x16x32_bf16 v[90:93], v[154:157], v[204:207], v[90:93]
	v_mfma_f32_16x16x32_bf16 v[78:81], v[134:137], v[212:215], v[78:81]
	v_mfma_f32_16x16x32_bf16 v[74:77], v[154:157], v[212:215], v[74:77]
	s_setprio 2
	s_setprio 0
	v_mfma_f32_16x16x32_bf16 v[118:121], v[158:161], v[184:187], v[118:121]
	v_mfma_f32_16x16x32_bf16 v[114:117], v[176:179], v[184:187], v[114:117]
	v_mfma_f32_16x16x32_bf16 v[102:105], v[158:161], v[192:195], v[102:105]
	v_mfma_f32_16x16x32_bf16 v[98:101], v[176:179], v[192:195], v[98:101]
	v_mfma_f32_16x16x32_bf16 v[86:89], v[158:161], v[200:203], v[86:89]
	v_mfma_f32_16x16x32_bf16 v[82:85], v[176:179], v[200:203], v[82:85]
	v_mfma_f32_16x16x32_bf16 v[70:73], v[158:161], v[208:211], v[70:73]
	v_mfma_f32_16x16x32_bf16 v[66:69], v[176:179], v[208:211], v[66:69]
	v_mfma_f32_16x16x32_bf16 v[118:121], v[172:175], v[188:191], v[118:121]
	v_mfma_f32_16x16x32_bf16 v[114:117], v[180:183], v[188:191], v[114:117]
	v_mfma_f32_16x16x32_bf16 v[102:105], v[172:175], v[196:199], v[102:105]
	v_mfma_f32_16x16x32_bf16 v[98:101], v[180:183], v[196:199], v[98:101]
	v_mfma_f32_16x16x32_bf16 v[86:89], v[172:175], v[204:207], v[86:89]
	v_mfma_f32_16x16x32_bf16 v[82:85], v[180:183], v[204:207], v[82:85]
	v_mfma_f32_16x16x32_bf16 v[70:73], v[172:175], v[212:215], v[70:73]
	v_mfma_f32_16x16x32_bf16 v[66:69], v[180:183], v[212:215], v[66:69]
	s_setprio 2
	s_barrier
	s_mov_b32 m0, s63
	v_lshl_add_u64 v[162:163], s[48:49], 0, v[140:141]
	ds_read_b128 v[184:187], v168 offset:16384
	ds_read_b128 v[188:191], v168 offset:17408
	ds_read_b128 v[192:195], v168 offset:18432
	ds_read_b128 v[196:199], v168 offset:19456
	ds_read_b128 v[200:203], v168 offset:20480
	ds_read_b128 v[204:207], v168 offset:21504
	ds_read_b128 v[208:211], v168 offset:22528
	ds_read_b128 v[212:215], v168 offset:23552
	global_load_lds_dwordx4 v[162:163], off
	v_lshl_add_u64 v[216:217], s[48:49], 0, v[144:145]
	s_mov_b32 m0, s74
	v_lshl_add_u64 v[218:219], s[52:53], 0, v[140:141]
	global_load_lds_dwordx4 v[216:217], off
	s_mov_b32 m0, s62
	v_lshl_add_u64 v[220:221], s[46:47], 0, v[142:143]
	global_load_lds_dwordx4 v[218:219], off
	v_lshl_add_u64 v[218:219], s[52:53], 0, v[144:145]
	s_mov_b32 m0, s75
	s_nop 0
	global_load_lds_dwordx4 v[218:219], off
	v_lshl_add_u64 v[218:219], s[46:47], 0, v[138:139]
	s_mov_b32 m0, s73
	s_nop 0
	global_load_lds_dwordx4 v[218:219], off
	s_mov_b32 m0, s79
	s_nop 0
	global_load_lds_dwordx4 v[220:221], off
	s_waitcnt vmcnt(8)
	s_waitcnt lgkmcnt(0)
	s_barrier
; #define PG8_STAGE(bufoff, gbase, voff) do { _Pragma("unroll") for (int _i = 0; _i < 2; ++_i) \
;         __builtin_amdgcn_global_load_lds((const unsigned*)((const char*)(gbase) + (voff)[_i]), (LAS unsigned*)(lds + (bufoff) + ldsw + _i * 8192), 16, 0, 0); } while (0)
; #define PG8_LDA(dst, b, h) do { _Pragma("unroll") for (int m = 0; m < 4; ++m) _Pragma("unroll") for (int k = 0; k < 2; ++k) dst[m][k] = *(const LAS bf16x8*)(lds + PG8_SA(b, h) + aoff + m * 2048 + k * 1024); } while (0)
; #define PG8_LDB(dst, b, h) do { _Pragma("unroll") for (int n = 0; n < 2; ++n) _Pragma("unroll") for (int k = 0; k < 2; ++k) dst[n][k] = *(const LAS bf16x8*)(lds + PG8_SB(b, h) + boff + n * 2048 + k * 1024); } while (0)
; #define PG8_MMA(ai, bj, At, Bt) do { __builtin_amdgcn_s_setprio(1); _Pragma("unroll") for (int m = 0; m < 4; ++m) _Pragma("unroll") for (int n = 0; n < 2; ++n) _Pragma("unroll") for (int k = 0; k < 2; ++k) \
;         acc[ai][bj][m][n] = __builtin_amdgcn_mfma_f32_16x16x32_bf16(Bt[n][k], At[m][k], acc[ai][bj][m][n], 0, 0, 0); __builtin_amdgcn_s_setprio(0); } while (0)
; #define PG8_WAIT_V(n) asm volatile("s_waitcnt vmcnt(" #n ")" ::: "memory")
; #define PG8_WAIT_L(n) asm volatile("s_waitcnt lgkmcnt(" #n ")" ::: "memory")
; #define PG8_BAR __builtin_amdgcn_s_barrier()
; #define PG8_SCHED __builtin_amdgcn_sched_barrier(0)
; template <class Epi>
; __device__ __forceinline__ void gemm_phase(LAS unsigned char* lds, const Gemm g, int G, int c, const Epi& E) {
;     ...
;             PG8_WAIT_V(8); PG8_WAIT_L(0); PG8_BAR; PG8_MMA(1, 0, At, B0); PG8_MMA(1, 1, At, B1); PG8_BAR; PG8_SCHED;
;             PG8_LDB(B0, 1, 0); PG8_LDB(B1, 1, 1); PG8_SCHED; PG8_LDA(At, 1, 0); PG8_STAGE(PG8_SA(0, 1), a2 + hstepA, voffA);
;             PG8_WAIT_V(8); PG8_WAIT_L(0); PG8_BAR; PG8_MMA(0, 0, At, B0); PG8_MMA(0, 1, At, B1); PG8_BAR; PG8_SCHED;
	s_setprio 0
	s_waitcnt lgkmcnt(0)
	v_mfma_f32_16x16x32_bf16 v[62:65], v[130:133], v[184:187], v[62:65]
	v_mfma_f32_16x16x32_bf16 v[58:61], v[150:153], v[184:187], v[58:61]
	v_mfma_f32_16x16x32_bf16 v[46:49], v[130:133], v[192:195], v[46:49]
	v_mfma_f32_16x16x32_bf16 v[42:45], v[150:153], v[192:195], v[42:45]
	v_mfma_f32_16x16x32_bf16 v[30:33], v[130:133], v[200:203], v[30:33]
	v_mfma_f32_16x16x32_bf16 v[26:29], v[150:153], v[200:203], v[26:29]
	v_mfma_f32_16x16x32_bf16 v[14:17], v[130:133], v[208:211], v[14:17]
	v_mfma_f32_16x16x32_bf16 v[10:13], v[150:153], v[208:211], v[10:13]
	v_mfma_f32_16x16x32_bf16 v[62:65], v[134:137], v[188:191], v[62:65]
	v_mfma_f32_16x16x32_bf16 v[58:61], v[154:157], v[188:191], v[58:61]
	v_mfma_f32_16x16x32_bf16 v[46:49], v[134:137], v[196:199], v[46:49]
	v_mfma_f32_16x16x32_bf16 v[42:45], v[154:157], v[196:199], v[42:45]
	v_mfma_f32_16x16x32_bf16 v[30:33], v[134:137], v[204:207], v[30:33]
	v_mfma_f32_16x16x32_bf16 v[26:29], v[154:157], v[204:207], v[26:29]
	v_mfma_f32_16x16x32_bf16 v[14:17], v[134:137], v[212:215], v[14:17]
	v_mfma_f32_16x16x32_bf16 v[10:13], v[154:157], v[212:215], v[10:13]
	s_setprio 2
	s_setprio 0
	v_mfma_f32_16x16x32_bf16 v[54:57], v[158:161], v[184:187], v[54:57]
	v_mfma_f32_16x16x32_bf16 v[50:53], v[176:179], v[184:187], v[50:53]
	v_mfma_f32_16x16x32_bf16 v[38:41], v[158:161], v[192:195], v[38:41]
	v_mfma_f32_16x16x32_bf16 v[34:37], v[176:179], v[192:195], v[34:37]
	v_mfma_f32_16x16x32_bf16 v[22:25], v[158:161], v[200:203], v[22:25]
	v_mfma_f32_16x16x32_bf16 v[18:21], v[176:179], v[200:203], v[18:21]
	v_mfma_f32_16x16x32_bf16 v[6:9], v[158:161], v[208:211], v[6:9]
	v_mfma_f32_16x16x32_bf16 v[2:5], v[176:179], v[208:211], v[2:5]
	v_mfma_f32_16x16x32_bf16 v[54:57], v[172:175], v[188:191], v[54:57]
	v_mfma_f32_16x16x32_bf16 v[50:53], v[180:183], v[188:191], v[50:53]
	v_mfma_f32_16x16x32_bf16 v[38:41], v[172:175], v[196:199], v[38:41]
	v_mfma_f32_16x16x32_bf16 v[34:37], v[180:183], v[196:199], v[34:37]
	v_mfma_f32_16x16x32_bf16 v[22:25], v[172:175], v[204:207], v[22:25]
	v_mfma_f32_16x16x32_bf16 v[18:21], v[180:183], v[204:207], v[18:21]
	v_mfma_f32_16x16x32_bf16 v[6:9], v[172:175], v[212:215], v[6:9]
	v_mfma_f32_16x16x32_bf16 v[2:5], v[180:183], v[212:215], v[2:5]
	s_setprio 2
	s_barrier
	v_add_u32_e32 v154, s97, v165
	v_add_u32_e32 v180, s33, v165
	ds_read_b128 v[130:133], v154
	ds_read_b128 v[134:137], v154 offset:1024
	ds_read_b128 v[150:153], v154 offset:2048
	ds_read_b128 v[154:157], v154 offset:3072
	ds_read_b128 v[158:161], v180
	ds_read_b128 v[172:175], v180 offset:1024
	ds_read_b128 v[176:179], v180 offset:2048
	ds_read_b128 v[180:183], v180 offset:3072
	s_mov_b32 m0, s80
	v_lshl_add_u64 v[222:223], s[44:45], 0, v[138:139]
	ds_read_b128 v[184:187], v168 offset:32768
	ds_read_b128 v[188:191], v168 offset:33792
	ds_read_b128 v[192:195], v168 offset:34816
	ds_read_b128 v[196:199], v168 offset:35840
	ds_read_b128 v[200:203], v168 offset:36864
	ds_read_b128 v[204:207], v168 offset:37888
	ds_read_b128 v[208:211], v168 offset:38912
	ds_read_b128 v[212:215], v168 offset:39936
	global_load_lds_dwordx4 v[222:223], off
	v_lshl_add_u64 v[222:223], s[44:45], 0, v[142:143]
	s_mov_b32 m0, s81
	s_nop 0
	global_load_lds_dwordx4 v[222:223], off
	s_waitcnt vmcnt(8)
	s_waitcnt lgkmcnt(0)
	s_barrier
	s_setprio 0
	s_waitcnt lgkmcnt(0)
	v_mfma_f32_16x16x32_bf16 v[126:129], v[130:133], v[184:187], v[126:129]
	v_mfma_f32_16x16x32_bf16 v[122:125], v[150:153], v[184:187], v[122:125]
	v_mfma_f32_16x16x32_bf16 v[110:113], v[130:133], v[192:195], v[110:113]
	v_mfma_f32_16x16x32_bf16 v[106:109], v[150:153], v[192:195], v[106:109]
	v_mfma_f32_16x16x32_bf16 v[94:97], v[130:133], v[200:203], v[94:97]
	v_mfma_f32_16x16x32_bf16 v[90:93], v[150:153], v[200:203], v[90:93]
	v_mfma_f32_16x16x32_bf16 v[78:81], v[130:133], v[208:211], v[78:81]
	v_mfma_f32_16x16x32_bf16 v[74:77], v[150:153], v[208:211], v[74:77]
	v_mfma_f32_16x16x32_bf16 v[126:129], v[134:137], v[188:191], v[126:129]
	v_mfma_f32_16x16x32_bf16 v[122:125], v[154:157], v[188:191], v[122:125]
	v_mfma_f32_16x16x32_bf16 v[110:113], v[134:137], v[196:199], v[110:113]
	v_mfma_f32_16x16x32_bf16 v[106:109], v[154:157], v[196:199], v[106:109]
	v_mfma_f32_16x16x32_bf16 v[94:97], v[134:137], v[204:207], v[94:97]
	v_mfma_f32_16x16x32_bf16 v[90:93], v[154:157], v[204:207], v[90:93]
	v_mfma_f32_16x16x32_bf16 v[78:81], v[134:137], v[212:215], v[78:81]
	v_mfma_f32_16x16x32_bf16 v[74:77], v[154:157], v[212:215], v[74:77]
	s_setprio 2
	s_setprio 0
	v_mfma_f32_16x16x32_bf16 v[118:121], v[158:161], v[184:187], v[118:121]
	v_mfma_f32_16x16x32_bf16 v[114:117], v[176:179], v[184:187], v[114:117]
	v_mfma_f32_16x16x32_bf16 v[102:105], v[158:161], v[192:195], v[102:105]
	v_mfma_f32_16x16x32_bf16 v[98:101], v[176:179], v[192:195], v[98:101]
	v_mfma_f32_16x16x32_bf16 v[86:89], v[158:161], v[200:203], v[86:89]
	v_mfma_f32_16x16x32_bf16 v[82:85], v[176:179], v[200:203], v[82:85]
	v_mfma_f32_16x16x32_bf16 v[70:73], v[158:161], v[208:211], v[70:73]
	v_mfma_f32_16x16x32_bf16 v[66:69], v[176:179], v[208:211], v[66:69]
	v_mfma_f32_16x16x32_bf16 v[118:121], v[172:175], v[188:191], v[118:121]
	v_mfma_f32_16x16x32_bf16 v[114:117], v[180:183], v[188:191], v[114:117]
	v_mfma_f32_16x16x32_bf16 v[102:105], v[172:175], v[196:199], v[102:105]
	v_mfma_f32_16x16x32_bf16 v[98:101], v[180:183], v[196:199], v[98:101]
	v_mfma_f32_16x16x32_bf16 v[86:89], v[172:175], v[204:207], v[86:89]
	v_mfma_f32_16x16x32_bf16 v[82:85], v[180:183], v[204:207], v[82:85]
	v_mfma_f32_16x16x32_bf16 v[70:73], v[172:175], v[212:215], v[70:73]
	v_mfma_f32_16x16x32_bf16 v[66:69], v[180:183], v[212:215], v[66:69]
	s_setprio 2
	s_barrier
; #define PG8_STAGE(bufoff, gbase, voff) do { _Pragma("unroll") for (int _i = 0; _i < 2; ++_i) \
;         __builtin_amdgcn_global_load_lds((const unsigned*)((const char*)(gbase) + (voff)[_i]), (LAS unsigned*)(lds + (bufoff) + ldsw + _i * 8192), 16, 0, 0); } while (0)
; #define PG8_LDA(dst, b, h) do { _Pragma("unroll") for (int m = 0; m < 4; ++m) _Pragma("unroll") for (int k = 0; k < 2; ++k) dst[m][k] = *(const LAS bf16x8*)(lds + PG8_SA(b, h) + aoff + m * 2048 + k * 1024); } while (0)
; #define PG8_MMA(ai, bj, At, Bt) do { __builtin_amdgcn_s_setprio(1); _Pragma("unroll") for (int m = 0; m < 4; ++m) _Pragma("unroll") for (int n = 0; n < 2; ++n) _Pragma("unroll") for (int k = 0; k < 2; ++k) \
;         acc[ai][bj][m][n] = __builtin_amdgcn_mfma_f32_16x16x32_bf16(Bt[n][k], At[m][k], acc[ai][bj][m][n], 0, 0, 0); __builtin_amdgcn_s_setprio(0); } while (0)
; #define PG8_WAIT_V(n) asm volatile("s_waitcnt vmcnt(" #n ")" ::: "memory")
; #define PG8_WAIT_L(n) asm volatile("s_waitcnt lgkmcnt(" #n ")" ::: "memory")
; #define PG8_BAR __builtin_amdgcn_s_barrier()
; #define PG8_SCHED __builtin_amdgcn_sched_barrier(0)
; template <class Epi>
; __device__ __forceinline__ void gemm_phase(LAS unsigned char* lds, const Gemm g, int G, int c, const Epi& E) {
;     ...
;             PG8_LDA(At, 1, 1); PG8_STAGE(PG8_SB(1, 0), b3, voffB); PG8_STAGE(PG8_SB(1, 1), b3 + hstepB, voffB); PG8_STAGE(PG8_SA(1, 0), a3, voffA);
;             PG8_WAIT_V(8); PG8_WAIT_L(0); PG8_BAR; PG8_MMA(1, 0, At, B0); PG8_MMA(1, 1, At, B1); PG8_BAR; PG8_SCHED;
;         }
;         if (wr == 0) PG8_BAR;
	s_mov_b32 m0, s96
	v_lshl_add_u64 v[162:163], v[162:163], 0, s[22:23]
	ds_read_b128 v[184:187], v168 offset:49152
	ds_read_b128 v[188:191], v168 offset:50176
	ds_read_b128 v[192:195], v168 offset:51200
	ds_read_b128 v[196:199], v168 offset:52224
	ds_read_b128 v[200:203], v168 offset:53248
	ds_read_b128 v[204:207], v168 offset:54272
	ds_read_b128 v[208:211], v168 offset:55296
	ds_read_b128 v[212:215], v168 offset:56320
	global_load_lds_dwordx4 v[162:163], off
	v_lshl_add_u64 v[162:163], v[216:217], 0, s[22:23]
	s_mov_b32 m0, s94
	s_nop 0
	global_load_lds_dwordx4 v[162:163], off
	v_lshl_add_u64 v[162:163], s[10:11], 0, v[140:141]
	s_mov_b32 m0, s95
	s_nop 0
	global_load_lds_dwordx4 v[162:163], off
	v_lshl_add_u64 v[162:163], s[10:11], 0, v[144:145]
	s_mov_b32 m0, s93
	s_nop 0
	global_load_lds_dwordx4 v[162:163], off
	v_lshl_add_u64 v[162:163], v[218:219], 0, s[22:23]
	s_mov_b32 m0, s85
	s_nop 0
	global_load_lds_dwordx4 v[162:163], off
	v_lshl_add_u64 v[162:163], v[220:221], 0, s[22:23]
	s_mov_b32 m0, s86
	s_nop 0
	global_load_lds_dwordx4 v[162:163], off
	s_waitcnt vmcnt(8)
	s_waitcnt lgkmcnt(0)
	s_barrier
	s_setprio 0
	s_waitcnt lgkmcnt(0)
	v_mfma_f32_16x16x32_bf16 v[62:65], v[130:133], v[184:187], v[62:65]
	v_mfma_f32_16x16x32_bf16 v[58:61], v[150:153], v[184:187], v[58:61]
	v_mfma_f32_16x16x32_bf16 v[46:49], v[130:133], v[192:195], v[46:49]
	v_mfma_f32_16x16x32_bf16 v[42:45], v[150:153], v[192:195], v[42:45]
	v_mfma_f32_16x16x32_bf16 v[30:33], v[130:133], v[200:203], v[30:33]
	v_mfma_f32_16x16x32_bf16 v[26:29], v[150:153], v[200:203], v[26:29]
	v_mfma_f32_16x16x32_bf16 v[14:17], v[130:133], v[208:211], v[14:17]
	v_mfma_f32_16x16x32_bf16 v[10:13], v[150:153], v[208:211], v[10:13]
	v_mfma_f32_16x16x32_bf16 v[62:65], v[134:137], v[188:191], v[62:65]
	v_mfma_f32_16x16x32_bf16 v[58:61], v[154:157], v[188:191], v[58:61]
	v_mfma_f32_16x16x32_bf16 v[46:49], v[134:137], v[196:199], v[46:49]
	v_mfma_f32_16x16x32_bf16 v[42:45], v[154:157], v[196:199], v[42:45]
	v_mfma_f32_16x16x32_bf16 v[30:33], v[134:137], v[204:207], v[30:33]
	v_mfma_f32_16x16x32_bf16 v[26:29], v[154:157], v[204:207], v[26:29]
	v_mfma_f32_16x16x32_bf16 v[14:17], v[134:137], v[212:215], v[14:17]
	v_mfma_f32_16x16x32_bf16 v[10:13], v[154:157], v[212:215], v[10:13]
	s_setprio 2
	s_setprio 0
	v_mfma_f32_16x16x32_bf16 v[54:57], v[158:161], v[184:187], v[54:57]
	v_mfma_f32_16x16x32_bf16 v[50:53], v[176:179], v[184:187], v[50:53]
	v_mfma_f32_16x16x32_bf16 v[38:41], v[158:161], v[192:195], v[38:41]
	v_mfma_f32_16x16x32_bf16 v[34:37], v[176:179], v[192:195], v[34:37]
	v_mfma_f32_16x16x32_bf16 v[22:25], v[158:161], v[200:203], v[22:25]
	v_mfma_f32_16x16x32_bf16 v[18:21], v[176:179], v[200:203], v[18:21]
	v_mfma_f32_16x16x32_bf16 v[6:9], v[158:161], v[208:211], v[6:9]
	v_mfma_f32_16x16x32_bf16 v[2:5], v[176:179], v[208:211], v[2:5]
	v_mfma_f32_16x16x32_bf16 v[54:57], v[172:175], v[188:191], v[54:57]
	v_mfma_f32_16x16x32_bf16 v[50:53], v[180:183], v[188:191], v[50:53]
	v_mfma_f32_16x16x32_bf16 v[38:41], v[172:175], v[196:199], v[38:41]
	v_mfma_f32_16x16x32_bf16 v[34:37], v[180:183], v[196:199], v[34:37]
	v_mfma_f32_16x16x32_bf16 v[22:25], v[172:175], v[204:207], v[22:25]
	v_mfma_f32_16x16x32_bf16 v[18:21], v[180:183], v[204:207], v[18:21]
	v_mfma_f32_16x16x32_bf16 v[6:9], v[172:175], v[212:215], v[6:9]
	v_mfma_f32_16x16x32_bf16 v[2:5], v[180:183], v[212:215], v[2:5]
	s_setprio 2
	s_barrier
	s_movk_i32 s44, 0x100
	s_andn2_b64 vcc, exec, s[4:5]
	s_mov_b64 s[10:11], -1
	s_mov_b64 s[4:5], 0
	s_cbranch_vccz .LBB0_1537
	s_and_b64 vcc, exec, s[24:25]
	s_cbranch_vccz .LBB0_1540
	s_barrier

; #define PG8_STAGE(bufoff, gbase, voff) do { _Pragma("unroll") for (int _i = 0; _i < 2; ++_i) \
;         __builtin_amdgcn_global_load_lds((const unsigned*)((const char*)(gbase) + (voff)[_i]), (LAS unsigned*)(lds + (bufoff) + ldsw + _i * 8192), 16, 0, 0); } while (0)
; #define PG8_LDA(dst, b, h) do { _Pragma("unroll") for (int m = 0; m < 4; ++m) _Pragma("unroll") for (int k = 0; k < 2; ++k) dst[m][k] = *(const LAS bf16x8*)(lds + PG8_SA(b, h) + aoff + m * 2048 + k * 1024); } while (0)
; #define PG8_LDB(dst, b, h) do { _Pragma("unroll") for (int n = 0; n < 2; ++n) _Pragma("unroll") for (int k = 0; k < 2; ++k) dst[n][k] = *(const LAS bf16x8*)(lds + PG8_SB(b, h) + boff + n * 2048 + k * 1024); } while (0)
; #define PG8_MMA(ai, bj, At, Bt) do { __builtin_amdgcn_s_setprio(1); _Pragma("unroll") for (int m = 0; m < 4; ++m) _Pragma("unroll") for (int n = 0; n < 2; ++n) _Pragma("unroll") for (int k = 0; k < 2; ++k) \
;         acc[ai][bj][m][n] = __builtin_amdgcn_mfma_f32_16x16x32_bf16(Bt[n][k], At[m][k], acc[ai][bj][m][n], 0, 0, 0); __builtin_amdgcn_s_setprio(0); } while (0)
; #define PG8_WAIT_V(n) asm volatile("s_waitcnt vmcnt(" #n ")" ::: "memory")
; #define PG8_WAIT_L(n) asm volatile("s_waitcnt lgkmcnt(" #n ")" ::: "memory")
; #define PG8_BAR __builtin_amdgcn_s_barrier()
; #define PG8_SCHED __builtin_amdgcn_sched_barrier(0)
; template <class Epi>
; __device__ __forceinline__ void gemm_phase(LAS unsigned char* lds, const Gemm g, int G, int c, const Epi& E) {
;     ...
;         for (int t = 0; t < nt; t += 2) {
;             const bool last = (t == nt - 2);
;             const char* a1 = cA + (size_t)(t + 1) * kstep;
;             const char* a2 = last ? nA : cA + (size_t)(t + 2) * kstep; const char* b2 = last ? nB : cB + (size_t)(t + 2) * kstep;
;             const char* a3 = a2 + kstep; const char* b3 = b2 + kstep;
;             PG8_LDB(B0, 0, 0); PG8_LDB(B1, 0, 1); PG8_SCHED; PG8_LDA(At, 0, 0); PG8_STAGE(PG8_SA(1, 1), a1 + hstepA, voffA);
;             PG8_WAIT_V(8); PG8_WAIT_L(0); PG8_BAR; PG8_MMA(0, 0, At, B0); PG8_MMA(0, 1, At, B1); PG8_BAR; PG8_SCHED;
;             PG8_LDA(At, 0, 1); PG8_STAGE(PG8_SB(0, 0), b2, voffB); PG8_STAGE(PG8_SB(0, 1), b2 + hstepB, voffB); PG8_STAGE(PG8_SA(0, 0), a2, voffA);
.LBB0_1653:
	s_add_u32 s33, s8, s48
	s_addc_u32 s49, s9, 0
	s_add_u32 s54, s33, 0x100
	s_addc_u32 s55, s49, 0
	s_and_b64 s[52:53], s[46:47], exec
	s_cselect_b32 s53, s41, s55
	s_cselect_b32 s52, s40, s54
	s_add_u32 s48, s6, s48
	s_addc_u32 s54, s7, 0
	s_add_u32 s48, s48, 0x100
	s_addc_u32 s54, s54, 0
	s_and_b64 s[46:47], s[46:47], exec
	s_cselect_b32 s55, s43, s54
	s_cselect_b32 s54, s42, s48
	s_add_u32 s58, s33, 0xb0080
	ds_read_b128 v[142:145], v166
	ds_read_b128 v[146:149], v166 offset:1024
	ds_read_b128 v[150:153], v166 offset:2048
	ds_read_b128 v[154:157], v166 offset:3072
	ds_read_b128 v[158:161], v167
	ds_read_b128 v[170:173], v167 offset:1024
	ds_read_b128 v[174:177], v167 offset:2048
	ds_read_b128 v[178:181], v167 offset:3072
	s_addc_u32 s59, s49, 0
	s_add_i32 s63, s80, s23
	s_add_i32 m0, s68, 0xc000
	s_add_i32 s64, s68, 0xe000
	s_add_i32 s74, s63, 0x2000
	s_add_u32 s56, s54, 0xb0000
	s_addc_u32 s57, s55, 0
	s_add_i32 s62, s81, s23
	s_add_i32 s75, s62, 0x2000
	s_add_i32 s93, 0, 0x18000
	s_add_i32 s33, 0, 0x1c000
	s_add_u32 s48, s52, 0xb0000
	s_addc_u32 s49, s53, 0
	s_add_i32 s92, s93, s23
	s_add_i32 s90, s92, 0x2000
	s_add_u32 s46, s54, 0xb0080
	s_addc_u32 s47, s55, 0
	s_add_i32 s91, s33, s23
	s_add_i32 s89, s91, 0x2000
	v_lshl_add_u64 v[162:163], s[58:59], 0, v[136:137]
	ds_read_b128 v[182:185], v168
	ds_read_b128 v[186:189], v168 offset:1024
	ds_read_b128 v[190:193], v168 offset:2048
	ds_read_b128 v[194:197], v168 offset:3072
	ds_read_b128 v[198:201], v168 offset:4096
	ds_read_b128 v[202:205], v168 offset:5120
	ds_read_b128 v[206:209], v168 offset:6144
	ds_read_b128 v[210:213], v168 offset:7168
	global_load_lds_dwordx4 v[162:163], off
	v_lshl_add_u64 v[162:163], s[58:59], 0, v[132:133]
	s_mov_b32 m0, s64
	s_nop 0
	global_load_lds_dwordx4 v[162:163], off
	s_waitcnt vmcnt(8)
	s_waitcnt lgkmcnt(0)
	s_barrier
	s_setprio 0
	s_waitcnt lgkmcnt(0)
	v_mfma_f32_16x16x32_bf16 v[126:129], v[142:145], v[182:185], v[126:129]
	v_mfma_f32_16x16x32_bf16 v[122:125], v[150:153], v[182:185], v[122:125]
	v_mfma_f32_16x16x32_bf16 v[110:113], v[142:145], v[190:193], v[110:113]
	v_mfma_f32_16x16x32_bf16 v[106:109], v[150:153], v[190:193], v[106:109]
	v_mfma_f32_16x16x32_bf16 v[94:97], v[142:145], v[198:201], v[94:97]
	v_mfma_f32_16x16x32_bf16 v[90:93], v[150:153], v[198:201], v[90:93]
	v_mfma_f32_16x16x32_bf16 v[78:81], v[142:145], v[206:209], v[78:81]
	v_mfma_f32_16x16x32_bf16 v[74:77], v[150:153], v[206:209], v[74:77]
	v_mfma_f32_16x16x32_bf16 v[126:129], v[146:149], v[186:189], v[126:129]
	v_mfma_f32_16x16x32_bf16 v[122:125], v[154:157], v[186:189], v[122:125]
	v_mfma_f32_16x16x32_bf16 v[110:113], v[146:149], v[194:197], v[110:113]
	v_mfma_f32_16x16x32_bf16 v[106:109], v[154:157], v[194:197], v[106:109]
	v_mfma_f32_16x16x32_bf16 v[94:97], v[146:149], v[202:205], v[94:97]
	v_mfma_f32_16x16x32_bf16 v[90:93], v[154:157], v[202:205], v[90:93]
	v_mfma_f32_16x16x32_bf16 v[78:81], v[146:149], v[210:213], v[78:81]
	v_mfma_f32_16x16x32_bf16 v[74:77], v[154:157], v[210:213], v[74:77]
	s_setprio 2
	s_setprio 0
	v_mfma_f32_16x16x32_bf16 v[118:121], v[158:161], v[182:185], v[118:121]
	v_mfma_f32_16x16x32_bf16 v[114:117], v[174:177], v[182:185], v[114:117]
	v_mfma_f32_16x16x32_bf16 v[102:105], v[158:161], v[190:193], v[102:105]
	v_mfma_f32_16x16x32_bf16 v[98:101], v[174:177], v[190:193], v[98:101]
	v_mfma_f32_16x16x32_bf16 v[86:89], v[158:161], v[198:201], v[86:89]
	v_mfma_f32_16x16x32_bf16 v[82:85], v[174:177], v[198:201], v[82:85]
	v_mfma_f32_16x16x32_bf16 v[70:73], v[158:161], v[206:209], v[70:73]
	v_mfma_f32_16x16x32_bf16 v[66:69], v[174:177], v[206:209], v[66:69]
	v_mfma_f32_16x16x32_bf16 v[118:121], v[170:173], v[186:189], v[118:121]
	v_mfma_f32_16x16x32_bf16 v[114:117], v[178:181], v[186:189], v[114:117]
	v_mfma_f32_16x16x32_bf16 v[102:105], v[170:173], v[194:197], v[102:105]
	v_mfma_f32_16x16x32_bf16 v[98:101], v[178:181], v[194:197], v[98:101]
	v_mfma_f32_16x16x32_bf16 v[86:89], v[170:173], v[202:205], v[86:89]
	v_mfma_f32_16x16x32_bf16 v[82:85], v[178:181], v[202:205], v[82:85]
	v_mfma_f32_16x16x32_bf16 v[70:73], v[170:173], v[210:213], v[70:73]
	v_mfma_f32_16x16x32_bf16 v[66:69], v[178:181], v[210:213], v[66:69]
	s_setprio 2
	s_barrier
	s_mov_b32 m0, s63
	v_lshl_add_u64 v[162:163], s[54:55], 0, v[134:135]
	ds_read_b128 v[182:185], v168 offset:16384
	ds_read_b128 v[186:189], v168 offset:17408
	ds_read_b128 v[190:193], v168 offset:18432
	ds_read_b128 v[194:197], v168 offset:19456
	ds_read_b128 v[198:201], v168 offset:20480
	ds_read_b128 v[202:205], v168 offset:21504
	ds_read_b128 v[206:209], v168 offset:22528
	ds_read_b128 v[210:213], v168 offset:23552
	global_load_lds_dwordx4 v[162:163], off
	v_lshl_add_u64 v[214:215], s[54:55], 0, v[130:131]
	s_mov_b32 m0, s74
	v_lshl_add_u64 v[216:217], s[56:57], 0, v[134:135]
	global_load_lds_dwordx4 v[214:215], off
	s_mov_b32 m0, s62
	v_lshl_add_u64 v[218:219], s[52:53], 0, v[132:133]
	global_load_lds_dwordx4 v[216:217], off
	v_lshl_add_u64 v[216:217], s[56:57], 0, v[130:131]
	s_mov_b32 m0, s75
	s_nop 0
	global_load_lds_dwordx4 v[216:217], off
	v_lshl_add_u64 v[216:217], s[52:53], 0, v[136:137]
	s_mov_b32 m0, s68
	s_nop 0
	global_load_lds_dwordx4 v[216:217], off
	s_mov_b32 m0, s69
	s_nop 0
	global_load_lds_dwordx4 v[218:219], off
	s_waitcnt vmcnt(8)
	s_waitcnt lgkmcnt(0)
	s_barrier
; #define PG8_STAGE(bufoff, gbase, voff) do { _Pragma("unroll") for (int _i = 0; _i < 2; ++_i) \
;         __builtin_amdgcn_global_load_lds((const unsigned*)((const char*)(gbase) + (voff)[_i]), (LAS unsigned*)(lds + (bufoff) + ldsw + _i * 8192), 16, 0, 0); } while (0)
; #define PG8_LDA(dst, b, h) do { _Pragma("unroll") for (int m = 0; m < 4; ++m) _Pragma("unroll") for (int k = 0; k < 2; ++k) dst[m][k] = *(const LAS bf16x8*)(lds + PG8_SA(b, h) + aoff + m * 2048 + k * 1024); } while (0)
; #define PG8_LDB(dst, b, h) do { _Pragma("unroll") for (int n = 0; n < 2; ++n) _Pragma("unroll") for (int k = 0; k < 2; ++k) dst[n][k] = *(const LAS bf16x8*)(lds + PG8_SB(b, h) + boff + n * 2048 + k * 1024); } while (0)
; #define PG8_MMA(ai, bj, At, Bt) do { __builtin_amdgcn_s_setprio(1); _Pragma("unroll") for (int m = 0; m < 4; ++m) _Pragma("unroll") for (int n = 0; n < 2; ++n) _Pragma("unroll") for (int k = 0; k < 2; ++k) \
;         acc[ai][bj][m][n] = __builtin_amdgcn_mfma_f32_16x16x32_bf16(Bt[n][k], At[m][k], acc[ai][bj][m][n], 0, 0, 0); __builtin_amdgcn_s_setprio(0); } while (0)
; #define PG8_WAIT_V(n) asm volatile("s_waitcnt vmcnt(" #n ")" ::: "memory")
; #define PG8_WAIT_L(n) asm volatile("s_waitcnt lgkmcnt(" #n ")" ::: "memory")
; #define PG8_BAR __builtin_amdgcn_s_barrier()
; #define PG8_SCHED __builtin_amdgcn_sched_barrier(0)
; template <class Epi>
; __device__ __forceinline__ void gemm_phase(LAS unsigned char* lds, const Gemm g, int G, int c, const Epi& E) {
;     ...
;             PG8_WAIT_V(8); PG8_WAIT_L(0); PG8_BAR; PG8_MMA(1, 0, At, B0); PG8_MMA(1, 1, At, B1); PG8_BAR; PG8_SCHED;
;             PG8_LDB(B0, 1, 0); PG8_LDB(B1, 1, 1); PG8_SCHED; PG8_LDA(At, 1, 0); PG8_STAGE(PG8_SA(0, 1), a2 + hstepA, voffA);
;             PG8_WAIT_V(8); PG8_WAIT_L(0); PG8_BAR; PG8_MMA(0, 0, At, B0); PG8_MMA(0, 1, At, B1); PG8_BAR; PG8_SCHED;
	s_setprio 0
	s_waitcnt lgkmcnt(0)
	v_mfma_f32_16x16x32_bf16 v[62:65], v[142:145], v[182:185], v[62:65]
	v_mfma_f32_16x16x32_bf16 v[58:61], v[150:153], v[182:185], v[58:61]
	v_mfma_f32_16x16x32_bf16 v[46:49], v[142:145], v[190:193], v[46:49]
	v_mfma_f32_16x16x32_bf16 v[42:45], v[150:153], v[190:193], v[42:45]
	v_mfma_f32_16x16x32_bf16 v[30:33], v[142:145], v[198:201], v[30:33]
	v_mfma_f32_16x16x32_bf16 v[26:29], v[150:153], v[198:201], v[26:29]
	v_mfma_f32_16x16x32_bf16 v[14:17], v[142:145], v[206:209], v[14:17]
	v_mfma_f32_16x16x32_bf16 v[10:13], v[150:153], v[206:209], v[10:13]
	v_mfma_f32_16x16x32_bf16 v[62:65], v[146:149], v[186:189], v[62:65]
	v_mfma_f32_16x16x32_bf16 v[58:61], v[154:157], v[186:189], v[58:61]
	v_mfma_f32_16x16x32_bf16 v[46:49], v[146:149], v[194:197], v[46:49]
	v_mfma_f32_16x16x32_bf16 v[42:45], v[154:157], v[194:197], v[42:45]
	v_mfma_f32_16x16x32_bf16 v[30:33], v[146:149], v[202:205], v[30:33]
	v_mfma_f32_16x16x32_bf16 v[26:29], v[154:157], v[202:205], v[26:29]
	v_mfma_f32_16x16x32_bf16 v[14:17], v[146:149], v[210:213], v[14:17]
	v_mfma_f32_16x16x32_bf16 v[10:13], v[154:157], v[210:213], v[10:13]
	s_setprio 2
	s_setprio 0
	v_mfma_f32_16x16x32_bf16 v[54:57], v[158:161], v[182:185], v[54:57]
	v_mfma_f32_16x16x32_bf16 v[50:53], v[174:177], v[182:185], v[50:53]
	v_mfma_f32_16x16x32_bf16 v[38:41], v[158:161], v[190:193], v[38:41]
	v_mfma_f32_16x16x32_bf16 v[34:37], v[174:177], v[190:193], v[34:37]
	v_mfma_f32_16x16x32_bf16 v[22:25], v[158:161], v[198:201], v[22:25]
	v_mfma_f32_16x16x32_bf16 v[18:21], v[174:177], v[198:201], v[18:21]
	v_mfma_f32_16x16x32_bf16 v[6:9], v[158:161], v[206:209], v[6:9]
	v_mfma_f32_16x16x32_bf16 v[2:5], v[174:177], v[206:209], v[2:5]
	v_mfma_f32_16x16x32_bf16 v[54:57], v[170:173], v[186:189], v[54:57]
	v_mfma_f32_16x16x32_bf16 v[50:53], v[178:181], v[186:189], v[50:53]
	v_mfma_f32_16x16x32_bf16 v[38:41], v[170:173], v[194:197], v[38:41]
	v_mfma_f32_16x16x32_bf16 v[34:37], v[178:181], v[194:197], v[34:37]
	v_mfma_f32_16x16x32_bf16 v[22:25], v[170:173], v[202:205], v[22:25]
	v_mfma_f32_16x16x32_bf16 v[18:21], v[178:181], v[202:205], v[18:21]
	v_mfma_f32_16x16x32_bf16 v[6:9], v[170:173], v[210:213], v[6:9]
	v_mfma_f32_16x16x32_bf16 v[2:5], v[178:181], v[210:213], v[2:5]
	s_setprio 2
	s_barrier
	v_add_u32_e32 v154, s93, v165
	v_add_u32_e32 v178, s33, v165
	ds_read_b128 v[142:145], v154
	ds_read_b128 v[146:149], v154 offset:1024
	ds_read_b128 v[150:153], v154 offset:2048
	ds_read_b128 v[154:157], v154 offset:3072
	ds_read_b128 v[158:161], v178
	ds_read_b128 v[170:173], v178 offset:1024
	ds_read_b128 v[174:177], v178 offset:2048
	ds_read_b128 v[178:181], v178 offset:3072
	s_mov_b32 m0, s70
	v_lshl_add_u64 v[220:221], s[48:49], 0, v[136:137]
	ds_read_b128 v[182:185], v168 offset:32768
	ds_read_b128 v[186:189], v168 offset:33792
	ds_read_b128 v[190:193], v168 offset:34816
	ds_read_b128 v[194:197], v168 offset:35840
	ds_read_b128 v[198:201], v168 offset:36864
	ds_read_b128 v[202:205], v168 offset:37888
	ds_read_b128 v[206:209], v168 offset:38912
	ds_read_b128 v[210:213], v168 offset:39936
	global_load_lds_dwordx4 v[220:221], off
	v_lshl_add_u64 v[220:221], s[48:49], 0, v[132:133]
	s_mov_b32 m0, s71
	s_nop 0
	global_load_lds_dwordx4 v[220:221], off
	s_waitcnt vmcnt(8)
	s_waitcnt lgkmcnt(0)
	s_barrier
	s_setprio 0
	s_waitcnt lgkmcnt(0)
	v_mfma_f32_16x16x32_bf16 v[126:129], v[142:145], v[182:185], v[126:129]
	v_mfma_f32_16x16x32_bf16 v[122:125], v[150:153], v[182:185], v[122:125]
	v_mfma_f32_16x16x32_bf16 v[110:113], v[142:145], v[190:193], v[110:113]
	v_mfma_f32_16x16x32_bf16 v[106:109], v[150:153], v[190:193], v[106:109]
	v_mfma_f32_16x16x32_bf16 v[94:97], v[142:145], v[198:201], v[94:97]
	v_mfma_f32_16x16x32_bf16 v[90:93], v[150:153], v[198:201], v[90:93]
	v_mfma_f32_16x16x32_bf16 v[78:81], v[142:145], v[206:209], v[78:81]
	v_mfma_f32_16x16x32_bf16 v[74:77], v[150:153], v[206:209], v[74:77]
	v_mfma_f32_16x16x32_bf16 v[126:129], v[146:149], v[186:189], v[126:129]
	v_mfma_f32_16x16x32_bf16 v[122:125], v[154:157], v[186:189], v[122:125]
	v_mfma_f32_16x16x32_bf16 v[110:113], v[146:149], v[194:197], v[110:113]
	v_mfma_f32_16x16x32_bf16 v[106:109], v[154:157], v[194:197], v[106:109]
	v_mfma_f32_16x16x32_bf16 v[94:97], v[146:149], v[202:205], v[94:97]
	v_mfma_f32_16x16x32_bf16 v[90:93], v[154:157], v[202:205], v[90:93]
	v_mfma_f32_16x16x32_bf16 v[78:81], v[146:149], v[210:213], v[78:81]
	v_mfma_f32_16x16x32_bf16 v[74:77], v[154:157], v[210:213], v[74:77]
	s_setprio 2
	s_setprio 0
	v_mfma_f32_16x16x32_bf16 v[118:121], v[158:161], v[182:185], v[118:121]
	v_mfma_f32_16x16x32_bf16 v[114:117], v[174:177], v[182:185], v[114:117]
	v_mfma_f32_16x16x32_bf16 v[102:105], v[158:161], v[190:193], v[102:105]
	v_mfma_f32_16x16x32_bf16 v[98:101], v[174:177], v[190:193], v[98:101]
	v_mfma_f32_16x16x32_bf16 v[86:89], v[158:161], v[198:201], v[86:89]
	v_mfma_f32_16x16x32_bf16 v[82:85], v[174:177], v[198:201], v[82:85]
	v_mfma_f32_16x16x32_bf16 v[70:73], v[158:161], v[206:209], v[70:73]
	v_mfma_f32_16x16x32_bf16 v[66:69], v[174:177], v[206:209], v[66:69]
	v_mfma_f32_16x16x32_bf16 v[118:121], v[170:173], v[186:189], v[118:121]
	v_mfma_f32_16x16x32_bf16 v[114:117], v[178:181], v[186:189], v[114:117]
	v_mfma_f32_16x16x32_bf16 v[102:105], v[170:173], v[194:197], v[102:105]
	v_mfma_f32_16x16x32_bf16 v[98:101], v[178:181], v[194:197], v[98:101]
	v_mfma_f32_16x16x32_bf16 v[86:89], v[170:173], v[202:205], v[86:89]
	v_mfma_f32_16x16x32_bf16 v[82:85], v[178:181], v[202:205], v[82:85]
	v_mfma_f32_16x16x32_bf16 v[70:73], v[170:173], v[210:213], v[70:73]
	v_mfma_f32_16x16x32_bf16 v[66:69], v[178:181], v[210:213], v[66:69]
	s_setprio 2
	s_barrier
; #define PG8_STAGE(bufoff, gbase, voff) do { _Pragma("unroll") for (int _i = 0; _i < 2; ++_i) \
;         __builtin_amdgcn_global_load_lds((const unsigned*)((const char*)(gbase) + (voff)[_i]), (LAS unsigned*)(lds + (bufoff) + ldsw + _i * 8192), 16, 0, 0); } while (0)
; #define PG8_LDA(dst, b, h) do { _Pragma("unroll") for (int m = 0; m < 4; ++m) _Pragma("unroll") for (int k = 0; k < 2; ++k) dst[m][k] = *(const LAS bf16x8*)(lds + PG8_SA(b, h) + aoff + m * 2048 + k * 1024); } while (0)
; #define PG8_MMA(ai, bj, At, Bt) do { __builtin_amdgcn_s_setprio(1); _Pragma("unroll") for (int m = 0; m < 4; ++m) _Pragma("unroll") for (int n = 0; n < 2; ++n) _Pragma("unroll") for (int k = 0; k < 2; ++k) \
;         acc[ai][bj][m][n] = __builtin_amdgcn_mfma_f32_16x16x32_bf16(Bt[n][k], At[m][k], acc[ai][bj][m][n], 0, 0, 0); __builtin_amdgcn_s_setprio(0); } while (0)
; #define PG8_WAIT_V(n) asm volatile("s_waitcnt vmcnt(" #n ")" ::: "memory")
; #define PG8_WAIT_L(n) asm volatile("s_waitcnt lgkmcnt(" #n ")" ::: "memory")
; #define PG8_BAR __builtin_amdgcn_s_barrier()
; #define PG8_SCHED __builtin_amdgcn_sched_barrier(0)
; template <class Epi>
; __device__ __forceinline__ void gemm_phase(LAS unsigned char* lds, const Gemm g, int G, int c, const Epi& E) {
;     ...
;             PG8_LDA(At, 1, 1); PG8_STAGE(PG8_SB(1, 0), b3, voffB); PG8_STAGE(PG8_SB(1, 1), b3 + hstepB, voffB); PG8_STAGE(PG8_SA(1, 0), a3, voffA);
;             PG8_WAIT_V(8); PG8_WAIT_L(0); PG8_BAR; PG8_MMA(1, 0, At, B0); PG8_MMA(1, 1, At, B1); PG8_BAR; PG8_SCHED;
;         }
;         if (wr == 0) PG8_BAR;
	s_mov_b32 m0, s92
	v_lshl_add_u64 v[162:163], v[162:163], 0, s[18:19]
	ds_read_b128 v[182:185], v168 offset:49152
	ds_read_b128 v[186:189], v168 offset:50176
	ds_read_b128 v[190:193], v168 offset:51200
	ds_read_b128 v[194:197], v168 offset:52224
	ds_read_b128 v[198:201], v168 offset:53248
	ds_read_b128 v[202:205], v168 offset:54272
	ds_read_b128 v[206:209], v168 offset:55296
	ds_read_b128 v[210:213], v168 offset:56320
	global_load_lds_dwordx4 v[162:163], off
	v_lshl_add_u64 v[162:163], v[214:215], 0, s[18:19]
	s_mov_b32 m0, s90
	s_nop 0
	global_load_lds_dwordx4 v[162:163], off
	v_lshl_add_u64 v[162:163], s[46:47], 0, v[134:135]
	s_mov_b32 m0, s91
	s_nop 0
	global_load_lds_dwordx4 v[162:163], off
	v_lshl_add_u64 v[162:163], s[46:47], 0, v[130:131]
	s_mov_b32 m0, s89
	s_nop 0
	global_load_lds_dwordx4 v[162:163], off
	v_lshl_add_u64 v[162:163], v[216:217], 0, s[18:19]
	s_mov_b32 m0, s78
	s_nop 0
	global_load_lds_dwordx4 v[162:163], off
	v_lshl_add_u64 v[162:163], v[218:219], 0, s[18:19]
	s_mov_b32 m0, s79
	s_nop 0
	global_load_lds_dwordx4 v[162:163], off
	s_waitcnt vmcnt(8)
	s_waitcnt lgkmcnt(0)
	s_barrier
	s_setprio 0
	s_waitcnt lgkmcnt(0)
	v_mfma_f32_16x16x32_bf16 v[62:65], v[142:145], v[182:185], v[62:65]
	v_mfma_f32_16x16x32_bf16 v[58:61], v[150:153], v[182:185], v[58:61]
	v_mfma_f32_16x16x32_bf16 v[46:49], v[142:145], v[190:193], v[46:49]
	v_mfma_f32_16x16x32_bf16 v[42:45], v[150:153], v[190:193], v[42:45]
	v_mfma_f32_16x16x32_bf16 v[30:33], v[142:145], v[198:201], v[30:33]
	v_mfma_f32_16x16x32_bf16 v[26:29], v[150:153], v[198:201], v[26:29]
	v_mfma_f32_16x16x32_bf16 v[14:17], v[142:145], v[206:209], v[14:17]
	v_mfma_f32_16x16x32_bf16 v[10:13], v[150:153], v[206:209], v[10:13]
	v_mfma_f32_16x16x32_bf16 v[62:65], v[146:149], v[186:189], v[62:65]
	v_mfma_f32_16x16x32_bf16 v[58:61], v[154:157], v[186:189], v[58:61]
	v_mfma_f32_16x16x32_bf16 v[46:49], v[146:149], v[194:197], v[46:49]
	v_mfma_f32_16x16x32_bf16 v[42:45], v[154:157], v[194:197], v[42:45]
	v_mfma_f32_16x16x32_bf16 v[30:33], v[146:149], v[202:205], v[30:33]
	v_mfma_f32_16x16x32_bf16 v[26:29], v[154:157], v[202:205], v[26:29]
	v_mfma_f32_16x16x32_bf16 v[14:17], v[146:149], v[210:213], v[14:17]
	v_mfma_f32_16x16x32_bf16 v[10:13], v[154:157], v[210:213], v[10:13]
	s_setprio 2
	s_setprio 0
	v_mfma_f32_16x16x32_bf16 v[54:57], v[158:161], v[182:185], v[54:57]
	v_mfma_f32_16x16x32_bf16 v[50:53], v[174:177], v[182:185], v[50:53]
	v_mfma_f32_16x16x32_bf16 v[38:41], v[158:161], v[190:193], v[38:41]
	v_mfma_f32_16x16x32_bf16 v[34:37], v[174:177], v[190:193], v[34:37]
	v_mfma_f32_16x16x32_bf16 v[22:25], v[158:161], v[198:201], v[22:25]
	v_mfma_f32_16x16x32_bf16 v[18:21], v[174:177], v[198:201], v[18:21]
	v_mfma_f32_16x16x32_bf16 v[6:9], v[158:161], v[206:209], v[6:9]
	v_mfma_f32_16x16x32_bf16 v[2:5], v[174:177], v[206:209], v[2:5]
	v_mfma_f32_16x16x32_bf16 v[54:57], v[170:173], v[186:189], v[54:57]
	v_mfma_f32_16x16x32_bf16 v[50:53], v[178:181], v[186:189], v[50:53]
	v_mfma_f32_16x16x32_bf16 v[38:41], v[170:173], v[194:197], v[38:41]
	v_mfma_f32_16x16x32_bf16 v[34:37], v[178:181], v[194:197], v[34:37]
	v_mfma_f32_16x16x32_bf16 v[22:25], v[170:173], v[202:205], v[22:25]
	v_mfma_f32_16x16x32_bf16 v[18:21], v[178:181], v[202:205], v[18:21]
	v_mfma_f32_16x16x32_bf16 v[6:9], v[170:173], v[210:213], v[6:9]
	v_mfma_f32_16x16x32_bf16 v[2:5], v[178:181], v[210:213], v[2:5]
	s_setprio 2
	s_barrier
	s_movk_i32 s48, 0x100
	s_andn2_b64 vcc, exec, s[4:5]
	s_mov_b64 s[46:47], -1
	s_mov_b64 s[4:5], 0
	s_cbranch_vccz .LBB0_1653
	s_and_b64 vcc, exec, s[20:21]
	s_cbranch_vccz .LBB0_1656
	s_barrier

; #define PG8_STAGE(bufoff, gbase, voff) do { _Pragma("unroll") for (int _i = 0; _i < 2; ++_i) \
;         __builtin_amdgcn_global_load_lds((const unsigned*)((const char*)(gbase) + (voff)[_i]), (LAS unsigned*)(lds + (bufoff) + ldsw + _i * 8192), 16, 0, 0); } while (0)
; #define PG8_LDA(dst, b, h) do { _Pragma("unroll") for (int m = 0; m < 4; ++m) _Pragma("unroll") for (int k = 0; k < 2; ++k) dst[m][k] = *(const LAS bf16x8*)(lds + PG8_SA(b, h) + aoff + m * 2048 + k * 1024); } while (0)
; #define PG8_LDB(dst, b, h) do { _Pragma("unroll") for (int n = 0; n < 2; ++n) _Pragma("unroll") for (int k = 0; k < 2; ++k) dst[n][k] = *(const LAS bf16x8*)(lds + PG8_SB(b, h) + boff + n * 2048 + k * 1024); } while (0)
; #define PG8_MMA(ai, bj, At, Bt) do { __builtin_amdgcn_s_setprio(1); _Pragma("unroll") for (int m = 0; m < 4; ++m) _Pragma("unroll") for (int n = 0; n < 2; ++n) _Pragma("unroll") for (int k = 0; k < 2; ++k) \
;         acc[ai][bj][m][n] = __builtin_amdgcn_mfma_f32_16x16x32_bf16(Bt[n][k], At[m][k], acc[ai][bj][m][n], 0, 0, 0); __builtin_amdgcn_s_setprio(0); } while (0)
; #define PG8_WAIT_V(n) asm volatile("s_waitcnt vmcnt(" #n ")" ::: "memory")
; #define PG8_WAIT_L(n) asm volatile("s_waitcnt lgkmcnt(" #n ")" ::: "memory")
; #define PG8_BAR __builtin_amdgcn_s_barrier()
; #define PG8_SCHED __builtin_amdgcn_sched_barrier(0)
; template <class Epi>
; __device__ __forceinline__ void gemm_phase(LAS unsigned char* lds, const Gemm g, int G, int c, const Epi& E) {
;     ...
;         for (int t = 0; t < nt; t += 2) {
;             const bool last = (t == nt - 2);
;             const char* a1 = cA + (size_t)(t + 1) * kstep;
;             const char* a2 = last ? nA : cA + (size_t)(t + 2) * kstep; const char* b2 = last ? nB : cB + (size_t)(t + 2) * kstep;
;             const char* a3 = a2 + kstep; const char* b3 = b2 + kstep;
;             PG8_LDB(B0, 0, 0); PG8_LDB(B1, 0, 1); PG8_SCHED; PG8_LDA(At, 0, 0); PG8_STAGE(PG8_SA(1, 1), a1 + hstepA, voffA);
;             PG8_WAIT_V(8); PG8_WAIT_L(0); PG8_BAR; PG8_MMA(0, 0, At, B0); PG8_MMA(0, 1, At, B1); PG8_BAR; PG8_SCHED;
;             PG8_LDA(At, 0, 1); PG8_STAGE(PG8_SB(0, 0), b2, voffB); PG8_STAGE(PG8_SB(0, 1), b2 + hstepB, voffB); PG8_STAGE(PG8_SA(0, 0), a2, voffA);
.LBB0_1825:
	ds_read_b128 v[146:149], v152
	ds_read_b128 v[156:159], v152 offset:1024
	ds_read_b128 v[160:163], v152 offset:2048
	ds_read_b128 v[164:167], v152 offset:3072
	ds_read_b128 v[168:171], v153
	ds_read_b128 v[172:175], v153 offset:1024
	ds_read_b128 v[176:179], v153 offset:2048
	ds_read_b128 v[180:183], v153 offset:3072
	s_add_u32 s33, s40, 0xfff00080
	s_addc_u32 s42, s41, -1
	s_cmp_eq_u32 s68, 60
	s_cselect_b32 s45, s15, s42
	s_cselect_b32 s44, s63, s33
	s_cselect_b32 s43, s11, s67
	s_cselect_b32 s42, s13, s66
	v_lshl_add_u64 v[216:217], s[40:41], 0, v[138:139]
	s_add_i32 m0, s17, 0xc000
	ds_read_b128 v[184:187], v154
	ds_read_b128 v[188:191], v154 offset:1024
	ds_read_b128 v[192:195], v154 offset:2048
	ds_read_b128 v[196:199], v154 offset:3072
	ds_read_b128 v[200:203], v154 offset:4096
	ds_read_b128 v[204:207], v154 offset:5120
	ds_read_b128 v[208:211], v154 offset:6144
	ds_read_b128 v[212:215], v154 offset:7168
	global_load_lds_dwordx4 v[216:217], off
	v_lshl_add_u64 v[216:217], s[40:41], 0, v[140:141]
	s_add_i32 m0, s17, 0xe000
	s_nop 0
	global_load_lds_dwordx4 v[216:217], off
	s_waitcnt vmcnt(8)
	s_waitcnt lgkmcnt(0)
	s_barrier
	s_setprio 0
	s_waitcnt lgkmcnt(0)
	v_mfma_f32_16x16x32_bf16 v[126:129], v[146:149], v[184:187], v[126:129]
	v_mfma_f32_16x16x32_bf16 v[122:125], v[160:163], v[184:187], v[122:125]
	v_mfma_f32_16x16x32_bf16 v[118:121], v[146:149], v[192:195], v[118:121]
	v_mfma_f32_16x16x32_bf16 v[110:113], v[160:163], v[192:195], v[110:113]
	v_mfma_f32_16x16x32_bf16 v[102:105], v[146:149], v[200:203], v[102:105]
	v_mfma_f32_16x16x32_bf16 v[94:97], v[160:163], v[200:203], v[94:97]
	v_mfma_f32_16x16x32_bf16 v[86:89], v[146:149], v[208:211], v[86:89]
	v_mfma_f32_16x16x32_bf16 v[78:81], v[160:163], v[208:211], v[78:81]
	v_mfma_f32_16x16x32_bf16 v[126:129], v[156:159], v[188:191], v[126:129]
	v_mfma_f32_16x16x32_bf16 v[122:125], v[164:167], v[188:191], v[122:125]
	v_mfma_f32_16x16x32_bf16 v[118:121], v[156:159], v[196:199], v[118:121]
	v_mfma_f32_16x16x32_bf16 v[110:113], v[164:167], v[196:199], v[110:113]
	v_mfma_f32_16x16x32_bf16 v[102:105], v[156:159], v[204:207], v[102:105]
	v_mfma_f32_16x16x32_bf16 v[94:97], v[164:167], v[204:207], v[94:97]
	v_mfma_f32_16x16x32_bf16 v[86:89], v[156:159], v[212:215], v[86:89]
	v_mfma_f32_16x16x32_bf16 v[78:81], v[164:167], v[212:215], v[78:81]
	s_setprio 2
	s_setprio 0
	v_mfma_f32_16x16x32_bf16 v[114:117], v[168:171], v[184:187], v[114:117]
	v_mfma_f32_16x16x32_bf16 v[106:109], v[176:179], v[184:187], v[106:109]
	v_mfma_f32_16x16x32_bf16 v[98:101], v[168:171], v[192:195], v[98:101]
	v_mfma_f32_16x16x32_bf16 v[90:93], v[176:179], v[192:195], v[90:93]
	v_mfma_f32_16x16x32_bf16 v[82:85], v[168:171], v[200:203], v[82:85]
	v_mfma_f32_16x16x32_bf16 v[74:77], v[176:179], v[200:203], v[74:77]
	v_mfma_f32_16x16x32_bf16 v[70:73], v[168:171], v[208:211], v[70:73]
	v_mfma_f32_16x16x32_bf16 v[66:69], v[176:179], v[208:211], v[66:69]
	v_mfma_f32_16x16x32_bf16 v[114:117], v[172:175], v[188:191], v[114:117]
	v_mfma_f32_16x16x32_bf16 v[106:109], v[180:183], v[188:191], v[106:109]
	v_mfma_f32_16x16x32_bf16 v[98:101], v[172:175], v[196:199], v[98:101]
	v_mfma_f32_16x16x32_bf16 v[90:93], v[180:183], v[196:199], v[90:93]
	v_mfma_f32_16x16x32_bf16 v[82:85], v[172:175], v[204:207], v[82:85]
	v_mfma_f32_16x16x32_bf16 v[74:77], v[180:183], v[204:207], v[74:77]
	v_mfma_f32_16x16x32_bf16 v[70:73], v[172:175], v[212:215], v[70:73]
	v_mfma_f32_16x16x32_bf16 v[66:69], v[180:183], v[212:215], v[66:69]
	s_setprio 2
	s_barrier
	s_add_i32 s33, s61, s52
	v_lshl_add_u64 v[216:217], s[42:43], 0, v[134:135]
	s_mov_b32 m0, s33
	ds_read_b128 v[184:187], v154 offset:16384
	ds_read_b128 v[188:191], v154 offset:17408
	ds_read_b128 v[192:195], v154 offset:18432
	ds_read_b128 v[196:199], v154 offset:19456
	ds_read_b128 v[200:203], v154 offset:20480
	ds_read_b128 v[204:207], v154 offset:21504
	ds_read_b128 v[208:211], v154 offset:22528
	ds_read_b128 v[212:215], v154 offset:23552
	global_load_lds_dwordx4 v[216:217], off
	s_add_i32 m0, s33, 0x2000
	s_add_u32 s64, s42, 0x100000
	v_lshl_add_u64 v[218:219], s[42:43], 0, v[130:131]
	s_addc_u32 s65, s43, 0
	s_add_i32 s33, s62, s52
	global_load_lds_dwordx4 v[218:219], off
	v_lshl_add_u64 v[220:221], s[64:65], 0, v[134:135]
	s_mov_b32 m0, s33
	v_lshl_add_u64 v[222:223], s[44:45], 0, v[132:133]
	global_load_lds_dwordx4 v[220:221], off
	v_lshl_add_u64 v[220:221], s[64:65], 0, v[130:131]
	s_add_i32 m0, s33, 0x2000
	s_nop 0
	global_load_lds_dwordx4 v[220:221], off
	v_lshl_add_u64 v[220:221], s[44:45], 0, v[136:137]
	s_mov_b32 m0, s17
	s_nop 0
	global_load_lds_dwordx4 v[220:221], off
	s_mov_b32 m0, s37
	s_nop 0
	global_load_lds_dwordx4 v[222:223], off
	s_waitcnt vmcnt(8)
	s_waitcnt lgkmcnt(0)
	s_barrier
; #define PG8_STAGE(bufoff, gbase, voff) do { _Pragma("unroll") for (int _i = 0; _i < 2; ++_i) \
;         __builtin_amdgcn_global_load_lds((const unsigned*)((const char*)(gbase) + (voff)[_i]), (LAS unsigned*)(lds + (bufoff) + ldsw + _i * 8192), 16, 0, 0); } while (0)
; #define PG8_LDA(dst, b, h) do { _Pragma("unroll") for (int m = 0; m < 4; ++m) _Pragma("unroll") for (int k = 0; k < 2; ++k) dst[m][k] = *(const LAS bf16x8*)(lds + PG8_SA(b, h) + aoff + m * 2048 + k * 1024); } while (0)
; #define PG8_LDB(dst, b, h) do { _Pragma("unroll") for (int n = 0; n < 2; ++n) _Pragma("unroll") for (int k = 0; k < 2; ++k) dst[n][k] = *(const LAS bf16x8*)(lds + PG8_SB(b, h) + boff + n * 2048 + k * 1024); } while (0)
; #define PG8_MMA(ai, bj, At, Bt) do { __builtin_amdgcn_s_setprio(1); _Pragma("unroll") for (int m = 0; m < 4; ++m) _Pragma("unroll") for (int n = 0; n < 2; ++n) _Pragma("unroll") for (int k = 0; k < 2; ++k) \
;         acc[ai][bj][m][n] = __builtin_amdgcn_mfma_f32_16x16x32_bf16(Bt[n][k], At[m][k], acc[ai][bj][m][n], 0, 0, 0); __builtin_amdgcn_s_setprio(0); } while (0)
; #define PG8_WAIT_V(n) asm volatile("s_waitcnt vmcnt(" #n ")" ::: "memory")
; #define PG8_WAIT_L(n) asm volatile("s_waitcnt lgkmcnt(" #n ")" ::: "memory")
; #define PG8_BAR __builtin_amdgcn_s_barrier()
; #define PG8_SCHED __builtin_amdgcn_sched_barrier(0)
; template <class Epi>
; __device__ __forceinline__ void gemm_phase(LAS unsigned char* lds, const Gemm g, int G, int c, const Epi& E) {
;     ...
;             PG8_WAIT_V(8); PG8_WAIT_L(0); PG8_BAR; PG8_MMA(1, 0, At, B0); PG8_MMA(1, 1, At, B1); PG8_BAR; PG8_SCHED;
;             PG8_LDB(B0, 1, 0); PG8_LDB(B1, 1, 1); PG8_SCHED; PG8_LDA(At, 1, 0); PG8_STAGE(PG8_SA(0, 1), a2 + hstepA, voffA);
;             PG8_WAIT_V(8); PG8_WAIT_L(0); PG8_BAR; PG8_MMA(0, 0, At, B0); PG8_MMA(0, 1, At, B1); PG8_BAR; PG8_SCHED;
	s_setprio 0
	s_waitcnt lgkmcnt(0)
	v_mfma_f32_16x16x32_bf16 v[62:65], v[146:149], v[184:187], v[62:65]
	v_mfma_f32_16x16x32_bf16 v[58:61], v[160:163], v[184:187], v[58:61]
	v_mfma_f32_16x16x32_bf16 v[54:57], v[146:149], v[192:195], v[54:57]
	v_mfma_f32_16x16x32_bf16 v[46:49], v[160:163], v[192:195], v[46:49]
	v_mfma_f32_16x16x32_bf16 v[38:41], v[146:149], v[200:203], v[38:41]
	v_mfma_f32_16x16x32_bf16 v[30:33], v[160:163], v[200:203], v[30:33]
	v_mfma_f32_16x16x32_bf16 v[22:25], v[146:149], v[208:211], v[22:25]
	v_mfma_f32_16x16x32_bf16 v[14:17], v[160:163], v[208:211], v[14:17]
	v_mfma_f32_16x16x32_bf16 v[62:65], v[156:159], v[188:191], v[62:65]
	v_mfma_f32_16x16x32_bf16 v[58:61], v[164:167], v[188:191], v[58:61]
	v_mfma_f32_16x16x32_bf16 v[54:57], v[156:159], v[196:199], v[54:57]
	v_mfma_f32_16x16x32_bf16 v[46:49], v[164:167], v[196:199], v[46:49]
	v_mfma_f32_16x16x32_bf16 v[38:41], v[156:159], v[204:207], v[38:41]
	v_mfma_f32_16x16x32_bf16 v[30:33], v[164:167], v[204:207], v[30:33]
	v_mfma_f32_16x16x32_bf16 v[22:25], v[156:159], v[212:215], v[22:25]
	v_mfma_f32_16x16x32_bf16 v[14:17], v[164:167], v[212:215], v[14:17]
	s_setprio 2
	s_setprio 0
	v_mfma_f32_16x16x32_bf16 v[50:53], v[168:171], v[184:187], v[50:53]
	v_mfma_f32_16x16x32_bf16 v[42:45], v[176:179], v[184:187], v[42:45]
	v_mfma_f32_16x16x32_bf16 v[34:37], v[168:171], v[192:195], v[34:37]
	v_mfma_f32_16x16x32_bf16 v[26:29], v[176:179], v[192:195], v[26:29]
	v_mfma_f32_16x16x32_bf16 v[18:21], v[168:171], v[200:203], v[18:21]
	v_mfma_f32_16x16x32_bf16 v[10:13], v[176:179], v[200:203], v[10:13]
	v_mfma_f32_16x16x32_bf16 v[6:9], v[168:171], v[208:211], v[6:9]
	v_mfma_f32_16x16x32_bf16 v[2:5], v[176:179], v[208:211], v[2:5]
	v_mfma_f32_16x16x32_bf16 v[50:53], v[172:175], v[188:191], v[50:53]
	v_mfma_f32_16x16x32_bf16 v[42:45], v[180:183], v[188:191], v[42:45]
	v_mfma_f32_16x16x32_bf16 v[34:37], v[172:175], v[196:199], v[34:37]
	v_mfma_f32_16x16x32_bf16 v[26:29], v[180:183], v[196:199], v[26:29]
	v_mfma_f32_16x16x32_bf16 v[18:21], v[172:175], v[204:207], v[18:21]
	v_mfma_f32_16x16x32_bf16 v[10:13], v[180:183], v[204:207], v[10:13]
	v_mfma_f32_16x16x32_bf16 v[6:9], v[172:175], v[212:215], v[6:9]
	v_mfma_f32_16x16x32_bf16 v[2:5], v[180:183], v[212:215], v[2:5]
	s_setprio 2
	s_barrier
	s_add_i32 s33, 0, 0x18000
	v_add_u32_e32 v155, s33, v151
	s_add_i32 s64, 0, 0x1c000
	ds_read_b128 v[146:149], v155
	ds_read_b128 v[156:159], v155 offset:1024
	ds_read_b128 v[160:163], v155 offset:2048
	ds_read_b128 v[164:167], v155 offset:3072
	v_add_u32_e32 v155, s64, v151
	ds_read_b128 v[168:171], v155
	ds_read_b128 v[172:175], v155 offset:1024
	ds_read_b128 v[176:179], v155 offset:2048
	ds_read_b128 v[180:183], v155 offset:3072
	s_add_u32 s44, s44, 0x100000
	s_addc_u32 s45, s45, 0
	s_mov_b32 m0, s39
	v_lshl_add_u64 v[226:227], s[44:45], 0, v[136:137]
	ds_read_b128 v[184:187], v154 offset:32768
	ds_read_b128 v[188:191], v154 offset:33792
	ds_read_b128 v[192:195], v154 offset:34816
	ds_read_b128 v[196:199], v154 offset:35840
	ds_read_b128 v[200:203], v154 offset:36864
	ds_read_b128 v[204:207], v154 offset:37888
	ds_read_b128 v[208:211], v154 offset:38912
	ds_read_b128 v[212:215], v154 offset:39936
	global_load_lds_dwordx4 v[226:227], off
	v_lshl_add_u64 v[226:227], s[44:45], 0, v[132:133]
	s_mov_b32 m0, s53
	s_nop 0
	global_load_lds_dwordx4 v[226:227], off
	s_waitcnt vmcnt(8)
	s_waitcnt lgkmcnt(0)
	s_barrier
	s_setprio 0
	s_waitcnt lgkmcnt(0)
	v_mfma_f32_16x16x32_bf16 v[126:129], v[146:149], v[184:187], v[126:129]
	v_mfma_f32_16x16x32_bf16 v[122:125], v[160:163], v[184:187], v[122:125]
	v_mfma_f32_16x16x32_bf16 v[118:121], v[146:149], v[192:195], v[118:121]
	v_mfma_f32_16x16x32_bf16 v[110:113], v[160:163], v[192:195], v[110:113]
	v_mfma_f32_16x16x32_bf16 v[102:105], v[146:149], v[200:203], v[102:105]
	v_mfma_f32_16x16x32_bf16 v[94:97], v[160:163], v[200:203], v[94:97]
	v_mfma_f32_16x16x32_bf16 v[86:89], v[146:149], v[208:211], v[86:89]
	v_mfma_f32_16x16x32_bf16 v[78:81], v[160:163], v[208:211], v[78:81]
	v_mfma_f32_16x16x32_bf16 v[126:129], v[156:159], v[188:191], v[126:129]
	v_mfma_f32_16x16x32_bf16 v[122:125], v[164:167], v[188:191], v[122:125]
	v_mfma_f32_16x16x32_bf16 v[118:121], v[156:159], v[196:199], v[118:121]
	v_mfma_f32_16x16x32_bf16 v[110:113], v[164:167], v[196:199], v[110:113]
	v_mfma_f32_16x16x32_bf16 v[102:105], v[156:159], v[204:207], v[102:105]
	v_mfma_f32_16x16x32_bf16 v[94:97], v[164:167], v[204:207], v[94:97]
	v_mfma_f32_16x16x32_bf16 v[86:89], v[156:159], v[212:215], v[86:89]
	v_mfma_f32_16x16x32_bf16 v[78:81], v[164:167], v[212:215], v[78:81]
	s_setprio 2
	s_setprio 0
	v_mfma_f32_16x16x32_bf16 v[114:117], v[168:171], v[184:187], v[114:117]
	v_mfma_f32_16x16x32_bf16 v[106:109], v[176:179], v[184:187], v[106:109]
	v_mfma_f32_16x16x32_bf16 v[98:101], v[168:171], v[192:195], v[98:101]
	v_mfma_f32_16x16x32_bf16 v[90:93], v[176:179], v[192:195], v[90:93]
	v_mfma_f32_16x16x32_bf16 v[82:85], v[168:171], v[200:203], v[82:85]
	v_mfma_f32_16x16x32_bf16 v[74:77], v[176:179], v[200:203], v[74:77]
	v_mfma_f32_16x16x32_bf16 v[70:73], v[168:171], v[208:211], v[70:73]
	v_mfma_f32_16x16x32_bf16 v[66:69], v[176:179], v[208:211], v[66:69]
	v_mfma_f32_16x16x32_bf16 v[114:117], v[172:175], v[188:191], v[114:117]
	v_mfma_f32_16x16x32_bf16 v[106:109], v[180:183], v[188:191], v[106:109]
	v_mfma_f32_16x16x32_bf16 v[98:101], v[172:175], v[196:199], v[98:101]
	v_mfma_f32_16x16x32_bf16 v[90:93], v[180:183], v[196:199], v[90:93]
	v_mfma_f32_16x16x32_bf16 v[82:85], v[172:175], v[204:207], v[82:85]
	v_mfma_f32_16x16x32_bf16 v[74:77], v[180:183], v[204:207], v[74:77]
	v_mfma_f32_16x16x32_bf16 v[70:73], v[172:175], v[212:215], v[70:73]
	v_mfma_f32_16x16x32_bf16 v[66:69], v[180:183], v[212:215], v[66:69]
	s_setprio 2
	s_barrier
; #define PG8_STAGE(bufoff, gbase, voff) do { _Pragma("unroll") for (int _i = 0; _i < 2; ++_i) \
;         __builtin_amdgcn_global_load_lds((const unsigned*)((const char*)(gbase) + (voff)[_i]), (LAS unsigned*)(lds + (bufoff) + ldsw + _i * 8192), 16, 0, 0); } while (0)
; #define PG8_LDA(dst, b, h) do { _Pragma("unroll") for (int m = 0; m < 4; ++m) _Pragma("unroll") for (int k = 0; k < 2; ++k) dst[m][k] = *(const LAS bf16x8*)(lds + PG8_SA(b, h) + aoff + m * 2048 + k * 1024); } while (0)
; #define PG8_MMA(ai, bj, At, Bt) do { __builtin_amdgcn_s_setprio(1); _Pragma("unroll") for (int m = 0; m < 4; ++m) _Pragma("unroll") for (int n = 0; n < 2; ++n) _Pragma("unroll") for (int k = 0; k < 2; ++k) \
;         acc[ai][bj][m][n] = __builtin_amdgcn_mfma_f32_16x16x32_bf16(Bt[n][k], At[m][k], acc[ai][bj][m][n], 0, 0, 0); __builtin_amdgcn_s_setprio(0); } while (0)
; #define PG8_WAIT_V(n) asm volatile("s_waitcnt vmcnt(" #n ")" ::: "memory")
; #define PG8_WAIT_L(n) asm volatile("s_waitcnt lgkmcnt(" #n ")" ::: "memory")
; #define PG8_BAR __builtin_amdgcn_s_barrier()
; #define PG8_SCHED __builtin_amdgcn_sched_barrier(0)
; template <class Epi>
; __device__ __forceinline__ void gemm_phase(LAS unsigned char* lds, const Gemm g, int G, int c, const Epi& E) {
;     ...
;             PG8_LDA(At, 1, 1); PG8_STAGE(PG8_SB(1, 0), b3, voffB); PG8_STAGE(PG8_SB(1, 1), b3 + hstepB, voffB); PG8_STAGE(PG8_SA(1, 0), a3, voffA);
;             PG8_WAIT_V(8); PG8_WAIT_L(0); PG8_BAR; PG8_MMA(1, 0, At, B0); PG8_MMA(1, 1, At, B1); PG8_BAR; PG8_SCHED;
;         }
;         if (wr == 0) PG8_BAR;
	s_add_i32 s33, s33, s52
	v_lshl_add_u64 v[216:217], v[216:217], 0, s[6:7]
	s_mov_b32 m0, s33
	ds_read_b128 v[184:187], v154 offset:49152
	ds_read_b128 v[188:191], v154 offset:50176
	ds_read_b128 v[192:195], v154 offset:51200
	ds_read_b128 v[196:199], v154 offset:52224
	ds_read_b128 v[200:203], v154 offset:53248
	ds_read_b128 v[204:207], v154 offset:54272
	ds_read_b128 v[208:211], v154 offset:55296
	ds_read_b128 v[212:215], v154 offset:56320
	global_load_lds_dwordx4 v[216:217], off
	s_add_i32 m0, s33, 0x2000
	s_add_u32 s42, s42, 0x100080
	v_lshl_add_u64 v[216:217], v[218:219], 0, s[6:7]
	s_addc_u32 s43, s43, 0
	s_add_i32 s33, s64, s52
	global_load_lds_dwordx4 v[216:217], off
	v_lshl_add_u64 v[216:217], s[42:43], 0, v[134:135]
	s_mov_b32 m0, s33
	s_nop 0
	global_load_lds_dwordx4 v[216:217], off
	v_lshl_add_u64 v[216:217], s[42:43], 0, v[130:131]
	s_add_i32 m0, s33, 0x2000
	s_nop 0
	global_load_lds_dwordx4 v[216:217], off
	v_lshl_add_u64 v[216:217], v[220:221], 0, s[6:7]
	s_mov_b32 m0, s59
	s_nop 0
	global_load_lds_dwordx4 v[216:217], off
	v_lshl_add_u64 v[216:217], v[222:223], 0, s[6:7]
	s_mov_b32 m0, s60
	s_nop 0
	global_load_lds_dwordx4 v[216:217], off
	s_waitcnt vmcnt(8)
	s_waitcnt lgkmcnt(0)
	s_barrier
	s_setprio 0
	s_waitcnt lgkmcnt(0)
	v_mfma_f32_16x16x32_bf16 v[62:65], v[146:149], v[184:187], v[62:65]
	v_mfma_f32_16x16x32_bf16 v[58:61], v[160:163], v[184:187], v[58:61]
	v_mfma_f32_16x16x32_bf16 v[54:57], v[146:149], v[192:195], v[54:57]
	v_mfma_f32_16x16x32_bf16 v[46:49], v[160:163], v[192:195], v[46:49]
	v_mfma_f32_16x16x32_bf16 v[38:41], v[146:149], v[200:203], v[38:41]
	v_mfma_f32_16x16x32_bf16 v[30:33], v[160:163], v[200:203], v[30:33]
	v_mfma_f32_16x16x32_bf16 v[22:25], v[146:149], v[208:211], v[22:25]
	v_mfma_f32_16x16x32_bf16 v[14:17], v[160:163], v[208:211], v[14:17]
	v_mfma_f32_16x16x32_bf16 v[62:65], v[156:159], v[188:191], v[62:65]
	v_mfma_f32_16x16x32_bf16 v[58:61], v[164:167], v[188:191], v[58:61]
	v_mfma_f32_16x16x32_bf16 v[54:57], v[156:159], v[196:199], v[54:57]
	v_mfma_f32_16x16x32_bf16 v[46:49], v[164:167], v[196:199], v[46:49]
	v_mfma_f32_16x16x32_bf16 v[38:41], v[156:159], v[204:207], v[38:41]
	v_mfma_f32_16x16x32_bf16 v[30:33], v[164:167], v[204:207], v[30:33]
	v_mfma_f32_16x16x32_bf16 v[22:25], v[156:159], v[212:215], v[22:25]
	v_mfma_f32_16x16x32_bf16 v[14:17], v[164:167], v[212:215], v[14:17]
	s_setprio 2
	s_setprio 0
	v_mfma_f32_16x16x32_bf16 v[50:53], v[168:171], v[184:187], v[50:53]
	v_mfma_f32_16x16x32_bf16 v[42:45], v[176:179], v[184:187], v[42:45]
	v_mfma_f32_16x16x32_bf16 v[34:37], v[168:171], v[192:195], v[34:37]
	v_mfma_f32_16x16x32_bf16 v[26:29], v[176:179], v[192:195], v[26:29]
	v_mfma_f32_16x16x32_bf16 v[18:21], v[168:171], v[200:203], v[18:21]
	v_mfma_f32_16x16x32_bf16 v[10:13], v[176:179], v[200:203], v[10:13]
	v_mfma_f32_16x16x32_bf16 v[6:9], v[168:171], v[208:211], v[6:9]
	v_mfma_f32_16x16x32_bf16 v[2:5], v[176:179], v[208:211], v[2:5]
	v_mfma_f32_16x16x32_bf16 v[50:53], v[172:175], v[188:191], v[50:53]
	v_mfma_f32_16x16x32_bf16 v[42:45], v[180:183], v[188:191], v[42:45]
	v_mfma_f32_16x16x32_bf16 v[34:37], v[172:175], v[196:199], v[34:37]
	v_mfma_f32_16x16x32_bf16 v[26:29], v[180:183], v[196:199], v[26:29]
	v_mfma_f32_16x16x32_bf16 v[18:21], v[172:175], v[204:207], v[18:21]
	v_mfma_f32_16x16x32_bf16 v[10:13], v[180:183], v[204:207], v[10:13]
	v_mfma_f32_16x16x32_bf16 v[6:9], v[172:175], v[212:215], v[6:9]
	v_mfma_f32_16x16x32_bf16 v[2:5], v[180:183], v[212:215], v[2:5]
	s_setprio 2
	s_barrier
	s_add_i32 s68, s68, 2
	s_add_u32 s40, s40, 0x100
	s_addc_u32 s41, s41, 0
	s_add_u32 s66, s66, 0x100
	s_addc_u32 s67, s67, 0
	s_cmp_gt_u32 s68, 61
	s_cbranch_scc0 .LBB0_1825
	s_and_b64 vcc, exec, s[8:9]
	s_cbranch_vccz .LBB0_1828
	s_barrier

; #define PG8_STAGE(bufoff, gbase, voff) do { _Pragma("unroll") for (int _i = 0; _i < 2; ++_i) \
;         __builtin_amdgcn_global_load_lds((const unsigned*)((const char*)(gbase) + (voff)[_i]), (LAS unsigned*)(lds + (bufoff) + ldsw + _i * 8192), 16, 0, 0); } while (0)
; #define PG8_LDA(dst, b, h) do { _Pragma("unroll") for (int m = 0; m < 4; ++m) _Pragma("unroll") for (int k = 0; k < 2; ++k) dst[m][k] = *(const LAS bf16x8*)(lds + PG8_SA(b, h) + aoff + m * 2048 + k * 1024); } while (0)
; #define PG8_LDB(dst, b, h) do { _Pragma("unroll") for (int n = 0; n < 2; ++n) _Pragma("unroll") for (int k = 0; k < 2; ++k) dst[n][k] = *(const LAS bf16x8*)(lds + PG8_SB(b, h) + boff + n * 2048 + k * 1024); } while (0)
; #define PG8_MMA(ai, bj, At, Bt) do { __builtin_amdgcn_s_setprio(1); _Pragma("unroll") for (int m = 0; m < 4; ++m) _Pragma("unroll") for (int n = 0; n < 2; ++n) _Pragma("unroll") for (int k = 0; k < 2; ++k) \
;         acc[ai][bj][m][n] = __builtin_amdgcn_mfma_f32_16x16x32_bf16(Bt[n][k], At[m][k], acc[ai][bj][m][n], 0, 0, 0); __builtin_amdgcn_s_setprio(0); } while (0)
; #define PG8_WAIT_V(n) asm volatile("s_waitcnt vmcnt(" #n ")" ::: "memory")
; #define PG8_WAIT_L(n) asm volatile("s_waitcnt lgkmcnt(" #n ")" ::: "memory")
; #define PG8_BAR __builtin_amdgcn_s_barrier()
; #define PG8_SCHED __builtin_amdgcn_sched_barrier(0)
; template <class Epi>
; __device__ __forceinline__ void gemm_phase(LAS unsigned char* lds, const Gemm g, int G, int c, const Epi& E) {
;     ...
;         for (int t = 0; t < nt; t += 2) {
;             const bool last = (t == nt - 2);
;             const char* a1 = cA + (size_t)(t + 1) * kstep;
;             const char* a2 = last ? nA : cA + (size_t)(t + 2) * kstep; const char* b2 = last ? nB : cB + (size_t)(t + 2) * kstep;
;             const char* a3 = a2 + kstep; const char* b3 = b2 + kstep;
;             PG8_LDB(B0, 0, 0); PG8_LDB(B1, 0, 1); PG8_SCHED; PG8_LDA(At, 0, 0); PG8_STAGE(PG8_SA(1, 1), a1 + hstepA, voffA);
;             PG8_WAIT_V(8); PG8_WAIT_L(0); PG8_BAR; PG8_MMA(0, 0, At, B0); PG8_MMA(0, 1, At, B1); PG8_BAR; PG8_SCHED;
;             PG8_LDA(At, 0, 1); PG8_STAGE(PG8_SB(0, 0), b2, voffB); PG8_STAGE(PG8_SB(0, 1), b2 + hstepB, voffB); PG8_STAGE(PG8_SA(0, 0), a2, voffA);
.LBB0_1931:
	ds_read_b128 v[122:125], v168
	ds_read_b128 v[126:129], v168 offset:1024
	ds_read_b128 v[130:133], v168 offset:2048
	ds_read_b128 v[134:137], v168 offset:3072
	ds_read_b128 v[162:165], v169
	ds_read_b128 v[172:175], v169 offset:1024
	ds_read_b128 v[176:179], v169 offset:2048
	ds_read_b128 v[180:183], v169 offset:3072
	s_add_u32 s33, s4, 0xfffc0080
	s_addc_u32 s36, s5, -1
	s_cmp_eq_u32 s62, 12
	s_cselect_b32 s39, s19, s36
	s_cselect_b32 s38, s18, s33
	s_cselect_b32 s37, s15, s61
	s_cselect_b32 s36, s17, s60
	v_lshl_add_u64 v[216:217], s[4:5], 0, v[154:155]
	s_add_i32 m0, s23, 0xc000
	ds_read_b128 v[184:187], v170
	ds_read_b128 v[188:191], v170 offset:1024
	ds_read_b128 v[192:195], v170 offset:2048
	ds_read_b128 v[196:199], v170 offset:3072
	ds_read_b128 v[200:203], v170 offset:4096
	ds_read_b128 v[204:207], v170 offset:5120
	ds_read_b128 v[208:211], v170 offset:6144
	ds_read_b128 v[212:215], v170 offset:7168
	global_load_lds_dwordx4 v[216:217], off
	v_lshl_add_u64 v[216:217], s[4:5], 0, v[156:157]
	s_add_i32 m0, s23, 0xe000
	s_nop 0
	global_load_lds_dwordx4 v[216:217], off
	s_waitcnt vmcnt(8)
	s_waitcnt lgkmcnt(0)
	s_barrier
	s_setprio 0
	s_waitcnt lgkmcnt(0)
	v_mfma_f32_16x16x32_bf16 v[142:145], v[122:125], v[184:187], v[142:145]
	v_mfma_f32_16x16x32_bf16 v[138:141], v[130:133], v[184:187], v[138:141]
	v_mfma_f32_16x16x32_bf16 v[118:121], v[122:125], v[192:195], v[118:121]
	v_mfma_f32_16x16x32_bf16 v[106:109], v[130:133], v[192:195], v[106:109]
	v_mfma_f32_16x16x32_bf16 v[102:105], v[122:125], v[200:203], v[102:105]
	v_mfma_f32_16x16x32_bf16 v[90:93], v[130:133], v[200:203], v[90:93]
	v_mfma_f32_16x16x32_bf16 v[86:89], v[122:125], v[208:211], v[86:89]
	v_mfma_f32_16x16x32_bf16 v[74:77], v[130:133], v[208:211], v[74:77]
	v_mfma_f32_16x16x32_bf16 v[142:145], v[126:129], v[188:191], v[142:145]
	v_mfma_f32_16x16x32_bf16 v[138:141], v[134:137], v[188:191], v[138:141]
	v_mfma_f32_16x16x32_bf16 v[118:121], v[126:129], v[196:199], v[118:121]
	v_mfma_f32_16x16x32_bf16 v[106:109], v[134:137], v[196:199], v[106:109]
	v_mfma_f32_16x16x32_bf16 v[102:105], v[126:129], v[204:207], v[102:105]
	v_mfma_f32_16x16x32_bf16 v[90:93], v[134:137], v[204:207], v[90:93]
	v_mfma_f32_16x16x32_bf16 v[86:89], v[126:129], v[212:215], v[86:89]
	v_mfma_f32_16x16x32_bf16 v[74:77], v[134:137], v[212:215], v[74:77]
	s_setprio 2
	s_setprio 0
	v_mfma_f32_16x16x32_bf16 v[114:117], v[162:165], v[184:187], v[114:117]
	v_mfma_f32_16x16x32_bf16 v[110:113], v[176:179], v[184:187], v[110:113]
	v_mfma_f32_16x16x32_bf16 v[98:101], v[162:165], v[192:195], v[98:101]
	v_mfma_f32_16x16x32_bf16 v[94:97], v[176:179], v[192:195], v[94:97]
	v_mfma_f32_16x16x32_bf16 v[82:85], v[162:165], v[200:203], v[82:85]
	v_mfma_f32_16x16x32_bf16 v[78:81], v[176:179], v[200:203], v[78:81]
	v_mfma_f32_16x16x32_bf16 v[70:73], v[162:165], v[208:211], v[70:73]
	v_mfma_f32_16x16x32_bf16 v[66:69], v[176:179], v[208:211], v[66:69]
	v_mfma_f32_16x16x32_bf16 v[114:117], v[172:175], v[188:191], v[114:117]
	v_mfma_f32_16x16x32_bf16 v[110:113], v[180:183], v[188:191], v[110:113]
	v_mfma_f32_16x16x32_bf16 v[98:101], v[172:175], v[196:199], v[98:101]
	v_mfma_f32_16x16x32_bf16 v[94:97], v[180:183], v[196:199], v[94:97]
	v_mfma_f32_16x16x32_bf16 v[82:85], v[172:175], v[204:207], v[82:85]
	v_mfma_f32_16x16x32_bf16 v[78:81], v[180:183], v[204:207], v[78:81]
	v_mfma_f32_16x16x32_bf16 v[70:73], v[172:175], v[212:215], v[70:73]
	v_mfma_f32_16x16x32_bf16 v[66:69], v[180:183], v[212:215], v[66:69]
	s_setprio 2
	s_barrier
	s_add_i32 s33, s56, s42
	v_lshl_add_u64 v[216:217], s[36:37], 0, v[150:151]
	s_mov_b32 m0, s33
	ds_read_b128 v[184:187], v170 offset:16384
	ds_read_b128 v[188:191], v170 offset:17408
	ds_read_b128 v[192:195], v170 offset:18432
	ds_read_b128 v[196:199], v170 offset:19456
	ds_read_b128 v[200:203], v170 offset:20480
	ds_read_b128 v[204:207], v170 offset:21504
	ds_read_b128 v[208:211], v170 offset:22528
	ds_read_b128 v[212:215], v170 offset:23552
	global_load_lds_dwordx4 v[216:217], off
	s_add_i32 m0, s33, 0x2000
	s_add_u32 s64, s36, 0x40000
	v_lshl_add_u64 v[218:219], s[36:37], 0, v[146:147]
	s_addc_u32 s65, s37, 0
	s_add_i32 s33, s57, s42
	global_load_lds_dwordx4 v[218:219], off
	v_lshl_add_u64 v[220:221], s[64:65], 0, v[150:151]
	s_mov_b32 m0, s33
	v_lshl_add_u64 v[222:223], s[38:39], 0, v[148:149]
	global_load_lds_dwordx4 v[220:221], off
	v_lshl_add_u64 v[220:221], s[64:65], 0, v[146:147]
	s_add_i32 m0, s33, 0x2000
	s_nop 0
	global_load_lds_dwordx4 v[220:221], off
	v_lshl_add_u64 v[220:221], s[38:39], 0, v[152:153]
	s_mov_b32 m0, s23
	s_nop 0
	global_load_lds_dwordx4 v[220:221], off
	s_mov_b32 m0, s25
	s_nop 0
	global_load_lds_dwordx4 v[222:223], off
	s_waitcnt vmcnt(8)
	s_waitcnt lgkmcnt(0)
	s_barrier
; #define PG8_STAGE(bufoff, gbase, voff) do { _Pragma("unroll") for (int _i = 0; _i < 2; ++_i) \
;         __builtin_amdgcn_global_load_lds((const unsigned*)((const char*)(gbase) + (voff)[_i]), (LAS unsigned*)(lds + (bufoff) + ldsw + _i * 8192), 16, 0, 0); } while (0)
; #define PG8_LDA(dst, b, h) do { _Pragma("unroll") for (int m = 0; m < 4; ++m) _Pragma("unroll") for (int k = 0; k < 2; ++k) dst[m][k] = *(const LAS bf16x8*)(lds + PG8_SA(b, h) + aoff + m * 2048 + k * 1024); } while (0)
; #define PG8_LDB(dst, b, h) do { _Pragma("unroll") for (int n = 0; n < 2; ++n) _Pragma("unroll") for (int k = 0; k < 2; ++k) dst[n][k] = *(const LAS bf16x8*)(lds + PG8_SB(b, h) + boff + n * 2048 + k * 1024); } while (0)
; #define PG8_MMA(ai, bj, At, Bt) do { __builtin_amdgcn_s_setprio(1); _Pragma("unroll") for (int m = 0; m < 4; ++m) _Pragma("unroll") for (int n = 0; n < 2; ++n) _Pragma("unroll") for (int k = 0; k < 2; ++k) \
;         acc[ai][bj][m][n] = __builtin_amdgcn_mfma_f32_16x16x32_bf16(Bt[n][k], At[m][k], acc[ai][bj][m][n], 0, 0, 0); __builtin_amdgcn_s_setprio(0); } while (0)
; #define PG8_WAIT_V(n) asm volatile("s_waitcnt vmcnt(" #n ")" ::: "memory")
; #define PG8_WAIT_L(n) asm volatile("s_waitcnt lgkmcnt(" #n ")" ::: "memory")
; #define PG8_BAR __builtin_amdgcn_s_barrier()
; #define PG8_SCHED __builtin_amdgcn_sched_barrier(0)
; template <class Epi>
; __device__ __forceinline__ void gemm_phase(LAS unsigned char* lds, const Gemm g, int G, int c, const Epi& E) {
;     ...
;             PG8_WAIT_V(8); PG8_WAIT_L(0); PG8_BAR; PG8_MMA(1, 0, At, B0); PG8_MMA(1, 1, At, B1); PG8_BAR; PG8_SCHED;
;             PG8_LDB(B0, 1, 0); PG8_LDB(B1, 1, 1); PG8_SCHED; PG8_LDA(At, 1, 0); PG8_STAGE(PG8_SA(0, 1), a2 + hstepA, voffA);
;             PG8_WAIT_V(8); PG8_WAIT_L(0); PG8_BAR; PG8_MMA(0, 0, At, B0); PG8_MMA(0, 1, At, B1); PG8_BAR; PG8_SCHED;
	s_setprio 0
	s_waitcnt lgkmcnt(0)
	v_mfma_f32_16x16x32_bf16 v[62:65], v[122:125], v[184:187], v[62:65]
	v_mfma_f32_16x16x32_bf16 v[58:61], v[130:133], v[184:187], v[58:61]
	v_mfma_f32_16x16x32_bf16 v[54:57], v[122:125], v[192:195], v[54:57]
	v_mfma_f32_16x16x32_bf16 v[42:45], v[130:133], v[192:195], v[42:45]
	v_mfma_f32_16x16x32_bf16 v[38:41], v[122:125], v[200:203], v[38:41]
	v_mfma_f32_16x16x32_bf16 v[26:29], v[130:133], v[200:203], v[26:29]
	v_mfma_f32_16x16x32_bf16 v[22:25], v[122:125], v[208:211], v[22:25]
	v_mfma_f32_16x16x32_bf16 v[10:13], v[130:133], v[208:211], v[10:13]
	v_mfma_f32_16x16x32_bf16 v[62:65], v[126:129], v[188:191], v[62:65]
	v_mfma_f32_16x16x32_bf16 v[58:61], v[134:137], v[188:191], v[58:61]
	v_mfma_f32_16x16x32_bf16 v[54:57], v[126:129], v[196:199], v[54:57]
	v_mfma_f32_16x16x32_bf16 v[42:45], v[134:137], v[196:199], v[42:45]
	v_mfma_f32_16x16x32_bf16 v[38:41], v[126:129], v[204:207], v[38:41]
	v_mfma_f32_16x16x32_bf16 v[26:29], v[134:137], v[204:207], v[26:29]
	v_mfma_f32_16x16x32_bf16 v[22:25], v[126:129], v[212:215], v[22:25]
	v_mfma_f32_16x16x32_bf16 v[10:13], v[134:137], v[212:215], v[10:13]
	s_setprio 2
	s_setprio 0
	v_mfma_f32_16x16x32_bf16 v[50:53], v[162:165], v[184:187], v[50:53]
	v_mfma_f32_16x16x32_bf16 v[46:49], v[176:179], v[184:187], v[46:49]
	v_mfma_f32_16x16x32_bf16 v[34:37], v[162:165], v[192:195], v[34:37]
	v_mfma_f32_16x16x32_bf16 v[30:33], v[176:179], v[192:195], v[30:33]
	v_mfma_f32_16x16x32_bf16 v[18:21], v[162:165], v[200:203], v[18:21]
	v_mfma_f32_16x16x32_bf16 v[14:17], v[176:179], v[200:203], v[14:17]
	v_mfma_f32_16x16x32_bf16 v[6:9], v[162:165], v[208:211], v[6:9]
	v_mfma_f32_16x16x32_bf16 v[2:5], v[176:179], v[208:211], v[2:5]
	v_mfma_f32_16x16x32_bf16 v[50:53], v[172:175], v[188:191], v[50:53]
	v_mfma_f32_16x16x32_bf16 v[46:49], v[180:183], v[188:191], v[46:49]
	v_mfma_f32_16x16x32_bf16 v[34:37], v[172:175], v[196:199], v[34:37]
	v_mfma_f32_16x16x32_bf16 v[30:33], v[180:183], v[196:199], v[30:33]
	v_mfma_f32_16x16x32_bf16 v[18:21], v[172:175], v[204:207], v[18:21]
	v_mfma_f32_16x16x32_bf16 v[14:17], v[180:183], v[204:207], v[14:17]
	v_mfma_f32_16x16x32_bf16 v[6:9], v[172:175], v[212:215], v[6:9]
	v_mfma_f32_16x16x32_bf16 v[2:5], v[180:183], v[212:215], v[2:5]
	s_setprio 2
	s_barrier
	s_add_i32 s33, 0, 0x18000
	s_add_i32 s63, 0, 0x1c000
	v_add_u32_e32 v134, s33, v167
	v_add_u32_e32 v171, s63, v167
	ds_read_b128 v[122:125], v134
	ds_read_b128 v[126:129], v134 offset:1024
	ds_read_b128 v[130:133], v134 offset:2048
	ds_read_b128 v[134:137], v134 offset:3072
	ds_read_b128 v[162:165], v171
	ds_read_b128 v[172:175], v171 offset:1024
	ds_read_b128 v[176:179], v171 offset:2048
	ds_read_b128 v[180:183], v171 offset:3072
	s_add_u32 s38, s38, 0x40000
	s_addc_u32 s39, s39, 0
	s_mov_b32 m0, s44
	v_lshl_add_u64 v[224:225], s[38:39], 0, v[152:153]
	ds_read_b128 v[184:187], v170 offset:32768
	ds_read_b128 v[188:191], v170 offset:33792
	ds_read_b128 v[192:195], v170 offset:34816
	ds_read_b128 v[196:199], v170 offset:35840
	ds_read_b128 v[200:203], v170 offset:36864
	ds_read_b128 v[204:207], v170 offset:37888
	ds_read_b128 v[208:211], v170 offset:38912
	ds_read_b128 v[212:215], v170 offset:39936
	global_load_lds_dwordx4 v[224:225], off
	v_lshl_add_u64 v[224:225], s[38:39], 0, v[148:149]
	s_mov_b32 m0, s45
	s_nop 0
	global_load_lds_dwordx4 v[224:225], off
	s_waitcnt vmcnt(8)
	s_waitcnt lgkmcnt(0)
	s_barrier
	s_setprio 0
	s_waitcnt lgkmcnt(0)
	v_mfma_f32_16x16x32_bf16 v[142:145], v[122:125], v[184:187], v[142:145]
	v_mfma_f32_16x16x32_bf16 v[138:141], v[130:133], v[184:187], v[138:141]
	v_mfma_f32_16x16x32_bf16 v[118:121], v[122:125], v[192:195], v[118:121]
	v_mfma_f32_16x16x32_bf16 v[106:109], v[130:133], v[192:195], v[106:109]
	v_mfma_f32_16x16x32_bf16 v[102:105], v[122:125], v[200:203], v[102:105]
	v_mfma_f32_16x16x32_bf16 v[90:93], v[130:133], v[200:203], v[90:93]
	v_mfma_f32_16x16x32_bf16 v[86:89], v[122:125], v[208:211], v[86:89]
	v_mfma_f32_16x16x32_bf16 v[74:77], v[130:133], v[208:211], v[74:77]
	v_mfma_f32_16x16x32_bf16 v[142:145], v[126:129], v[188:191], v[142:145]
	v_mfma_f32_16x16x32_bf16 v[138:141], v[134:137], v[188:191], v[138:141]
	v_mfma_f32_16x16x32_bf16 v[118:121], v[126:129], v[196:199], v[118:121]
	v_mfma_f32_16x16x32_bf16 v[106:109], v[134:137], v[196:199], v[106:109]
	v_mfma_f32_16x16x32_bf16 v[102:105], v[126:129], v[204:207], v[102:105]
	v_mfma_f32_16x16x32_bf16 v[90:93], v[134:137], v[204:207], v[90:93]
	v_mfma_f32_16x16x32_bf16 v[86:89], v[126:129], v[212:215], v[86:89]
	v_mfma_f32_16x16x32_bf16 v[74:77], v[134:137], v[212:215], v[74:77]
	s_setprio 2
	s_setprio 0
	v_mfma_f32_16x16x32_bf16 v[114:117], v[162:165], v[184:187], v[114:117]
	v_mfma_f32_16x16x32_bf16 v[110:113], v[176:179], v[184:187], v[110:113]
	v_mfma_f32_16x16x32_bf16 v[98:101], v[162:165], v[192:195], v[98:101]
	v_mfma_f32_16x16x32_bf16 v[94:97], v[176:179], v[192:195], v[94:97]
	v_mfma_f32_16x16x32_bf16 v[82:85], v[162:165], v[200:203], v[82:85]
	v_mfma_f32_16x16x32_bf16 v[78:81], v[176:179], v[200:203], v[78:81]
	v_mfma_f32_16x16x32_bf16 v[70:73], v[162:165], v[208:211], v[70:73]
	v_mfma_f32_16x16x32_bf16 v[66:69], v[176:179], v[208:211], v[66:69]
	v_mfma_f32_16x16x32_bf16 v[114:117], v[172:175], v[188:191], v[114:117]
	v_mfma_f32_16x16x32_bf16 v[110:113], v[180:183], v[188:191], v[110:113]
	v_mfma_f32_16x16x32_bf16 v[98:101], v[172:175], v[196:199], v[98:101]
	v_mfma_f32_16x16x32_bf16 v[94:97], v[180:183], v[196:199], v[94:97]
	v_mfma_f32_16x16x32_bf16 v[82:85], v[172:175], v[204:207], v[82:85]
	v_mfma_f32_16x16x32_bf16 v[78:81], v[180:183], v[204:207], v[78:81]
	v_mfma_f32_16x16x32_bf16 v[70:73], v[172:175], v[212:215], v[70:73]
	v_mfma_f32_16x16x32_bf16 v[66:69], v[180:183], v[212:215], v[66:69]
	s_setprio 2
	s_barrier
; #define PG8_STAGE(bufoff, gbase, voff) do { _Pragma("unroll") for (int _i = 0; _i < 2; ++_i) \
;         __builtin_amdgcn_global_load_lds((const unsigned*)((const char*)(gbase) + (voff)[_i]), (LAS unsigned*)(lds + (bufoff) + ldsw + _i * 8192), 16, 0, 0); } while (0)
; #define PG8_LDA(dst, b, h) do { _Pragma("unroll") for (int m = 0; m < 4; ++m) _Pragma("unroll") for (int k = 0; k < 2; ++k) dst[m][k] = *(const LAS bf16x8*)(lds + PG8_SA(b, h) + aoff + m * 2048 + k * 1024); } while (0)
; #define PG8_MMA(ai, bj, At, Bt) do { __builtin_amdgcn_s_setprio(1); _Pragma("unroll") for (int m = 0; m < 4; ++m) _Pragma("unroll") for (int n = 0; n < 2; ++n) _Pragma("unroll") for (int k = 0; k < 2; ++k) \
;         acc[ai][bj][m][n] = __builtin_amdgcn_mfma_f32_16x16x32_bf16(Bt[n][k], At[m][k], acc[ai][bj][m][n], 0, 0, 0); __builtin_amdgcn_s_setprio(0); } while (0)
; #define PG8_WAIT_V(n) asm volatile("s_waitcnt vmcnt(" #n ")" ::: "memory")
; #define PG8_WAIT_L(n) asm volatile("s_waitcnt lgkmcnt(" #n ")" ::: "memory")
; #define PG8_BAR __builtin_amdgcn_s_barrier()
; #define PG8_SCHED __builtin_amdgcn_sched_barrier(0)
; template <class Epi>
; __device__ __forceinline__ void gemm_phase(LAS unsigned char* lds, const Gemm g, int G, int c, const Epi& E) {
;     ...
;             PG8_LDA(At, 1, 1); PG8_STAGE(PG8_SB(1, 0), b3, voffB); PG8_STAGE(PG8_SB(1, 1), b3 + hstepB, voffB); PG8_STAGE(PG8_SA(1, 0), a3, voffA);
;             PG8_WAIT_V(8); PG8_WAIT_L(0); PG8_BAR; PG8_MMA(1, 0, At, B0); PG8_MMA(1, 1, At, B1); PG8_BAR; PG8_SCHED;
;         }
;         if (wr == 0) PG8_BAR;
	s_add_i32 s33, s33, s42
	v_lshl_add_u64 v[216:217], v[216:217], 0, s[10:11]
	s_mov_b32 m0, s33
	ds_read_b128 v[184:187], v170 offset:49152
	ds_read_b128 v[188:191], v170 offset:50176
	ds_read_b128 v[192:195], v170 offset:51200
	ds_read_b128 v[196:199], v170 offset:52224
	ds_read_b128 v[200:203], v170 offset:53248
	ds_read_b128 v[204:207], v170 offset:54272
	ds_read_b128 v[208:211], v170 offset:55296
	ds_read_b128 v[212:215], v170 offset:56320
	global_load_lds_dwordx4 v[216:217], off
	s_add_i32 m0, s33, 0x2000
	s_add_u32 s36, s36, 0x40080
	v_lshl_add_u64 v[216:217], v[218:219], 0, s[10:11]
	s_addc_u32 s37, s37, 0
	s_add_i32 s33, s63, s42
	global_load_lds_dwordx4 v[216:217], off
	v_lshl_add_u64 v[216:217], s[36:37], 0, v[150:151]
	s_mov_b32 m0, s33
	s_nop 0
	global_load_lds_dwordx4 v[216:217], off
	v_lshl_add_u64 v[216:217], s[36:37], 0, v[146:147]
	s_add_i32 m0, s33, 0x2000
	s_nop 0
	global_load_lds_dwordx4 v[216:217], off
	v_lshl_add_u64 v[216:217], v[220:221], 0, s[10:11]
	s_mov_b32 m0, s53
	s_nop 0
	global_load_lds_dwordx4 v[216:217], off
	v_lshl_add_u64 v[216:217], v[222:223], 0, s[10:11]
	s_mov_b32 m0, s54
	s_nop 0
	global_load_lds_dwordx4 v[216:217], off
	s_waitcnt vmcnt(8)
	s_waitcnt lgkmcnt(0)
	s_barrier
	s_setprio 0
	s_waitcnt lgkmcnt(0)
	v_mfma_f32_16x16x32_bf16 v[62:65], v[122:125], v[184:187], v[62:65]
	v_mfma_f32_16x16x32_bf16 v[58:61], v[130:133], v[184:187], v[58:61]
	v_mfma_f32_16x16x32_bf16 v[54:57], v[122:125], v[192:195], v[54:57]
	v_mfma_f32_16x16x32_bf16 v[42:45], v[130:133], v[192:195], v[42:45]
	v_mfma_f32_16x16x32_bf16 v[38:41], v[122:125], v[200:203], v[38:41]
	v_mfma_f32_16x16x32_bf16 v[26:29], v[130:133], v[200:203], v[26:29]
	v_mfma_f32_16x16x32_bf16 v[22:25], v[122:125], v[208:211], v[22:25]
	v_mfma_f32_16x16x32_bf16 v[10:13], v[130:133], v[208:211], v[10:13]
	v_mfma_f32_16x16x32_bf16 v[62:65], v[126:129], v[188:191], v[62:65]
	v_mfma_f32_16x16x32_bf16 v[58:61], v[134:137], v[188:191], v[58:61]
	v_mfma_f32_16x16x32_bf16 v[54:57], v[126:129], v[196:199], v[54:57]
	v_mfma_f32_16x16x32_bf16 v[42:45], v[134:137], v[196:199], v[42:45]
	v_mfma_f32_16x16x32_bf16 v[38:41], v[126:129], v[204:207], v[38:41]
	v_mfma_f32_16x16x32_bf16 v[26:29], v[134:137], v[204:207], v[26:29]
	v_mfma_f32_16x16x32_bf16 v[22:25], v[126:129], v[212:215], v[22:25]
	v_mfma_f32_16x16x32_bf16 v[10:13], v[134:137], v[212:215], v[10:13]
	s_setprio 2
	s_setprio 0
	v_mfma_f32_16x16x32_bf16 v[50:53], v[162:165], v[184:187], v[50:53]
	v_mfma_f32_16x16x32_bf16 v[46:49], v[176:179], v[184:187], v[46:49]
	v_mfma_f32_16x16x32_bf16 v[34:37], v[162:165], v[192:195], v[34:37]
	v_mfma_f32_16x16x32_bf16 v[30:33], v[176:179], v[192:195], v[30:33]
	v_mfma_f32_16x16x32_bf16 v[18:21], v[162:165], v[200:203], v[18:21]
	v_mfma_f32_16x16x32_bf16 v[14:17], v[176:179], v[200:203], v[14:17]
	v_mfma_f32_16x16x32_bf16 v[6:9], v[162:165], v[208:211], v[6:9]
	v_mfma_f32_16x16x32_bf16 v[2:5], v[176:179], v[208:211], v[2:5]
	v_mfma_f32_16x16x32_bf16 v[50:53], v[172:175], v[188:191], v[50:53]
	v_mfma_f32_16x16x32_bf16 v[46:49], v[180:183], v[188:191], v[46:49]
	v_mfma_f32_16x16x32_bf16 v[34:37], v[172:175], v[196:199], v[34:37]
	v_mfma_f32_16x16x32_bf16 v[30:33], v[180:183], v[196:199], v[30:33]
	v_mfma_f32_16x16x32_bf16 v[18:21], v[172:175], v[204:207], v[18:21]
	v_mfma_f32_16x16x32_bf16 v[14:17], v[180:183], v[204:207], v[14:17]
	v_mfma_f32_16x16x32_bf16 v[6:9], v[172:175], v[212:215], v[6:9]
	v_mfma_f32_16x16x32_bf16 v[2:5], v[180:183], v[212:215], v[2:5]
	s_setprio 2
	s_barrier
	s_add_i32 s62, s62, 2
	s_add_u32 s4, s4, 0x100
	s_addc_u32 s5, s5, 0
	s_add_u32 s60, s60, 0x100
	s_addc_u32 s61, s61, 0
	s_cmp_gt_u32 s62, 13
	s_cbranch_scc0 .LBB0_1931
	s_and_b64 vcc, exec, s[12:13]
	s_cbranch_vccz .LBB0_1934
	s_barrier

; #define PG8_STAGE(bufoff, gbase, voff) do { _Pragma("unroll") for (int _i = 0; _i < 2; ++_i) \
;         __builtin_amdgcn_global_load_lds((const unsigned*)((const char*)(gbase) + (voff)[_i]), (LAS unsigned*)(lds + (bufoff) + ldsw + _i * 8192), 16, 0, 0); } while (0)
; #define PG8_LDA(dst, b, h) do { _Pragma("unroll") for (int m = 0; m < 4; ++m) _Pragma("unroll") for (int k = 0; k < 2; ++k) dst[m][k] = *(const LAS bf16x8*)(lds + PG8_SA(b, h) + aoff + m * 2048 + k * 1024); } while (0)
; #define PG8_LDB(dst, b, h) do { _Pragma("unroll") for (int n = 0; n < 2; ++n) _Pragma("unroll") for (int k = 0; k < 2; ++k) dst[n][k] = *(const LAS bf16x8*)(lds + PG8_SB(b, h) + boff + n * 2048 + k * 1024); } while (0)
; #define PG8_MMA(ai, bj, At, Bt) do { __builtin_amdgcn_s_setprio(1); _Pragma("unroll") for (int m = 0; m < 4; ++m) _Pragma("unroll") for (int n = 0; n < 2; ++n) _Pragma("unroll") for (int k = 0; k < 2; ++k) \
;         acc[ai][bj][m][n] = __builtin_amdgcn_mfma_f32_16x16x32_bf16(Bt[n][k], At[m][k], acc[ai][bj][m][n], 0, 0, 0); __builtin_amdgcn_s_setprio(0); } while (0)
; #define PG8_WAIT_V(n) asm volatile("s_waitcnt vmcnt(" #n ")" ::: "memory")
; #define PG8_WAIT_L(n) asm volatile("s_waitcnt lgkmcnt(" #n ")" ::: "memory")
; #define PG8_BAR __builtin_amdgcn_s_barrier()
; #define PG8_SCHED __builtin_amdgcn_sched_barrier(0)
; template <class Epi>
; __device__ __forceinline__ void gemm_phase(LAS unsigned char* lds, const Gemm g, int G, int c, const Epi& E) {
;     ...
;         for (int t = 0; t < nt; t += 2) {
;             const bool last = (t == nt - 2);
;             const char* a1 = cA + (size_t)(t + 1) * kstep;
;             const char* a2 = last ? nA : cA + (size_t)(t + 2) * kstep; const char* b2 = last ? nB : cB + (size_t)(t + 2) * kstep;
;             const char* a3 = a2 + kstep; const char* b3 = b2 + kstep;
;             PG8_LDB(B0, 0, 0); PG8_LDB(B1, 0, 1); PG8_SCHED; PG8_LDA(At, 0, 0); PG8_STAGE(PG8_SA(1, 1), a1 + hstepA, voffA);
;             PG8_WAIT_V(8); PG8_WAIT_L(0); PG8_BAR; PG8_MMA(0, 0, At, B0); PG8_MMA(0, 1, At, B1); PG8_BAR; PG8_SCHED;
;             PG8_LDA(At, 0, 1); PG8_STAGE(PG8_SB(0, 0), b2, voffB); PG8_STAGE(PG8_SB(0, 1), b2 + hstepB, voffB); PG8_STAGE(PG8_SA(0, 0), a2, voffA);
.LBB0_2084:
	ds_read_b128 v[152:155], v148
	ds_read_b128 v[156:159], v148 offset:1024
	ds_read_b128 v[160:163], v148 offset:2048
	ds_read_b128 v[164:167], v148 offset:3072
	ds_read_b128 v[168:171], v149
	ds_read_b128 v[172:175], v149 offset:1024
	ds_read_b128 v[176:179], v149 offset:2048
	ds_read_b128 v[180:183], v149 offset:3072
	s_add_u32 s33, s4, 0xfffc0080
	s_addc_u32 s38, s5, -1
	s_cmp_eq_u32 s68, 12
	s_cselect_b32 s41, s21, s38
	s_cselect_b32 s40, s20, s33
	s_cselect_b32 s39, s17, s67
	s_cselect_b32 s38, s19, s66
	v_lshl_add_u64 v[216:217], s[4:5], 0, v[138:139]
	s_add_i32 m0, s25, 0xc000
	ds_read_b128 v[184:187], v150
	ds_read_b128 v[188:191], v150 offset:1024
	ds_read_b128 v[192:195], v150 offset:2048
	ds_read_b128 v[196:199], v150 offset:3072
	ds_read_b128 v[200:203], v150 offset:4096
	ds_read_b128 v[204:207], v150 offset:5120
	ds_read_b128 v[208:211], v150 offset:6144
	ds_read_b128 v[212:215], v150 offset:7168
	global_load_lds_dwordx4 v[216:217], off
	v_lshl_add_u64 v[216:217], s[4:5], 0, v[140:141]
	s_add_i32 m0, s25, 0xe000
	s_nop 0
	global_load_lds_dwordx4 v[216:217], off
	s_waitcnt vmcnt(8)
	s_waitcnt lgkmcnt(0)
	s_barrier
	s_setprio 0
	s_waitcnt lgkmcnt(0)
	v_mfma_f32_16x16x32_bf16 v[126:129], v[152:155], v[184:187], v[126:129]
	v_mfma_f32_16x16x32_bf16 v[122:125], v[160:163], v[184:187], v[122:125]
	v_mfma_f32_16x16x32_bf16 v[110:113], v[152:155], v[192:195], v[110:113]
	v_mfma_f32_16x16x32_bf16 v[106:109], v[160:163], v[192:195], v[106:109]
	v_mfma_f32_16x16x32_bf16 v[94:97], v[152:155], v[200:203], v[94:97]
	v_mfma_f32_16x16x32_bf16 v[90:93], v[160:163], v[200:203], v[90:93]
	v_mfma_f32_16x16x32_bf16 v[78:81], v[152:155], v[208:211], v[78:81]
	v_mfma_f32_16x16x32_bf16 v[74:77], v[160:163], v[208:211], v[74:77]
	v_mfma_f32_16x16x32_bf16 v[126:129], v[156:159], v[188:191], v[126:129]
	v_mfma_f32_16x16x32_bf16 v[122:125], v[164:167], v[188:191], v[122:125]
	v_mfma_f32_16x16x32_bf16 v[110:113], v[156:159], v[196:199], v[110:113]
	v_mfma_f32_16x16x32_bf16 v[106:109], v[164:167], v[196:199], v[106:109]
	v_mfma_f32_16x16x32_bf16 v[94:97], v[156:159], v[204:207], v[94:97]
	v_mfma_f32_16x16x32_bf16 v[90:93], v[164:167], v[204:207], v[90:93]
	v_mfma_f32_16x16x32_bf16 v[78:81], v[156:159], v[212:215], v[78:81]
	v_mfma_f32_16x16x32_bf16 v[74:77], v[164:167], v[212:215], v[74:77]
	s_setprio 2
	s_setprio 0
	v_mfma_f32_16x16x32_bf16 v[118:121], v[168:171], v[184:187], v[118:121]
	v_mfma_f32_16x16x32_bf16 v[114:117], v[176:179], v[184:187], v[114:117]
	v_mfma_f32_16x16x32_bf16 v[102:105], v[168:171], v[192:195], v[102:105]
	v_mfma_f32_16x16x32_bf16 v[98:101], v[176:179], v[192:195], v[98:101]
	v_mfma_f32_16x16x32_bf16 v[86:89], v[168:171], v[200:203], v[86:89]
	v_mfma_f32_16x16x32_bf16 v[82:85], v[176:179], v[200:203], v[82:85]
	v_mfma_f32_16x16x32_bf16 v[70:73], v[168:171], v[208:211], v[70:73]
	v_mfma_f32_16x16x32_bf16 v[66:69], v[176:179], v[208:211], v[66:69]
	v_mfma_f32_16x16x32_bf16 v[118:121], v[172:175], v[188:191], v[118:121]
	v_mfma_f32_16x16x32_bf16 v[114:117], v[180:183], v[188:191], v[114:117]
	v_mfma_f32_16x16x32_bf16 v[102:105], v[172:175], v[196:199], v[102:105]
	v_mfma_f32_16x16x32_bf16 v[98:101], v[180:183], v[196:199], v[98:101]
	v_mfma_f32_16x16x32_bf16 v[86:89], v[172:175], v[204:207], v[86:89]
	v_mfma_f32_16x16x32_bf16 v[82:85], v[180:183], v[204:207], v[82:85]
	v_mfma_f32_16x16x32_bf16 v[70:73], v[172:175], v[212:215], v[70:73]
	v_mfma_f32_16x16x32_bf16 v[66:69], v[180:183], v[212:215], v[66:69]
	s_setprio 2
	s_barrier
	s_add_i32 s33, s56, s46
	v_lshl_add_u64 v[216:217], s[38:39], 0, v[134:135]
	s_mov_b32 m0, s33
	ds_read_b128 v[184:187], v150 offset:16384
	ds_read_b128 v[188:191], v150 offset:17408
	ds_read_b128 v[192:195], v150 offset:18432
	ds_read_b128 v[196:199], v150 offset:19456
	ds_read_b128 v[200:203], v150 offset:20480
	ds_read_b128 v[204:207], v150 offset:21504
	ds_read_b128 v[208:211], v150 offset:22528
	ds_read_b128 v[212:215], v150 offset:23552
	global_load_lds_dwordx4 v[216:217], off
	s_add_i32 m0, s33, 0x2000
	s_add_u32 s70, s38, 0x40000
	v_lshl_add_u64 v[218:219], s[38:39], 0, v[130:131]
	s_addc_u32 s71, s39, 0
	s_add_i32 s33, s57, s46
	global_load_lds_dwordx4 v[218:219], off
	v_lshl_add_u64 v[220:221], s[70:71], 0, v[134:135]
	s_mov_b32 m0, s33
	v_lshl_add_u64 v[222:223], s[40:41], 0, v[132:133]
	global_load_lds_dwordx4 v[220:221], off
	v_lshl_add_u64 v[220:221], s[70:71], 0, v[130:131]
	s_add_i32 m0, s33, 0x2000
	s_nop 0
	global_load_lds_dwordx4 v[220:221], off
	v_lshl_add_u64 v[220:221], s[40:41], 0, v[136:137]
	s_mov_b32 m0, s25
	s_nop 0
	global_load_lds_dwordx4 v[220:221], off
	s_mov_b32 m0, s37
	s_nop 0
	global_load_lds_dwordx4 v[222:223], off
	s_waitcnt vmcnt(8)
	s_waitcnt lgkmcnt(0)
	s_barrier
; #define PG8_STAGE(bufoff, gbase, voff) do { _Pragma("unroll") for (int _i = 0; _i < 2; ++_i) \
;         __builtin_amdgcn_global_load_lds((const unsigned*)((const char*)(gbase) + (voff)[_i]), (LAS unsigned*)(lds + (bufoff) + ldsw + _i * 8192), 16, 0, 0); } while (0)
; #define PG8_LDA(dst, b, h) do { _Pragma("unroll") for (int m = 0; m < 4; ++m) _Pragma("unroll") for (int k = 0; k < 2; ++k) dst[m][k] = *(const LAS bf16x8*)(lds + PG8_SA(b, h) + aoff + m * 2048 + k * 1024); } while (0)
; #define PG8_LDB(dst, b, h) do { _Pragma("unroll") for (int n = 0; n < 2; ++n) _Pragma("unroll") for (int k = 0; k < 2; ++k) dst[n][k] = *(const LAS bf16x8*)(lds + PG8_SB(b, h) + boff + n * 2048 + k * 1024); } while (0)
; #define PG8_MMA(ai, bj, At, Bt) do { __builtin_amdgcn_s_setprio(1); _Pragma("unroll") for (int m = 0; m < 4; ++m) _Pragma("unroll") for (int n = 0; n < 2; ++n) _Pragma("unroll") for (int k = 0; k < 2; ++k) \
;         acc[ai][bj][m][n] = __builtin_amdgcn_mfma_f32_16x16x32_bf16(Bt[n][k], At[m][k], acc[ai][bj][m][n], 0, 0, 0); __builtin_amdgcn_s_setprio(0); } while (0)
; #define PG8_WAIT_V(n) asm volatile("s_waitcnt vmcnt(" #n ")" ::: "memory")
; #define PG8_WAIT_L(n) asm volatile("s_waitcnt lgkmcnt(" #n ")" ::: "memory")
; #define PG8_BAR __builtin_amdgcn_s_barrier()
; #define PG8_SCHED __builtin_amdgcn_sched_barrier(0)
; template <class Epi>
; __device__ __forceinline__ void gemm_phase(LAS unsigned char* lds, const Gemm g, int G, int c, const Epi& E) {
;     ...
;             PG8_WAIT_V(8); PG8_WAIT_L(0); PG8_BAR; PG8_MMA(1, 0, At, B0); PG8_MMA(1, 1, At, B1); PG8_BAR; PG8_SCHED;
;             PG8_LDB(B0, 1, 0); PG8_LDB(B1, 1, 1); PG8_SCHED; PG8_LDA(At, 1, 0); PG8_STAGE(PG8_SA(0, 1), a2 + hstepA, voffA);
;             PG8_WAIT_V(8); PG8_WAIT_L(0); PG8_BAR; PG8_MMA(0, 0, At, B0); PG8_MMA(0, 1, At, B1); PG8_BAR; PG8_SCHED;
	s_setprio 0
	s_waitcnt lgkmcnt(0)
	v_mfma_f32_16x16x32_bf16 v[62:65], v[152:155], v[184:187], v[62:65]
	v_mfma_f32_16x16x32_bf16 v[58:61], v[160:163], v[184:187], v[58:61]
	v_mfma_f32_16x16x32_bf16 v[46:49], v[152:155], v[192:195], v[46:49]
	v_mfma_f32_16x16x32_bf16 v[42:45], v[160:163], v[192:195], v[42:45]
	v_mfma_f32_16x16x32_bf16 v[30:33], v[152:155], v[200:203], v[30:33]
	v_mfma_f32_16x16x32_bf16 v[26:29], v[160:163], v[200:203], v[26:29]
	v_mfma_f32_16x16x32_bf16 v[14:17], v[152:155], v[208:211], v[14:17]
	v_mfma_f32_16x16x32_bf16 v[10:13], v[160:163], v[208:211], v[10:13]
	v_mfma_f32_16x16x32_bf16 v[62:65], v[156:159], v[188:191], v[62:65]
	v_mfma_f32_16x16x32_bf16 v[58:61], v[164:167], v[188:191], v[58:61]
	v_mfma_f32_16x16x32_bf16 v[46:49], v[156:159], v[196:199], v[46:49]
	v_mfma_f32_16x16x32_bf16 v[42:45], v[164:167], v[196:199], v[42:45]
	v_mfma_f32_16x16x32_bf16 v[30:33], v[156:159], v[204:207], v[30:33]
	v_mfma_f32_16x16x32_bf16 v[26:29], v[164:167], v[204:207], v[26:29]
	v_mfma_f32_16x16x32_bf16 v[14:17], v[156:159], v[212:215], v[14:17]
	v_mfma_f32_16x16x32_bf16 v[10:13], v[164:167], v[212:215], v[10:13]
	s_setprio 2
	s_setprio 0
	v_mfma_f32_16x16x32_bf16 v[54:57], v[168:171], v[184:187], v[54:57]
	v_mfma_f32_16x16x32_bf16 v[50:53], v[176:179], v[184:187], v[50:53]
	v_mfma_f32_16x16x32_bf16 v[38:41], v[168:171], v[192:195], v[38:41]
	v_mfma_f32_16x16x32_bf16 v[34:37], v[176:179], v[192:195], v[34:37]
	v_mfma_f32_16x16x32_bf16 v[22:25], v[168:171], v[200:203], v[22:25]
	v_mfma_f32_16x16x32_bf16 v[18:21], v[176:179], v[200:203], v[18:21]
	v_mfma_f32_16x16x32_bf16 v[6:9], v[168:171], v[208:211], v[6:9]
	v_mfma_f32_16x16x32_bf16 v[2:5], v[176:179], v[208:211], v[2:5]
	v_mfma_f32_16x16x32_bf16 v[54:57], v[172:175], v[188:191], v[54:57]
	v_mfma_f32_16x16x32_bf16 v[50:53], v[180:183], v[188:191], v[50:53]
	v_mfma_f32_16x16x32_bf16 v[38:41], v[172:175], v[196:199], v[38:41]
	v_mfma_f32_16x16x32_bf16 v[34:37], v[180:183], v[196:199], v[34:37]
	v_mfma_f32_16x16x32_bf16 v[22:25], v[172:175], v[204:207], v[22:25]
	v_mfma_f32_16x16x32_bf16 v[18:21], v[180:183], v[204:207], v[18:21]
	v_mfma_f32_16x16x32_bf16 v[6:9], v[172:175], v[212:215], v[6:9]
	v_mfma_f32_16x16x32_bf16 v[2:5], v[180:183], v[212:215], v[2:5]
	s_setprio 2
	s_barrier
	s_add_i32 s33, 0, 0x18000
	s_add_i32 s69, 0, 0x1c000
	v_add_u32_e32 v164, s33, v147
	v_add_u32_e32 v180, s69, v147
	ds_read_b128 v[152:155], v164
	ds_read_b128 v[156:159], v164 offset:1024
	ds_read_b128 v[160:163], v164 offset:2048
	ds_read_b128 v[164:167], v164 offset:3072
	ds_read_b128 v[168:171], v180
	ds_read_b128 v[172:175], v180 offset:1024
	ds_read_b128 v[176:179], v180 offset:2048
	ds_read_b128 v[180:183], v180 offset:3072
	s_add_u32 s40, s40, 0x40000
	s_addc_u32 s41, s41, 0
	s_mov_b32 m0, s47
	v_lshl_add_u64 v[224:225], s[40:41], 0, v[136:137]
	ds_read_b128 v[184:187], v150 offset:32768
	ds_read_b128 v[188:191], v150 offset:33792
	ds_read_b128 v[192:195], v150 offset:34816
	ds_read_b128 v[196:199], v150 offset:35840
	ds_read_b128 v[200:203], v150 offset:36864
	ds_read_b128 v[204:207], v150 offset:37888
	ds_read_b128 v[208:211], v150 offset:38912
	ds_read_b128 v[212:215], v150 offset:39936
	global_load_lds_dwordx4 v[224:225], off
	v_lshl_add_u64 v[224:225], s[40:41], 0, v[132:133]
	s_mov_b32 m0, s48
	s_nop 0
	global_load_lds_dwordx4 v[224:225], off
	s_waitcnt vmcnt(8)
	s_waitcnt lgkmcnt(0)
	s_barrier
	s_setprio 0
	s_waitcnt lgkmcnt(0)
	v_mfma_f32_16x16x32_bf16 v[126:129], v[152:155], v[184:187], v[126:129]
	v_mfma_f32_16x16x32_bf16 v[122:125], v[160:163], v[184:187], v[122:125]
	v_mfma_f32_16x16x32_bf16 v[110:113], v[152:155], v[192:195], v[110:113]
	v_mfma_f32_16x16x32_bf16 v[106:109], v[160:163], v[192:195], v[106:109]
	v_mfma_f32_16x16x32_bf16 v[94:97], v[152:155], v[200:203], v[94:97]
	v_mfma_f32_16x16x32_bf16 v[90:93], v[160:163], v[200:203], v[90:93]
	v_mfma_f32_16x16x32_bf16 v[78:81], v[152:155], v[208:211], v[78:81]
	v_mfma_f32_16x16x32_bf16 v[74:77], v[160:163], v[208:211], v[74:77]
	v_mfma_f32_16x16x32_bf16 v[126:129], v[156:159], v[188:191], v[126:129]
	v_mfma_f32_16x16x32_bf16 v[122:125], v[164:167], v[188:191], v[122:125]
	v_mfma_f32_16x16x32_bf16 v[110:113], v[156:159], v[196:199], v[110:113]
	v_mfma_f32_16x16x32_bf16 v[106:109], v[164:167], v[196:199], v[106:109]
	v_mfma_f32_16x16x32_bf16 v[94:97], v[156:159], v[204:207], v[94:97]
	v_mfma_f32_16x16x32_bf16 v[90:93], v[164:167], v[204:207], v[90:93]
	v_mfma_f32_16x16x32_bf16 v[78:81], v[156:159], v[212:215], v[78:81]
	v_mfma_f32_16x16x32_bf16 v[74:77], v[164:167], v[212:215], v[74:77]
	s_setprio 2
	s_setprio 0
	v_mfma_f32_16x16x32_bf16 v[118:121], v[168:171], v[184:187], v[118:121]
	v_mfma_f32_16x16x32_bf16 v[114:117], v[176:179], v[184:187], v[114:117]
	v_mfma_f32_16x16x32_bf16 v[102:105], v[168:171], v[192:195], v[102:105]
	v_mfma_f32_16x16x32_bf16 v[98:101], v[176:179], v[192:195], v[98:101]
	v_mfma_f32_16x16x32_bf16 v[86:89], v[168:171], v[200:203], v[86:89]
	v_mfma_f32_16x16x32_bf16 v[82:85], v[176:179], v[200:203], v[82:85]
	v_mfma_f32_16x16x32_bf16 v[70:73], v[168:171], v[208:211], v[70:73]
	v_mfma_f32_16x16x32_bf16 v[66:69], v[176:179], v[208:211], v[66:69]
	v_mfma_f32_16x16x32_bf16 v[118:121], v[172:175], v[188:191], v[118:121]
	v_mfma_f32_16x16x32_bf16 v[114:117], v[180:183], v[188:191], v[114:117]
	v_mfma_f32_16x16x32_bf16 v[102:105], v[172:175], v[196:199], v[102:105]
	v_mfma_f32_16x16x32_bf16 v[98:101], v[180:183], v[196:199], v[98:101]
	v_mfma_f32_16x16x32_bf16 v[86:89], v[172:175], v[204:207], v[86:89]
	v_mfma_f32_16x16x32_bf16 v[82:85], v[180:183], v[204:207], v[82:85]
	v_mfma_f32_16x16x32_bf16 v[70:73], v[172:175], v[212:215], v[70:73]
	v_mfma_f32_16x16x32_bf16 v[66:69], v[180:183], v[212:215], v[66:69]
	s_setprio 2
	s_barrier
; #define PG8_STAGE(bufoff, gbase, voff) do { _Pragma("unroll") for (int _i = 0; _i < 2; ++_i) \
;         __builtin_amdgcn_global_load_lds((const unsigned*)((const char*)(gbase) + (voff)[_i]), (LAS unsigned*)(lds + (bufoff) + ldsw + _i * 8192), 16, 0, 0); } while (0)
; #define PG8_LDA(dst, b, h) do { _Pragma("unroll") for (int m = 0; m < 4; ++m) _Pragma("unroll") for (int k = 0; k < 2; ++k) dst[m][k] = *(const LAS bf16x8*)(lds + PG8_SA(b, h) + aoff + m * 2048 + k * 1024); } while (0)
; #define PG8_MMA(ai, bj, At, Bt) do { __builtin_amdgcn_s_setprio(1); _Pragma("unroll") for (int m = 0; m < 4; ++m) _Pragma("unroll") for (int n = 0; n < 2; ++n) _Pragma("unroll") for (int k = 0; k < 2; ++k) \
;         acc[ai][bj][m][n] = __builtin_amdgcn_mfma_f32_16x16x32_bf16(Bt[n][k], At[m][k], acc[ai][bj][m][n], 0, 0, 0); __builtin_amdgcn_s_setprio(0); } while (0)
; #define PG8_WAIT_V(n) asm volatile("s_waitcnt vmcnt(" #n ")" ::: "memory")
; #define PG8_WAIT_L(n) asm volatile("s_waitcnt lgkmcnt(" #n ")" ::: "memory")
; #define PG8_BAR __builtin_amdgcn_s_barrier()
; #define PG8_SCHED __builtin_amdgcn_sched_barrier(0)
; template <class Epi>
; __device__ __forceinline__ void gemm_phase(LAS unsigned char* lds, const Gemm g, int G, int c, const Epi& E) {
;     ...
;             PG8_LDA(At, 1, 1); PG8_STAGE(PG8_SB(1, 0), b3, voffB); PG8_STAGE(PG8_SB(1, 1), b3 + hstepB, voffB); PG8_STAGE(PG8_SA(1, 0), a3, voffA);
;             PG8_WAIT_V(8); PG8_WAIT_L(0); PG8_BAR; PG8_MMA(1, 0, At, B0); PG8_MMA(1, 1, At, B1); PG8_BAR; PG8_SCHED;
;         }
;         if (wr == 0) PG8_BAR;
	s_add_i32 s33, s33, s46
	v_lshl_add_u64 v[216:217], v[216:217], 0, s[12:13]
	s_mov_b32 m0, s33
	ds_read_b128 v[184:187], v150 offset:49152
	ds_read_b128 v[188:191], v150 offset:50176
	ds_read_b128 v[192:195], v150 offset:51200
	ds_read_b128 v[196:199], v150 offset:52224
	ds_read_b128 v[200:203], v150 offset:53248
	ds_read_b128 v[204:207], v150 offset:54272
	ds_read_b128 v[208:211], v150 offset:55296
	ds_read_b128 v[212:215], v150 offset:56320
	global_load_lds_dwordx4 v[216:217], off
	s_add_i32 m0, s33, 0x2000
	s_add_u32 s38, s38, 0x40080
	v_lshl_add_u64 v[216:217], v[218:219], 0, s[12:13]
	s_addc_u32 s39, s39, 0
	s_add_i32 s33, s69, s46
	global_load_lds_dwordx4 v[216:217], off
	v_lshl_add_u64 v[216:217], s[38:39], 0, v[134:135]
	s_mov_b32 m0, s33
	s_nop 0
	global_load_lds_dwordx4 v[216:217], off
	v_lshl_add_u64 v[216:217], s[38:39], 0, v[130:131]
	s_add_i32 m0, s33, 0x2000
	s_nop 0
	global_load_lds_dwordx4 v[216:217], off
	v_lshl_add_u64 v[216:217], v[220:221], 0, s[12:13]
	s_mov_b32 m0, s53
	s_nop 0
	global_load_lds_dwordx4 v[216:217], off
	v_lshl_add_u64 v[216:217], v[222:223], 0, s[12:13]
	s_mov_b32 m0, s54
	s_nop 0
	global_load_lds_dwordx4 v[216:217], off
	s_waitcnt vmcnt(8)
	s_waitcnt lgkmcnt(0)
	s_barrier
	s_setprio 0
	s_waitcnt lgkmcnt(0)
	v_mfma_f32_16x16x32_bf16 v[62:65], v[152:155], v[184:187], v[62:65]
	v_mfma_f32_16x16x32_bf16 v[58:61], v[160:163], v[184:187], v[58:61]
	v_mfma_f32_16x16x32_bf16 v[46:49], v[152:155], v[192:195], v[46:49]
	v_mfma_f32_16x16x32_bf16 v[42:45], v[160:163], v[192:195], v[42:45]
	v_mfma_f32_16x16x32_bf16 v[30:33], v[152:155], v[200:203], v[30:33]
	v_mfma_f32_16x16x32_bf16 v[26:29], v[160:163], v[200:203], v[26:29]
	v_mfma_f32_16x16x32_bf16 v[14:17], v[152:155], v[208:211], v[14:17]
	v_mfma_f32_16x16x32_bf16 v[10:13], v[160:163], v[208:211], v[10:13]
	v_mfma_f32_16x16x32_bf16 v[62:65], v[156:159], v[188:191], v[62:65]
	v_mfma_f32_16x16x32_bf16 v[58:61], v[164:167], v[188:191], v[58:61]
	v_mfma_f32_16x16x32_bf16 v[46:49], v[156:159], v[196:199], v[46:49]
	v_mfma_f32_16x16x32_bf16 v[42:45], v[164:167], v[196:199], v[42:45]
	v_mfma_f32_16x16x32_bf16 v[30:33], v[156:159], v[204:207], v[30:33]
	v_mfma_f32_16x16x32_bf16 v[26:29], v[164:167], v[204:207], v[26:29]
	v_mfma_f32_16x16x32_bf16 v[14:17], v[156:159], v[212:215], v[14:17]
	v_mfma_f32_16x16x32_bf16 v[10:13], v[164:167], v[212:215], v[10:13]
	s_setprio 2
	s_setprio 0
	v_mfma_f32_16x16x32_bf16 v[54:57], v[168:171], v[184:187], v[54:57]
	v_mfma_f32_16x16x32_bf16 v[50:53], v[176:179], v[184:187], v[50:53]
	v_mfma_f32_16x16x32_bf16 v[38:41], v[168:171], v[192:195], v[38:41]
	v_mfma_f32_16x16x32_bf16 v[34:37], v[176:179], v[192:195], v[34:37]
	v_mfma_f32_16x16x32_bf16 v[22:25], v[168:171], v[200:203], v[22:25]
	v_mfma_f32_16x16x32_bf16 v[18:21], v[176:179], v[200:203], v[18:21]
	v_mfma_f32_16x16x32_bf16 v[6:9], v[168:171], v[208:211], v[6:9]
	v_mfma_f32_16x16x32_bf16 v[2:5], v[176:179], v[208:211], v[2:5]
	v_mfma_f32_16x16x32_bf16 v[54:57], v[172:175], v[188:191], v[54:57]
	v_mfma_f32_16x16x32_bf16 v[50:53], v[180:183], v[188:191], v[50:53]
	v_mfma_f32_16x16x32_bf16 v[38:41], v[172:175], v[196:199], v[38:41]
	v_mfma_f32_16x16x32_bf16 v[34:37], v[180:183], v[196:199], v[34:37]
	v_mfma_f32_16x16x32_bf16 v[22:25], v[172:175], v[204:207], v[22:25]
	v_mfma_f32_16x16x32_bf16 v[18:21], v[180:183], v[204:207], v[18:21]
	v_mfma_f32_16x16x32_bf16 v[6:9], v[172:175], v[212:215], v[6:9]
	v_mfma_f32_16x16x32_bf16 v[2:5], v[180:183], v[212:215], v[2:5]
	s_setprio 2
	s_barrier
	s_add_i32 s68, s68, 2
	s_add_u32 s4, s4, 0x100
	s_addc_u32 s5, s5, 0
	s_add_u32 s66, s66, 0x100
	s_addc_u32 s67, s67, 0
	s_cmp_gt_u32 s68, 13
	s_cbranch_scc0 .LBB0_2084
	s_and_b64 vcc, exec, s[14:15]
	s_cbranch_vccz .LBB0_2087
	s_barrier

; #define PG8_STAGE(bufoff, gbase, voff) do { _Pragma("unroll") for (int _i = 0; _i < 2; ++_i) \
;         __builtin_amdgcn_global_load_lds((const unsigned*)((const char*)(gbase) + (voff)[_i]), (LAS unsigned*)(lds + (bufoff) + ldsw + _i * 8192), 16, 0, 0); } while (0)
; #define PG8_LDA(dst, b, h) do { _Pragma("unroll") for (int m = 0; m < 4; ++m) _Pragma("unroll") for (int k = 0; k < 2; ++k) dst[m][k] = *(const LAS bf16x8*)(lds + PG8_SA(b, h) + aoff + m * 2048 + k * 1024); } while (0)
; #define PG8_LDB(dst, b, h) do { _Pragma("unroll") for (int n = 0; n < 2; ++n) _Pragma("unroll") for (int k = 0; k < 2; ++k) dst[n][k] = *(const LAS bf16x8*)(lds + PG8_SB(b, h) + boff + n * 2048 + k * 1024); } while (0)
; #define PG8_MMA(ai, bj, At, Bt) do { __builtin_amdgcn_s_setprio(1); _Pragma("unroll") for (int m = 0; m < 4; ++m) _Pragma("unroll") for (int n = 0; n < 2; ++n) _Pragma("unroll") for (int k = 0; k < 2; ++k) \
;         acc[ai][bj][m][n] = __builtin_amdgcn_mfma_f32_16x16x32_bf16(Bt[n][k], At[m][k], acc[ai][bj][m][n], 0, 0, 0); __builtin_amdgcn_s_setprio(0); } while (0)
; #define PG8_WAIT_V(n) asm volatile("s_waitcnt vmcnt(" #n ")" ::: "memory")
; #define PG8_WAIT_L(n) asm volatile("s_waitcnt lgkmcnt(" #n ")" ::: "memory")
; #define PG8_BAR __builtin_amdgcn_s_barrier()
; #define PG8_SCHED __builtin_amdgcn_sched_barrier(0)
; template <class Epi>
; __device__ __forceinline__ void gemm_phase(LAS unsigned char* lds, const Gemm g, int G, int c, const Epi& E) {
;     ...
;         for (int t = 0; t < nt; t += 2) {
;             const bool last = (t == nt - 2);
;             const char* a1 = cA + (size_t)(t + 1) * kstep;
;             const char* a2 = last ? nA : cA + (size_t)(t + 2) * kstep; const char* b2 = last ? nB : cB + (size_t)(t + 2) * kstep;
;             const char* a3 = a2 + kstep; const char* b3 = b2 + kstep;
;             PG8_LDB(B0, 0, 0); PG8_LDB(B1, 0, 1); PG8_SCHED; PG8_LDA(At, 0, 0); PG8_STAGE(PG8_SA(1, 1), a1 + hstepA, voffA);
;             PG8_WAIT_V(8); PG8_WAIT_L(0); PG8_BAR; PG8_MMA(0, 0, At, B0); PG8_MMA(0, 1, At, B1); PG8_BAR; PG8_SCHED;
;             PG8_LDA(At, 0, 1); PG8_STAGE(PG8_SB(0, 0), b2, voffB); PG8_STAGE(PG8_SB(0, 1), b2 + hstepB, voffB); PG8_STAGE(PG8_SA(0, 0), a2, voffA);
.LBB0_2169:
	ds_read_b128 v[106:109], v168
	ds_read_b128 v[110:113], v168 offset:1024
	ds_read_b128 v[114:117], v168 offset:2048
	ds_read_b128 v[118:121], v168 offset:3072
	ds_read_b128 v[162:165], v169
	ds_read_b128 v[172:175], v169 offset:1024
	ds_read_b128 v[176:179], v169 offset:2048
	ds_read_b128 v[180:183], v169 offset:3072
	s_add_u32 s20, s18, 0x100
	s_addc_u32 s21, s19, 0
	s_cmp_eq_u32 s62, 40
	s_cselect_b32 s25, s5, s21
	s_cselect_b32 s24, s4, s20
	s_cselect_b32 s23, s17, s61
	s_cselect_b32 s22, s16, s60
	v_lshl_add_u64 v[216:217], s[18:19], 0, v[154:155]
	s_add_i32 m0, s40, 0xc000
	ds_read_b128 v[184:187], v170
	ds_read_b128 v[188:191], v170 offset:1024
	ds_read_b128 v[192:195], v170 offset:2048
	ds_read_b128 v[196:199], v170 offset:3072
	ds_read_b128 v[200:203], v170 offset:4096
	ds_read_b128 v[204:207], v170 offset:5120
	ds_read_b128 v[208:211], v170 offset:6144
	ds_read_b128 v[212:215], v170 offset:7168
	global_load_lds_dwordx4 v[216:217], off
	v_lshl_add_u64 v[216:217], s[18:19], 0, v[156:157]
	s_add_i32 m0, s40, 0xe000
	s_nop 0
	global_load_lds_dwordx4 v[216:217], off
	s_waitcnt vmcnt(8)
	s_waitcnt lgkmcnt(0)
	s_barrier
	s_setprio 0
	s_waitcnt lgkmcnt(0)
	v_mfma_f32_16x16x32_bf16 v[142:145], v[106:109], v[184:187], v[142:145]
	v_mfma_f32_16x16x32_bf16 v[138:141], v[114:117], v[184:187], v[138:141]
	v_mfma_f32_16x16x32_bf16 v[126:129], v[106:109], v[192:195], v[126:129]
	v_mfma_f32_16x16x32_bf16 v[122:125], v[114:117], v[192:195], v[122:125]
	v_mfma_f32_16x16x32_bf16 v[94:97], v[106:109], v[200:203], v[94:97]
	v_mfma_f32_16x16x32_bf16 v[90:93], v[114:117], v[200:203], v[90:93]
	v_mfma_f32_16x16x32_bf16 v[78:81], v[106:109], v[208:211], v[78:81]
	v_mfma_f32_16x16x32_bf16 v[74:77], v[114:117], v[208:211], v[74:77]
	v_mfma_f32_16x16x32_bf16 v[142:145], v[110:113], v[188:191], v[142:145]
	v_mfma_f32_16x16x32_bf16 v[138:141], v[118:121], v[188:191], v[138:141]
	v_mfma_f32_16x16x32_bf16 v[126:129], v[110:113], v[196:199], v[126:129]
	v_mfma_f32_16x16x32_bf16 v[122:125], v[118:121], v[196:199], v[122:125]
	v_mfma_f32_16x16x32_bf16 v[94:97], v[110:113], v[204:207], v[94:97]
	v_mfma_f32_16x16x32_bf16 v[90:93], v[118:121], v[204:207], v[90:93]
	v_mfma_f32_16x16x32_bf16 v[78:81], v[110:113], v[212:215], v[78:81]
	v_mfma_f32_16x16x32_bf16 v[74:77], v[118:121], v[212:215], v[74:77]
	s_setprio 2
	s_setprio 0
	v_mfma_f32_16x16x32_bf16 v[134:137], v[162:165], v[184:187], v[134:137]
	v_mfma_f32_16x16x32_bf16 v[130:133], v[176:179], v[184:187], v[130:133]
	v_mfma_f32_16x16x32_bf16 v[102:105], v[162:165], v[192:195], v[102:105]
	v_mfma_f32_16x16x32_bf16 v[98:101], v[176:179], v[192:195], v[98:101]
	v_mfma_f32_16x16x32_bf16 v[86:89], v[162:165], v[200:203], v[86:89]
	v_mfma_f32_16x16x32_bf16 v[82:85], v[176:179], v[200:203], v[82:85]
	v_mfma_f32_16x16x32_bf16 v[70:73], v[162:165], v[208:211], v[70:73]
	v_mfma_f32_16x16x32_bf16 v[66:69], v[176:179], v[208:211], v[66:69]
	v_mfma_f32_16x16x32_bf16 v[134:137], v[172:175], v[188:191], v[134:137]
	v_mfma_f32_16x16x32_bf16 v[130:133], v[180:183], v[188:191], v[130:133]
	v_mfma_f32_16x16x32_bf16 v[102:105], v[172:175], v[196:199], v[102:105]
	v_mfma_f32_16x16x32_bf16 v[98:101], v[180:183], v[196:199], v[98:101]
	v_mfma_f32_16x16x32_bf16 v[86:89], v[172:175], v[204:207], v[86:89]
	v_mfma_f32_16x16x32_bf16 v[82:85], v[180:183], v[204:207], v[82:85]
	v_mfma_f32_16x16x32_bf16 v[70:73], v[172:175], v[212:215], v[70:73]
	v_mfma_f32_16x16x32_bf16 v[66:69], v[180:183], v[212:215], v[66:69]
	s_setprio 2
	s_barrier
	s_add_i32 s18, s52, s38
	v_lshl_add_u64 v[216:217], s[22:23], 0, v[150:151]
	s_mov_b32 m0, s18
	ds_read_b128 v[184:187], v170 offset:16384
	ds_read_b128 v[188:191], v170 offset:17408
	ds_read_b128 v[192:195], v170 offset:18432
	ds_read_b128 v[196:199], v170 offset:19456
	ds_read_b128 v[200:203], v170 offset:20480
	ds_read_b128 v[204:207], v170 offset:21504
	ds_read_b128 v[208:211], v170 offset:22528
	ds_read_b128 v[212:215], v170 offset:23552
	global_load_lds_dwordx4 v[216:217], off
	s_add_i32 m0, s18, 0x2000
	s_add_u32 s18, s22, 0xb0000
	v_lshl_add_u64 v[218:219], s[22:23], 0, v[146:147]
	s_addc_u32 s19, s23, 0
	s_add_i32 s33, s53, s38
	global_load_lds_dwordx4 v[218:219], off
	v_lshl_add_u64 v[220:221], s[18:19], 0, v[150:151]
	s_mov_b32 m0, s33
	v_lshl_add_u64 v[222:223], s[24:25], 0, v[148:149]
	global_load_lds_dwordx4 v[220:221], off
	v_lshl_add_u64 v[220:221], s[18:19], 0, v[146:147]
	s_add_i32 m0, s33, 0x2000
	s_nop 0
	global_load_lds_dwordx4 v[220:221], off
	v_lshl_add_u64 v[220:221], s[24:25], 0, v[152:153]
	s_mov_b32 m0, s40
	s_nop 0
	global_load_lds_dwordx4 v[220:221], off
	s_mov_b32 m0, s41
	s_nop 0
	global_load_lds_dwordx4 v[222:223], off
	s_waitcnt vmcnt(8)
	s_waitcnt lgkmcnt(0)
	s_barrier
; #define PG8_STAGE(bufoff, gbase, voff) do { _Pragma("unroll") for (int _i = 0; _i < 2; ++_i) \
;         __builtin_amdgcn_global_load_lds((const unsigned*)((const char*)(gbase) + (voff)[_i]), (LAS unsigned*)(lds + (bufoff) + ldsw + _i * 8192), 16, 0, 0); } while (0)
; #define PG8_LDA(dst, b, h) do { _Pragma("unroll") for (int m = 0; m < 4; ++m) _Pragma("unroll") for (int k = 0; k < 2; ++k) dst[m][k] = *(const LAS bf16x8*)(lds + PG8_SA(b, h) + aoff + m * 2048 + k * 1024); } while (0)
; #define PG8_LDB(dst, b, h) do { _Pragma("unroll") for (int n = 0; n < 2; ++n) _Pragma("unroll") for (int k = 0; k < 2; ++k) dst[n][k] = *(const LAS bf16x8*)(lds + PG8_SB(b, h) + boff + n * 2048 + k * 1024); } while (0)
; #define PG8_MMA(ai, bj, At, Bt) do { __builtin_amdgcn_s_setprio(1); _Pragma("unroll") for (int m = 0; m < 4; ++m) _Pragma("unroll") for (int n = 0; n < 2; ++n) _Pragma("unroll") for (int k = 0; k < 2; ++k) \
;         acc[ai][bj][m][n] = __builtin_amdgcn_mfma_f32_16x16x32_bf16(Bt[n][k], At[m][k], acc[ai][bj][m][n], 0, 0, 0); __builtin_amdgcn_s_setprio(0); } while (0)
; #define PG8_WAIT_V(n) asm volatile("s_waitcnt vmcnt(" #n ")" ::: "memory")
; #define PG8_WAIT_L(n) asm volatile("s_waitcnt lgkmcnt(" #n ")" ::: "memory")
; #define PG8_BAR __builtin_amdgcn_s_barrier()
; #define PG8_SCHED __builtin_amdgcn_sched_barrier(0)
; template <class Epi>
; __device__ __forceinline__ void gemm_phase(LAS unsigned char* lds, const Gemm g, int G, int c, const Epi& E) {
;     ...
;             PG8_WAIT_V(8); PG8_WAIT_L(0); PG8_BAR; PG8_MMA(1, 0, At, B0); PG8_MMA(1, 1, At, B1); PG8_BAR; PG8_SCHED;
;             PG8_LDB(B0, 1, 0); PG8_LDB(B1, 1, 1); PG8_SCHED; PG8_LDA(At, 1, 0); PG8_STAGE(PG8_SA(0, 1), a2 + hstepA, voffA);
;             PG8_WAIT_V(8); PG8_WAIT_L(0); PG8_BAR; PG8_MMA(0, 0, At, B0); PG8_MMA(0, 1, At, B1); PG8_BAR; PG8_SCHED;
	s_setprio 0
	s_waitcnt lgkmcnt(0)
	v_mfma_f32_16x16x32_bf16 v[62:65], v[106:109], v[184:187], v[62:65]
	v_mfma_f32_16x16x32_bf16 v[58:61], v[114:117], v[184:187], v[58:61]
	v_mfma_f32_16x16x32_bf16 v[46:49], v[106:109], v[192:195], v[46:49]
	v_mfma_f32_16x16x32_bf16 v[42:45], v[114:117], v[192:195], v[42:45]
	v_mfma_f32_16x16x32_bf16 v[30:33], v[106:109], v[200:203], v[30:33]
	v_mfma_f32_16x16x32_bf16 v[26:29], v[114:117], v[200:203], v[26:29]
	v_mfma_f32_16x16x32_bf16 v[14:17], v[106:109], v[208:211], v[14:17]
	v_mfma_f32_16x16x32_bf16 v[10:13], v[114:117], v[208:211], v[10:13]
	v_mfma_f32_16x16x32_bf16 v[62:65], v[110:113], v[188:191], v[62:65]
	v_mfma_f32_16x16x32_bf16 v[58:61], v[118:121], v[188:191], v[58:61]
	v_mfma_f32_16x16x32_bf16 v[46:49], v[110:113], v[196:199], v[46:49]
	v_mfma_f32_16x16x32_bf16 v[42:45], v[118:121], v[196:199], v[42:45]
	v_mfma_f32_16x16x32_bf16 v[30:33], v[110:113], v[204:207], v[30:33]
	v_mfma_f32_16x16x32_bf16 v[26:29], v[118:121], v[204:207], v[26:29]
	v_mfma_f32_16x16x32_bf16 v[14:17], v[110:113], v[212:215], v[14:17]
	v_mfma_f32_16x16x32_bf16 v[10:13], v[118:121], v[212:215], v[10:13]
	s_setprio 2
	s_setprio 0
	v_mfma_f32_16x16x32_bf16 v[54:57], v[162:165], v[184:187], v[54:57]
	v_mfma_f32_16x16x32_bf16 v[50:53], v[176:179], v[184:187], v[50:53]
	v_mfma_f32_16x16x32_bf16 v[38:41], v[162:165], v[192:195], v[38:41]
	v_mfma_f32_16x16x32_bf16 v[34:37], v[176:179], v[192:195], v[34:37]
	v_mfma_f32_16x16x32_bf16 v[22:25], v[162:165], v[200:203], v[22:25]
	v_mfma_f32_16x16x32_bf16 v[18:21], v[176:179], v[200:203], v[18:21]
	v_mfma_f32_16x16x32_bf16 v[6:9], v[162:165], v[208:211], v[6:9]
	v_mfma_f32_16x16x32_bf16 v[2:5], v[176:179], v[208:211], v[2:5]
	v_mfma_f32_16x16x32_bf16 v[54:57], v[172:175], v[188:191], v[54:57]
	v_mfma_f32_16x16x32_bf16 v[50:53], v[180:183], v[188:191], v[50:53]
	v_mfma_f32_16x16x32_bf16 v[38:41], v[172:175], v[196:199], v[38:41]
	v_mfma_f32_16x16x32_bf16 v[34:37], v[180:183], v[196:199], v[34:37]
	v_mfma_f32_16x16x32_bf16 v[22:25], v[172:175], v[204:207], v[22:25]
	v_mfma_f32_16x16x32_bf16 v[18:21], v[180:183], v[204:207], v[18:21]
	v_mfma_f32_16x16x32_bf16 v[6:9], v[172:175], v[212:215], v[6:9]
	v_mfma_f32_16x16x32_bf16 v[2:5], v[180:183], v[212:215], v[2:5]
	s_setprio 2
	s_barrier
	s_add_i32 s33, 0, 0x18000
	s_add_i32 s63, 0, 0x1c000
	v_add_u32_e32 v118, s33, v167
	v_add_u32_e32 v171, s63, v167
	ds_read_b128 v[106:109], v118
	ds_read_b128 v[110:113], v118 offset:1024
	ds_read_b128 v[114:117], v118 offset:2048
	ds_read_b128 v[118:121], v118 offset:3072
	ds_read_b128 v[162:165], v171
	ds_read_b128 v[172:175], v171 offset:1024
	ds_read_b128 v[176:179], v171 offset:2048
	ds_read_b128 v[180:183], v171 offset:3072
	s_add_u32 s18, s24, 0xb0000
	s_addc_u32 s19, s25, 0
	s_mov_b32 m0, s42
	v_lshl_add_u64 v[224:225], s[18:19], 0, v[152:153]
	ds_read_b128 v[184:187], v170 offset:32768
	ds_read_b128 v[188:191], v170 offset:33792
	ds_read_b128 v[192:195], v170 offset:34816
	ds_read_b128 v[196:199], v170 offset:35840
	ds_read_b128 v[200:203], v170 offset:36864
	ds_read_b128 v[204:207], v170 offset:37888
	ds_read_b128 v[208:211], v170 offset:38912
	ds_read_b128 v[212:215], v170 offset:39936
	global_load_lds_dwordx4 v[224:225], off
	v_lshl_add_u64 v[224:225], s[18:19], 0, v[148:149]
	s_mov_b32 m0, s43
	s_nop 0
	global_load_lds_dwordx4 v[224:225], off
	s_waitcnt vmcnt(8)
	s_waitcnt lgkmcnt(0)
	s_barrier
	s_setprio 0
	s_waitcnt lgkmcnt(0)
	v_mfma_f32_16x16x32_bf16 v[142:145], v[106:109], v[184:187], v[142:145]
	v_mfma_f32_16x16x32_bf16 v[138:141], v[114:117], v[184:187], v[138:141]
	v_mfma_f32_16x16x32_bf16 v[126:129], v[106:109], v[192:195], v[126:129]
	v_mfma_f32_16x16x32_bf16 v[122:125], v[114:117], v[192:195], v[122:125]
	v_mfma_f32_16x16x32_bf16 v[94:97], v[106:109], v[200:203], v[94:97]
	v_mfma_f32_16x16x32_bf16 v[90:93], v[114:117], v[200:203], v[90:93]
	v_mfma_f32_16x16x32_bf16 v[78:81], v[106:109], v[208:211], v[78:81]
	v_mfma_f32_16x16x32_bf16 v[74:77], v[114:117], v[208:211], v[74:77]
	v_mfma_f32_16x16x32_bf16 v[142:145], v[110:113], v[188:191], v[142:145]
	v_mfma_f32_16x16x32_bf16 v[138:141], v[118:121], v[188:191], v[138:141]
	v_mfma_f32_16x16x32_bf16 v[126:129], v[110:113], v[196:199], v[126:129]
	v_mfma_f32_16x16x32_bf16 v[122:125], v[118:121], v[196:199], v[122:125]
	v_mfma_f32_16x16x32_bf16 v[94:97], v[110:113], v[204:207], v[94:97]
	v_mfma_f32_16x16x32_bf16 v[90:93], v[118:121], v[204:207], v[90:93]
	v_mfma_f32_16x16x32_bf16 v[78:81], v[110:113], v[212:215], v[78:81]
	v_mfma_f32_16x16x32_bf16 v[74:77], v[118:121], v[212:215], v[74:77]
	s_setprio 2
	s_setprio 0
	v_mfma_f32_16x16x32_bf16 v[134:137], v[162:165], v[184:187], v[134:137]
	v_mfma_f32_16x16x32_bf16 v[130:133], v[176:179], v[184:187], v[130:133]
	v_mfma_f32_16x16x32_bf16 v[102:105], v[162:165], v[192:195], v[102:105]
	v_mfma_f32_16x16x32_bf16 v[98:101], v[176:179], v[192:195], v[98:101]
	v_mfma_f32_16x16x32_bf16 v[86:89], v[162:165], v[200:203], v[86:89]
	v_mfma_f32_16x16x32_bf16 v[82:85], v[176:179], v[200:203], v[82:85]
	v_mfma_f32_16x16x32_bf16 v[70:73], v[162:165], v[208:211], v[70:73]
	v_mfma_f32_16x16x32_bf16 v[66:69], v[176:179], v[208:211], v[66:69]
	v_mfma_f32_16x16x32_bf16 v[134:137], v[172:175], v[188:191], v[134:137]
	v_mfma_f32_16x16x32_bf16 v[130:133], v[180:183], v[188:191], v[130:133]
	v_mfma_f32_16x16x32_bf16 v[102:105], v[172:175], v[196:199], v[102:105]
	v_mfma_f32_16x16x32_bf16 v[98:101], v[180:183], v[196:199], v[98:101]
	v_mfma_f32_16x16x32_bf16 v[86:89], v[172:175], v[204:207], v[86:89]
	v_mfma_f32_16x16x32_bf16 v[82:85], v[180:183], v[204:207], v[82:85]
	v_mfma_f32_16x16x32_bf16 v[70:73], v[172:175], v[212:215], v[70:73]
	v_mfma_f32_16x16x32_bf16 v[66:69], v[180:183], v[212:215], v[66:69]
	s_setprio 2
	s_barrier
; #define PG8_STAGE(bufoff, gbase, voff) do { _Pragma("unroll") for (int _i = 0; _i < 2; ++_i) \
;         __builtin_amdgcn_global_load_lds((const unsigned*)((const char*)(gbase) + (voff)[_i]), (LAS unsigned*)(lds + (bufoff) + ldsw + _i * 8192), 16, 0, 0); } while (0)
; #define PG8_LDA(dst, b, h) do { _Pragma("unroll") for (int m = 0; m < 4; ++m) _Pragma("unroll") for (int k = 0; k < 2; ++k) dst[m][k] = *(const LAS bf16x8*)(lds + PG8_SA(b, h) + aoff + m * 2048 + k * 1024); } while (0)
; #define PG8_MMA(ai, bj, At, Bt) do { __builtin_amdgcn_s_setprio(1); _Pragma("unroll") for (int m = 0; m < 4; ++m) _Pragma("unroll") for (int n = 0; n < 2; ++n) _Pragma("unroll") for (int k = 0; k < 2; ++k) \
;         acc[ai][bj][m][n] = __builtin_amdgcn_mfma_f32_16x16x32_bf16(Bt[n][k], At[m][k], acc[ai][bj][m][n], 0, 0, 0); __builtin_amdgcn_s_setprio(0); } while (0)
; #define PG8_WAIT_V(n) asm volatile("s_waitcnt vmcnt(" #n ")" ::: "memory")
; #define PG8_WAIT_L(n) asm volatile("s_waitcnt lgkmcnt(" #n ")" ::: "memory")
; #define PG8_BAR __builtin_amdgcn_s_barrier()
; #define PG8_SCHED __builtin_amdgcn_sched_barrier(0)
; template <class Epi>
; __device__ __forceinline__ void gemm_phase(LAS unsigned char* lds, const Gemm g, int G, int c, const Epi& E) {
;     ...
;             PG8_LDA(At, 1, 1); PG8_STAGE(PG8_SB(1, 0), b3, voffB); PG8_STAGE(PG8_SB(1, 1), b3 + hstepB, voffB); PG8_STAGE(PG8_SA(1, 0), a3, voffA);
;             PG8_WAIT_V(8); PG8_WAIT_L(0); PG8_BAR; PG8_MMA(1, 0, At, B0); PG8_MMA(1, 1, At, B1); PG8_BAR; PG8_SCHED;
	s_add_i32 s18, s33, s38
	v_lshl_add_u64 v[216:217], v[216:217], 0, s[12:13]
	s_mov_b32 m0, s18
	ds_read_b128 v[184:187], v170 offset:49152
	ds_read_b128 v[188:191], v170 offset:50176
	ds_read_b128 v[192:195], v170 offset:51200
	ds_read_b128 v[196:199], v170 offset:52224
	ds_read_b128 v[200:203], v170 offset:53248
	ds_read_b128 v[204:207], v170 offset:54272
	ds_read_b128 v[208:211], v170 offset:55296
	ds_read_b128 v[212:215], v170 offset:56320
	global_load_lds_dwordx4 v[216:217], off
	s_add_i32 m0, s18, 0x2000
	s_add_u32 s18, s22, 0xb0080
	v_lshl_add_u64 v[216:217], v[218:219], 0, s[12:13]
	s_addc_u32 s19, s23, 0
	s_add_i32 s22, s63, s38
	global_load_lds_dwordx4 v[216:217], off
	v_lshl_add_u64 v[216:217], s[18:19], 0, v[150:151]
	s_mov_b32 m0, s22
	s_nop 0
	global_load_lds_dwordx4 v[216:217], off
	v_lshl_add_u64 v[216:217], s[18:19], 0, v[146:147]
	s_add_i32 m0, s22, 0x2000
	s_nop 0
	global_load_lds_dwordx4 v[216:217], off
	v_lshl_add_u64 v[216:217], v[220:221], 0, s[12:13]
	s_mov_b32 m0, s49
	s_nop 0
	global_load_lds_dwordx4 v[216:217], off
	v_lshl_add_u64 v[216:217], v[222:223], 0, s[12:13]
	s_mov_b32 m0, s50
	s_nop 0
	global_load_lds_dwordx4 v[216:217], off
	s_waitcnt vmcnt(8)
	s_waitcnt lgkmcnt(0)
	s_barrier
	s_setprio 0
	s_waitcnt lgkmcnt(0)
	v_mfma_f32_16x16x32_bf16 v[62:65], v[106:109], v[184:187], v[62:65]
	v_mfma_f32_16x16x32_bf16 v[58:61], v[114:117], v[184:187], v[58:61]
	v_mfma_f32_16x16x32_bf16 v[46:49], v[106:109], v[192:195], v[46:49]
	v_mfma_f32_16x16x32_bf16 v[42:45], v[114:117], v[192:195], v[42:45]
	v_mfma_f32_16x16x32_bf16 v[30:33], v[106:109], v[200:203], v[30:33]
	v_mfma_f32_16x16x32_bf16 v[26:29], v[114:117], v[200:203], v[26:29]
	v_mfma_f32_16x16x32_bf16 v[14:17], v[106:109], v[208:211], v[14:17]
	v_mfma_f32_16x16x32_bf16 v[10:13], v[114:117], v[208:211], v[10:13]
	v_mfma_f32_16x16x32_bf16 v[62:65], v[110:113], v[188:191], v[62:65]
	v_mfma_f32_16x16x32_bf16 v[58:61], v[118:121], v[188:191], v[58:61]
	v_mfma_f32_16x16x32_bf16 v[46:49], v[110:113], v[196:199], v[46:49]
	v_mfma_f32_16x16x32_bf16 v[42:45], v[118:121], v[196:199], v[42:45]
	v_mfma_f32_16x16x32_bf16 v[30:33], v[110:113], v[204:207], v[30:33]
	v_mfma_f32_16x16x32_bf16 v[26:29], v[118:121], v[204:207], v[26:29]
	v_mfma_f32_16x16x32_bf16 v[14:17], v[110:113], v[212:215], v[14:17]
	v_mfma_f32_16x16x32_bf16 v[10:13], v[118:121], v[212:215], v[10:13]
	s_setprio 2
	s_setprio 0
	v_mfma_f32_16x16x32_bf16 v[54:57], v[162:165], v[184:187], v[54:57]
	v_mfma_f32_16x16x32_bf16 v[50:53], v[176:179], v[184:187], v[50:53]
	v_mfma_f32_16x16x32_bf16 v[38:41], v[162:165], v[192:195], v[38:41]
	v_mfma_f32_16x16x32_bf16 v[34:37], v[176:179], v[192:195], v[34:37]
	v_mfma_f32_16x16x32_bf16 v[22:25], v[162:165], v[200:203], v[22:25]
	v_mfma_f32_16x16x32_bf16 v[18:21], v[176:179], v[200:203], v[18:21]
	v_mfma_f32_16x16x32_bf16 v[6:9], v[162:165], v[208:211], v[6:9]
	v_mfma_f32_16x16x32_bf16 v[2:5], v[176:179], v[208:211], v[2:5]
	v_mfma_f32_16x16x32_bf16 v[54:57], v[172:175], v[188:191], v[54:57]
	v_mfma_f32_16x16x32_bf16 v[50:53], v[180:183], v[188:191], v[50:53]
	v_mfma_f32_16x16x32_bf16 v[38:41], v[172:175], v[196:199], v[38:41]
	v_mfma_f32_16x16x32_bf16 v[34:37], v[180:183], v[196:199], v[34:37]
	v_mfma_f32_16x16x32_bf16 v[22:25], v[172:175], v[204:207], v[22:25]
	v_mfma_f32_16x16x32_bf16 v[18:21], v[180:183], v[204:207], v[18:21]
	v_mfma_f32_16x16x32_bf16 v[6:9], v[172:175], v[212:215], v[6:9]
	v_mfma_f32_16x16x32_bf16 v[2:5], v[180:183], v[212:215], v[2:5]
	s_setprio 2
	s_barrier
	s_add_i32 s62, s62, 2
	s_add_u32 s60, s60, 0x100
	s_addc_u32 s61, s61, 0
	s_cmp_gt_u32 s62, 41
	s_mov_b64 s[18:19], s[20:21]
	s_cbranch_scc0 .LBB0_2169
	s_and_b64 vcc, exec, s[14:15]
	s_cbranch_vccz .LBB0_2172
	s_barrier
